# GEMM loop: one LDS write + trailing global load per MFMA gap; attnC: LDS fragment prefetch via AGPR pool, accumulators kept resident (S tiles in VGPRs); gla_gates: hoisted LDS reads, f32 Kahan log1p
# speedup vs baseline: 1.0514x; 1.0514x over previous
.LBB0_273:
	s_and_b32 s7, s6, 1
	s_mul_i32 s14, s7, 0xd800
	s_xor_b32 s7, s7, 1
	s_mul_i32 s7, s7, 0xd800
	s_add_i32 s6, s6, 1
	v_add_u32_e32 v186, s7, v146
	ds_read_b128 v[12:15], v189 offset:32
	ds_read_b128 v[24:27], v187 offset:36896
	ds_read_b128 v[16:19], v189 offset:4640
	ds_read_b128 v[28:31], v187 offset:41504
	ds_read_b128 v[20:23], v189 offset:9248
	ds_read_b128 v[48:51], v188 offset:32
	s_waitcnt lgkmcnt(6)
	v_mfma_f32_32x32x16_bf16 a[32:47], v[52:55], v[4:7], a[32:47]
	s_waitcnt vmcnt(11)
	ds_write_b128 v186, v[250:253]
	v_mfma_f32_32x32x16_bf16 a[48:63], v[52:55], v[8:11], a[48:63]
	s_waitcnt vmcnt(10)
	ds_write_b128 v186, v[246:249] offset:4608
	global_load_dwordx4 v[250:253], v254, s[100:101] offset:512
	v_mfma_f32_32x32x16_bf16 a[64:79], v[56:59], v[4:7], a[64:79]
	s_waitcnt vmcnt(10)
	ds_write_b128 v186, v[242:245] offset:9216
	global_load_dwordx4 v[246:249], v205, s[100:101] offset:512
	v_mfma_f32_32x32x16_bf16 a[96:111], v[56:59], v[8:11], a[96:111]
	s_waitcnt vmcnt(10)
	ds_write_b128 v186, v[238:241] offset:13824
	global_load_dwordx4 v[242:245], v204, s[100:101] offset:512
	v_mfma_f32_32x32x16_bf16 a[80:95], v[60:63], v[4:7], a[80:95]
	s_waitcnt vmcnt(10)
	ds_write_b128 v186, v[234:237] offset:18432
	global_load_dwordx4 v[238:241], v203, s[100:101] offset:512
	v_mfma_f32_32x32x16_bf16 a[112:127], v[60:63], v[8:11], a[112:127]
	s_waitcnt vmcnt(10)
	ds_write_b128 v186, v[230:233] offset:23040
	global_load_dwordx4 v[234:237], v202, s[100:101] offset:512
	s_waitcnt lgkmcnt(6)
	v_mfma_f32_32x32x16_bf16 a[16:31], v[64:67], v[4:7], a[16:31]
	s_waitcnt vmcnt(10)
	ds_write_b128 v186, v[226:229] offset:27648
	global_load_dwordx4 v[230:233], v201, s[100:101] offset:512
	v_mfma_f32_32x32x16_bf16 a[0:15], v[64:67], v[8:11], a[0:15]
	s_waitcnt vmcnt(10)
	ds_write_b128 v186, v[222:225] offset:32256
	global_load_dwordx4 v[226:229], v200, s[100:101] offset:512
	s_waitcnt lgkmcnt(8)
	ds_read_b128 v[52:55], v189 offset:64
	ds_read_b128 v[4:7], v187 offset:36928
	ds_read_b128 v[56:59], v189 offset:4672
	ds_read_b128 v[8:11], v187 offset:41536
	ds_read_b128 v[60:63], v189 offset:9280
	ds_read_b128 v[64:67], v188 offset:64
	v_mfma_f32_32x32x16_bf16 a[32:47], v[12:15], v[24:27], a[32:47]
	s_waitcnt lgkmcnt(12)
	s_waitcnt vmcnt(10)
	ds_write_b128 v186, v[218:221] offset:36864
	global_load_dwordx4 v[222:225], v199, s[100:101] offset:512
	v_mfma_f32_32x32x16_bf16 a[48:63], v[12:15], v[28:31], a[48:63]
	s_waitcnt lgkmcnt(12)
	s_waitcnt vmcnt(10)
	ds_write_b128 v186, v[214:217] offset:41472
	global_load_dwordx4 v[218:221], v198, s[98:99] offset:256
	v_mfma_f32_32x32x16_bf16 a[64:79], v[16:19], v[24:27], a[64:79]
	s_waitcnt lgkmcnt(12)
	s_waitcnt vmcnt(10)
	ds_write_b128 v186, v[210:213] offset:46080
	global_load_dwordx4 v[214:217], v197, s[98:99] offset:256
	v_mfma_f32_32x32x16_bf16 a[96:111], v[16:19], v[28:31], a[96:111]
	s_waitcnt lgkmcnt(12)
	s_waitcnt vmcnt(10)
	ds_write_b128 v186, v[206:209] offset:50688
	global_load_dwordx4 v[210:213], v196, s[98:99] offset:256
	v_mfma_f32_32x32x16_bf16 a[80:95], v[20:23], v[24:27], a[80:95]
	global_load_dwordx4 v[206:209], v195, s[98:99] offset:256
	s_add_u32 s100, s100, 0x80
	s_addc_u32 s101, s101, 0
	s_add_u32 s98, s98, 0x80
	s_addc_u32 s99, s99, 0
	v_mfma_f32_32x32x16_bf16 a[112:127], v[20:23], v[28:31], a[112:127]
	v_mfma_f32_32x32x16_bf16 a[16:31], v[48:51], v[24:27], a[16:31]
	v_mfma_f32_32x32x16_bf16 a[0:15], v[48:51], v[28:31], a[0:15]
	s_waitcnt lgkmcnt(4)
	ds_read_b128 v[12:15], v189 offset:96
	ds_read_b128 v[24:27], v187 offset:36960
	ds_read_b128 v[16:19], v189 offset:4704
	ds_read_b128 v[28:31], v187 offset:41568
	ds_read_b128 v[20:23], v189 offset:9312
	ds_read_b128 v[48:51], v188 offset:96
	v_mfma_f32_32x32x16_bf16 a[32:47], v[52:55], v[4:7], a[32:47]
	v_mfma_f32_32x32x16_bf16 a[48:63], v[52:55], v[8:11], a[48:63]
	v_mfma_f32_32x32x16_bf16 a[64:79], v[56:59], v[4:7], a[64:79]
	v_mfma_f32_32x32x16_bf16 a[96:111], v[56:59], v[8:11], a[96:111]
	v_mfma_f32_32x32x16_bf16 a[80:95], v[60:63], v[4:7], a[80:95]
	v_mfma_f32_32x32x16_bf16 a[112:127], v[60:63], v[8:11], a[112:127]
	v_mfma_f32_32x32x16_bf16 a[16:31], v[64:67], v[4:7], a[16:31]
	v_mfma_f32_32x32x16_bf16 a[0:15], v[64:67], v[8:11], a[0:15]
	s_waitcnt lgkmcnt(0)
	v_mfma_f32_32x32x16_bf16 a[32:47], v[12:15], v[24:27], a[32:47]
	v_mfma_f32_32x32x16_bf16 a[48:63], v[12:15], v[28:31], a[48:63]
	v_mfma_f32_32x32x16_bf16 a[64:79], v[16:19], v[24:27], a[64:79]
	v_mfma_f32_32x32x16_bf16 a[96:111], v[16:19], v[28:31], a[96:111]
	s_barrier
	v_add_u32_e32 v189, s7, v192
	v_add_u32_e32 v188, s7, v191
	v_add_u32_e32 v187, s7, v190
	ds_read_b128 v[52:55], v189
	ds_read_b128 v[4:7], v187 offset:36864
	ds_read_b128 v[56:59], v189 offset:4608
	ds_read_b128 v[8:11], v187 offset:41472
	ds_read_b128 v[60:63], v189 offset:9216
	ds_read_b128 v[64:67], v188
	v_mfma_f32_32x32x16_bf16 a[80:95], v[20:23], v[24:27], a[80:95]
	v_mfma_f32_32x32x16_bf16 a[112:127], v[20:23], v[28:31], a[112:127]
	v_mfma_f32_32x32x16_bf16 a[16:31], v[48:51], v[24:27], a[16:31]
	v_mfma_f32_32x32x16_bf16 a[0:15], v[48:51], v[28:31], a[0:15]
	s_add_u32 s2, s2, 0x80
	s_addc_u32 s3, s3, 0
	s_cmpk_lg_i32 s2, 0x700
	s_cbranch_scc1 .LBB0_273
	ds_read_b128 v[0:3], v164
	ds_read_b128 v[52:55], v164 offset:4608
	ds_read_b128 v[56:59], v164 offset:9216
	ds_read_b128 v[60:63], v165
	ds_read_b128 v[64:67], v166 offset:36864
	ds_read_b128 v[68:71], v166 offset:41472
	s_waitcnt vmcnt(5)
	s_waitcnt vmcnt(0)
	ds_write_b128 v167, v[250:253] offset:55296
	ds_write_b128 v167, v[246:249] offset:59904
	ds_write_b128 v167, v[242:245] offset:64512
	ds_write_b128 v153, v[238:241] offset:55296
	ds_write_b128 v154, v[234:237] offset:55296
	ds_write_b128 v155, v[230:233] offset:55296
	ds_write_b128 v156, v[226:229] offset:55296
	s_waitcnt vmcnt(3)
	ds_write_b128 v157, v[222:225] offset:55296
	ds_write_b128 v158, v[218:221]
	s_waitcnt vmcnt(2)
	ds_write_b128 v158, v[214:217] offset:4608
	s_waitcnt vmcnt(1)
	ds_write_b128 v158, v[210:213] offset:9216
	s_waitcnt vmcnt(0)
	ds_write_b128 v158, v[206:209] offset:13824
	s_lshl_b32 s23, s97, 8
	s_cmp_gt_u32 s97, 31
	s_waitcnt lgkmcnt(13)
	v_mfma_f32_32x32x16_bf16 a[144:159], v[52:55], v[64:67], a[64:79]
	s_cselect_b64 s[2:3], -1, 0
	s_add_i32 s6, s23, 0xffffe000
	s_lshr_b32 s14, s6, 12
	s_cmp_lt_u32 s97, 32
	s_cselect_b64 s[72:73], -1, 0
	s_and_b64 s[6:7], s[72:73], exec
	s_cselect_b32 s6, 32, 0xf00
	s_waitcnt lgkmcnt(12)
	v_mfma_f32_32x32x16_bf16 a[160:175], v[0:3], v[68:71], a[48:63]
	s_cselect_b32 s25, s97, s14
	s_and_b32 s24, s6, s23
	s_cmp_lg_u32 s9, 5
	s_cselect_b64 s[74:75], -1, 0
	s_mov_b64 s[6:7], -1
	s_and_b64 vcc, exec, s[74:75]
	v_mfma_f32_32x32x16_bf16 a[128:143], v[52:55], v[68:71], a[96:111]
	v_mfma_f32_32x32x16_bf16 a[64:79], v[56:59], v[64:67], a[80:95]
	v_mfma_f32_32x32x16_bf16 a[48:63], v[56:59], v[68:71], a[112:127]
	v_mfma_f32_32x32x16_bf16 a[176:191], v[0:3], v[64:67], a[32:47]
	ds_read_b128 v[0:3], v164 offset:4640
	ds_read_b128 v[4:7], v164 offset:9248
	ds_read_b128 v[8:11], v166 offset:41504
	ds_read_b128 v[12:15], v166 offset:36896
	ds_read_b128 v[16:19], v166 offset:36928
	ds_read_b128 v[20:23], v164 offset:32
	ds_read_b128 v[24:27], v164 offset:64
	v_mfma_f32_32x32x16_bf16 a[32:47], v[60:63], v[64:67], a[16:31]
	v_mfma_f32_32x32x16_bf16 a[16:31], v[60:63], v[68:71], a[0:15]
	s_waitcnt lgkmcnt(3)
	v_mfma_f32_32x32x16_bf16 a[144:159], v[0:3], v[12:15], a[144:159]
	v_mfma_f32_32x32x16_bf16 a[128:143], v[0:3], v[8:11], a[128:143]
	v_mfma_f32_32x32x16_bf16 a[64:79], v[4:7], v[12:15], a[64:79]
	v_mfma_f32_32x32x16_bf16 a[48:63], v[4:7], v[8:11], a[48:63]
	ds_read_b128 v[0:3], v165 offset:32
	ds_read_b128 v[4:7], v165 offset:64
	s_waitcnt lgkmcnt(3)
	v_mfma_f32_32x32x16_bf16 a[176:191], v[20:23], v[12:15], a[176:191]
	v_mfma_f32_32x32x16_bf16 a[160:175], v[20:23], v[8:11], a[160:175]
	s_waitcnt lgkmcnt(1)
	v_mfma_f32_32x32x16_bf16 a[32:47], v[0:3], v[12:15], a[32:47]
	v_mfma_f32_32x32x16_bf16 a[16:31], v[0:3], v[8:11], a[16:31]
	ds_read_b128 v[0:3], v166 offset:41536
	ds_read_b128 v[8:11], v164 offset:9280
	ds_read_b128 v[12:15], v164 offset:4672
	v_mfma_f32_32x32x16_bf16 a[176:191], v[24:27], v[16:19], a[176:191]
	s_waitcnt lgkmcnt(0)
	v_mfma_f32_32x32x16_bf16 a[144:159], v[12:15], v[16:19], a[144:159]
	v_mfma_f32_32x32x16_bf16 a[128:143], v[12:15], v[0:3], a[128:143]
	v_mfma_f32_32x32x16_bf16 a[64:79], v[8:11], v[16:19], a[64:79]
	v_mfma_f32_32x32x16_bf16 a[48:63], v[8:11], v[0:3], a[48:63]
	v_mfma_f32_32x32x16_bf16 a[160:175], v[24:27], v[0:3], a[160:175]
	v_mfma_f32_32x32x16_bf16 a[32:47], v[4:7], v[16:19], a[32:47]
	v_mfma_f32_32x32x16_bf16 a[16:31], v[4:7], v[0:3], a[16:31]
	ds_read_b128 v[0:3], v166 offset:41568
	ds_read_b128 v[4:7], v166 offset:36960
	ds_read_b128 v[8:11], v165 offset:96
	ds_read_b128 v[12:15], v164 offset:9312
	ds_read_b128 v[16:19], v164 offset:4704
	ds_read_b128 v[20:23], v164 offset:96
	s_waitcnt lgkmcnt(0)
	s_barrier
	v_mfma_f32_32x32x16_bf16 a[176:191], v[20:23], v[4:7], a[176:191]
	v_mfma_f32_32x32x16_bf16 a[144:159], v[16:19], v[4:7], a[144:159]
	v_mfma_f32_32x32x16_bf16 a[128:143], v[16:19], v[0:3], a[128:143]
	v_mfma_f32_32x32x16_bf16 a[64:79], v[12:15], v[4:7], a[64:79]
	v_mfma_f32_32x32x16_bf16 a[48:63], v[12:15], v[0:3], a[48:63]
	v_mfma_f32_32x32x16_bf16 a[160:175], v[20:23], v[0:3], a[160:175]
	v_mfma_f32_32x32x16_bf16 a[32:47], v[8:11], v[4:7], a[32:47]
	v_mfma_f32_32x32x16_bf16 a[16:31], v[8:11], v[0:3], a[16:31]
	ds_read_b128 v[0:3], v164 offset:59904
	ds_read_b128 v[4:7], v164 offset:64512
	ds_read_b128 v[8:11], v159 offset:4608
	ds_read_b128 v[12:15], v164 offset:55296
	ds_read_b128 v[16:19], v164 offset:55328
	ds_read_b128 v[20:23], v159
	ds_read_b128 v[24:27], v159 offset:32
	s_waitcnt lgkmcnt(1)
	v_mfma_f32_32x32x16_bf16 a[176:191], v[12:15], v[20:23], a[176:191]
	v_mfma_f32_32x32x16_bf16 a[144:159], v[0:3], v[20:23], a[144:159]
	v_mfma_f32_32x32x16_bf16 a[128:143], v[0:3], v[8:11], a[128:143]
	v_mfma_f32_32x32x16_bf16 a[64:79], v[4:7], v[20:23], a[64:79]
	v_mfma_f32_32x32x16_bf16 a[48:63], v[4:7], v[8:11], a[48:63]
	ds_read_b128 v[0:3], v165 offset:55296
	ds_read_b128 v[4:7], v165 offset:55328
	v_mfma_f32_32x32x16_bf16 a[160:175], v[12:15], v[8:11], a[160:175]
	s_waitcnt lgkmcnt(1)
	v_mfma_f32_32x32x16_bf16 a[32:47], v[0:3], v[20:23], a[32:47]
	v_mfma_f32_32x32x16_bf16 a[16:31], v[0:3], v[8:11], a[16:31]
	ds_read_b128 v[0:3], v164 offset:64544
	ds_read_b128 v[8:11], v164 offset:59936
	ds_read_b128 v[12:15], v159 offset:4640
	v_mfma_f32_32x32x16_bf16 a[176:191], v[16:19], v[24:27], a[176:191]
	s_waitcnt lgkmcnt(0)
	v_mfma_f32_32x32x16_bf16 a[160:175], v[16:19], v[12:15], a[160:175]
	v_mfma_f32_32x32x16_bf16 a[144:159], v[8:11], v[24:27], a[144:159]
	v_mfma_f32_32x32x16_bf16 a[128:143], v[8:11], v[12:15], a[128:143]
	v_mfma_f32_32x32x16_bf16 a[64:79], v[0:3], v[24:27], a[64:79]
	v_mfma_f32_32x32x16_bf16 a[48:63], v[0:3], v[12:15], a[48:63]
	v_mfma_f32_32x32x16_bf16 a[32:47], v[4:7], v[24:27], a[32:47]
	v_mfma_f32_32x32x16_bf16 a[16:31], v[4:7], v[12:15], a[16:31]
	ds_read_b128 v[0:3], v165 offset:55360
	ds_read_b128 v[4:7], v164 offset:64576
	ds_read_b128 v[8:11], v164 offset:59968
	ds_read_b128 v[12:15], v164 offset:55360
	ds_read_b128 v[16:19], v159 offset:64
	ds_read_b128 v[20:23], v159 offset:4672
	s_waitcnt lgkmcnt(1)
	v_mfma_f32_32x32x16_bf16 a[176:191], v[12:15], v[16:19], a[176:191]
	s_waitcnt lgkmcnt(0)
	v_mfma_f32_32x32x16_bf16 a[160:175], v[12:15], v[20:23], a[160:175]
	v_mfma_f32_32x32x16_bf16 a[144:159], v[8:11], v[16:19], a[144:159]
	v_mfma_f32_32x32x16_bf16 a[128:143], v[8:11], v[20:23], a[128:143]
	v_mfma_f32_32x32x16_bf16 a[64:79], v[4:7], v[16:19], a[64:79]
	v_mfma_f32_32x32x16_bf16 a[48:63], v[4:7], v[20:23], a[48:63]
	v_mfma_f32_32x32x16_bf16 a[32:47], v[0:3], v[16:19], a[32:47]
	v_mfma_f32_32x32x16_bf16 a[16:31], v[0:3], v[20:23], a[16:31]
	ds_read_b128 v[0:3], v165 offset:55392
	ds_read_b128 v[4:7], v164 offset:64608
	ds_read_b128 v[8:11], v164 offset:60000
	ds_read_b128 v[12:15], v164 offset:55392
	ds_read_b128 v[16:19], v159 offset:96
	ds_read_b128 v[20:23], v159 offset:4704
	s_waitcnt lgkmcnt(0)
	s_barrier
	v_mfma_f32_32x32x16_bf16 a[176:191], v[12:15], v[16:19], a[176:191]
	v_mfma_f32_32x32x16_bf16 a[32:47], v[0:3], v[16:19], a[32:47]
	v_mfma_f32_32x32x16_bf16 a[16:31], v[0:3], v[20:23], a[16:31]
	v_accvgpr_read_b32 v0, a212
	v_lshlrev_b32_e32 v0, 5, v0
	v_lshlrev_b32_e32 v104, 1, v0
	v_mfma_f32_32x32x16_bf16 a[160:175], v[12:15], v[20:23], a[160:175]
	v_mfma_f32_32x32x16_bf16 a[144:159], v[8:11], v[16:19], a[144:159]
	v_mfma_f32_32x32x16_bf16 a[128:143], v[8:11], v[20:23], a[128:143]
	v_mfma_f32_32x32x16_bf16 a[64:79], v[4:7], v[16:19], a[64:79]
	v_mfma_f32_32x32x16_bf16 a[48:63], v[4:7], v[20:23], a[48:63]
	s_nop 1
	ds_write_b32 v152, a176
	ds_write_b32 v152, a177 offset:516
	ds_write_b32 v152, a178 offset:1032
	ds_write_b32 v152, a179 offset:1548
	ds_write_b32 v152, a180 offset:4128
	ds_write_b32 v152, a181 offset:4644
	ds_write_b32 v152, a182 offset:5160
	ds_write_b32 v152, a183 offset:5676
	ds_write_b32 v152, a184 offset:8256
	ds_write_b32 v152, a185 offset:8772
	ds_write_b32 v152, a186 offset:9288
	ds_write_b32 v152, a187 offset:9804
	ds_write_b32 v152, a188 offset:12384
	ds_write_b32 v152, a189 offset:12900
	ds_write_b32 v152, a190 offset:13416
	ds_write_b32 v152, a191 offset:13932
	ds_write_b32 v152, a160 offset:128
	ds_write_b32 v152, a161 offset:644
	ds_write_b32 v152, a162 offset:1160
	ds_write_b32 v152, a163 offset:1676
	ds_write_b32 v152, a164 offset:4256
	ds_write_b32 v152, a165 offset:4772
	ds_write_b32 v152, a166 offset:5288
	ds_write_b32 v152, a167 offset:5804
	ds_write_b32 v152, a168 offset:8384
	ds_write_b32 v152, a169 offset:8900
	ds_write_b32 v152, a170 offset:9416
	ds_write_b32 v152, a171 offset:9932
	ds_write_b32 v152, a172 offset:12512
	ds_write_b32 v152, a173 offset:13028
	ds_write_b32 v152, a174 offset:13544
	ds_write_b32 v152, a175 offset:14060
	ds_write_b32 v152, a144 offset:16512
	ds_write_b32 v152, a145 offset:17028
	ds_write_b32 v152, a146 offset:17544
	ds_write_b32 v152, a147 offset:18060
	ds_write_b32 v152, a148 offset:20640
	ds_write_b32 v152, a149 offset:21156
	ds_write_b32 v152, a150 offset:21672
	ds_write_b32 v152, a151 offset:22188
	ds_write_b32 v152, a152 offset:24768
	ds_write_b32 v152, a153 offset:25284
	ds_write_b32 v152, a154 offset:25800
	ds_write_b32 v152, a155 offset:26316
	ds_write_b32 v152, a156 offset:28896
	ds_write_b32 v152, a157 offset:29412
	ds_write_b32 v152, a158 offset:29928
	ds_write_b32 v152, a159 offset:30444
	ds_write_b32 v152, a128 offset:16640
	ds_write_b32 v152, a129 offset:17156
	ds_write_b32 v152, a130 offset:17672
	ds_write_b32 v152, a131 offset:18188
	ds_write_b32 v152, a132 offset:20768
	ds_write_b32 v152, a133 offset:21284
	ds_write_b32 v152, a134 offset:21800
	ds_write_b32 v152, a135 offset:22316
	ds_write_b32 v152, a136 offset:24896
	ds_write_b32 v152, a137 offset:25412
	ds_write_b32 v152, a138 offset:25928
	ds_write_b32 v152, a139 offset:26444
	ds_write_b32 v152, a140 offset:29024
	ds_write_b32 v152, a141 offset:29540
	ds_write_b32 v152, a142 offset:30056
	ds_write_b32 v152, a143 offset:30572
	ds_write_b32 v152, a64 offset:33024
	ds_write_b32 v152, a65 offset:33540
	ds_write_b32 v152, a66 offset:34056
	ds_write_b32 v152, a67 offset:34572
	ds_write_b32 v152, a68 offset:37152
	ds_write_b32 v152, a69 offset:37668
	ds_write_b32 v152, a70 offset:38184
	ds_write_b32 v152, a71 offset:38700
	ds_write_b32 v152, a72 offset:41280
	ds_write_b32 v152, a73 offset:41796
	ds_write_b32 v152, a74 offset:42312
	ds_write_b32 v152, a75 offset:42828
	ds_write_b32 v152, a76 offset:45408
	ds_write_b32 v152, a77 offset:45924
	ds_write_b32 v152, a78 offset:46440
	ds_write_b32 v152, a79 offset:46956
	ds_write_b32 v152, a48 offset:33152
	ds_write_b32 v152, a49 offset:33668
	ds_write_b32 v152, a50 offset:34184
	ds_write_b32 v152, a51 offset:34700
	ds_write_b32 v152, a52 offset:37280
	ds_write_b32 v152, a53 offset:37796
	ds_write_b32 v152, a54 offset:38312
	ds_write_b32 v152, a55 offset:38828
	ds_write_b32 v152, a56 offset:41408
	ds_write_b32 v152, a57 offset:41924
	ds_write_b32 v152, a58 offset:42440
	ds_write_b32 v152, a59 offset:42956
	ds_write_b32 v152, a60 offset:45536
	ds_write_b32 v152, a61 offset:46052
	ds_write_b32 v152, a62 offset:46568
	ds_write_b32 v152, a63 offset:47084
	ds_write_b32 v152, a32 offset:49536
	ds_write_b32 v152, a33 offset:50052
	ds_write_b32 v152, a34 offset:50568
	ds_write_b32 v152, a35 offset:51084
	ds_write_b32 v152, a36 offset:53664
	ds_write_b32 v152, a37 offset:54180
	ds_write_b32 v152, a38 offset:54696
	ds_write_b32 v152, a39 offset:55212
	ds_write_b32 v152, a40 offset:57792
	ds_write_b32 v152, a41 offset:58308
	ds_write_b32 v152, a42 offset:58824
	ds_write_b32 v152, a43 offset:59340
	ds_write_b32 v152, a44 offset:61920
	ds_write_b32 v152, a45 offset:62436
	ds_write_b32 v152, a46 offset:62952
	ds_write_b32 v152, a47 offset:63468
	ds_write_b32 v152, a16 offset:49664
	ds_write_b32 v152, a17 offset:50180
	ds_write_b32 v152, a18 offset:50696
	ds_write_b32 v152, a19 offset:51212
	ds_write_b32 v152, a20 offset:53792
	ds_write_b32 v152, a21 offset:54308
	ds_write_b32 v152, a22 offset:54824
	ds_write_b32 v152, a23 offset:55340
	ds_write_b32 v152, a24 offset:57920
	ds_write_b32 v152, a25 offset:58436
	ds_write_b32 v152, a26 offset:58952
	ds_write_b32 v152, a27 offset:59468
	ds_write_b32 v152, a28 offset:62048
	ds_write_b32 v152, a29 offset:62564
	ds_write_b32 v152, a30 offset:63080
	ds_write_b32 v152, a31 offset:63596
	s_waitcnt lgkmcnt(0)
	s_barrier
	s_cbranch_vccz .LBB0_313
	s_cmp_eq_u32 s9, 18
	s_cselect_b64 s[76:77], -1, 0
	s_cmp_gt_u32 s9, 3
	s_cselect_b64 s[78:79], -1, 0
	s_cmp_lg_u32 s9, 4
	v_accvgpr_read_b32 v0, a210
	s_cselect_b64 s[80:81], -1, 0
	s_cmp_gt_u32 s9, 7
	v_add_u32_e32 v4, s23, v0
	s_cselect_b64 s[82:83], -1, 0
	s_cmp_gt_u32 s9, 9
	s_cselect_b64 s[84:85], -1, 0
	s_cmp_gt_u32 s9, 13
	v_lshlrev_b32_e32 v80, 7, v4
	s_cselect_b64 s[86:87], -1, 0
	s_cmp_gt_u32 s9, 17
	v_lshl_add_u64 v[106:107], s[18:19], 0, v[80:81]
	v_lshlrev_b32_e32 v80, 10, v4
	v_add_u32_e32 v5, s24, v0
	s_cselect_b64 s[88:89], -1, 0
	v_lshl_add_u64 v[0:1], s[10:11], 0, v[80:81]
	s_lshl_b32 s14, s9, 8
	v_lshl_add_u64 v[2:3], v[0:1], 0, s[14:15]
	v_mov_b32_e32 v105, v81
	v_lshl_add_u64 v[2:3], v[2:3], 0, v[104:105]
	v_lshl_add_u64 v[108:109], v[2:3], 0, s[60:61]
	v_lshl_add_u64 v[110:111], v[2:3], 0, s[62:63]
	v_lshlrev_b32_e32 v2, 9, v4
	v_sub_co_u32_e32 v2, vcc, 0, v2
	s_lshl_b32 s26, s9, 7
	s_nop 0
	v_subb_co_u32_e64 v3, s[6:7], 0, 0, vcc
	v_lshl_add_u64 v[0:1], v[0:1], 0, v[2:3]
	v_lshl_add_u64 v[0:1], v[0:1], 0, s[14:15]
	v_lshl_add_u64 v[0:1], v[0:1], 0, v[104:105]
	v_lshl_add_u64 v[112:113], v[0:1], 0, s[64:65]
	v_lshl_add_u64 v[114:115], v[0:1], 0, s[66:67]
	v_lshrrev_b32_e32 v0, 6, v5
	v_accvgpr_read_b32 v1, a211
	v_cndmask_b32_e64 v0, v1, v0, s[4:5]
	v_lshlrev_b32_e32 v80, 7, v0
	v_lshlrev_b32_e32 v0, 7, v5
	v_mov_b32_e32 v1, v81
	v_lshl_add_u64 v[118:119], v[88:89], 0, v[0:1]
	v_lshl_add_u32 v0, s25, 9, v5
	v_lshlrev_b64 v[0:1], 9, v[0:1]
	v_lshlrev_b32_e32 v2, 11, v4
	v_mov_b32_e32 v3, v81
	v_lshl_add_u64 v[116:117], s[16:17], 0, v[80:81]
	s_lshl_b32 s27, s25, 1
	v_mov_b32_e32 v80, v5
	v_lshl_add_u64 v[120:121], v[90:91], 0, v[2:3]
	v_lshl_add_u64 v[122:123], v[94:95], 0, v[0:1]
	s_mov_b32 s94, 0
	s_mov_b64 s[92:93], -1
	s_mov_b64 s[90:91], 0
	s_branch .LBB0_278

.LBB0_455:
	ds_read2_b32 v[58:59], v54 offset1:1
	ds_read2_b32 a[0:1], v54 offset0:2 offset1:3
	ds_read2_b32 a[2:3], v54 offset0:4 offset1:5
	ds_read2_b32 a[4:5], v54 offset0:6 offset1:7
	ds_read2_b32 a[6:7], v54 offset0:8 offset1:9
	ds_read2_b32 a[8:9], v54 offset0:10 offset1:11
	ds_read2_b32 a[10:11], v54 offset0:12 offset1:13
	ds_read2_b32 a[12:13], v54 offset0:14 offset1:15
	s_mov_b32 s2, 0xbfb8aa3b
	v_add_u32_e32 v56, -1, v56
	s_waitcnt vmcnt(15) lgkmcnt(7)
	v_fma_f32 v57, v48, v58, v47
	s_waitcnt vmcnt(14)
	v_fmac_f32_e32 v57, v49, v59
	s_waitcnt vmcnt(13) lgkmcnt(6)
	v_accvgpr_read_b32 v58, a0
	v_accvgpr_read_b32 v59, a1
	v_fmac_f32_e32 v57, v50, v58
	s_waitcnt vmcnt(12)
	v_fmac_f32_e32 v57, v51, v59
	s_waitcnt vmcnt(11) lgkmcnt(5)
	v_accvgpr_read_b32 v58, a2
	v_accvgpr_read_b32 v59, a3
	v_fmac_f32_e32 v57, v52, v58
	s_waitcnt vmcnt(10)
	v_fmac_f32_e32 v57, v53, v59
	s_waitcnt vmcnt(8) lgkmcnt(4)
	v_accvgpr_read_b32 v58, a4
	v_accvgpr_read_b32 v59, a5
	v_pk_mul_f32 v[58:59], v[36:37], v[58:59]
	s_nop 0
	v_add_f32_e32 v57, v57, v58
	v_add_f32_e32 v57, v57, v59
	s_waitcnt vmcnt(6) lgkmcnt(3)
	v_accvgpr_read_b32 v58, a6
	v_accvgpr_read_b32 v59, a7
	v_pk_mul_f32 v[58:59], v[38:39], v[58:59]
	s_nop 0
	v_add_f32_e32 v57, v57, v58
	v_add_f32_e32 v57, v57, v59
	s_waitcnt vmcnt(4) lgkmcnt(2)
	v_accvgpr_read_b32 v58, a8
	v_accvgpr_read_b32 v59, a9
	v_pk_mul_f32 v[58:59], v[40:41], v[58:59]
	s_nop 0
	v_add_f32_e32 v57, v57, v58
	v_add_f32_e32 v57, v57, v59
	s_waitcnt vmcnt(2) lgkmcnt(1)
	v_accvgpr_read_b32 v58, a10
	v_accvgpr_read_b32 v59, a11
	v_pk_mul_f32 v[58:59], v[42:43], v[58:59]
	s_nop 0
	v_add_f32_e32 v57, v57, v58
	v_add_f32_e32 v57, v57, v59
	v_add_u32_e32 v54, 0x84, v54
	s_waitcnt vmcnt(0) lgkmcnt(0)
	v_accvgpr_read_b32 v58, a12
	v_accvgpr_read_b32 v59, a13
	v_pk_mul_f32 v[58:59], v[44:45], v[58:59]
	s_nop 0
	v_add_f32_e32 v57, v57, v58
	v_add_f32_e32 v57, v57, v59
	v_min_f32_e32 v72, 0, v57
	v_mul_f32_e64 v57, |v57|, s2
	v_exp_f32_e32 v57, v57
	s_mov_b32 s2, 0x3f2aaaab
	s_mov_b32 s2, 0x3f317218
	s_mov_b32 s2, 0x7f800000
	s_mov_b32 s2, 0x33800000
	s_nop 0
	v_add_f32_e32 v60, 1.0, v57
	v_log_f32_e32 v58, v60
	v_add_f32_e32 v61, -1.0, v60
	v_cmp_eq_f32_e32 vcc, 1.0, v60
	v_rcp_f32_e32 v66, v61
	v_mul_f32_e32 v58, 0x3f317218, v58
	v_mul_f32_e32 v66, v57, v66
	s_nop 0
	v_mul_f32_e32 v58, v58, v66
	s_nop 0
	v_cndmask_b32_e32 v57, v58, v57, vcc
	v_sub_f32_e32 v57, v72, v57
	v_mul_f32_e32 v57, 0x3d800000, v57
	v_cmp_eq_u32_e32 vcc, 0, v56
	ds_write_b32 v55, v57
	v_add_u32_e32 v55, 0x104, v55
	s_or_b64 s[64:65], vcc, s[64:65]
	s_andn2_b64 exec, exec, s[64:65]
	s_cbranch_execnz .LBB0_455
	s_or_b64 exec, exec, s[64:65]
	v_cndmask_b32_e64 v36, 0, 1, s[8:9]
	v_cmp_ne_u32_e64 s[8:9], 1, v36
	s_waitcnt lgkmcnt(0)
	s_barrier
	s_and_saveexec_b64 s[64:65], s[4:5]
	s_cbranch_execz .LBB0_461
	s_mov_b64 s[66:67], -1
	s_and_b64 vcc, exec, s[8:9]
	v_add_u32_e32 v36, 0xa600, v169
	v_add_u32_e32 v37, 0xa400, v169
	v_add_u32_e32 v38, 0xa200, v169
	v_add_u32_e32 v39, 0xa000, v169
	v_add_u32_e32 v40, 0x9e00, v169
	v_add_u32_e32 v41, 0x9c00, v169
	v_add_u32_e32 v42, 0x9a00, v169
	v_add_u32_e32 v43, 0x9800, v169
	v_add_u32_e32 v44, 0x9600, v169
	v_add_u32_e32 v45, 0x9400, v169
	v_add_u32_e32 v47, 0x9200, v169
	v_add_u32_e32 v48, 0x9000, v169
	v_add_u32_e32 v49, 0x8e00, v169
	v_add_u32_e32 v50, 0x8c00, v169
	v_add_u32_e32 v51, 0x8a00, v169
	v_add_u32_e32 v52, 0x8800, v169
	v_add_u32_e32 v53, 0x8600, v169
	v_add_u32_e32 v54, 0x8400, v169
	v_add_u32_e32 v55, 0x8200, v169
	v_add_u32_e32 v56, 0x8000, v169
	v_add_u32_e32 v57, 0x7e00, v169
	v_add_u32_e32 v58, 0x7c00, v169
	v_add_u32_e32 v59, 0x7a00, v169
	v_add_u32_e32 v60, 0x7800, v169
	v_add_u32_e32 v61, 0x7600, v169
	v_add_u32_e32 v62, 0x7400, v169
	v_add_u32_e32 v63, 0x7200, v169
	v_add_u32_e32 v64, 0x7000, v169
	v_add_u32_e32 v65, 0x6e00, v169
	v_add_u32_e32 v66, 0x6c00, v169
	v_add_u32_e32 v67, 0x6a00, v169
	v_add_u32_e32 v68, 0x6800, v169
	s_cbranch_vccnz .LBB0_459
	ds_read2_b32 v[70:71], v36 offset0:126 offset1:191
	s_mov_b64 s[66:67], 0
	s_waitcnt lgkmcnt(0)
	v_add_f32_e32 v69, 0, v71
	v_add_f32_e32 v72, v69, v70
	ds_read2_b32 v[70:71], v37 offset0:124 offset1:189
	ds_write2_b32 v36, v72, v69 offset0:126 offset1:191
	s_waitcnt lgkmcnt(1)
	v_add_f32_e32 v69, v72, v71
	v_add_f32_e32 v72, v69, v70
	ds_read2_b32 v[70:71], v38 offset0:122 offset1:187
	ds_write2_b32 v37, v72, v69 offset0:124 offset1:189
	s_waitcnt lgkmcnt(1)
	v_add_f32_e32 v69, v72, v71
	v_add_f32_e32 v72, v69, v70
	ds_read2_b32 v[70:71], v39 offset0:120 offset1:185
	ds_write2_b32 v38, v72, v69 offset0:122 offset1:187
	s_waitcnt lgkmcnt(1)
	v_add_f32_e32 v69, v72, v71
	v_add_f32_e32 v72, v69, v70
	ds_read2_b32 v[70:71], v40 offset0:118 offset1:183
	ds_write2_b32 v39, v72, v69 offset0:120 offset1:185
	s_waitcnt lgkmcnt(1)
	v_add_f32_e32 v69, v72, v71
	v_add_f32_e32 v72, v69, v70
	ds_read2_b32 v[70:71], v41 offset0:116 offset1:181
	ds_write2_b32 v40, v72, v69 offset0:118 offset1:183
	s_waitcnt lgkmcnt(1)
	v_add_f32_e32 v69, v72, v71
	v_add_f32_e32 v72, v69, v70
	ds_read2_b32 v[70:71], v42 offset0:114 offset1:179
	ds_write2_b32 v41, v72, v69 offset0:116 offset1:181
	s_waitcnt lgkmcnt(1)
	v_add_f32_e32 v69, v72, v71
	v_add_f32_e32 v72, v69, v70
	ds_read2_b32 v[70:71], v43 offset0:112 offset1:177
	ds_write2_b32 v42, v72, v69 offset0:114 offset1:179
	s_waitcnt lgkmcnt(1)
	v_add_f32_e32 v69, v72, v71
	v_add_f32_e32 v72, v69, v70
	ds_read2_b32 v[70:71], v44 offset0:110 offset1:175
	ds_write2_b32 v43, v72, v69 offset0:112 offset1:177
	s_waitcnt lgkmcnt(1)
	v_add_f32_e32 v69, v72, v71
	v_add_f32_e32 v72, v69, v70
	ds_read2_b32 v[70:71], v45 offset0:108 offset1:173
	ds_write2_b32 v44, v72, v69 offset0:110 offset1:175
	s_waitcnt lgkmcnt(1)
	v_add_f32_e32 v69, v72, v71
	v_add_f32_e32 v72, v69, v70
	ds_read2_b32 v[70:71], v47 offset0:106 offset1:171
	ds_write2_b32 v45, v72, v69 offset0:108 offset1:173
	s_waitcnt lgkmcnt(1)
	v_add_f32_e32 v69, v72, v71
	v_add_f32_e32 v72, v69, v70
	ds_read2_b32 v[70:71], v48 offset0:104 offset1:169
	ds_write2_b32 v47, v72, v69 offset0:106 offset1:171
	s_waitcnt lgkmcnt(1)
	v_add_f32_e32 v69, v72, v71
	v_add_f32_e32 v72, v69, v70
	ds_read2_b32 v[70:71], v49 offset0:102 offset1:167
	ds_write2_b32 v48, v72, v69 offset0:104 offset1:169
	s_waitcnt lgkmcnt(1)
	v_add_f32_e32 v69, v72, v71
	v_add_f32_e32 v72, v69, v70
	ds_read2_b32 v[70:71], v50 offset0:100 offset1:165
	ds_write2_b32 v49, v72, v69 offset0:102 offset1:167
	s_waitcnt lgkmcnt(1)
	v_add_f32_e32 v69, v72, v71
	v_add_f32_e32 v72, v69, v70
	ds_read2_b32 v[70:71], v51 offset0:98 offset1:163
	ds_write2_b32 v50, v72, v69 offset0:100 offset1:165
	s_waitcnt lgkmcnt(1)
	v_add_f32_e32 v69, v72, v71
	v_add_f32_e32 v72, v69, v70
	ds_read2_b32 v[70:71], v52 offset0:96 offset1:161
	ds_write2_b32 v51, v72, v69 offset0:98 offset1:163
	s_waitcnt lgkmcnt(1)
	v_add_f32_e32 v69, v72, v71
	v_add_f32_e32 v72, v69, v70
	ds_read2_b32 v[70:71], v53 offset0:94 offset1:159
	ds_write2_b32 v52, v72, v69 offset0:96 offset1:161
	s_waitcnt lgkmcnt(1)
	v_add_f32_e32 v69, v72, v71
	v_add_f32_e32 v72, v69, v70
	ds_read2_b32 v[70:71], v54 offset0:92 offset1:157
	ds_write2_b32 v53, v72, v69 offset0:94 offset1:159
	s_waitcnt lgkmcnt(1)
	v_add_f32_e32 v69, v72, v71
	v_add_f32_e32 v72, v69, v70
	ds_read2_b32 v[70:71], v55 offset0:90 offset1:155
	ds_write2_b32 v54, v72, v69 offset0:92 offset1:157
	s_waitcnt lgkmcnt(1)
	v_add_f32_e32 v69, v72, v71
	v_add_f32_e32 v72, v69, v70
	ds_read2_b32 v[70:71], v56 offset0:88 offset1:153
	ds_write2_b32 v55, v72, v69 offset0:90 offset1:155
	s_waitcnt lgkmcnt(1)
	v_add_f32_e32 v69, v72, v71
	v_add_f32_e32 v72, v69, v70
	ds_read2_b32 v[70:71], v57 offset0:86 offset1:151
	ds_write2_b32 v56, v72, v69 offset0:88 offset1:153
	s_waitcnt lgkmcnt(1)
	v_add_f32_e32 v69, v72, v71
	v_add_f32_e32 v72, v69, v70
	ds_read2_b32 v[70:71], v58 offset0:84 offset1:149
	ds_write2_b32 v57, v72, v69 offset0:86 offset1:151
	s_waitcnt lgkmcnt(1)
	v_add_f32_e32 v69, v72, v71
	v_add_f32_e32 v72, v69, v70
	ds_read2_b32 v[70:71], v59 offset0:82 offset1:147
	ds_write2_b32 v58, v72, v69 offset0:84 offset1:149
	s_waitcnt lgkmcnt(1)
	v_add_f32_e32 v69, v72, v71
	v_add_f32_e32 v72, v69, v70
	ds_read2_b32 v[70:71], v60 offset0:80 offset1:145
	ds_write2_b32 v59, v72, v69 offset0:82 offset1:147
	s_waitcnt lgkmcnt(1)
	v_add_f32_e32 v69, v72, v71
	v_add_f32_e32 v72, v69, v70
	ds_read2_b32 v[70:71], v61 offset0:78 offset1:143
	ds_write2_b32 v60, v72, v69 offset0:80 offset1:145
	s_waitcnt lgkmcnt(1)
	v_add_f32_e32 v69, v72, v71
	v_add_f32_e32 v72, v69, v70
	ds_read2_b32 v[70:71], v62 offset0:76 offset1:141
	ds_write2_b32 v61, v72, v69 offset0:78 offset1:143
	s_waitcnt lgkmcnt(1)
	v_add_f32_e32 v69, v72, v71
	v_add_f32_e32 v72, v69, v70
	ds_read2_b32 v[70:71], v63 offset0:74 offset1:139
	ds_write2_b32 v62, v72, v69 offset0:76 offset1:141
	s_waitcnt lgkmcnt(1)
	v_add_f32_e32 v69, v72, v71
	v_add_f32_e32 v72, v69, v70
	ds_read2_b32 v[70:71], v64 offset0:72 offset1:137
	ds_write2_b32 v63, v72, v69 offset0:74 offset1:139
	s_waitcnt lgkmcnt(1)
	v_add_f32_e32 v69, v72, v71
	v_add_f32_e32 v72, v69, v70
	ds_read2_b32 v[70:71], v65 offset0:70 offset1:135
	ds_write2_b32 v64, v72, v69 offset0:72 offset1:137
	s_waitcnt lgkmcnt(1)
	v_add_f32_e32 v69, v72, v71
	v_add_f32_e32 v72, v69, v70
	ds_read2_b32 v[70:71], v66 offset0:68 offset1:133
	ds_write2_b32 v65, v72, v69 offset0:70 offset1:135
	s_waitcnt lgkmcnt(1)
	v_add_f32_e32 v69, v72, v71
	v_add_f32_e32 v72, v69, v70
	ds_read2_b32 v[70:71], v67 offset0:66 offset1:131
	ds_write2_b32 v66, v72, v69 offset0:68 offset1:133
	s_waitcnt lgkmcnt(1)
	v_add_f32_e32 v69, v72, v71
	v_add_f32_e32 v72, v69, v70
	ds_read2_b32 v[70:71], v68 offset0:64 offset1:129
	ds_write2_b32 v67, v72, v69 offset0:66 offset1:131
	s_waitcnt lgkmcnt(1)
	v_add_f32_e32 v69, v72, v71
	v_add_f32_e32 v70, v69, v70
	ds_write2_b32 v68, v70, v69 offset0:64 offset1:129

.LBB0_595:
	ds_read2_b32 v[20:21], v17 offset1:1
	ds_read2_b32 a[0:1], v17 offset0:2 offset1:3
	ds_read2_b32 a[2:3], v17 offset0:4 offset1:5
	ds_read2_b32 a[4:5], v17 offset0:6 offset1:7
	ds_read2_b32 a[6:7], v17 offset0:8 offset1:9
	ds_read2_b32 a[8:9], v17 offset0:10 offset1:11
	ds_read2_b32 a[10:11], v17 offset0:12 offset1:13
	ds_read2_b32 a[12:13], v17 offset0:14 offset1:15
	v_add_u32_e32 v19, 1, v19
	s_waitcnt vmcnt(15) lgkmcnt(7)
	v_fma_f32 v22, v11, v20, v10
	s_waitcnt vmcnt(14)
	v_fmac_f32_e32 v22, v12, v21
	s_waitcnt vmcnt(13) lgkmcnt(6)
	v_accvgpr_read_b32 v20, a0
	v_accvgpr_read_b32 v21, a1
	v_fmac_f32_e32 v22, v13, v20
	s_waitcnt vmcnt(12)
	v_fmac_f32_e32 v22, v14, v21
	s_waitcnt vmcnt(7) lgkmcnt(5)
	v_accvgpr_read_b32 v20, a2
	v_accvgpr_read_b32 v21, a3
	v_fmac_f32_e32 v22, v15, v20
	s_waitcnt vmcnt(6)
	v_fmac_f32_e32 v22, v16, v21
	s_waitcnt vmcnt(4) lgkmcnt(4)
	v_accvgpr_read_b32 v20, a4
	v_accvgpr_read_b32 v21, a5
	v_pk_mul_f32 v[20:21], v[4:5], v[20:21]
	s_nop 0
	v_add_f32_e32 v20, v22, v20
	v_add_f32_e32 v22, v20, v21
	s_waitcnt lgkmcnt(3)
	v_accvgpr_read_b32 v20, a6
	v_accvgpr_read_b32 v21, a7
	v_pk_mul_f32 v[20:21], v[0:1], v[20:21]
	s_nop 0
	v_add_f32_e32 v20, v22, v20
	v_add_f32_e32 v22, v20, v21
	s_waitcnt lgkmcnt(2)
	v_accvgpr_read_b32 v20, a8
	v_accvgpr_read_b32 v21, a9
	v_pk_mul_f32 v[20:21], v[2:3], v[20:21]
	s_nop 0
	v_add_f32_e32 v20, v22, v20
	v_add_f32_e32 v22, v20, v21
	s_waitcnt vmcnt(2) lgkmcnt(1)
	v_accvgpr_read_b32 v20, a10
	v_accvgpr_read_b32 v21, a11
	v_pk_mul_f32 v[20:21], v[6:7], v[20:21]
	s_nop 0
	v_add_f32_e32 v20, v22, v20
	v_add_f32_e32 v22, v20, v21
	v_add_u32_e32 v17, 0x84, v17
	s_waitcnt vmcnt(0) lgkmcnt(0)
	v_accvgpr_read_b32 v20, a12
	v_accvgpr_read_b32 v21, a13
	v_pk_mul_f32 v[20:21], v[8:9], v[20:21]
	s_nop 0
	v_add_f32_e32 v20, v22, v20
	v_add_f32_e32 v20, v20, v21
	v_min_f32_e32 v34, 0, v20
	v_mul_f32_e64 v20, |v20|, s12
	v_exp_f32_e32 v35, v20
	s_nop 0
	v_add_f32_e32 v22, 1.0, v35
	v_log_f32_e32 v21, v22
	v_add_f32_e32 v23, -1.0, v22
	v_cmp_eq_f32_e32 vcc, 1.0, v22
	v_rcp_f32_e32 v28, v23
	v_mul_f32_e32 v21, 0x3f317218, v21
	v_mul_f32_e32 v28, v35, v28
	s_nop 0
	v_mul_f32_e32 v21, v21, v28
	s_nop 0
	v_cndmask_b32_e32 v20, v21, v35, vcc
	v_sub_f32_e32 v20, v34, v20
	v_mul_f32_e32 v20, 0x3d800000, v20
	v_cmp_eq_u32_e32 vcc, v132, v19
	ds_write_b32 v18, v20
	v_add_u32_e32 v18, 0x104, v18
	s_or_b64 s[94:95], vcc, s[94:95]
	s_andn2_b64 exec, exec, s[94:95]
	s_cbranch_execnz .LBB0_595
	s_or_b64 exec, exec, s[94:95]
	s_waitcnt lgkmcnt(0)
	s_barrier
	s_and_saveexec_b64 s[94:95], s[4:5]
	s_cbranch_execz .LBB0_598
	v_accvgpr_read_b32 v3, a84
	ds_read2_b32 v[0:1], v3 offset0:64 offset1:129
	s_waitcnt lgkmcnt(0)
	v_add_f32_e32 v0, 0, v0
	v_add_f32_e32 v2, v0, v1
	ds_write2_b32 v3, v0, v2 offset0:64 offset1:129
	v_accvgpr_read_b32 v3, a85
	ds_read2_b32 v[0:1], v3 offset0:66 offset1:131
	s_waitcnt lgkmcnt(0)
	v_add_f32_e32 v0, v2, v0
	v_add_f32_e32 v2, v0, v1
	ds_write2_b32 v3, v0, v2 offset0:66 offset1:131
	v_accvgpr_read_b32 v3, a86
	ds_read2_b32 v[0:1], v3 offset0:68 offset1:133
	s_waitcnt lgkmcnt(0)
	v_add_f32_e32 v0, v2, v0
	v_add_f32_e32 v2, v0, v1
	ds_write2_b32 v3, v0, v2 offset0:68 offset1:133
	v_accvgpr_read_b32 v3, a87
	ds_read2_b32 v[0:1], v3 offset0:70 offset1:135
	s_waitcnt lgkmcnt(0)
	v_add_f32_e32 v0, v2, v0
	v_add_f32_e32 v2, v0, v1
	ds_write2_b32 v3, v0, v2 offset0:70 offset1:135
	v_accvgpr_read_b32 v3, a88
	ds_read2_b32 v[0:1], v3 offset0:72 offset1:137
	s_waitcnt lgkmcnt(0)
	v_add_f32_e32 v0, v2, v0
	v_add_f32_e32 v2, v0, v1
	ds_write2_b32 v3, v0, v2 offset0:72 offset1:137
	v_accvgpr_read_b32 v3, a89
	ds_read2_b32 v[0:1], v3 offset0:74 offset1:139
	s_waitcnt lgkmcnt(0)
	v_add_f32_e32 v0, v2, v0
	v_add_f32_e32 v2, v0, v1
	ds_write2_b32 v3, v0, v2 offset0:74 offset1:139
	v_accvgpr_read_b32 v3, a90
	ds_read2_b32 v[0:1], v3 offset0:76 offset1:141
	s_waitcnt lgkmcnt(0)
	v_add_f32_e32 v0, v2, v0
	v_add_f32_e32 v2, v0, v1
	ds_write2_b32 v3, v0, v2 offset0:76 offset1:141
	v_accvgpr_read_b32 v3, a91
	ds_read2_b32 v[0:1], v3 offset0:78 offset1:143
	s_waitcnt lgkmcnt(0)
	v_add_f32_e32 v0, v2, v0
	v_add_f32_e32 v2, v0, v1
	ds_write2_b32 v3, v0, v2 offset0:78 offset1:143
	v_accvgpr_read_b32 v3, a92
	ds_read2_b32 v[0:1], v3 offset0:80 offset1:145
	s_waitcnt lgkmcnt(0)
	v_add_f32_e32 v0, v2, v0
	v_add_f32_e32 v2, v0, v1
	ds_write2_b32 v3, v0, v2 offset0:80 offset1:145
	v_accvgpr_read_b32 v3, a93
	ds_read2_b32 v[0:1], v3 offset0:82 offset1:147
	s_waitcnt lgkmcnt(0)
	v_add_f32_e32 v0, v2, v0
	v_add_f32_e32 v2, v0, v1
	ds_write2_b32 v3, v0, v2 offset0:82 offset1:147
	v_accvgpr_read_b32 v3, a94
	ds_read2_b32 v[0:1], v3 offset0:84 offset1:149
	s_waitcnt lgkmcnt(0)
	v_add_f32_e32 v0, v2, v0
	v_add_f32_e32 v2, v0, v1
	ds_write2_b32 v3, v0, v2 offset0:84 offset1:149
	v_accvgpr_read_b32 v3, a95
	ds_read2_b32 v[0:1], v3 offset0:86 offset1:151
	s_waitcnt lgkmcnt(0)
	v_add_f32_e32 v0, v2, v0
	v_add_f32_e32 v2, v0, v1
	ds_write2_b32 v3, v0, v2 offset0:86 offset1:151
	v_accvgpr_read_b32 v3, a96
	ds_read2_b32 v[0:1], v3 offset0:88 offset1:153
	s_waitcnt lgkmcnt(0)
	v_add_f32_e32 v0, v2, v0
	v_add_f32_e32 v2, v0, v1
	ds_write2_b32 v3, v0, v2 offset0:88 offset1:153
	v_accvgpr_read_b32 v3, a97
	ds_read2_b32 v[0:1], v3 offset0:90 offset1:155
	s_waitcnt lgkmcnt(0)
	v_add_f32_e32 v0, v2, v0
	v_add_f32_e32 v2, v0, v1
	ds_write2_b32 v3, v0, v2 offset0:90 offset1:155
	v_accvgpr_read_b32 v3, a98
	ds_read2_b32 v[0:1], v3 offset0:92 offset1:157
	s_waitcnt lgkmcnt(0)
	v_add_f32_e32 v0, v2, v0
	v_add_f32_e32 v2, v0, v1
	ds_write2_b32 v3, v0, v2 offset0:92 offset1:157
	v_accvgpr_read_b32 v3, a99
	ds_read2_b32 v[0:1], v3 offset0:94 offset1:159
	s_waitcnt lgkmcnt(0)
	v_add_f32_e32 v0, v2, v0
	v_add_f32_e32 v2, v0, v1
	ds_write2_b32 v3, v0, v2 offset0:94 offset1:159
	v_accvgpr_read_b32 v3, a100
	ds_read2_b32 v[0:1], v3 offset0:96 offset1:161
	s_waitcnt lgkmcnt(0)
	v_add_f32_e32 v0, v2, v0
	v_add_f32_e32 v2, v0, v1
	ds_write2_b32 v3, v0, v2 offset0:96 offset1:161
	v_accvgpr_read_b32 v3, a101
	ds_read2_b32 v[0:1], v3 offset0:98 offset1:163
	s_waitcnt lgkmcnt(0)
	v_add_f32_e32 v0, v2, v0
	v_add_f32_e32 v2, v0, v1
	ds_write2_b32 v3, v0, v2 offset0:98 offset1:163
	v_accvgpr_read_b32 v3, a102
	ds_read2_b32 v[0:1], v3 offset0:100 offset1:165
	s_waitcnt lgkmcnt(0)
	v_add_f32_e32 v0, v2, v0
	v_add_f32_e32 v2, v0, v1
	ds_write2_b32 v3, v0, v2 offset0:100 offset1:165
	v_accvgpr_read_b32 v3, a103
	ds_read2_b32 v[0:1], v3 offset0:102 offset1:167
	s_waitcnt lgkmcnt(0)
	v_add_f32_e32 v0, v2, v0
	v_add_f32_e32 v2, v0, v1
	ds_write2_b32 v3, v0, v2 offset0:102 offset1:167
	v_accvgpr_read_b32 v3, a104
	ds_read2_b32 v[0:1], v3 offset0:104 offset1:169
	s_waitcnt lgkmcnt(0)
	v_add_f32_e32 v0, v2, v0
	v_add_f32_e32 v2, v0, v1
	ds_write2_b32 v3, v0, v2 offset0:104 offset1:169
	v_accvgpr_read_b32 v3, a105
	ds_read2_b32 v[0:1], v3 offset0:106 offset1:171
	s_waitcnt lgkmcnt(0)
	v_add_f32_e32 v0, v2, v0
	v_add_f32_e32 v2, v0, v1
	ds_write2_b32 v3, v0, v2 offset0:106 offset1:171
	v_accvgpr_read_b32 v3, a106
	ds_read2_b32 v[0:1], v3 offset0:108 offset1:173
	s_waitcnt lgkmcnt(0)
	v_add_f32_e32 v0, v2, v0
	v_add_f32_e32 v2, v0, v1
	ds_write2_b32 v3, v0, v2 offset0:108 offset1:173
	v_accvgpr_read_b32 v3, a107
	ds_read2_b32 v[0:1], v3 offset0:110 offset1:175
	s_waitcnt lgkmcnt(0)
	v_add_f32_e32 v0, v2, v0
	v_add_f32_e32 v2, v0, v1
	ds_write2_b32 v3, v0, v2 offset0:110 offset1:175
	v_accvgpr_read_b32 v3, a108
	ds_read2_b32 v[0:1], v3 offset0:112 offset1:177
	s_waitcnt lgkmcnt(0)
	v_add_f32_e32 v0, v2, v0
	v_add_f32_e32 v2, v0, v1
	ds_write2_b32 v3, v0, v2 offset0:112 offset1:177
	v_accvgpr_read_b32 v3, a109
	ds_read2_b32 v[0:1], v3 offset0:114 offset1:179
	s_waitcnt lgkmcnt(0)
	v_add_f32_e32 v0, v2, v0
	v_add_f32_e32 v2, v0, v1
	ds_write2_b32 v3, v0, v2 offset0:114 offset1:179
	v_accvgpr_read_b32 v3, a110
	ds_read2_b32 v[0:1], v3 offset0:116 offset1:181
	s_waitcnt lgkmcnt(0)
	v_add_f32_e32 v0, v2, v0
	v_add_f32_e32 v2, v0, v1
	ds_write2_b32 v3, v0, v2 offset0:116 offset1:181
	v_accvgpr_read_b32 v3, a111
	ds_read2_b32 v[0:1], v3 offset0:118 offset1:183
	s_waitcnt lgkmcnt(0)
	v_add_f32_e32 v0, v2, v0
	v_add_f32_e32 v2, v0, v1
	ds_write2_b32 v3, v0, v2 offset0:118 offset1:183
	v_accvgpr_read_b32 v3, a112
	ds_read2_b32 v[0:1], v3 offset0:120 offset1:185
	s_waitcnt lgkmcnt(0)
	v_add_f32_e32 v0, v2, v0
	v_add_f32_e32 v2, v0, v1
	ds_write2_b32 v3, v0, v2 offset0:120 offset1:185
	v_accvgpr_read_b32 v3, a113
	ds_read2_b32 v[0:1], v3 offset0:122 offset1:187
	s_waitcnt lgkmcnt(0)
	v_add_f32_e32 v0, v2, v0
	v_add_f32_e32 v2, v0, v1
	ds_write2_b32 v3, v0, v2 offset0:122 offset1:187
	v_accvgpr_read_b32 v3, a114
	ds_read2_b32 v[0:1], v3 offset0:124 offset1:189
	s_waitcnt lgkmcnt(0)
	v_add_f32_e32 v0, v2, v0
	v_add_f32_e32 v2, v0, v1
	ds_write2_b32 v3, v0, v2 offset0:124 offset1:189
	v_accvgpr_read_b32 v3, a115
	ds_read2_b32 v[0:1], v3 offset0:126 offset1:191
	s_waitcnt lgkmcnt(0)
	v_add_f32_e32 v0, v2, v0
	v_add_f32_e32 v1, v0, v1
	ds_write2_b32 v3, v0, v1 offset0:126 offset1:191

.LBB0_599:
	ds_read2_b32 v[70:71], v163 offset1:1
	ds_read2_b32 a[0:1], v163 offset0:2 offset1:3
	ds_read2_b32 a[2:3], v163 offset0:4 offset1:5
	ds_read2_b32 a[4:5], v163 offset0:6 offset1:7
	ds_read2_b32 a[6:7], v163 offset0:8 offset1:9
	ds_read2_b32 a[8:9], v163 offset0:10 offset1:11
	ds_read2_b32 a[10:11], v163 offset0:12 offset1:13
	ds_read2_b32 a[12:13], v163 offset0:14 offset1:15
	v_add_u32_e32 v167, -1, v167
	s_waitcnt vmcnt(15) lgkmcnt(7)
	v_fma_f32 v74, v151, v70, v149
	s_waitcnt vmcnt(14)
	v_fmac_f32_e32 v74, v153, v71
	s_waitcnt vmcnt(13) lgkmcnt(6)
	v_accvgpr_read_b32 v70, a0
	v_accvgpr_read_b32 v71, a1
	v_fmac_f32_e32 v74, v155, v70
	s_waitcnt vmcnt(12)
	v_fmac_f32_e32 v74, v157, v71
	s_waitcnt vmcnt(11) lgkmcnt(5)
	v_accvgpr_read_b32 v70, a2
	v_accvgpr_read_b32 v71, a3
	v_fmac_f32_e32 v74, v159, v70
	s_waitcnt vmcnt(10)
	v_fmac_f32_e32 v74, v161, v71
	s_waitcnt vmcnt(8) lgkmcnt(4)
	v_accvgpr_read_b32 v70, a4
	v_accvgpr_read_b32 v71, a5
	v_pk_mul_f32 v[70:71], v[184:185], v[70:71]
	s_nop 0
	v_add_f32_e32 v70, v74, v70
	v_add_f32_e32 v74, v70, v71
	s_waitcnt vmcnt(6) lgkmcnt(3)
	v_accvgpr_read_b32 v70, a6
	v_accvgpr_read_b32 v71, a7
	v_pk_mul_f32 v[70:71], v[242:243], v[70:71]
	s_nop 0
	v_add_f32_e32 v70, v74, v70
	v_add_f32_e32 v74, v70, v71
	s_waitcnt vmcnt(4) lgkmcnt(2)
	v_accvgpr_read_b32 v70, a8
	v_accvgpr_read_b32 v71, a9
	v_pk_mul_f32 v[70:71], v[244:245], v[70:71]
	s_nop 0
	v_add_f32_e32 v70, v74, v70
	v_add_f32_e32 v74, v70, v71
	s_waitcnt vmcnt(2) lgkmcnt(1)
	v_accvgpr_read_b32 v70, a10
	v_accvgpr_read_b32 v71, a11
	v_pk_mul_f32 v[70:71], v[246:247], v[70:71]
	s_nop 0
	v_add_f32_e32 v70, v74, v70
	v_add_f32_e32 v74, v70, v71
	v_add_u32_e32 v163, 0x84, v163
	s_waitcnt vmcnt(0) lgkmcnt(0)
	v_accvgpr_read_b32 v70, a12
	v_accvgpr_read_b32 v71, a13
	v_pk_mul_f32 v[70:71], v[248:249], v[70:71]
	s_nop 0
	v_add_f32_e32 v70, v74, v70
	v_add_f32_e32 v70, v70, v71
	v_min_f32_e32 v169, 0, v70
	v_mul_f32_e64 v70, |v70|, s12
	v_exp_f32_e32 v171, v70
	s_nop 0
	v_add_f32_e32 v74, 1.0, v171
	v_log_f32_e32 v71, v74
	v_add_f32_e32 v75, -1.0, v74
	v_cmp_eq_f32_e32 vcc, 1.0, v74
	v_rcp_f32_e32 v173, v75
	v_mul_f32_e32 v71, 0x3f317218, v71
	v_mul_f32_e32 v173, v171, v173
	s_nop 0
	v_mul_f32_e32 v71, v71, v173
	s_nop 0
	v_cndmask_b32_e32 v70, v71, v171, vcc
	v_sub_f32_e32 v70, v169, v70
	v_mul_f32_e32 v70, 0x3d800000, v70
	v_cmp_eq_u32_e32 vcc, 0, v167
	ds_write_b32 v165, v70
	v_add_u32_e32 v165, 0x104, v165
	s_or_b64 s[96:97], vcc, s[96:97]
	s_andn2_b64 exec, exec, s[96:97]
	s_cbranch_execnz .LBB0_599
	s_or_b64 exec, exec, s[96:97]
	v_mfma_f32_32x32x16_bf16 a[32:47], v[4:7], v[24:27], 0
	s_waitcnt lgkmcnt(0)
	s_barrier
	v_mfma_f32_32x32x16_bf16 a[32:47], v[0:3], v[12:15], a[32:47]
	v_cvt_pk_bf16_f32 v0, v79, v81
	v_cvt_pk_bf16_f32 v1, v83, v85
	v_cvt_pk_bf16_f32 v2, v87, v89
	v_cvt_pk_bf16_f32 v3, v91, v93
	s_nop 1
	v_mfma_f32_32x32x16_bf16 a[16:31], v[36:39], v[0:3], 0
	v_mfma_f32_32x32x16_bf16 a[0:15], v[40:43], v[0:3], 0
	v_cvt_pk_bf16_f32 v0, v95, v97
	v_cvt_pk_bf16_f32 v1, v99, v101
	v_cvt_pk_bf16_f32 v2, v103, v105
	v_cvt_pk_bf16_f32 v3, v107, v109
	s_nop 1
	v_mfma_f32_32x32x16_bf16 a[16:31], v[32:35], v[0:3], a[16:31]
	v_mfma_f32_32x32x16_bf16 a[0:15], v[44:47], v[0:3], a[0:15]
	v_cvt_pk_bf16_f32 v0, v111, v113
	v_cvt_pk_bf16_f32 v1, v117, v119
	v_cvt_pk_bf16_f32 v2, v121, v123
	v_cvt_pk_bf16_f32 v3, v125, v127
	v_mfma_f32_32x32x16_bf16 a[32:47], v[8:11], v[16:19], a[32:47]
	s_nop 0
	v_mfma_f32_32x32x16_bf16 a[16:31], v[52:55], v[0:3], a[16:31]
	v_mfma_f32_32x32x16_bf16 a[0:15], v[48:51], v[0:3], a[0:15]
	v_cvt_pk_bf16_f32 v0, v135, v137
	v_cvt_pk_bf16_f32 v1, v139, v141
	v_cvt_pk_bf16_f32 v2, v143, v145
	v_cvt_pk_bf16_f32 v3, v147, v148
	v_mfma_f32_32x32x16_bf16 a[32:47], v[20:23], v[28:31], a[32:47]
	s_nop 0
	v_mfma_f32_32x32x16_bf16 a[16:31], v[60:63], v[0:3], a[16:31]
	v_mfma_f32_32x32x16_bf16 a[0:15], v[56:59], v[0:3], a[0:15]
	s_and_saveexec_b64 s[96:97], s[4:5]
	s_cbranch_execz .LBB0_591
	v_accvgpr_read_b32 v3, a115
	ds_read2_b32 v[0:1], v3 offset0:126 offset1:191
	s_waitcnt lgkmcnt(0)
	v_add_f32_e32 v1, 0, v1
	v_add_f32_e32 v2, v1, v0
	ds_write2_b32 v3, v2, v1 offset0:126 offset1:191
	v_accvgpr_read_b32 v3, a114
	ds_read2_b32 v[0:1], v3 offset0:124 offset1:189
	s_waitcnt lgkmcnt(0)
	v_add_f32_e32 v1, v2, v1
	v_add_f32_e32 v2, v1, v0
	ds_write2_b32 v3, v2, v1 offset0:124 offset1:189
	v_accvgpr_read_b32 v3, a113
	ds_read2_b32 v[0:1], v3 offset0:122 offset1:187
	s_waitcnt lgkmcnt(0)
	v_add_f32_e32 v1, v2, v1
	v_add_f32_e32 v2, v1, v0
	ds_write2_b32 v3, v2, v1 offset0:122 offset1:187
	v_accvgpr_read_b32 v3, a112
	ds_read2_b32 v[0:1], v3 offset0:120 offset1:185
	s_waitcnt lgkmcnt(0)
	v_add_f32_e32 v1, v2, v1
	v_add_f32_e32 v2, v1, v0
	ds_write2_b32 v3, v2, v1 offset0:120 offset1:185
	v_accvgpr_read_b32 v3, a111
	ds_read2_b32 v[0:1], v3 offset0:118 offset1:183
	s_waitcnt lgkmcnt(0)
	v_add_f32_e32 v1, v2, v1
	v_add_f32_e32 v2, v1, v0
	ds_write2_b32 v3, v2, v1 offset0:118 offset1:183
	v_accvgpr_read_b32 v3, a110
	ds_read2_b32 v[0:1], v3 offset0:116 offset1:181
	s_waitcnt lgkmcnt(0)
	v_add_f32_e32 v1, v2, v1
	v_add_f32_e32 v2, v1, v0
	ds_write2_b32 v3, v2, v1 offset0:116 offset1:181
	v_accvgpr_read_b32 v3, a109
	ds_read2_b32 v[0:1], v3 offset0:114 offset1:179
	s_waitcnt lgkmcnt(0)
	v_add_f32_e32 v1, v2, v1
	v_add_f32_e32 v2, v1, v0
	ds_write2_b32 v3, v2, v1 offset0:114 offset1:179
	v_accvgpr_read_b32 v3, a108
	ds_read2_b32 v[0:1], v3 offset0:112 offset1:177
	s_waitcnt lgkmcnt(0)
	v_add_f32_e32 v1, v2, v1
	v_add_f32_e32 v2, v1, v0
	ds_write2_b32 v3, v2, v1 offset0:112 offset1:177
	v_accvgpr_read_b32 v3, a107
	ds_read2_b32 v[0:1], v3 offset0:110 offset1:175
	s_waitcnt lgkmcnt(0)
	v_add_f32_e32 v1, v2, v1
	v_add_f32_e32 v2, v1, v0
	ds_write2_b32 v3, v2, v1 offset0:110 offset1:175
	v_accvgpr_read_b32 v3, a106
	ds_read2_b32 v[0:1], v3 offset0:108 offset1:173
	s_waitcnt lgkmcnt(0)
	v_add_f32_e32 v1, v2, v1
	v_add_f32_e32 v2, v1, v0
	ds_write2_b32 v3, v2, v1 offset0:108 offset1:173
	v_accvgpr_read_b32 v3, a105
	ds_read2_b32 v[0:1], v3 offset0:106 offset1:171
	s_waitcnt lgkmcnt(0)
	v_add_f32_e32 v1, v2, v1
	v_add_f32_e32 v2, v1, v0
	ds_write2_b32 v3, v2, v1 offset0:106 offset1:171
	v_accvgpr_read_b32 v3, a104
	ds_read2_b32 v[0:1], v3 offset0:104 offset1:169
	s_waitcnt lgkmcnt(0)
	v_add_f32_e32 v1, v2, v1
	v_add_f32_e32 v2, v1, v0
	ds_write2_b32 v3, v2, v1 offset0:104 offset1:169
	v_accvgpr_read_b32 v3, a103
	ds_read2_b32 v[0:1], v3 offset0:102 offset1:167
	s_waitcnt lgkmcnt(0)
	v_add_f32_e32 v1, v2, v1
	v_add_f32_e32 v2, v1, v0
	ds_write2_b32 v3, v2, v1 offset0:102 offset1:167
	v_accvgpr_read_b32 v3, a102
	ds_read2_b32 v[0:1], v3 offset0:100 offset1:165
	s_waitcnt lgkmcnt(0)
	v_add_f32_e32 v1, v2, v1
	v_add_f32_e32 v2, v1, v0
	ds_write2_b32 v3, v2, v1 offset0:100 offset1:165
	v_accvgpr_read_b32 v3, a101
	ds_read2_b32 v[0:1], v3 offset0:98 offset1:163
	s_waitcnt lgkmcnt(0)
	v_add_f32_e32 v1, v2, v1
	v_add_f32_e32 v2, v1, v0
	ds_write2_b32 v3, v2, v1 offset0:98 offset1:163
	v_accvgpr_read_b32 v3, a100
	ds_read2_b32 v[0:1], v3 offset0:96 offset1:161
	s_waitcnt lgkmcnt(0)
	v_add_f32_e32 v1, v2, v1
	v_add_f32_e32 v2, v1, v0
	ds_write2_b32 v3, v2, v1 offset0:96 offset1:161
	v_accvgpr_read_b32 v3, a99
	ds_read2_b32 v[0:1], v3 offset0:94 offset1:159
	s_waitcnt lgkmcnt(0)
	v_add_f32_e32 v1, v2, v1
	v_add_f32_e32 v2, v1, v0
	ds_write2_b32 v3, v2, v1 offset0:94 offset1:159
	v_accvgpr_read_b32 v3, a98
	ds_read2_b32 v[0:1], v3 offset0:92 offset1:157
	s_waitcnt lgkmcnt(0)
	v_add_f32_e32 v1, v2, v1
	v_add_f32_e32 v2, v1, v0
	ds_write2_b32 v3, v2, v1 offset0:92 offset1:157
	v_accvgpr_read_b32 v3, a97
	ds_read2_b32 v[0:1], v3 offset0:90 offset1:155
	s_waitcnt lgkmcnt(0)
	v_add_f32_e32 v1, v2, v1
	v_add_f32_e32 v2, v1, v0
	ds_write2_b32 v3, v2, v1 offset0:90 offset1:155
	v_accvgpr_read_b32 v3, a96
	ds_read2_b32 v[0:1], v3 offset0:88 offset1:153
	s_waitcnt lgkmcnt(0)
	v_add_f32_e32 v1, v2, v1
	v_add_f32_e32 v2, v1, v0
	ds_write2_b32 v3, v2, v1 offset0:88 offset1:153
	v_accvgpr_read_b32 v3, a95
	ds_read2_b32 v[0:1], v3 offset0:86 offset1:151
	s_waitcnt lgkmcnt(0)
	v_add_f32_e32 v1, v2, v1
	v_add_f32_e32 v2, v1, v0
	ds_write2_b32 v3, v2, v1 offset0:86 offset1:151
	v_accvgpr_read_b32 v3, a94
	ds_read2_b32 v[0:1], v3 offset0:84 offset1:149
	s_waitcnt lgkmcnt(0)
	v_add_f32_e32 v1, v2, v1
	v_add_f32_e32 v2, v1, v0
	ds_write2_b32 v3, v2, v1 offset0:84 offset1:149
	v_accvgpr_read_b32 v3, a93
	ds_read2_b32 v[0:1], v3 offset0:82 offset1:147
	s_waitcnt lgkmcnt(0)
	v_add_f32_e32 v1, v2, v1
	v_add_f32_e32 v2, v1, v0
	ds_write2_b32 v3, v2, v1 offset0:82 offset1:147
	v_accvgpr_read_b32 v3, a92
	ds_read2_b32 v[0:1], v3 offset0:80 offset1:145
	s_waitcnt lgkmcnt(0)
	v_add_f32_e32 v1, v2, v1
	v_add_f32_e32 v2, v1, v0
	ds_write2_b32 v3, v2, v1 offset0:80 offset1:145
	v_accvgpr_read_b32 v3, a91
	ds_read2_b32 v[0:1], v3 offset0:78 offset1:143
	s_waitcnt lgkmcnt(0)
	v_add_f32_e32 v1, v2, v1
	v_add_f32_e32 v2, v1, v0
	ds_write2_b32 v3, v2, v1 offset0:78 offset1:143
	v_accvgpr_read_b32 v3, a90
	ds_read2_b32 v[0:1], v3 offset0:76 offset1:141
	s_waitcnt lgkmcnt(0)
	v_add_f32_e32 v1, v2, v1
	v_add_f32_e32 v2, v1, v0
	ds_write2_b32 v3, v2, v1 offset0:76 offset1:141
	v_accvgpr_read_b32 v3, a89
	ds_read2_b32 v[0:1], v3 offset0:74 offset1:139
	s_waitcnt lgkmcnt(0)
	v_add_f32_e32 v1, v2, v1
	v_add_f32_e32 v2, v1, v0
	ds_write2_b32 v3, v2, v1 offset0:74 offset1:139
	v_accvgpr_read_b32 v3, a88
	ds_read2_b32 v[0:1], v3 offset0:72 offset1:137
	s_waitcnt lgkmcnt(0)
	v_add_f32_e32 v1, v2, v1
	v_add_f32_e32 v2, v1, v0
	ds_write2_b32 v3, v2, v1 offset0:72 offset1:137
	v_accvgpr_read_b32 v3, a87
	ds_read2_b32 v[0:1], v3 offset0:70 offset1:135
	s_waitcnt lgkmcnt(0)
	v_add_f32_e32 v1, v2, v1
	v_add_f32_e32 v2, v1, v0
	ds_write2_b32 v3, v2, v1 offset0:70 offset1:135
	v_accvgpr_read_b32 v3, a86
	ds_read2_b32 v[0:1], v3 offset0:68 offset1:133
	s_waitcnt lgkmcnt(0)
	v_add_f32_e32 v1, v2, v1
	v_add_f32_e32 v2, v1, v0
	ds_write2_b32 v3, v2, v1 offset0:68 offset1:133
	v_accvgpr_read_b32 v3, a85
	ds_read2_b32 v[0:1], v3 offset0:66 offset1:131
	s_waitcnt lgkmcnt(0)
	v_add_f32_e32 v1, v2, v1
	v_add_f32_e32 v2, v1, v0
	ds_write2_b32 v3, v2, v1 offset0:66 offset1:131
	v_accvgpr_read_b32 v3, a84
	ds_read2_b32 v[0:1], v3 offset0:64 offset1:129
	s_waitcnt lgkmcnt(0)
	v_add_f32_e32 v1, v2, v1
	v_add_f32_e32 v0, v1, v0
	ds_write2_b32 v3, v0, v1 offset0:64 offset1:129
	s_branch .LBB0_591

.LBB0_778:
	s_and_b32 s52, s44, 1
	s_mul_i32 s53, s52, 0xd800
	s_xor_b32 s52, s52, 1
	s_mul_i32 s52, s52, 0xd800
	s_add_i32 s44, s44, 1
	v_add_u32_e32 v186, s52, v45
	ds_read_b128 v[68:71], v189 offset:32
	ds_read_b128 v[80:83], v187 offset:36896
	ds_read_b128 v[72:75], v189 offset:4640
	ds_read_b128 v[84:87], v187 offset:41504
	ds_read_b128 v[76:79], v189 offset:9248
	ds_read_b128 v[104:107], v188 offset:32
	s_waitcnt lgkmcnt(6)
	v_mfma_f32_32x32x16_bf16 a[32:47], v[108:111], v[14:17], a[32:47]
	s_waitcnt vmcnt(11)
	ds_write_b128 v186, v[250:253]
	v_mfma_f32_32x32x16_bf16 a[48:63], v[108:111], v[64:67], a[48:63]
	s_waitcnt vmcnt(10)
	ds_write_b128 v186, v[246:249] offset:4608
	global_load_dwordx4 v[250:253], v254, s[100:101] offset:512
	v_mfma_f32_32x32x16_bf16 a[64:79], v[112:115], v[14:17], a[64:79]
	s_waitcnt vmcnt(10)
	ds_write_b128 v186, v[242:245] offset:9216
	global_load_dwordx4 v[246:249], v205, s[100:101] offset:512
	v_mfma_f32_32x32x16_bf16 a[96:111], v[112:115], v[64:67], a[96:111]
	s_waitcnt vmcnt(10)
	ds_write_b128 v186, v[238:241] offset:13824
	global_load_dwordx4 v[242:245], v204, s[100:101] offset:512
	v_mfma_f32_32x32x16_bf16 a[80:95], v[116:119], v[14:17], a[80:95]
	s_waitcnt vmcnt(10)
	ds_write_b128 v186, v[234:237] offset:18432
	global_load_dwordx4 v[238:241], v203, s[100:101] offset:512
	v_mfma_f32_32x32x16_bf16 a[112:127], v[116:119], v[64:67], a[112:127]
	s_waitcnt vmcnt(10)
	ds_write_b128 v186, v[230:233] offset:23040
	global_load_dwordx4 v[234:237], v202, s[100:101] offset:512
	s_waitcnt lgkmcnt(6)
	v_mfma_f32_32x32x16_bf16 a[16:31], v[120:123], v[14:17], a[16:31]
	s_waitcnt vmcnt(10)
	ds_write_b128 v186, v[226:229] offset:27648
	global_load_dwordx4 v[230:233], v201, s[100:101] offset:512
	v_mfma_f32_32x32x16_bf16 a[0:15], v[120:123], v[64:67], a[0:15]
	s_waitcnt vmcnt(10)
	ds_write_b128 v186, v[222:225] offset:32256
	global_load_dwordx4 v[226:229], v200, s[100:101] offset:512
	s_waitcnt lgkmcnt(8)
	ds_read_b128 v[108:111], v189 offset:64
	ds_read_b128 v[14:17], v187 offset:36928
	ds_read_b128 v[112:115], v189 offset:4672
	ds_read_b128 v[64:67], v187 offset:41536
	ds_read_b128 v[116:119], v189 offset:9280
	ds_read_b128 v[120:123], v188 offset:64
	v_mfma_f32_32x32x16_bf16 a[32:47], v[68:71], v[80:83], a[32:47]
	s_waitcnt lgkmcnt(12)
	s_waitcnt vmcnt(10)
	ds_write_b128 v186, v[218:221] offset:36864
	global_load_dwordx4 v[222:225], v199, s[100:101] offset:512
	v_mfma_f32_32x32x16_bf16 a[48:63], v[68:71], v[84:87], a[48:63]
	s_waitcnt lgkmcnt(12)
	s_waitcnt vmcnt(10)
	ds_write_b128 v186, v[214:217] offset:41472
	global_load_dwordx4 v[218:221], v198, s[98:99] offset:256
	v_mfma_f32_32x32x16_bf16 a[64:79], v[72:75], v[80:83], a[64:79]
	s_waitcnt lgkmcnt(12)
	s_waitcnt vmcnt(10)
	ds_write_b128 v186, v[210:213] offset:46080
	global_load_dwordx4 v[214:217], v197, s[98:99] offset:256
	v_mfma_f32_32x32x16_bf16 a[96:111], v[72:75], v[84:87], a[96:111]
	s_waitcnt lgkmcnt(12)
	s_waitcnt vmcnt(10)
	ds_write_b128 v186, v[206:209] offset:50688
	global_load_dwordx4 v[210:213], v196, s[98:99] offset:256
	v_mfma_f32_32x32x16_bf16 a[80:95], v[76:79], v[80:83], a[80:95]
	global_load_dwordx4 v[206:209], v195, s[98:99] offset:256
	s_add_u32 s100, s100, 0x80
	s_addc_u32 s101, s101, 0
	s_add_u32 s98, s98, 0x80
	s_addc_u32 s99, s99, 0
	v_mfma_f32_32x32x16_bf16 a[112:127], v[76:79], v[84:87], a[112:127]
	v_mfma_f32_32x32x16_bf16 a[16:31], v[104:107], v[80:83], a[16:31]
	v_mfma_f32_32x32x16_bf16 a[0:15], v[104:107], v[84:87], a[0:15]
	s_waitcnt lgkmcnt(4)
	ds_read_b128 v[68:71], v189 offset:96
	ds_read_b128 v[80:83], v187 offset:36960
	ds_read_b128 v[72:75], v189 offset:4704
	ds_read_b128 v[84:87], v187 offset:41568
	ds_read_b128 v[76:79], v189 offset:9312
	ds_read_b128 v[104:107], v188 offset:96
	v_mfma_f32_32x32x16_bf16 a[32:47], v[108:111], v[14:17], a[32:47]
	v_mfma_f32_32x32x16_bf16 a[48:63], v[108:111], v[64:67], a[48:63]
	v_mfma_f32_32x32x16_bf16 a[64:79], v[112:115], v[14:17], a[64:79]
	v_mfma_f32_32x32x16_bf16 a[96:111], v[112:115], v[64:67], a[96:111]
	v_mfma_f32_32x32x16_bf16 a[80:95], v[116:119], v[14:17], a[80:95]
	v_mfma_f32_32x32x16_bf16 a[112:127], v[116:119], v[64:67], a[112:127]
	v_mfma_f32_32x32x16_bf16 a[16:31], v[120:123], v[14:17], a[16:31]
	v_mfma_f32_32x32x16_bf16 a[0:15], v[120:123], v[64:67], a[0:15]
	s_waitcnt lgkmcnt(0)
	v_mfma_f32_32x32x16_bf16 a[32:47], v[68:71], v[80:83], a[32:47]
	v_mfma_f32_32x32x16_bf16 a[48:63], v[68:71], v[84:87], a[48:63]
	v_mfma_f32_32x32x16_bf16 a[64:79], v[72:75], v[80:83], a[64:79]
	v_mfma_f32_32x32x16_bf16 a[96:111], v[72:75], v[84:87], a[96:111]
	s_barrier
	v_add_u32_e32 v189, s52, v192
	v_add_u32_e32 v188, s52, v191
	v_add_u32_e32 v187, s52, v190
	ds_read_b128 v[108:111], v189
	ds_read_b128 v[14:17], v187 offset:36864
	ds_read_b128 v[112:115], v189 offset:4608
	ds_read_b128 v[64:67], v187 offset:41472
	ds_read_b128 v[116:119], v189 offset:9216
	ds_read_b128 v[120:123], v188
	v_mfma_f32_32x32x16_bf16 a[80:95], v[76:79], v[80:83], a[80:95]
	v_mfma_f32_32x32x16_bf16 a[112:127], v[76:79], v[84:87], a[112:127]
	v_mfma_f32_32x32x16_bf16 a[16:31], v[104:107], v[80:83], a[16:31]
	v_mfma_f32_32x32x16_bf16 a[0:15], v[104:107], v[84:87], a[0:15]
	s_add_u32 s46, s46, 0x80
	s_addc_u32 s47, s47, 0
	s_cmpk_lg_i32 s46, 0x700
	s_cbranch_scc1 .LBB0_778
	ds_read_b128 v[10:13], v60
	ds_read_b128 v[108:111], v62 offset:36864
	ds_read_b128 v[112:115], v60 offset:4608
	ds_read_b128 v[116:119], v62 offset:41472
	s_lshl_b32 s46, s50, 8
	s_lshl_b32 s44, s51, 8
	s_waitcnt lgkmcnt(2)
	v_mfma_f32_32x32x16_bf16 a[176:191], v[10:13], v[108:111], a[32:47]
	s_add_i32 s49, s49, s79
	s_add_i32 s48, s48, s79
	s_waitcnt lgkmcnt(0)
	v_mfma_f32_32x32x16_bf16 a[160:175], v[10:13], v[116:119], a[48:63]
	v_mfma_f32_32x32x16_bf16 a[144:159], v[112:115], v[108:111], a[64:79]
	v_mfma_f32_32x32x16_bf16 a[128:143], v[112:115], v[116:119], a[96:111]
	ds_read_b128 v[10:13], v60 offset:9216
	ds_read_b128 v[112:115], v61
	s_waitcnt vmcnt(11)
	s_waitcnt vmcnt(0)
	ds_write_b128 v63, v[250:253] offset:55296
	s_waitcnt vmcnt(10)
	ds_write_b128 v63, v[246:249] offset:59904
	s_waitcnt vmcnt(9)
	ds_write_b128 v63, v[242:245] offset:64512
	s_waitcnt vmcnt(8)
	ds_write_b128 v50, v[238:241] offset:55296
	s_waitcnt vmcnt(7)
	ds_write_b128 v51, v[234:237] offset:55296
	s_waitcnt vmcnt(6)
	ds_write_b128 v52, v[230:233] offset:55296
	s_waitcnt vmcnt(5)
	ds_write_b128 v53, v[226:229] offset:55296
	s_waitcnt vmcnt(4)
	ds_write_b128 v54, v[222:225] offset:55296
	s_waitcnt vmcnt(3)
	ds_write_b128 v55, v[218:221]
	s_waitcnt vmcnt(2)
	ds_write_b128 v55, v[214:217] offset:4608
	s_waitcnt vmcnt(1)
	ds_write_b128 v55, v[210:213] offset:9216
	s_waitcnt vmcnt(0)
	ds_write_b128 v55, v[206:209] offset:13824
	s_waitcnt lgkmcnt(13)
	v_mfma_f32_32x32x16_bf16 a[64:79], v[10:13], v[108:111], a[80:95]
	v_mfma_f32_32x32x16_bf16 a[48:63], v[10:13], v[116:119], a[112:127]
	ds_read_b128 v[10:13], v60 offset:32
	ds_read_b128 v[14:17], v62 offset:36896
	ds_read_b128 v[64:67], v62 offset:36928
	ds_read_b128 v[68:71], v60 offset:64
	ds_read_b128 v[72:75], v62 offset:41504
	ds_read_b128 v[76:79], v62 offset:36960
	s_waitcnt lgkmcnt(4)
	v_mfma_f32_32x32x16_bf16 a[176:191], v[10:13], v[14:17], a[176:191]
	s_waitcnt lgkmcnt(1)
	v_mfma_f32_32x32x16_bf16 a[160:175], v[10:13], v[72:75], a[160:175]
	ds_read_b128 v[10:13], v60 offset:4640
	ds_read_b128 v[80:83], v60 offset:96
	v_mfma_f32_32x32x16_bf16 a[32:47], v[112:115], v[108:111], a[16:31]
	v_mfma_f32_32x32x16_bf16 a[16:31], v[112:115], v[116:119], a[0:15]
	s_waitcnt lgkmcnt(1)
	v_mfma_f32_32x32x16_bf16 a[144:159], v[10:13], v[14:17], a[144:159]
	v_mfma_f32_32x32x16_bf16 a[128:143], v[10:13], v[72:75], a[128:143]
	ds_read_b128 v[10:13], v60 offset:9248
	ds_read_b128 v[84:87], v60 offset:9280
	s_waitcnt lgkmcnt(1)
	v_mfma_f32_32x32x16_bf16 a[64:79], v[10:13], v[14:17], a[64:79]
	v_mfma_f32_32x32x16_bf16 a[48:63], v[10:13], v[72:75], a[48:63]
	ds_read_b128 v[10:13], v61 offset:32
	ds_read_b128 v[88:91], v60 offset:9312
	s_waitcnt lgkmcnt(1)
	v_mfma_f32_32x32x16_bf16 a[32:47], v[10:13], v[14:17], a[32:47]
	v_mfma_f32_32x32x16_bf16 a[16:31], v[10:13], v[72:75], a[16:31]
	ds_read_b128 v[10:13], v62 offset:41536
	ds_read_b128 v[14:17], v62 offset:41568
	v_mfma_f32_32x32x16_bf16 a[176:191], v[68:71], v[64:67], a[176:191]
	s_waitcnt lgkmcnt(1)
	v_mfma_f32_32x32x16_bf16 a[160:175], v[68:71], v[10:13], a[160:175]
	ds_read_b128 v[68:71], v60 offset:4672
	ds_read_b128 v[72:75], v60 offset:4704
	s_waitcnt lgkmcnt(1)
	v_mfma_f32_32x32x16_bf16 a[144:159], v[68:71], v[64:67], a[144:159]
	v_mfma_f32_32x32x16_bf16 a[128:143], v[68:71], v[10:13], a[128:143]
	v_mfma_f32_32x32x16_bf16 a[64:79], v[84:87], v[64:67], a[64:79]
	v_mfma_f32_32x32x16_bf16 a[48:63], v[84:87], v[10:13], a[48:63]
	ds_read_b128 v[68:71], v61 offset:64
	ds_read_b128 v[84:87], v61 offset:96
	s_waitcnt lgkmcnt(0)
	s_barrier
	v_mfma_f32_32x32x16_bf16 a[32:47], v[68:71], v[64:67], a[32:47]
	v_mfma_f32_32x32x16_bf16 a[16:31], v[68:71], v[10:13], a[16:31]
	v_mfma_f32_32x32x16_bf16 a[176:191], v[80:83], v[76:79], a[176:191]
	v_mfma_f32_32x32x16_bf16 a[160:175], v[80:83], v[14:17], a[160:175]
	v_mfma_f32_32x32x16_bf16 a[144:159], v[72:75], v[76:79], a[144:159]
	v_mfma_f32_32x32x16_bf16 a[128:143], v[72:75], v[14:17], a[128:143]
	v_mfma_f32_32x32x16_bf16 a[64:79], v[88:91], v[76:79], a[64:79]
	v_mfma_f32_32x32x16_bf16 a[48:63], v[88:91], v[14:17], a[48:63]
	v_mfma_f32_32x32x16_bf16 a[32:47], v[84:87], v[76:79], a[32:47]
	v_mfma_f32_32x32x16_bf16 a[16:31], v[84:87], v[14:17], a[16:31]
	ds_read_b128 v[10:13], v60 offset:55296
	ds_read_b128 v[14:17], v56
	ds_read_b128 v[64:67], v60 offset:55328
	ds_read_b128 v[68:71], v56 offset:32
	ds_read_b128 v[72:75], v56 offset:4608
	ds_read_b128 v[76:79], v56 offset:4640
	s_waitcnt lgkmcnt(4)
	v_mfma_f32_32x32x16_bf16 a[176:191], v[10:13], v[14:17], a[176:191]
	s_waitcnt lgkmcnt(1)
	v_mfma_f32_32x32x16_bf16 a[160:175], v[10:13], v[72:75], a[160:175]
	ds_read_b128 v[10:13], v60 offset:59904
	ds_read_b128 v[80:83], v60 offset:59936
	s_waitcnt lgkmcnt(1)
	v_mfma_f32_32x32x16_bf16 a[144:159], v[10:13], v[14:17], a[144:159]
	v_mfma_f32_32x32x16_bf16 a[128:143], v[10:13], v[72:75], a[128:143]
	ds_read_b128 v[10:13], v60 offset:64512
	ds_read_b128 v[84:87], v60 offset:64544
	s_waitcnt lgkmcnt(1)
	v_mfma_f32_32x32x16_bf16 a[64:79], v[10:13], v[14:17], a[64:79]
	v_mfma_f32_32x32x16_bf16 a[48:63], v[10:13], v[72:75], a[48:63]
	ds_read_b128 v[10:13], v61 offset:55296
	ds_read_b128 v[88:91], v61 offset:55328
	s_waitcnt lgkmcnt(1)
	v_mfma_f32_32x32x16_bf16 a[32:47], v[10:13], v[14:17], a[32:47]
	v_mfma_f32_32x32x16_bf16 a[16:31], v[10:13], v[72:75], a[16:31]
	ds_read_b128 v[10:13], v60 offset:55360
	v_mfma_f32_32x32x16_bf16 a[176:191], v[64:67], v[68:71], a[176:191]
	v_mfma_f32_32x32x16_bf16 a[160:175], v[64:67], v[76:79], a[160:175]
	v_mfma_f32_32x32x16_bf16 a[144:159], v[80:83], v[68:71], a[144:159]
	v_mfma_f32_32x32x16_bf16 a[128:143], v[80:83], v[76:79], a[128:143]
	v_mfma_f32_32x32x16_bf16 a[64:79], v[84:87], v[68:71], a[64:79]
	v_mfma_f32_32x32x16_bf16 a[48:63], v[84:87], v[76:79], a[48:63]
	ds_read_b128 v[14:17], v56 offset:64
	ds_read_b128 v[64:67], v61 offset:55360
	ds_read_b128 v[72:75], v61 offset:55392
	ds_read_b128 v[80:83], v60 offset:64576
	ds_read_b128 v[84:87], v60 offset:64608
	ds_read_b128 v[92:95], v60 offset:55392
	ds_read_b128 v[96:99], v56 offset:96
	ds_read_b128 v[100:103], v60 offset:59968
	ds_read_b128 v[104:107], v60 offset:60000
	ds_read_b128 v[108:111], v56 offset:4672
	ds_read_b128 v[112:115], v56 offset:4704
	s_waitcnt lgkmcnt(0)
	s_barrier
	v_mfma_f32_32x32x16_bf16 a[32:47], v[88:91], v[68:71], a[32:47]
	v_add_u32_e32 v70, 0x2048, v21
	v_mfma_f32_32x32x16_bf16 a[16:31], v[88:91], v[76:79], a[16:31]
	v_accvgpr_read_b32 v76, a222
	v_accvgpr_read_b32 v77, a223
	v_accvgpr_read_b32 v78, a224
	v_accvgpr_read_b32 v79, a225
	v_mfma_f32_32x32x16_bf16 a[176:191], v[10:13], v[14:17], a[176:191]
	v_mfma_f32_32x32x16_bf16 a[160:175], v[10:13], v[108:111], a[160:175]
	v_lshl_add_u64 v[10:11], v[6:7], 0, s[44:45]
	v_mfma_f32_32x32x16_bf16 a[144:159], v[100:103], v[14:17], a[144:159]
	v_mfma_f32_32x32x16_bf16 a[128:143], v[100:103], v[108:111], a[128:143]
	v_mfma_f32_32x32x16_bf16 a[64:79], v[80:83], v[14:17], a[64:79]
	v_mfma_f32_32x32x16_bf16 a[48:63], v[80:83], v[108:111], a[48:63]
	v_accvgpr_read_b32 v80, a226
	v_mfma_f32_32x32x16_bf16 a[32:47], v[64:67], v[14:17], a[32:47]
	v_mfma_f32_32x32x16_bf16 a[16:31], v[64:67], v[108:111], a[16:31]
	v_add_u32_e32 v66, 0x1028, v21
	v_mfma_f32_32x32x16_bf16 a[176:191], v[92:95], v[96:99], a[176:191]
	s_nop 11
	ds_write_b32 v49, a176
	ds_write_b32 v49, a177 offset:516
	ds_write_b32 v49, a178 offset:1032
	ds_write_b32 v49, a179 offset:1548
	ds_write_b32 v49, a180 offset:4128
	ds_write_b32 v49, a181 offset:4644
	ds_write_b32 v49, a182 offset:5160
	v_mfma_f32_32x32x16_bf16 a[160:175], v[92:95], v[112:115], a[160:175]
	ds_write_b32 v49, a183 offset:5676
	ds_write_b32 v49, a184 offset:8256
	ds_write_b32 v49, a185 offset:8772
	ds_write_b32 v49, a186 offset:9288
	ds_write_b32 v49, a187 offset:9804
	ds_write_b32 v49, a188 offset:12384
	ds_write_b32 v49, a189 offset:12900
	ds_write_b32 v49, a190 offset:13416
	ds_write_b32 v49, a191 offset:13932
	s_nop 2
	ds_write_b32 v49, a160 offset:128
	ds_write_b32 v49, a161 offset:644
	ds_write_b32 v49, a162 offset:1160
	ds_write_b32 v49, a163 offset:1676
	ds_write_b32 v49, a164 offset:4256
	ds_write_b32 v49, a165 offset:4772
	ds_write_b32 v49, a166 offset:5288
	ds_write_b32 v49, a167 offset:5804
	ds_write_b32 v49, a168 offset:8384
	ds_write_b32 v49, a169 offset:8900
	ds_write_b32 v49, a170 offset:9416
	ds_write_b32 v49, a171 offset:9932
	v_mfma_f32_32x32x16_bf16 a[144:159], v[104:107], v[96:99], a[144:159]
	ds_write_b32 v49, a172 offset:12512
	ds_write_b32 v49, a173 offset:13028
	ds_write_b32 v49, a174 offset:13544
	ds_write_b32 v49, a175 offset:14060
	s_nop 7
	ds_write_b32 v49, a144 offset:16512
	ds_write_b32 v49, a145 offset:17028
	ds_write_b32 v49, a146 offset:17544
	ds_write_b32 v49, a147 offset:18060
	ds_write_b32 v49, a148 offset:20640
	ds_write_b32 v49, a149 offset:21156
	ds_write_b32 v49, a150 offset:21672
	ds_write_b32 v49, a151 offset:22188
	ds_write_b32 v49, a152 offset:24768
	ds_write_b32 v49, a153 offset:25284
	v_mfma_f32_32x32x16_bf16 a[128:143], v[104:107], v[112:115], a[128:143]
	ds_write_b32 v49, a154 offset:25800
	ds_write_b32 v49, a155 offset:26316
	ds_write_b32 v49, a156 offset:28896
	ds_write_b32 v49, a157 offset:29412
	ds_write_b32 v49, a158 offset:29928
	ds_write_b32 v49, a159 offset:30444
	s_nop 5
	ds_write_b32 v49, a128 offset:16640
	ds_write_b32 v49, a129 offset:17156
	ds_write_b32 v49, a130 offset:17672
	ds_write_b32 v49, a131 offset:18188
	ds_write_b32 v49, a132 offset:20768
	ds_write_b32 v49, a133 offset:21284
	ds_write_b32 v49, a134 offset:21800
	ds_write_b32 v49, a135 offset:22316
	v_mfma_f32_32x32x16_bf16 a[64:79], v[84:87], v[96:99], a[64:79]
	ds_write_b32 v49, a136 offset:24896
	ds_write_b32 v49, a137 offset:25412
	ds_write_b32 v49, a138 offset:25928
	ds_write_b32 v49, a139 offset:26444
	ds_write_b32 v49, a140 offset:29024
	ds_write_b32 v49, a141 offset:29540
	ds_write_b32 v49, a142 offset:30056
	ds_write_b32 v49, a143 offset:30572
	s_nop 3
	ds_write_b32 v49, a64 offset:33024
	ds_write_b32 v49, a65 offset:33540
	ds_write_b32 v49, a66 offset:34056
	ds_write_b32 v49, a67 offset:34572
	ds_write_b32 v49, a68 offset:37152
	ds_write_b32 v49, a69 offset:37668
	v_mfma_f32_32x32x16_bf16 a[48:63], v[84:87], v[112:115], a[48:63]
	ds_write_b32 v49, a70 offset:38184
	ds_write_b32 v49, a71 offset:38700
	ds_write_b32 v49, a72 offset:41280
	ds_write_b32 v49, a73 offset:41796
	ds_write_b32 v49, a74 offset:42312
	ds_write_b32 v49, a75 offset:42828
	ds_write_b32 v49, a76 offset:45408
	ds_write_b32 v49, a77 offset:45924
	ds_write_b32 v49, a78 offset:46440
	ds_write_b32 v49, a79 offset:46956
	s_nop 1
	ds_write_b32 v49, a48 offset:33152
	ds_write_b32 v49, a49 offset:33668
	ds_write_b32 v49, a50 offset:34184
	ds_write_b32 v49, a51 offset:34700
	ds_write_b32 v49, a52 offset:37280
	ds_write_b32 v49, a53 offset:37796
	ds_write_b32 v49, a54 offset:38312
	ds_write_b32 v49, a55 offset:38828
	ds_write_b32 v49, a56 offset:41408
	ds_write_b32 v49, a57 offset:41924
	ds_write_b32 v49, a58 offset:42440
	v_mfma_f32_32x32x16_bf16 a[32:47], v[72:75], v[96:99], a[32:47]
	ds_write_b32 v49, a59 offset:42956
	ds_write_b32 v49, a60 offset:45536
	ds_write_b32 v49, a61 offset:46052
	ds_write_b32 v49, a62 offset:46568
	ds_write_b32 v49, a63 offset:47084
	s_nop 6
	ds_write_b32 v49, a32 offset:49536
	ds_write_b32 v49, a33 offset:50052
	ds_write_b32 v49, a34 offset:50568
	ds_write_b32 v49, a35 offset:51084
	ds_write_b32 v49, a36 offset:53664
	ds_write_b32 v49, a37 offset:54180
	ds_write_b32 v49, a38 offset:54696
	ds_write_b32 v49, a39 offset:55212
	ds_write_b32 v49, a40 offset:57792
	v_mfma_f32_32x32x16_bf16 a[16:31], v[72:75], v[112:115], a[16:31]
	ds_write_b32 v49, a41 offset:58308
	ds_write_b32 v49, a42 offset:58824
	ds_write_b32 v49, a43 offset:59340
	ds_write_b32 v49, a44 offset:61920
	ds_write_b32 v49, a45 offset:62436
	ds_write_b32 v49, a46 offset:62952
	ds_write_b32 v49, a47 offset:63468
	s_nop 4
	ds_write_b32 v49, a16 offset:49664
	ds_write_b32 v49, a17 offset:50180
	ds_write_b32 v49, a18 offset:50696
	ds_write_b32 v49, a19 offset:51212
	ds_write_b32 v49, a20 offset:53792
	ds_write_b32 v49, a21 offset:54308
	ds_write_b32 v49, a22 offset:54824
	ds_write_b32 v49, a23 offset:55340
	ds_write_b32 v49, a24 offset:57920
	ds_write_b32 v49, a25 offset:58436
	ds_write_b32 v49, a26 offset:58952
	ds_write_b32 v49, a27 offset:59468
	ds_write_b32 v49, a28 offset:62048
	ds_write_b32 v49, a29 offset:62564
	ds_write_b32 v49, a30 offset:63080
	ds_write_b32 v49, a31 offset:63596
	s_waitcnt lgkmcnt(0)
	s_barrier
	ds_read2_b32 v[16:17], v21 offset1:1
	ds_read2_b32 v[18:19], v21 offset0:2 offset1:3
	v_accvgpr_read_b32 v72, a218
	v_or_b32_e32 v0, s46, v72
	v_lshlrev_b32_e32 v0, 11, v0
	s_waitcnt lgkmcnt(1)
	v_cvt_pk_bf16_f32 v16, v16, v17
	s_waitcnt lgkmcnt(0)
	v_cvt_pk_bf16_f32 v17, v18, v19
	v_lshl_add_u64 v[18:19], v[10:11], 0, v[0:1]
	v_add_u32_e32 v0, 0x1020, v21
	ds_read2_b32 v[12:13], v29 offset1:1
	ds_read2_b32 v[14:15], v29 offset0:2 offset1:3
	ds_read2_b32 v[64:65], v0 offset1:1
	ds_read2_b32 v[66:67], v66 offset1:1
	v_accvgpr_read_b32 v73, a219
	v_or_b32_e32 v0, s46, v73
	v_lshlrev_b32_e32 v0, 11, v0
	global_store_dwordx2 v[18:19], v[16:17], off
	s_waitcnt lgkmcnt(1)
	v_cvt_pk_bf16_f32 v64, v64, v65
	s_waitcnt lgkmcnt(0)
	v_cvt_pk_bf16_f32 v65, v66, v67
	v_lshl_add_u64 v[66:67], v[10:11], 0, v[0:1]
	v_add_u32_e32 v0, 0x2040, v21
	ds_read2_b32 v[16:17], v44 offset1:1
	ds_read2_b32 v[18:19], v44 offset0:2 offset1:3
	ds_read2_b32 v[68:69], v0 offset1:1
	ds_read2_b32 v[70:71], v70 offset1:1
	global_store_dwordx2 v[66:67], v[64:65], off
	v_add_u32_e32 v0, 0x3060, v21
	v_add_u32_e32 v66, 0x3068, v21
	ds_read2_b32 v[64:65], v0 offset1:1
	ds_read2_b32 v[66:67], v66 offset1:1
	v_accvgpr_read_b32 v74, a220
	v_or_b32_e32 v0, s46, v74
	v_lshlrev_b32_e32 v0, 11, v0
	v_accvgpr_read_b32 v75, a221
	s_waitcnt lgkmcnt(3)
	v_cvt_pk_bf16_f32 v68, v68, v69
	s_waitcnt lgkmcnt(2)
	v_cvt_pk_bf16_f32 v69, v70, v71
	v_lshl_add_u64 v[70:71], v[10:11], 0, v[0:1]
	v_or_b32_e32 v0, s46, v75
	v_lshlrev_b32_e32 v0, 11, v0
	global_store_dwordx2 v[70:71], v[68:69], off
	s_waitcnt lgkmcnt(1)
	v_cvt_pk_bf16_f32 v64, v64, v65
	s_waitcnt lgkmcnt(0)
	v_cvt_pk_bf16_f32 v65, v66, v67
	v_lshl_add_u64 v[66:67], v[10:11], 0, v[0:1]
	v_add_u32_e32 v0, 0x4080, v21
	v_add_u32_e32 v70, 0x4088, v21
	ds_read2_b32 v[68:69], v0 offset1:1
	ds_read2_b32 v[70:71], v70 offset1:1
	global_store_dwordx2 v[66:67], v[64:65], off
	v_add_u32_e32 v0, 0x50a0, v21
	v_add_u32_e32 v66, 0x50a8, v21
	ds_read2_b32 v[64:65], v0 offset1:1
	ds_read2_b32 v[66:67], v66 offset1:1
	v_or_b32_e32 v0, s46, v76
	v_lshlrev_b32_e32 v0, 11, v0
	s_waitcnt lgkmcnt(3)
	v_cvt_pk_bf16_f32 v68, v68, v69
	s_waitcnt lgkmcnt(2)
	v_cvt_pk_bf16_f32 v69, v70, v71
	v_lshl_add_u64 v[70:71], v[10:11], 0, v[0:1]
	v_or_b32_e32 v0, s46, v77
	v_lshlrev_b32_e32 v0, 11, v0
	global_store_dwordx2 v[70:71], v[68:69], off
	s_waitcnt lgkmcnt(1)
	v_cvt_pk_bf16_f32 v64, v64, v65
	s_waitcnt lgkmcnt(0)
	v_cvt_pk_bf16_f32 v65, v66, v67
	v_lshl_add_u64 v[66:67], v[10:11], 0, v[0:1]
	v_add_u32_e32 v0, 0x60c0, v21
	v_add_u32_e32 v70, 0x60c8, v21
	ds_read2_b32 v[68:69], v0 offset1:1
	ds_read2_b32 v[70:71], v70 offset1:1
	global_store_dwordx2 v[66:67], v[64:65], off
	v_add_u32_e32 v0, 0x70e0, v21
	v_add_u32_e32 v66, 0x70e8, v21
	ds_read2_b32 v[64:65], v0 offset1:1
	ds_read2_b32 v[66:67], v66 offset1:1
	v_or_b32_e32 v0, s46, v78
	v_lshlrev_b32_e32 v0, 11, v0
	s_waitcnt lgkmcnt(3)
	v_cvt_pk_bf16_f32 v68, v68, v69
	s_waitcnt lgkmcnt(2)
	v_cvt_pk_bf16_f32 v69, v70, v71
	v_lshl_add_u64 v[70:71], v[10:11], 0, v[0:1]
	v_or_b32_e32 v0, s46, v79
	v_lshlrev_b32_e32 v0, 11, v0
	global_store_dwordx2 v[70:71], v[68:69], off
	s_waitcnt lgkmcnt(1)
	v_cvt_pk_bf16_f32 v64, v64, v65
	s_waitcnt lgkmcnt(0)
	v_cvt_pk_bf16_f32 v65, v66, v67
	v_lshl_add_u64 v[66:67], v[10:11], 0, v[0:1]
	v_add_u32_e32 v0, 0x8100, v21
	v_add_u32_e32 v70, 0x8108, v21
	ds_read2_b32 v[68:69], v0 offset1:1
	ds_read2_b32 v[70:71], v70 offset1:1
	global_store_dwordx2 v[66:67], v[64:65], off
	v_add_u32_e32 v0, 0x9120, v21
	v_add_u32_e32 v66, 0x9128, v21
	ds_read2_b32 v[64:65], v0 offset1:1
	ds_read2_b32 v[66:67], v66 offset1:1
	v_or_b32_e32 v0, s46, v80
	v_lshlrev_b32_e32 v0, 11, v0
	s_waitcnt lgkmcnt(3)
	v_cvt_pk_bf16_f32 v68, v68, v69
	s_waitcnt lgkmcnt(2)
	v_cvt_pk_bf16_f32 v69, v70, v71
	v_lshl_add_u64 v[70:71], v[10:11], 0, v[0:1]
	v_or_b32_e32 v0, s46, v22
	v_lshlrev_b32_e32 v0, 11, v0
	global_store_dwordx2 v[70:71], v[68:69], off
	s_waitcnt lgkmcnt(1)
	v_cvt_pk_bf16_f32 v64, v64, v65
	s_waitcnt lgkmcnt(0)
	v_cvt_pk_bf16_f32 v65, v66, v67
	v_lshl_add_u64 v[66:67], v[10:11], 0, v[0:1]
	v_add_u32_e32 v0, 0xa140, v21
	v_add_u32_e32 v70, 0xa148, v21
	ds_read2_b32 v[68:69], v0 offset1:1
	ds_read2_b32 v[70:71], v70 offset1:1
	global_store_dwordx2 v[66:67], v[64:65], off
	v_add_u32_e32 v0, 0xb160, v21
	v_add_u32_e32 v66, 0xb168, v21
	ds_read2_b32 v[64:65], v0 offset1:1
	ds_read2_b32 v[66:67], v66 offset1:1
	v_or_b32_e32 v0, s46, v23
	v_lshlrev_b32_e32 v0, 11, v0
	s_waitcnt lgkmcnt(3)
	v_cvt_pk_bf16_f32 v68, v68, v69
	s_waitcnt lgkmcnt(2)
	v_cvt_pk_bf16_f32 v69, v70, v71
	v_lshl_add_u64 v[70:71], v[10:11], 0, v[0:1]
	v_or_b32_e32 v0, s46, v24
	v_lshlrev_b32_e32 v0, 11, v0
	global_store_dwordx2 v[70:71], v[68:69], off
	s_waitcnt lgkmcnt(1)
	v_cvt_pk_bf16_f32 v64, v64, v65
	s_waitcnt lgkmcnt(0)
	v_cvt_pk_bf16_f32 v65, v66, v67
	v_lshl_add_u64 v[66:67], v[10:11], 0, v[0:1]
	v_add_u32_e32 v0, 0xc180, v21
	v_add_u32_e32 v70, 0xc188, v21
	ds_read2_b32 v[68:69], v0 offset1:1
	ds_read2_b32 v[70:71], v70 offset1:1
	global_store_dwordx2 v[66:67], v[64:65], off
	v_add_u32_e32 v0, 0xd1a0, v21
	v_add_u32_e32 v66, 0xd1a8, v21
	ds_read2_b32 v[64:65], v0 offset1:1
	ds_read2_b32 v[66:67], v66 offset1:1
	v_or_b32_e32 v0, s46, v25
	v_lshlrev_b32_e32 v0, 11, v0
	s_waitcnt lgkmcnt(3)
	v_cvt_pk_bf16_f32 v68, v68, v69
	s_waitcnt lgkmcnt(2)
	v_cvt_pk_bf16_f32 v69, v70, v71
	v_lshl_add_u64 v[70:71], v[10:11], 0, v[0:1]
	v_or_b32_e32 v0, s46, v26
	v_lshlrev_b32_e32 v0, 11, v0
	global_store_dwordx2 v[70:71], v[68:69], off
	s_waitcnt lgkmcnt(1)
	v_cvt_pk_bf16_f32 v64, v64, v65
	s_waitcnt lgkmcnt(0)
	v_cvt_pk_bf16_f32 v65, v66, v67
	v_lshl_add_u64 v[66:67], v[10:11], 0, v[0:1]
	v_add_u32_e32 v0, 0xe1c0, v21
	v_add_u32_e32 v70, 0xe1c8, v21
	ds_read2_b32 v[68:69], v0 offset1:1
	ds_read2_b32 v[70:71], v70 offset1:1
	global_store_dwordx2 v[66:67], v[64:65], off
	v_add_u32_e32 v0, 0xf1e0, v21
	v_add_u32_e32 v66, 0xf1e8, v21
	ds_read2_b32 v[64:65], v0 offset1:1
	ds_read2_b32 v[66:67], v66 offset1:1
	v_or_b32_e32 v0, s46, v27
	v_lshlrev_b32_e32 v0, 11, v0
	s_waitcnt lgkmcnt(3)
	v_cvt_pk_bf16_f32 v68, v68, v69
	s_waitcnt lgkmcnt(2)
	v_cvt_pk_bf16_f32 v69, v70, v71
	v_lshl_add_u64 v[70:71], v[10:11], 0, v[0:1]
	v_or_b32_e32 v0, s46, v28
	v_lshlrev_b32_e32 v0, 11, v0
	s_bitset1_b32 s46, 7
	s_waitcnt lgkmcnt(1)
	v_cvt_pk_bf16_f32 v64, v64, v65
	s_waitcnt lgkmcnt(0)
	v_cvt_pk_bf16_f32 v65, v66, v67
	v_lshl_add_u64 v[66:67], v[10:11], 0, v[0:1]
	v_or_b32_e32 v0, s46, v72
	global_store_dwordx2 v[70:71], v[68:69], off
	global_store_dwordx2 v[66:67], v[64:65], off
	v_lshlrev_b32_e32 v0, 11, v0
	v_cvt_pk_bf16_f32 v12, v12, v13
	v_cvt_pk_bf16_f32 v13, v14, v15
	v_lshl_add_u64 v[14:15], v[10:11], 0, v[0:1]
	ds_read2_b32 v[64:65], v30 offset1:1
	ds_read2_b32 v[66:67], v30 offset0:2 offset1:3
	global_store_dwordx2 v[14:15], v[12:13], off
	ds_read2_b32 v[12:13], v31 offset1:1
	ds_read2_b32 v[14:15], v31 offset0:2 offset1:3
	v_or_b32_e32 v0, s46, v73
	v_lshlrev_b32_e32 v0, 11, v0
	s_waitcnt lgkmcnt(3)
	v_cvt_pk_bf16_f32 v64, v64, v65
	s_waitcnt lgkmcnt(2)
	v_cvt_pk_bf16_f32 v65, v66, v67
	v_lshl_add_u64 v[66:67], v[10:11], 0, v[0:1]
	v_or_b32_e32 v0, s46, v74
	global_store_dwordx2 v[66:67], v[64:65], off
	v_lshlrev_b32_e32 v0, 11, v0
	s_waitcnt lgkmcnt(1)
	v_cvt_pk_bf16_f32 v12, v12, v13
	s_waitcnt lgkmcnt(0)
	v_cvt_pk_bf16_f32 v13, v14, v15
	v_lshl_add_u64 v[14:15], v[10:11], 0, v[0:1]
	ds_read2_b32 v[64:65], v32 offset1:1
	ds_read2_b32 v[66:67], v32 offset0:2 offset1:3
	global_store_dwordx2 v[14:15], v[12:13], off
	ds_read2_b32 v[12:13], v33 offset1:1
	ds_read2_b32 v[14:15], v33 offset0:2 offset1:3
	v_or_b32_e32 v0, s46, v75
	v_lshlrev_b32_e32 v0, 11, v0
	s_waitcnt lgkmcnt(3)
	v_cvt_pk_bf16_f32 v64, v64, v65
	s_waitcnt lgkmcnt(2)
	v_cvt_pk_bf16_f32 v65, v66, v67
	v_lshl_add_u64 v[66:67], v[10:11], 0, v[0:1]
	v_or_b32_e32 v0, s46, v76
	global_store_dwordx2 v[66:67], v[64:65], off
	v_lshlrev_b32_e32 v0, 11, v0
	s_waitcnt lgkmcnt(1)
	v_cvt_pk_bf16_f32 v12, v12, v13
	s_waitcnt lgkmcnt(0)
	v_cvt_pk_bf16_f32 v13, v14, v15
	v_lshl_add_u64 v[14:15], v[10:11], 0, v[0:1]
	ds_read2_b32 v[64:65], v34 offset1:1
	ds_read2_b32 v[66:67], v34 offset0:2 offset1:3
	global_store_dwordx2 v[14:15], v[12:13], off
	ds_read2_b32 v[12:13], v35 offset1:1
	ds_read2_b32 v[14:15], v35 offset0:2 offset1:3
	v_or_b32_e32 v0, s46, v77
	v_lshlrev_b32_e32 v0, 11, v0
	s_waitcnt lgkmcnt(3)
	v_cvt_pk_bf16_f32 v64, v64, v65
	s_waitcnt lgkmcnt(2)
	v_cvt_pk_bf16_f32 v65, v66, v67
	v_lshl_add_u64 v[66:67], v[10:11], 0, v[0:1]
	v_or_b32_e32 v0, s46, v78
	global_store_dwordx2 v[66:67], v[64:65], off
	v_lshlrev_b32_e32 v0, 11, v0
	s_waitcnt lgkmcnt(1)
	v_cvt_pk_bf16_f32 v12, v12, v13
	s_waitcnt lgkmcnt(0)
	v_cvt_pk_bf16_f32 v13, v14, v15
	v_lshl_add_u64 v[14:15], v[10:11], 0, v[0:1]
	ds_read2_b32 v[64:65], v36 offset1:1
	ds_read2_b32 v[66:67], v36 offset0:2 offset1:3
	global_store_dwordx2 v[14:15], v[12:13], off
	ds_read2_b32 v[12:13], v37 offset1:1
	ds_read2_b32 v[14:15], v37 offset0:2 offset1:3
	v_or_b32_e32 v0, s46, v79
	v_lshlrev_b32_e32 v0, 11, v0
	s_waitcnt lgkmcnt(3)
	v_cvt_pk_bf16_f32 v64, v64, v65
	s_waitcnt lgkmcnt(2)
	v_cvt_pk_bf16_f32 v65, v66, v67
	v_lshl_add_u64 v[66:67], v[10:11], 0, v[0:1]
	v_or_b32_e32 v0, s46, v80
	global_store_dwordx2 v[66:67], v[64:65], off
	v_lshlrev_b32_e32 v0, 11, v0
	s_waitcnt lgkmcnt(1)
	v_cvt_pk_bf16_f32 v12, v12, v13
	s_waitcnt lgkmcnt(0)
	v_cvt_pk_bf16_f32 v13, v14, v15
	v_lshl_add_u64 v[14:15], v[10:11], 0, v[0:1]
	ds_read2_b32 v[64:65], v38 offset1:1
	ds_read2_b32 v[66:67], v38 offset0:2 offset1:3
	global_store_dwordx2 v[14:15], v[12:13], off
	ds_read2_b32 v[12:13], v39 offset1:1
	ds_read2_b32 v[14:15], v39 offset0:2 offset1:3
	v_or_b32_e32 v0, s46, v22
	v_lshlrev_b32_e32 v0, 11, v0
	s_waitcnt lgkmcnt(3)
	v_cvt_pk_bf16_f32 v64, v64, v65
	s_waitcnt lgkmcnt(2)
	v_cvt_pk_bf16_f32 v65, v66, v67
	v_lshl_add_u64 v[66:67], v[10:11], 0, v[0:1]
	v_or_b32_e32 v0, s46, v23
	global_store_dwordx2 v[66:67], v[64:65], off
	v_lshlrev_b32_e32 v0, 11, v0
	s_waitcnt lgkmcnt(1)
	v_cvt_pk_bf16_f32 v12, v12, v13
	s_waitcnt lgkmcnt(0)
	v_cvt_pk_bf16_f32 v13, v14, v15
	v_lshl_add_u64 v[14:15], v[10:11], 0, v[0:1]
	ds_read2_b32 v[64:65], v40 offset1:1
	ds_read2_b32 v[66:67], v40 offset0:2 offset1:3
	global_store_dwordx2 v[14:15], v[12:13], off
	ds_read2_b32 v[12:13], v41 offset1:1
	ds_read2_b32 v[14:15], v41 offset0:2 offset1:3
	v_or_b32_e32 v0, s46, v24
	v_lshlrev_b32_e32 v0, 11, v0
	s_waitcnt lgkmcnt(3)
	v_cvt_pk_bf16_f32 v64, v64, v65
	s_waitcnt lgkmcnt(2)
	v_cvt_pk_bf16_f32 v65, v66, v67
	v_lshl_add_u64 v[66:67], v[10:11], 0, v[0:1]
	v_or_b32_e32 v0, s46, v25
	v_lshlrev_b32_e32 v0, 11, v0
	global_store_dwordx2 v[66:67], v[64:65], off
	s_waitcnt lgkmcnt(1)
	v_cvt_pk_bf16_f32 v12, v12, v13
	s_waitcnt lgkmcnt(0)
	v_cvt_pk_bf16_f32 v13, v14, v15
	v_lshl_add_u64 v[14:15], v[10:11], 0, v[0:1]
	ds_read2_b32 v[64:65], v42 offset1:1
	ds_read2_b32 v[66:67], v42 offset0:2 offset1:3
	global_store_dwordx2 v[14:15], v[12:13], off
	ds_read2_b32 v[12:13], v43 offset1:1
	ds_read2_b32 v[14:15], v43 offset0:2 offset1:3
	v_add_lshl_u32 v0, s46, v26, 11
	s_waitcnt lgkmcnt(3)
	v_cvt_pk_bf16_f32 v64, v64, v65
	s_waitcnt lgkmcnt(2)
	v_cvt_pk_bf16_f32 v65, v66, v67
	v_lshl_add_u64 v[66:67], v[10:11], 0, v[0:1]
	v_add_lshl_u32 v0, s46, v27, 11
	s_waitcnt lgkmcnt(1)
	v_cvt_pk_bf16_f32 v12, v12, v13
	s_waitcnt lgkmcnt(0)
	v_cvt_pk_bf16_f32 v13, v14, v15
	v_lshl_add_u64 v[14:15], v[10:11], 0, v[0:1]
	v_add_lshl_u32 v0, s46, v28, 11
	global_store_dwordx2 v[14:15], v[12:13], off
	v_cvt_pk_bf16_f32 v12, v16, v17
	v_cvt_pk_bf16_f32 v13, v18, v19
	v_lshl_add_u64 v[10:11], v[10:11], 0, v[0:1]
	s_cmpk_lt_u32 s49, 0x60
	global_store_dwordx2 v[66:67], v[64:65], off
	global_store_dwordx2 v[10:11], v[12:13], off
	s_barrier
	s_cbranch_scc1 .LBB0_777

.LBB0_977:
	s_and_b32 s9, s8, 1
	s_mul_i32 s12, s9, 0xd800
	s_xor_b32 s9, s9, 1
	s_mul_i32 s9, s9, 0xd800
	s_add_i32 s8, s8, 1
	v_add_u32_e32 v186, s9, v131
	ds_read_b128 v[12:15], v189 offset:32
	ds_read_b128 v[24:27], v187 offset:36896
	ds_read_b128 v[16:19], v189 offset:4640
	ds_read_b128 v[28:31], v187 offset:41504
	ds_read_b128 v[20:23], v189 offset:9248
	ds_read_b128 v[74:77], v188 offset:32
	s_waitcnt lgkmcnt(6)
	v_mfma_f32_32x32x16_bf16 a[32:47], v[78:81], v[4:7], a[32:47]
	s_waitcnt vmcnt(11)
	ds_write_b128 v186, v[250:253]
	v_mfma_f32_32x32x16_bf16 a[48:63], v[78:81], v[8:11], a[48:63]
	s_waitcnt vmcnt(10)
	ds_write_b128 v186, v[246:249] offset:4608
	global_load_dwordx4 v[250:253], v254, s[100:101] offset:512
	v_mfma_f32_32x32x16_bf16 a[64:79], v[82:85], v[4:7], a[64:79]
	s_waitcnt vmcnt(10)
	ds_write_b128 v186, v[242:245] offset:9216
	global_load_dwordx4 v[246:249], v205, s[100:101] offset:512
	v_mfma_f32_32x32x16_bf16 a[96:111], v[82:85], v[8:11], a[96:111]
	s_waitcnt vmcnt(10)
	ds_write_b128 v186, v[238:241] offset:13824
	global_load_dwordx4 v[242:245], v204, s[100:101] offset:512
	v_mfma_f32_32x32x16_bf16 a[80:95], v[86:89], v[4:7], a[80:95]
	s_waitcnt vmcnt(10)
	ds_write_b128 v186, v[234:237] offset:18432
	global_load_dwordx4 v[238:241], v203, s[100:101] offset:512
	v_mfma_f32_32x32x16_bf16 a[112:127], v[86:89], v[8:11], a[112:127]
	s_waitcnt vmcnt(10)
	ds_write_b128 v186, v[230:233] offset:23040
	global_load_dwordx4 v[234:237], v202, s[100:101] offset:512
	s_waitcnt lgkmcnt(6)
	v_mfma_f32_32x32x16_bf16 a[16:31], v[90:93], v[4:7], a[16:31]
	s_waitcnt vmcnt(10)
	ds_write_b128 v186, v[226:229] offset:27648
	global_load_dwordx4 v[230:233], v201, s[100:101] offset:512
	v_mfma_f32_32x32x16_bf16 a[0:15], v[90:93], v[8:11], a[0:15]
	s_waitcnt vmcnt(10)
	ds_write_b128 v186, v[222:225] offset:32256
	global_load_dwordx4 v[226:229], v200, s[100:101] offset:512
	s_waitcnt lgkmcnt(8)
	ds_read_b128 v[78:81], v189 offset:64
	ds_read_b128 v[4:7], v187 offset:36928
	ds_read_b128 v[82:85], v189 offset:4672
	ds_read_b128 v[8:11], v187 offset:41536
	ds_read_b128 v[86:89], v189 offset:9280
	ds_read_b128 v[90:93], v188 offset:64
	v_mfma_f32_32x32x16_bf16 a[32:47], v[12:15], v[24:27], a[32:47]
	s_waitcnt lgkmcnt(12)
	s_waitcnt vmcnt(10)
	ds_write_b128 v186, v[218:221] offset:36864
	global_load_dwordx4 v[222:225], v199, s[100:101] offset:512
	v_mfma_f32_32x32x16_bf16 a[48:63], v[12:15], v[28:31], a[48:63]
	s_waitcnt lgkmcnt(12)
	s_waitcnt vmcnt(10)
	ds_write_b128 v186, v[214:217] offset:41472
	global_load_dwordx4 v[218:221], v198, s[98:99] offset:256
	v_mfma_f32_32x32x16_bf16 a[64:79], v[16:19], v[24:27], a[64:79]
	s_waitcnt lgkmcnt(12)
	s_waitcnt vmcnt(10)
	ds_write_b128 v186, v[210:213] offset:46080
	global_load_dwordx4 v[214:217], v197, s[98:99] offset:256
	v_mfma_f32_32x32x16_bf16 a[96:111], v[16:19], v[28:31], a[96:111]
	s_waitcnt lgkmcnt(12)
	s_waitcnt vmcnt(10)
	ds_write_b128 v186, v[206:209] offset:50688
	global_load_dwordx4 v[210:213], v196, s[98:99] offset:256
	v_mfma_f32_32x32x16_bf16 a[80:95], v[20:23], v[24:27], a[80:95]
	global_load_dwordx4 v[206:209], v195, s[98:99] offset:256
	s_add_u32 s100, s100, 0x80
	s_addc_u32 s101, s101, 0
	s_add_u32 s98, s98, 0x80
	s_addc_u32 s99, s99, 0
	v_mfma_f32_32x32x16_bf16 a[112:127], v[20:23], v[28:31], a[112:127]
	v_mfma_f32_32x32x16_bf16 a[16:31], v[74:77], v[24:27], a[16:31]
	v_mfma_f32_32x32x16_bf16 a[0:15], v[74:77], v[28:31], a[0:15]
	s_waitcnt lgkmcnt(4)
	ds_read_b128 v[12:15], v189 offset:96
	ds_read_b128 v[24:27], v187 offset:36960
	ds_read_b128 v[16:19], v189 offset:4704
	ds_read_b128 v[28:31], v187 offset:41568
	ds_read_b128 v[20:23], v189 offset:9312
	ds_read_b128 v[74:77], v188 offset:96
	v_mfma_f32_32x32x16_bf16 a[32:47], v[78:81], v[4:7], a[32:47]
	v_mfma_f32_32x32x16_bf16 a[48:63], v[78:81], v[8:11], a[48:63]
	v_mfma_f32_32x32x16_bf16 a[64:79], v[82:85], v[4:7], a[64:79]
	v_mfma_f32_32x32x16_bf16 a[96:111], v[82:85], v[8:11], a[96:111]
	v_mfma_f32_32x32x16_bf16 a[80:95], v[86:89], v[4:7], a[80:95]
	v_mfma_f32_32x32x16_bf16 a[112:127], v[86:89], v[8:11], a[112:127]
	v_mfma_f32_32x32x16_bf16 a[16:31], v[90:93], v[4:7], a[16:31]
	v_mfma_f32_32x32x16_bf16 a[0:15], v[90:93], v[8:11], a[0:15]
	s_waitcnt lgkmcnt(0)
	v_mfma_f32_32x32x16_bf16 a[32:47], v[12:15], v[24:27], a[32:47]
	v_mfma_f32_32x32x16_bf16 a[48:63], v[12:15], v[28:31], a[48:63]
	v_mfma_f32_32x32x16_bf16 a[64:79], v[16:19], v[24:27], a[64:79]
	v_mfma_f32_32x32x16_bf16 a[96:111], v[16:19], v[28:31], a[96:111]
	s_barrier
	v_add_u32_e32 v189, s9, v192
	v_add_u32_e32 v188, s9, v191
	v_add_u32_e32 v187, s9, v190
	ds_read_b128 v[78:81], v189
	ds_read_b128 v[4:7], v187 offset:36864
	ds_read_b128 v[82:85], v189 offset:4608
	ds_read_b128 v[8:11], v187 offset:41472
	ds_read_b128 v[86:89], v189 offset:9216
	ds_read_b128 v[90:93], v188
	v_mfma_f32_32x32x16_bf16 a[80:95], v[20:23], v[24:27], a[80:95]
	v_mfma_f32_32x32x16_bf16 a[112:127], v[20:23], v[28:31], a[112:127]
	v_mfma_f32_32x32x16_bf16 a[16:31], v[74:77], v[24:27], a[16:31]
	v_mfma_f32_32x32x16_bf16 a[0:15], v[74:77], v[28:31], a[0:15]
	s_add_u32 s6, s6, 0x80
	s_addc_u32 s7, s7, 0
	s_cmpk_lg_i32 s6, 0x700
	s_cbranch_scc1 .LBB0_977
	ds_read_b128 v[0:3], v152
	ds_read_b128 v[78:81], v152 offset:4608
	ds_read_b128 v[82:85], v152 offset:9216
	ds_read_b128 v[86:89], v153
	ds_read_b128 v[90:93], v154 offset:36864
	ds_read_b128 v[94:97], v154 offset:41472
	s_waitcnt vmcnt(11)
	s_waitcnt vmcnt(0)
	ds_write_b128 v155, v[250:253] offset:55296
	s_waitcnt vmcnt(10)
	ds_write_b128 v155, v[246:249] offset:59904
	s_waitcnt vmcnt(9)
	ds_write_b128 v155, v[242:245] offset:64512
	s_waitcnt vmcnt(8)
	ds_write_b128 v53, v[238:241] offset:55296
	s_waitcnt vmcnt(7)
	ds_write_b128 v135, v[234:237] offset:55296
	s_waitcnt vmcnt(6)
	ds_write_b128 v139, v[230:233] offset:55296
	s_waitcnt vmcnt(5)
	ds_write_b128 v144, v[226:229] offset:55296
	s_waitcnt vmcnt(4)
	ds_write_b128 v145, v[222:225] offset:55296
	s_waitcnt vmcnt(3)
	ds_write_b128 v146, v[218:221]
	s_waitcnt vmcnt(2)
	ds_write_b128 v146, v[214:217] offset:4608
	s_waitcnt vmcnt(1)
	ds_write_b128 v146, v[210:213] offset:9216
	s_waitcnt vmcnt(0)
	ds_write_b128 v146, v[206:209] offset:13824
	s_lshl_b32 s75, s74, 8
	s_cmp_gt_u32 s74, 31
	s_waitcnt lgkmcnt(13)
	v_mfma_f32_32x32x16_bf16 a[144:159], v[78:81], v[90:93], a[64:79]
	s_cselect_b64 s[60:61], -1, 0
	s_add_i32 s6, s75, 0xffffe000
	s_lshr_b32 s12, s6, 12
	s_cmp_lt_u32 s74, 32
	s_cselect_b64 s[8:9], -1, 0
	s_and_b64 s[6:7], s[8:9], exec
	s_cselect_b32 s6, 32, 0xf00
	s_waitcnt lgkmcnt(12)
	v_mfma_f32_32x32x16_bf16 a[160:175], v[0:3], v[94:97], a[48:63]
	s_cselect_b32 s93, s74, s12
	s_and_b32 s92, s6, s75
	s_cmp_lt_u32 s73, 16
	s_cselect_b64 s[62:63], -1, 0
	s_mov_b64 s[6:7], -1
	s_and_b64 vcc, exec, s[62:63]
	v_mfma_f32_32x32x16_bf16 a[128:143], v[78:81], v[94:97], a[96:111]
	v_mfma_f32_32x32x16_bf16 a[64:79], v[82:85], v[90:93], a[80:95]
	v_mfma_f32_32x32x16_bf16 a[48:63], v[82:85], v[94:97], a[112:127]
	v_mfma_f32_32x32x16_bf16 a[176:191], v[0:3], v[90:93], a[32:47]
	ds_read_b128 v[0:3], v152 offset:4640
	ds_read_b128 v[4:7], v152 offset:9248
	ds_read_b128 v[8:11], v154 offset:41504
	ds_read_b128 v[12:15], v154 offset:36896
	ds_read_b128 v[16:19], v154 offset:36928
	ds_read_b128 v[20:23], v152 offset:32
	ds_read_b128 v[24:27], v152 offset:64
	v_mfma_f32_32x32x16_bf16 a[32:47], v[86:89], v[90:93], a[16:31]
	v_mfma_f32_32x32x16_bf16 a[16:31], v[86:89], v[94:97], a[0:15]
	s_waitcnt lgkmcnt(3)
	v_mfma_f32_32x32x16_bf16 a[144:159], v[0:3], v[12:15], a[144:159]
	v_mfma_f32_32x32x16_bf16 a[128:143], v[0:3], v[8:11], a[128:143]
	v_mfma_f32_32x32x16_bf16 a[64:79], v[4:7], v[12:15], a[64:79]
	v_mfma_f32_32x32x16_bf16 a[48:63], v[4:7], v[8:11], a[48:63]
	ds_read_b128 v[0:3], v153 offset:32
	ds_read_b128 v[4:7], v153 offset:64
	s_waitcnt lgkmcnt(3)
	v_mfma_f32_32x32x16_bf16 a[176:191], v[20:23], v[12:15], a[176:191]
	v_mfma_f32_32x32x16_bf16 a[160:175], v[20:23], v[8:11], a[160:175]
	s_waitcnt lgkmcnt(1)
	v_mfma_f32_32x32x16_bf16 a[32:47], v[0:3], v[12:15], a[32:47]
	v_mfma_f32_32x32x16_bf16 a[16:31], v[0:3], v[8:11], a[16:31]
	ds_read_b128 v[0:3], v154 offset:41536
	ds_read_b128 v[8:11], v152 offset:9280
	ds_read_b128 v[12:15], v152 offset:4672
	v_mfma_f32_32x32x16_bf16 a[176:191], v[24:27], v[16:19], a[176:191]
	s_waitcnt lgkmcnt(0)
	v_mfma_f32_32x32x16_bf16 a[144:159], v[12:15], v[16:19], a[144:159]
	v_mfma_f32_32x32x16_bf16 a[128:143], v[12:15], v[0:3], a[128:143]
	v_mfma_f32_32x32x16_bf16 a[64:79], v[8:11], v[16:19], a[64:79]
	v_mfma_f32_32x32x16_bf16 a[48:63], v[8:11], v[0:3], a[48:63]
	v_mfma_f32_32x32x16_bf16 a[160:175], v[24:27], v[0:3], a[160:175]
	v_mfma_f32_32x32x16_bf16 a[32:47], v[4:7], v[16:19], a[32:47]
	v_mfma_f32_32x32x16_bf16 a[16:31], v[4:7], v[0:3], a[16:31]
	ds_read_b128 v[0:3], v154 offset:41568
	ds_read_b128 v[4:7], v154 offset:36960
	ds_read_b128 v[8:11], v153 offset:96
	ds_read_b128 v[12:15], v152 offset:9312
	ds_read_b128 v[16:19], v152 offset:4704
	ds_read_b128 v[20:23], v152 offset:96
	s_waitcnt lgkmcnt(0)
	s_barrier
	v_mfma_f32_32x32x16_bf16 a[176:191], v[20:23], v[4:7], a[176:191]
	v_mfma_f32_32x32x16_bf16 a[144:159], v[16:19], v[4:7], a[144:159]
	v_mfma_f32_32x32x16_bf16 a[128:143], v[16:19], v[0:3], a[128:143]
	v_mfma_f32_32x32x16_bf16 a[64:79], v[12:15], v[4:7], a[64:79]
	v_mfma_f32_32x32x16_bf16 a[48:63], v[12:15], v[0:3], a[48:63]
	v_mfma_f32_32x32x16_bf16 a[160:175], v[20:23], v[0:3], a[160:175]
	v_mfma_f32_32x32x16_bf16 a[32:47], v[8:11], v[4:7], a[32:47]
	v_mfma_f32_32x32x16_bf16 a[16:31], v[8:11], v[0:3], a[16:31]
	ds_read_b128 v[0:3], v152 offset:59904
	ds_read_b128 v[4:7], v152 offset:64512
	ds_read_b128 v[8:11], v147 offset:4608
	ds_read_b128 v[12:15], v152 offset:55296
	ds_read_b128 v[16:19], v152 offset:55328
	ds_read_b128 v[20:23], v147
	ds_read_b128 v[24:27], v147 offset:32
	s_waitcnt lgkmcnt(1)
	v_mfma_f32_32x32x16_bf16 a[176:191], v[12:15], v[20:23], a[176:191]
	v_mfma_f32_32x32x16_bf16 a[144:159], v[0:3], v[20:23], a[144:159]
	v_mfma_f32_32x32x16_bf16 a[128:143], v[0:3], v[8:11], a[128:143]
	v_mfma_f32_32x32x16_bf16 a[64:79], v[4:7], v[20:23], a[64:79]
	v_mfma_f32_32x32x16_bf16 a[48:63], v[4:7], v[8:11], a[48:63]
	ds_read_b128 v[0:3], v153 offset:55296
	ds_read_b128 v[4:7], v153 offset:55328
	v_mfma_f32_32x32x16_bf16 a[160:175], v[12:15], v[8:11], a[160:175]
	s_waitcnt lgkmcnt(1)
	v_mfma_f32_32x32x16_bf16 a[32:47], v[0:3], v[20:23], a[32:47]
	v_mfma_f32_32x32x16_bf16 a[16:31], v[0:3], v[8:11], a[16:31]
	ds_read_b128 v[0:3], v152 offset:64544
	ds_read_b128 v[8:11], v152 offset:59936
	ds_read_b128 v[12:15], v147 offset:4640
	v_mfma_f32_32x32x16_bf16 a[176:191], v[16:19], v[24:27], a[176:191]
	s_waitcnt lgkmcnt(0)
	v_mfma_f32_32x32x16_bf16 a[160:175], v[16:19], v[12:15], a[160:175]
	v_mfma_f32_32x32x16_bf16 a[144:159], v[8:11], v[24:27], a[144:159]
	v_mfma_f32_32x32x16_bf16 a[128:143], v[8:11], v[12:15], a[128:143]
	v_mfma_f32_32x32x16_bf16 a[64:79], v[0:3], v[24:27], a[64:79]
	v_mfma_f32_32x32x16_bf16 a[48:63], v[0:3], v[12:15], a[48:63]
	v_mfma_f32_32x32x16_bf16 a[32:47], v[4:7], v[24:27], a[32:47]
	v_mfma_f32_32x32x16_bf16 a[16:31], v[4:7], v[12:15], a[16:31]
	ds_read_b128 v[0:3], v153 offset:55360
	ds_read_b128 v[4:7], v152 offset:64576
	ds_read_b128 v[8:11], v152 offset:59968
	ds_read_b128 v[12:15], v152 offset:55360
	ds_read_b128 v[16:19], v147 offset:64
	ds_read_b128 v[20:23], v147 offset:4672
	s_waitcnt lgkmcnt(1)
	v_mfma_f32_32x32x16_bf16 a[176:191], v[12:15], v[16:19], a[176:191]
	s_waitcnt lgkmcnt(0)
	v_mfma_f32_32x32x16_bf16 a[160:175], v[12:15], v[20:23], a[160:175]
	v_mfma_f32_32x32x16_bf16 a[144:159], v[8:11], v[16:19], a[144:159]
	v_mfma_f32_32x32x16_bf16 a[128:143], v[8:11], v[20:23], a[128:143]
	v_mfma_f32_32x32x16_bf16 a[64:79], v[4:7], v[16:19], a[64:79]
	v_mfma_f32_32x32x16_bf16 a[48:63], v[4:7], v[20:23], a[48:63]
	v_mfma_f32_32x32x16_bf16 a[32:47], v[0:3], v[16:19], a[32:47]
	v_mfma_f32_32x32x16_bf16 a[16:31], v[0:3], v[20:23], a[16:31]
	ds_read_b128 v[0:3], v153 offset:55392
	ds_read_b128 v[4:7], v152 offset:64608
	ds_read_b128 v[8:11], v152 offset:60000
	ds_read_b128 v[12:15], v152 offset:55392
	ds_read_b128 v[16:19], v147 offset:96
	ds_read_b128 v[20:23], v147 offset:4704
	s_waitcnt lgkmcnt(0)
	s_barrier
	v_mfma_f32_32x32x16_bf16 a[176:191], v[12:15], v[16:19], a[176:191]
	v_mfma_f32_32x32x16_bf16 a[32:47], v[0:3], v[16:19], a[32:47]
	v_mfma_f32_32x32x16_bf16 a[16:31], v[0:3], v[20:23], a[16:31]
	v_accvgpr_read_b32 v0, a212
	v_lshlrev_b32_e32 v0, 5, v0
	v_lshlrev_b32_e32 v74, 1, v0
	v_mfma_f32_32x32x16_bf16 a[160:175], v[12:15], v[20:23], a[160:175]
	v_mfma_f32_32x32x16_bf16 a[144:159], v[8:11], v[16:19], a[144:159]
	v_mfma_f32_32x32x16_bf16 a[128:143], v[8:11], v[20:23], a[128:143]
	v_mfma_f32_32x32x16_bf16 a[64:79], v[4:7], v[16:19], a[64:79]
	v_mfma_f32_32x32x16_bf16 a[48:63], v[4:7], v[20:23], a[48:63]
	s_nop 1
	ds_write_b32 v137, a176
	ds_write_b32 v137, a177 offset:516
	ds_write_b32 v137, a178 offset:1032
	ds_write_b32 v137, a179 offset:1548
	ds_write_b32 v137, a180 offset:4128
	ds_write_b32 v137, a181 offset:4644
	ds_write_b32 v137, a182 offset:5160
	ds_write_b32 v137, a183 offset:5676
	ds_write_b32 v137, a184 offset:8256
	ds_write_b32 v137, a185 offset:8772
	ds_write_b32 v137, a186 offset:9288
	ds_write_b32 v137, a187 offset:9804
	ds_write_b32 v137, a188 offset:12384
	ds_write_b32 v137, a189 offset:12900
	ds_write_b32 v137, a190 offset:13416
	ds_write_b32 v137, a191 offset:13932
	ds_write_b32 v137, a160 offset:128
	ds_write_b32 v137, a161 offset:644
	ds_write_b32 v137, a162 offset:1160
	ds_write_b32 v137, a163 offset:1676
	ds_write_b32 v137, a164 offset:4256
	ds_write_b32 v137, a165 offset:4772
	ds_write_b32 v137, a166 offset:5288
	ds_write_b32 v137, a167 offset:5804
	ds_write_b32 v137, a168 offset:8384
	ds_write_b32 v137, a169 offset:8900
	ds_write_b32 v137, a170 offset:9416
	ds_write_b32 v137, a171 offset:9932
	ds_write_b32 v137, a172 offset:12512
	ds_write_b32 v137, a173 offset:13028
	ds_write_b32 v137, a174 offset:13544
	ds_write_b32 v137, a175 offset:14060
	ds_write_b32 v137, a144 offset:16512
	ds_write_b32 v137, a145 offset:17028
	ds_write_b32 v137, a146 offset:17544
	ds_write_b32 v137, a147 offset:18060
	ds_write_b32 v137, a148 offset:20640
	ds_write_b32 v137, a149 offset:21156
	ds_write_b32 v137, a150 offset:21672
	ds_write_b32 v137, a151 offset:22188
	ds_write_b32 v137, a152 offset:24768
	ds_write_b32 v137, a153 offset:25284
	ds_write_b32 v137, a154 offset:25800
	ds_write_b32 v137, a155 offset:26316
	ds_write_b32 v137, a156 offset:28896
	ds_write_b32 v137, a157 offset:29412
	ds_write_b32 v137, a158 offset:29928
	ds_write_b32 v137, a159 offset:30444
	ds_write_b32 v137, a128 offset:16640
	ds_write_b32 v137, a129 offset:17156
	ds_write_b32 v137, a130 offset:17672
	ds_write_b32 v137, a131 offset:18188
	ds_write_b32 v137, a132 offset:20768
	ds_write_b32 v137, a133 offset:21284
	ds_write_b32 v137, a134 offset:21800
	ds_write_b32 v137, a135 offset:22316
	ds_write_b32 v137, a136 offset:24896
	ds_write_b32 v137, a137 offset:25412
	ds_write_b32 v137, a138 offset:25928
	ds_write_b32 v137, a139 offset:26444
	ds_write_b32 v137, a140 offset:29024
	ds_write_b32 v137, a141 offset:29540
	ds_write_b32 v137, a142 offset:30056
	ds_write_b32 v137, a143 offset:30572
	ds_write_b32 v137, a64 offset:33024
	ds_write_b32 v137, a65 offset:33540
	ds_write_b32 v137, a66 offset:34056
	ds_write_b32 v137, a67 offset:34572
	ds_write_b32 v137, a68 offset:37152
	ds_write_b32 v137, a69 offset:37668
	ds_write_b32 v137, a70 offset:38184
	ds_write_b32 v137, a71 offset:38700
	ds_write_b32 v137, a72 offset:41280
	ds_write_b32 v137, a73 offset:41796
	ds_write_b32 v137, a74 offset:42312
	ds_write_b32 v137, a75 offset:42828
	ds_write_b32 v137, a76 offset:45408
	ds_write_b32 v137, a77 offset:45924
	ds_write_b32 v137, a78 offset:46440
	ds_write_b32 v137, a79 offset:46956
	ds_write_b32 v137, a48 offset:33152
	ds_write_b32 v137, a49 offset:33668
	ds_write_b32 v137, a50 offset:34184
	ds_write_b32 v137, a51 offset:34700
	ds_write_b32 v137, a52 offset:37280
	ds_write_b32 v137, a53 offset:37796
	ds_write_b32 v137, a54 offset:38312
	ds_write_b32 v137, a55 offset:38828
	ds_write_b32 v137, a56 offset:41408
	ds_write_b32 v137, a57 offset:41924
	ds_write_b32 v137, a58 offset:42440
	ds_write_b32 v137, a59 offset:42956
	ds_write_b32 v137, a60 offset:45536
	ds_write_b32 v137, a61 offset:46052
	ds_write_b32 v137, a62 offset:46568
	ds_write_b32 v137, a63 offset:47084
	ds_write_b32 v137, a32 offset:49536
	ds_write_b32 v137, a33 offset:50052
	ds_write_b32 v137, a34 offset:50568
	ds_write_b32 v137, a35 offset:51084
	ds_write_b32 v137, a36 offset:53664
	ds_write_b32 v137, a37 offset:54180
	ds_write_b32 v137, a38 offset:54696
	ds_write_b32 v137, a39 offset:55212
	ds_write_b32 v137, a40 offset:57792
	ds_write_b32 v137, a41 offset:58308
	ds_write_b32 v137, a42 offset:58824
	ds_write_b32 v137, a43 offset:59340
	ds_write_b32 v137, a44 offset:61920
	ds_write_b32 v137, a45 offset:62436
	ds_write_b32 v137, a46 offset:62952
	ds_write_b32 v137, a47 offset:63468
	ds_write_b32 v137, a16 offset:49664
	ds_write_b32 v137, a17 offset:50180
	ds_write_b32 v137, a18 offset:50696
	ds_write_b32 v137, a19 offset:51212
	ds_write_b32 v137, a20 offset:53792
	ds_write_b32 v137, a21 offset:54308
	ds_write_b32 v137, a22 offset:54824
	ds_write_b32 v137, a23 offset:55340
	ds_write_b32 v137, a24 offset:57920
	ds_write_b32 v137, a25 offset:58436
	ds_write_b32 v137, a26 offset:58952
	ds_write_b32 v137, a27 offset:59468
	ds_write_b32 v137, a28 offset:62048
	ds_write_b32 v137, a29 offset:62564
	ds_write_b32 v137, a30 offset:63080
	ds_write_b32 v137, a31 offset:63596
	s_waitcnt lgkmcnt(0)
	s_barrier
	s_cbranch_vccz .LBB0_995
	v_accvgpr_read_b32 v1, a210
	v_add_u32_e32 v4, s92, v1
	v_add_u32_e32 v0, s75, v1
	v_lshrrev_b32_e32 v1, 6, v4
	v_accvgpr_read_b32 v2, a211
	s_cmp_gt_u32 s73, 7
	v_cndmask_b32_e64 v1, v2, v1, s[4:5]
	s_cselect_b64 s[64:65], -1, 0
	s_add_i32 s12, s73, -8
	v_lshlrev_b32_e32 v48, 7, v1
	s_lshl_b32 s6, s93, 3
	v_mov_b32_e32 v1, v49
	s_add_i32 s6, s6, s12
	v_lshlrev_b64 v[0:1], 11, v[0:1]
	s_ashr_i32 s7, s6, 31
	s_lshl_b64 s[68:69], s[12:13], 1
	v_lshl_add_u64 v[0:1], s[16:17], 0, v[0:1]
	s_lshl_b32 s12, s73, 8
	s_lshl_b64 s[66:67], s[6:7], 1
	v_lshl_add_u32 v2, s93, 9, v4
	v_mov_b32_e32 v3, v49
	v_lshl_add_u64 v[0:1], v[0:1], 0, s[12:13]
	v_mov_b32_e32 v75, v49
	s_lshl_b64 s[6:7], s[6:7], 16
	v_lshl_add_u64 v[78:79], v[2:3], 4, s[68:69]
	v_lshl_add_u64 v[80:81], v[0:1], 0, v[74:75]
	v_lshlrev_b32_e32 v0, 7, v4
	v_mov_b32_e32 v1, v49
	v_lshl_add_u64 v[2:3], v[60:61], 0, s[6:7]
	v_lshl_add_u64 v[82:83], v[2:3], 0, v[0:1]
	v_and_b32_e32 v1, 64, v156
	v_xor_b32_e32 v0, 1, v156
	v_add_u32_e32 v1, 64, v1
	v_cmp_lt_i32_e32 vcc, v0, v1
	v_lshl_add_u64 v[76:77], s[14:15], 0, v[48:49]
	v_mov_b32_e32 v48, v4
	v_cndmask_b32_e32 v0, v156, v0, vcc
	s_mov_b32 s12, 0
	v_lshlrev_b32_e32 v75, 2, v0
	s_mov_b64 s[68:69], -1
	s_branch .LBB0_982

.LBB0_1087:
	v_lshl_add_u64 v[32:33], v[82:83], 0, v[156:157]
	s_and_b32 s61, s60, 1
	s_waitcnt lgkmcnt(0)
	s_barrier
	v_accvgpr_read_b32 v188, a0
	v_accvgpr_read_b32 v189, a0
	v_accvgpr_read_b32 v190, a0
	v_accvgpr_read_b32 v191, a0
	v_accvgpr_read_b32 v192, a0
	v_accvgpr_read_b32 v193, a0
	v_accvgpr_read_b32 v194, a0
	v_accvgpr_read_b32 v195, a0
	v_accvgpr_read_b32 v196, a0
	v_accvgpr_read_b32 v197, a0
	v_accvgpr_read_b32 v198, a0
	v_accvgpr_read_b32 v199, a0
	v_accvgpr_read_b32 v200, a0
	v_accvgpr_read_b32 v201, a0
	v_accvgpr_read_b32 v202, a0
	v_accvgpr_read_b32 v203, a0
	v_accvgpr_read_b32 v172, a0
	v_accvgpr_read_b32 v173, a0
	v_accvgpr_read_b32 v174, a0
	v_accvgpr_read_b32 v175, a0
	v_accvgpr_read_b32 v176, a0
	v_accvgpr_read_b32 v177, a0
	v_accvgpr_read_b32 v178, a0
	v_accvgpr_read_b32 v179, a0
	v_accvgpr_read_b32 v180, a0
	v_accvgpr_read_b32 v181, a0
	v_accvgpr_read_b32 v182, a0
	v_accvgpr_read_b32 v183, a0
	v_accvgpr_read_b32 v184, a0
	v_accvgpr_read_b32 v185, a0
	v_accvgpr_read_b32 v186, a0
	v_accvgpr_read_b32 v187, a0
	v_accvgpr_read_b32 v204, a0
	v_accvgpr_read_b32 v205, a0
	v_accvgpr_read_b32 v206, a0
	v_accvgpr_read_b32 v207, a0
	v_accvgpr_read_b32 v208, a0
	v_accvgpr_read_b32 v209, a0
	v_accvgpr_read_b32 v210, a0
	v_accvgpr_read_b32 v211, a0
	v_accvgpr_read_b32 v212, a0
	v_accvgpr_read_b32 v213, a0
	v_accvgpr_read_b32 v214, a0
	v_accvgpr_read_b32 v215, a0
	v_accvgpr_read_b32 v216, a0
	v_accvgpr_read_b32 v217, a0
	v_accvgpr_read_b32 v218, a0
	v_accvgpr_read_b32 v219, a0
	v_accvgpr_read_b32 v100, a0
	v_accvgpr_read_b32 v101, a0
	v_accvgpr_read_b32 v102, a0
	v_accvgpr_read_b32 v103, a0
	v_accvgpr_read_b32 v104, a0
	v_accvgpr_read_b32 v105, a0
	v_accvgpr_read_b32 v106, a0
	v_accvgpr_read_b32 v107, a0
	v_accvgpr_read_b32 v108, a0
	v_accvgpr_read_b32 v109, a0
	v_accvgpr_read_b32 v110, a0
	v_accvgpr_read_b32 v111, a0
	v_accvgpr_read_b32 v112, a0
	v_accvgpr_read_b32 v113, a0
	v_accvgpr_read_b32 v114, a0
	v_accvgpr_read_b32 v115, a0
	global_load_dwordx4 v[64:67], v[32:33], off
	v_lshl_add_u64 v[32:33], v[84:85], 0, v[156:157]
	s_xor_b32 s62, s61, 1
	global_load_dwordx4 v[68:71], v[32:33], off
	v_lshl_add_u64 v[32:33], v[86:87], 0, v[156:157]
	s_mulk_i32 s61, 0x4800
	global_load_dwordx4 v[72:75], v[32:33], off
	v_lshl_add_u64 v[32:33], v[88:89], 0, v[156:157]
	v_add_u32_e32 v40, s61, v128
	global_load_dwordx4 v[76:79], v[32:33], off
	ds_read_b128 a[144:147], v40
	ds_read_b128 a[148:151], v40 offset:32
	ds_read_b128 a[152:155], v40 offset:64
	ds_read_b128 a[156:159], v40 offset:96
	s_waitcnt vmcnt(11)
	s_waitcnt lgkmcnt(3)
	v_mfma_f32_32x32x16_bf16 v[188:203], a[144:147], v[28:31], v[188:203]
	s_waitcnt vmcnt(7)
	v_mfma_f32_32x32x16_bf16 v[172:187], a[144:147], v[12:15], v[172:187]
	ds_read_b128 a[144:147], v40 offset:4608
	s_waitcnt lgkmcnt(3)
	v_mfma_f32_32x32x16_bf16 v[188:203], a[148:151], v[24:27], v[188:203]
	s_waitcnt vmcnt(6)
	v_mfma_f32_32x32x16_bf16 v[172:187], a[148:151], v[8:11], v[172:187]
	ds_read_b128 a[148:151], v40 offset:4640
	s_waitcnt lgkmcnt(3)
	v_mfma_f32_32x32x16_bf16 v[188:203], a[152:155], v[20:23], v[188:203]
	s_mulk_i32 s62, 0x4800
	s_add_i32 s60, s60, 1
	s_waitcnt vmcnt(5)
	v_mfma_f32_32x32x16_bf16 v[172:187], a[152:155], v[4:7], v[172:187]
	ds_read_b128 a[152:155], v40 offset:4672
	v_lshl_add_u64 v[82:83], v[82:83], 0, s[54:55]
	v_lshl_add_u64 v[84:85], v[84:85], 0, s[54:55]
	v_lshl_add_u64 v[86:87], v[86:87], 0, s[54:55]
	v_lshl_add_u64 v[88:89], v[88:89], 0, s[54:55]
	s_cmp_eq_u32 s8, s60
	s_waitcnt lgkmcnt(3)
	v_mfma_f32_32x32x16_bf16 v[188:203], a[156:159], v[16:19], v[188:203]
	s_waitcnt vmcnt(4)
	v_mfma_f32_32x32x16_bf16 v[172:187], a[156:159], v[0:3], v[172:187]
	ds_read_b128 a[156:159], v40 offset:4704
	s_waitcnt lgkmcnt(3)
	v_mfma_f32_32x32x16_bf16 v[204:219], a[144:147], v[28:31], v[204:219]
	v_mfma_f32_32x32x16_bf16 v[100:115], a[144:147], v[12:15], v[100:115]
	s_waitcnt lgkmcnt(2)
	v_mfma_f32_32x32x16_bf16 v[204:219], a[148:151], v[24:27], v[204:219]
	v_mfma_f32_32x32x16_bf16 v[100:115], a[148:151], v[8:11], v[100:115]
	s_waitcnt lgkmcnt(1)
	v_mfma_f32_32x32x16_bf16 v[204:219], a[152:155], v[20:23], v[204:219]
	v_mfma_f32_32x32x16_bf16 v[100:115], a[152:155], v[4:7], v[100:115]
	s_waitcnt lgkmcnt(0)
	v_mfma_f32_32x32x16_bf16 v[204:219], a[156:159], v[16:19], v[204:219]
	v_mfma_f32_32x32x16_bf16 v[100:115], a[156:159], v[0:3], v[100:115]
	v_exp_f32_e32 v45, v188
	v_exp_f32_e32 v47, v189
	v_exp_f32_e32 v49, v190
	v_exp_f32_e32 v51, v191
	v_exp_f32_e32 v53, v192
	v_exp_f32_e32 v55, v193
	v_exp_f32_e32 v99, v194
	v_exp_f32_e32 v117, v195
	v_exp_f32_e32 v119, v196
	v_exp_f32_e32 v121, v197
	v_exp_f32_e32 v123, v198
	v_exp_f32_e32 v125, v199
	v_exp_f32_e32 v127, v200
	v_exp_f32_e32 v131, v201
	v_exp_f32_e32 v133, v202
	v_exp_f32_e32 v137, v203
	v_exp_f32_e32 v141, v204
	v_exp_f32_e32 v143, v205
	v_exp_f32_e32 v145, v206
	v_exp_f32_e32 v147, v207
	v_exp_f32_e32 v149, v208
	v_exp_f32_e32 v221, v209
	v_exp_f32_e32 v223, v210
	v_exp_f32_e32 v225, v211
	v_exp_f32_e32 v227, v212
	v_exp_f32_e32 v229, v213
	v_exp_f32_e32 v231, v214
	v_exp_f32_e32 v233, v215
	v_exp_f32_e32 v235, v216
	v_exp_f32_e32 v237, v217
	v_exp_f32_e32 v239, v218
	v_exp_f32_e32 v241, v219
	v_exp_f32_e32 v44, v172
	v_exp_f32_e32 v46, v173
	v_exp_f32_e32 v48, v174
	v_exp_f32_e32 v50, v175
	v_exp_f32_e32 v52, v176
	v_exp_f32_e32 v54, v177
	v_exp_f32_e32 v98, v178
	v_exp_f32_e32 v116, v179
	v_exp_f32_e32 v118, v180
	v_exp_f32_e32 v120, v181
	v_exp_f32_e32 v122, v182
	v_pk_add_f32 v[32:33], v[44:45], 0 op_sel_hi:[1,0]
	v_pk_add_f32 v[32:33], v[46:47], v[32:33]
	v_exp_f32_e32 v222, v106
	v_pk_add_f32 v[32:33], v[48:49], v[32:33]
	v_pk_add_f32 v[32:33], v[50:51], v[32:33]
	v_exp_f32_e32 v224, v107
	v_pk_add_f32 v[32:33], v[52:53], v[32:33]
	v_pk_add_f32 v[32:33], v[54:55], v[32:33]
	v_exp_f32_e32 v226, v108
	v_pk_add_f32 v[32:33], v[98:99], v[32:33]
	v_pk_add_f32 v[32:33], v[116:117], v[32:33]
	v_exp_f32_e32 v228, v109
	v_pk_add_f32 v[32:33], v[118:119], v[32:33]
	v_pk_add_f32 v[32:33], v[120:121], v[32:33]
	v_exp_f32_e32 v230, v110
	v_pk_add_f32 v[40:41], v[122:123], v[32:33]
	v_exp_f32_e32 v124, v183
	v_exp_f32_e32 v126, v184
	v_exp_f32_e32 v130, v185
	v_exp_f32_e32 v132, v186
	v_exp_f32_e32 v136, v187
	v_pk_add_f32 v[40:41], v[124:125], v[40:41]
	v_exp_f32_e32 v140, v100
	v_pk_add_f32 v[40:41], v[126:127], v[40:41]
	v_exp_f32_e32 v142, v101
	v_pk_add_f32 v[40:41], v[130:131], v[40:41]
	v_exp_f32_e32 v144, v102
	v_pk_add_f32 v[40:41], v[132:133], v[40:41]
	v_exp_f32_e32 v146, v103
	v_pk_add_f32 v[40:41], v[136:137], v[40:41]
	v_exp_f32_e32 v148, v104
	v_pk_add_f32 v[40:41], v[140:141], v[40:41]
	v_exp_f32_e32 v220, v105
	v_pk_add_f32 v[40:41], v[142:143], v[40:41]
	v_pk_add_f32 v[40:41], v[144:145], v[40:41]
	v_exp_f32_e32 v232, v111
	v_pk_add_f32 v[40:41], v[146:147], v[40:41]
	v_pk_add_f32 v[40:41], v[148:149], v[40:41]
	v_exp_f32_e32 v234, v112
	v_pk_add_f32 v[40:41], v[220:221], v[40:41]
	v_pk_add_f32 v[40:41], v[222:223], v[40:41]
	v_exp_f32_e32 v236, v113
	v_pk_add_f32 v[40:41], v[224:225], v[40:41]
	v_pk_add_f32 v[40:41], v[226:227], v[40:41]
	v_exp_f32_e32 v238, v114
	v_pk_add_f32 v[40:41], v[228:229], v[40:41]
	v_pk_add_f32 v[40:41], v[230:231], v[40:41]
	v_cvt_pk_bf16_f32 v59, v99, v117
	v_exp_f32_e32 v240, v115
	v_pk_add_f32 v[40:41], v[232:233], v[40:41]
	v_cvt_pk_bf16_f32 v63, v98, v116
	v_add3_u32 v98, s62, v153, v134
	v_add3_u32 v99, s62, v158, v134
	v_cvt_pk_bf16_f32 v58, v53, v55
	v_pk_add_f32 v[40:41], v[234:235], v[40:41]
	v_cvt_pk_bf16_f32 v53, v122, v124
	s_waitcnt vmcnt(3)
	ds_write_b128 v98, v[64:67]
	s_waitcnt vmcnt(2)
	ds_write_b128 v99, v[68:71]
	s_waitcnt vmcnt(1)
	ds_write_b128 v98, v[72:75] offset:9216
	s_waitcnt vmcnt(0)
	ds_write_b128 v99, v[76:79] offset:9216
	v_lshl_add_u64 v[64:65], v[90:91], 0, v[156:157]
	v_lshl_add_u64 v[68:69], v[92:93], 0, v[156:157]
	v_lshl_add_u64 v[72:73], v[94:95], 0, v[156:157]
	v_lshl_add_u64 v[76:77], v[96:97], 0, v[156:157]
	v_add_u32_e32 v124, s61, v152
	v_cvt_pk_bf16_f32 v36, v119, v121
	v_cvt_pk_bf16_f32 v37, v123, v125
	v_pk_add_f32 v[40:41], v[236:237], v[40:41]
	v_cvt_pk_bf16_f32 v62, v52, v54
	v_cvt_pk_bf16_f32 v52, v118, v120
	global_load_dwordx4 v[64:67], v[64:65], off
	v_pk_add_f32 v[40:41], v[238:239], v[40:41]
	global_load_dwordx4 v[68:71], v[68:69], off
	v_pk_add_f32 v[60:61], v[240:241], v[40:41]
	global_load_dwordx4 v[72:75], v[72:73], off
	v_cvt_pk_bf16_f32 v56, v45, v47
	global_load_dwordx4 v[76:79], v[76:77], off
	ds_read_b128 a[144:147], v124 offset:36864
	ds_read_b128 a[148:151], v124 offset:36896
	ds_read_b128 a[152:155], v124 offset:36928
	ds_read_b128 a[156:159], v124 offset:36960
	v_cvt_pk_bf16_f32 v57, v49, v51
	v_pk_add_f32 v[80:81], v[80:81], v[60:61]
	v_cvt_pk_bf16_f32 v60, v44, v46
	v_cvt_pk_bf16_f32 v61, v48, v50
	s_waitcnt lgkmcnt(3)
	v_mfma_f32_32x32x16_bf16 a[128:143], a[144:147], v[56:59], a[128:143]
	v_cvt_pk_bf16_f32 v38, v127, v131
	v_cvt_pk_bf16_f32 v39, v133, v137
	v_cvt_pk_bf16_f32 v54, v126, v130
	v_cvt_pk_bf16_f32 v55, v132, v136
	v_cvt_pk_bf16_f32 v32, v141, v143
	v_cvt_pk_bf16_f32 v33, v145, v147
	v_cvt_pk_bf16_f32 v34, v149, v221
	v_mfma_f32_32x32x16_bf16 a[112:127], a[144:147], v[60:63], a[112:127]
	ds_read_b128 a[144:147], v124 offset:41472
	v_cvt_pk_bf16_f32 v35, v223, v225
	v_cvt_pk_bf16_f32 v48, v140, v142
	v_cvt_pk_bf16_f32 v49, v144, v146
	v_cvt_pk_bf16_f32 v50, v148, v220
	v_cvt_pk_bf16_f32 v51, v222, v224
	v_cvt_pk_bf16_f32 v40, v227, v229
	s_waitcnt lgkmcnt(3)
	v_mfma_f32_32x32x16_bf16 a[128:143], a[148:151], v[36:39], a[128:143]
	v_cvt_pk_bf16_f32 v41, v231, v233
	v_cvt_pk_bf16_f32 v42, v235, v237
	v_cvt_pk_bf16_f32 v43, v239, v241
	v_cvt_pk_bf16_f32 v44, v226, v228
	v_cvt_pk_bf16_f32 v45, v230, v232
	v_cvt_pk_bf16_f32 v46, v234, v236
	v_cvt_pk_bf16_f32 v47, v238, v240
	v_mfma_f32_32x32x16_bf16 a[112:127], a[148:151], v[52:55], a[112:127]
	ds_read_b128 a[148:151], v124 offset:41504
	s_waitcnt lgkmcnt(3)
	v_mfma_f32_32x32x16_bf16 a[128:143], a[152:155], v[32:35], a[128:143]
	v_mfma_f32_32x32x16_bf16 a[112:127], a[152:155], v[48:51], a[112:127]
	ds_read_b128 a[152:155], v124 offset:41536
	s_waitcnt lgkmcnt(3)
	v_mfma_f32_32x32x16_bf16 a[128:143], a[156:159], v[40:43], a[128:143]
	v_mfma_f32_32x32x16_bf16 a[112:127], a[156:159], v[44:47], a[112:127]
	ds_read_b128 a[156:159], v124 offset:41568
	s_waitcnt lgkmcnt(3)
	v_mfma_f32_32x32x16_bf16 a[48:63], a[144:147], v[56:59], a[48:63]
	v_mfma_f32_32x32x16_bf16 a[64:79], a[144:147], v[60:63], a[64:79]
	ds_read_b128 a[144:147], v124 offset:46080
	s_waitcnt lgkmcnt(3)
	v_mfma_f32_32x32x16_bf16 a[48:63], a[148:151], v[36:39], a[48:63]
	v_mfma_f32_32x32x16_bf16 a[64:79], a[148:151], v[52:55], a[64:79]
	ds_read_b128 a[148:151], v124 offset:46112
	s_waitcnt lgkmcnt(3)
	v_mfma_f32_32x32x16_bf16 a[48:63], a[152:155], v[32:35], a[48:63]
	v_lshl_add_u64 v[90:91], v[90:91], 0, s[56:57]
	v_lshl_add_u64 v[92:93], v[92:93], 0, s[56:57]
	v_mfma_f32_32x32x16_bf16 a[64:79], a[152:155], v[48:51], a[64:79]
	ds_read_b128 a[152:155], v124 offset:46144
	v_lshl_add_u64 v[94:95], v[94:95], 0, s[56:57]
	v_lshl_add_u64 v[96:97], v[96:97], 0, s[56:57]
	s_waitcnt lgkmcnt(3)
	v_mfma_f32_32x32x16_bf16 a[48:63], a[156:159], v[40:43], a[48:63]
	v_mfma_f32_32x32x16_bf16 a[64:79], a[156:159], v[44:47], a[64:79]
	ds_read_b128 a[156:159], v124 offset:46176
	s_waitcnt lgkmcnt(3)
	v_mfma_f32_32x32x16_bf16 a[80:95], a[144:147], v[56:59], a[80:95]
	v_mfma_f32_32x32x16_bf16 a[96:111], a[144:147], v[60:63], a[96:111]
	ds_read_b128 a[144:147], v124 offset:50688
	s_waitcnt lgkmcnt(3)
	v_mfma_f32_32x32x16_bf16 a[80:95], a[148:151], v[36:39], a[80:95]
	v_mfma_f32_32x32x16_bf16 a[96:111], a[148:151], v[52:55], a[96:111]
	ds_read_b128 a[148:151], v124 offset:50720
	s_waitcnt lgkmcnt(3)
	v_mfma_f32_32x32x16_bf16 a[80:95], a[152:155], v[32:35], a[80:95]
	v_mfma_f32_32x32x16_bf16 a[96:111], a[152:155], v[48:51], a[96:111]
	ds_read_b128 a[152:155], v124 offset:50752
	s_waitcnt lgkmcnt(3)
	v_mfma_f32_32x32x16_bf16 a[80:95], a[156:159], v[40:43], a[80:95]
	v_mfma_f32_32x32x16_bf16 a[96:111], a[156:159], v[44:47], a[96:111]
	ds_read_b128 a[156:159], v124 offset:50784
	s_waitcnt lgkmcnt(3)
	v_mfma_f32_32x32x16_bf16 a[32:47], a[144:147], v[56:59], a[32:47]
	v_mfma_f32_32x32x16_bf16 a[16:31], a[144:147], v[60:63], a[16:31]
	s_waitcnt lgkmcnt(2)
	v_mfma_f32_32x32x16_bf16 a[32:47], a[148:151], v[36:39], a[32:47]
	v_mfma_f32_32x32x16_bf16 a[16:31], a[148:151], v[52:55], a[16:31]
	s_waitcnt lgkmcnt(1)
	v_mfma_f32_32x32x16_bf16 a[32:47], a[152:155], v[32:35], a[32:47]
	s_waitcnt vmcnt(3)
	ds_write_b128 v98, v[64:67] offset:36864
	s_waitcnt vmcnt(2)
	ds_write_b128 v99, v[68:71] offset:36864
	v_mfma_f32_32x32x16_bf16 a[16:31], a[152:155], v[48:51], a[16:31]
	s_waitcnt lgkmcnt(2)
	v_mfma_f32_32x32x16_bf16 a[32:47], a[156:159], v[40:43], a[32:47]
	v_mfma_f32_32x32x16_bf16 a[16:31], a[156:159], v[44:47], a[16:31]
	v_add3_u32 v32, s62, v159, v134
	s_waitcnt vmcnt(1)
	ds_write_b128 v32, v[72:75] offset:36864
	v_add3_u32 v32, s62, v160, v134
	s_waitcnt vmcnt(0)
	ds_write_b128 v32, v[76:79] offset:36864
	s_cbranch_scc0 .LBB0_1087
	s_bitcmp1_b32 s8, 0
	s_cselect_b32 s8, 0x4800, 0
	v_add_u32_e32 v48, s8, v128
	s_waitcnt lgkmcnt(0)
	s_barrier
	ds_read_b128 v[32:35], v48
	ds_read_b128 v[36:39], v48 offset:32
	s_waitcnt lgkmcnt(1)
	v_mfma_f32_32x32x16_bf16 a[186:201], v[32:35], v[28:31], a[0:15]
	v_add_u32_e32 v83, s8, v152
	v_mfma_f32_32x32x16_bf16 a[144:159], v[32:35], v[12:15], a[0:15]
	s_waitcnt lgkmcnt(0)
	v_mfma_f32_32x32x16_bf16 a[186:201], v[36:39], v[24:27], a[186:201]
	v_mfma_f32_32x32x16_bf16 a[144:159], v[36:39], v[8:11], a[144:159]
	ds_read_b128 v[32:35], v48 offset:64
	ds_read_b128 v[36:39], v48 offset:96
	s_waitcnt lgkmcnt(1)
	v_mfma_f32_32x32x16_bf16 a[186:201], v[32:35], v[20:23], a[186:201]
	s_waitcnt lgkmcnt(0)
	v_mfma_f32_32x32x16_bf16 a[186:201], v[36:39], v[16:19], a[186:201]
	v_mfma_f32_32x32x16_bf16 a[144:159], v[32:35], v[4:7], a[144:159]
	ds_read_b128 v[32:35], v48 offset:4608
	ds_read_b128 v[40:43], v48 offset:4640
	ds_read_b128 v[44:47], v48 offset:4672
	ds_read_b128 v[48:51], v48 offset:4704
	s_nop 6
	v_accvgpr_read_b32 v52, a186
	v_accvgpr_read_b32 v53, a187
	v_accvgpr_read_b32 v54, a188
	v_exp_f32_e32 v52, v52
	v_exp_f32_e32 v53, v53
	s_waitcnt lgkmcnt(3)
	v_mfma_f32_32x32x16_bf16 a[172:187], v[32:35], v[28:31], a[0:15]
	v_accvgpr_read_b32 v28, a189
	v_exp_f32_e32 v55, v28
	v_accvgpr_read_b32 v28, a190
	v_exp_f32_e32 v56, v28
	v_accvgpr_read_b32 v28, a191
	v_exp_f32_e32 v54, v54
	v_exp_f32_e32 v57, v28
	s_waitcnt lgkmcnt(2)
	v_mfma_f32_32x32x16_bf16 a[172:187], v[40:43], v[24:27], a[172:187]
	v_accvgpr_read_b32 v24, a192
	v_exp_f32_e32 v58, v24
	v_accvgpr_read_b32 v24, a193
	v_exp_f32_e32 v59, v24
	v_accvgpr_read_b32 v24, a194
	v_exp_f32_e32 v60, v24
	v_accvgpr_read_b32 v24, a195
	s_waitcnt lgkmcnt(1)
	v_mfma_f32_32x32x16_bf16 a[172:187], v[44:47], v[20:23], a[172:187]
	v_accvgpr_read_b32 v20, a196
	v_exp_f32_e32 v62, v20
	v_accvgpr_read_b32 v20, a197
	v_exp_f32_e32 v63, v20
	v_accvgpr_read_b32 v20, a198
	v_exp_f32_e32 v64, v20
	v_exp_f32_e32 v61, v24
	s_waitcnt lgkmcnt(0)
	v_mfma_f32_32x32x16_bf16 a[172:187], v[48:51], v[16:19], a[172:187]
	v_accvgpr_read_b32 v16, a199
	v_exp_f32_e32 v65, v16
	v_accvgpr_read_b32 v16, a200
	v_exp_f32_e32 v66, v16
	v_accvgpr_read_b32 v16, a201
	v_exp_f32_e32 v67, v16
	ds_read_b128 v[28:31], v83 offset:36928
	v_mfma_f32_32x32x16_bf16 a[144:159], v[36:39], v[0:3], a[144:159]
	s_nop 3
	v_accvgpr_read_b32 v16, a172
	v_exp_f32_e32 v36, v16
	v_accvgpr_read_b32 v16, a173
	v_exp_f32_e32 v37, v16
	v_accvgpr_read_b32 v16, a174
	v_exp_f32_e32 v38, v16
	v_accvgpr_read_b32 v16, a175
	v_mfma_f32_32x32x16_bf16 a[160:175], v[32:35], v[12:15], a[0:15]
	v_exp_f32_e32 v39, v16
	v_accvgpr_read_b32 v16, a144
	v_accvgpr_read_b32 v12, a176
	v_exp_f32_e32 v68, v12
	v_accvgpr_read_b32 v12, a177
	v_accvgpr_read_b32 v20, a157
	v_exp_f32_e32 v69, v12
	v_mfma_f32_32x32x16_bf16 a[160:175], v[40:43], v[8:11], a[160:175]
	v_accvgpr_read_b32 v12, a178
	v_exp_f32_e32 v84, v20
	v_accvgpr_read_b32 v20, a158
	v_exp_f32_e32 v70, v12
	v_accvgpr_read_b32 v12, a179
	v_exp_f32_e32 v85, v20
	v_accvgpr_read_b32 v20, a159
	v_mfma_f32_32x32x16_bf16 a[160:175], v[44:47], v[4:7], a[160:175]
	v_exp_f32_e32 v40, v12
	v_cvt_pk_bf16_f32 v12, v52, v53
	v_cvt_pk_bf16_f32 v13, v54, v55
	v_cvt_pk_bf16_f32 v14, v56, v57
	v_cvt_pk_bf16_f32 v15, v58, v59
	v_exp_f32_e32 v86, v20
	ds_read_b128 v[20:23], v83 offset:36896
	v_mfma_f32_32x32x16_bf16 a[160:175], v[48:51], v[0:3], a[160:175]
	v_exp_f32_e32 v49, v16
	v_accvgpr_read_b32 v16, a145
	v_exp_f32_e32 v50, v16
	v_accvgpr_read_b32 v16, a146
	v_exp_f32_e32 v51, v16
	v_accvgpr_read_b32 v16, a147
	v_exp_f32_e32 v71, v16
	v_accvgpr_read_b32 v16, a148
	v_exp_f32_e32 v72, v16
	v_accvgpr_read_b32 v16, a149
	v_exp_f32_e32 v73, v16
	v_accvgpr_read_b32 v16, a150
	v_exp_f32_e32 v74, v16
	v_accvgpr_read_b32 v16, a151
	v_exp_f32_e32 v75, v16
	v_accvgpr_read_b32 v16, a152
	v_exp_f32_e32 v76, v16
	v_accvgpr_read_b32 v16, a153
	v_exp_f32_e32 v77, v16
	v_accvgpr_read_b32 v16, a154
	v_exp_f32_e32 v78, v16
	v_accvgpr_read_b32 v16, a155
	v_exp_f32_e32 v79, v16
	v_accvgpr_read_b32 v16, a156
	v_exp_f32_e32 v82, v16
	ds_read_b128 v[16:19], v83 offset:36864
	v_accvgpr_read_b32 v24, a160
	v_exp_f32_e32 v87, v24
	v_accvgpr_read_b32 v24, a161
	v_exp_f32_e32 v88, v24
	v_cvt_pk_bf16_f32 v24, v49, v50
	v_cvt_pk_bf16_f32 v25, v51, v71
	v_cvt_pk_bf16_f32 v26, v72, v73
	v_cvt_pk_bf16_f32 v27, v74, v75
	s_waitcnt lgkmcnt(0)
	v_mfma_f32_32x32x16_bf16 a[144:159], v[16:19], v[12:15], a[128:143]
	v_accvgpr_read_b32 v8, a180
	v_exp_f32_e32 v41, v8
	v_accvgpr_read_b32 v8, a181
	v_exp_f32_e32 v42, v8
	v_accvgpr_read_b32 v8, a182
	v_exp_f32_e32 v43, v8
	v_cvt_pk_bf16_f32 v8, v60, v61
	v_mfma_f32_32x32x16_bf16 a[128:143], v[16:19], v[24:27], a[112:127]
	v_accvgpr_read_b32 v16, a162
	v_exp_f32_e32 v89, v16
	v_accvgpr_read_b32 v16, a163
	v_exp_f32_e32 v90, v16
	v_accvgpr_read_b32 v16, a164
	v_exp_f32_e32 v91, v16
	v_accvgpr_read_b32 v16, a165
	v_cvt_pk_bf16_f32 v9, v62, v63
	v_cvt_pk_bf16_f32 v10, v64, v65
	v_cvt_pk_bf16_f32 v11, v66, v67
	v_exp_f32_e32 v92, v16
	v_cvt_pk_bf16_f32 v16, v76, v77
	v_cvt_pk_bf16_f32 v17, v78, v79
	v_cvt_pk_bf16_f32 v18, v82, v84
	v_cvt_pk_bf16_f32 v19, v85, v86
	v_mfma_f32_32x32x16_bf16 a[144:159], v[20:23], v[8:11], a[144:159]
	v_accvgpr_read_b32 v32, a166
	v_accvgpr_read_b32 v4, a183
	v_exp_f32_e32 v93, v32
	v_exp_f32_e32 v44, v4
	v_accvgpr_read_b32 v4, a184
	v_exp_f32_e32 v45, v4
	v_accvgpr_read_b32 v4, a185
	v_mfma_f32_32x32x16_bf16 a[128:143], v[20:23], v[16:19], a[128:143]
	v_accvgpr_read_b32 v20, a167
	v_exp_f32_e32 v94, v20
	v_accvgpr_read_b32 v32, a169
	v_exp_f32_e32 v46, v4
	v_accvgpr_read_b32 v4, a186
	v_exp_f32_e32 v96, v32
	v_accvgpr_read_b32 v32, a170
	v_exp_f32_e32 v47, v4
	v_cvt_pk_bf16_f32 v4, v36, v37
	v_cvt_pk_bf16_f32 v5, v38, v39
	v_cvt_pk_bf16_f32 v6, v68, v69
	v_cvt_pk_bf16_f32 v7, v70, v40
	v_accvgpr_read_b32 v20, a168
	v_exp_f32_e32 v97, v32
	v_cvt_pk_bf16_f32 v32, v87, v88
	v_cvt_pk_bf16_f32 v33, v89, v90
	v_cvt_pk_bf16_f32 v34, v91, v92
	v_cvt_pk_bf16_f32 v35, v93, v94
	v_exp_f32_e32 v95, v20
	ds_read_b128 v[20:23], v83 offset:36960
	v_mfma_f32_32x32x16_bf16 a[144:159], v[28:31], v[4:7], a[144:159]
	v_accvgpr_read_b32 v0, a187
	v_exp_f32_e32 v48, v0
	v_cvt_pk_bf16_f32 v0, v41, v42
	v_cvt_pk_bf16_f32 v1, v43, v44
	v_cvt_pk_bf16_f32 v2, v45, v46
	v_cvt_pk_bf16_f32 v3, v47, v48
	v_cvt_pk_bf16_f32 v130, v95, v96
	v_mfma_f32_32x32x16_bf16 a[128:143], v[28:31], v[32:35], a[128:143]
	v_accvgpr_read_b32 v28, a171
	v_exp_f32_e32 v98, v28
	v_accvgpr_read_b32 v28, a172
	v_exp_f32_e32 v99, v28
	v_accvgpr_read_b32 v28, a173
	v_exp_f32_e32 v100, v28
	v_accvgpr_read_b32 v28, a174
	v_exp_f32_e32 v101, v28
	v_accvgpr_read_b32 v28, a175
	v_exp_f32_e32 v102, v28
	v_cvt_pk_bf16_f32 v131, v97, v98
	v_cvt_pk_bf16_f32 v132, v99, v100
	s_waitcnt lgkmcnt(0)
	v_mfma_f32_32x32x16_bf16 a[144:159], v[20:23], v[0:3], a[144:159]
	v_cvt_pk_bf16_f32 v133, v101, v102
	s_nop 1
	v_mfma_f32_32x32x16_bf16 a[128:143], v[20:23], v[130:133], a[128:143]
	ds_read_b128 v[20:23], v83 offset:41472
	ds_read_b128 v[28:31], v83 offset:41504
	s_nop 5
	v_accvgpr_read_b32 v112, a144
	v_accvgpr_read_b32 v113, a145
	v_accvgpr_read_b32 v114, a146
	v_accvgpr_read_b32 v115, a147
	s_waitcnt lgkmcnt(1)
	v_mfma_f32_32x32x16_bf16 a[112:127], v[20:23], v[12:15], a[48:63]
	v_accvgpr_read_b32 v116, a148
	v_accvgpr_read_b32 v117, a149
	v_accvgpr_read_b32 v118, a150
	v_accvgpr_read_b32 v119, a151
	v_accvgpr_read_b32 v120, a152
	v_accvgpr_read_b32 v121, a153
	v_accvgpr_read_b32 v122, a154
	v_mfma_f32_32x32x16_bf16 a[48:63], v[20:23], v[24:27], a[64:79]
	v_accvgpr_read_b32 v123, a155
	v_accvgpr_read_b32 v124, a156
	v_accvgpr_read_b32 v125, a157
	v_accvgpr_read_b32 v126, a158
	v_accvgpr_read_b32 v127, a159
	s_waitcnt lgkmcnt(0)
	v_mfma_f32_32x32x16_bf16 a[112:127], v[28:31], v[8:11], a[112:127]
	v_mfma_f32_32x32x16_bf16 a[48:63], v[28:31], v[16:19], a[48:63]
	ds_read_b128 v[20:23], v83 offset:41536
	ds_read_b128 v[28:31], v83 offset:41568
	s_waitcnt lgkmcnt(1)
	v_mfma_f32_32x32x16_bf16 a[112:127], v[20:23], v[4:7], a[112:127]
	v_mfma_f32_32x32x16_bf16 a[48:63], v[20:23], v[32:35], a[48:63]
	s_waitcnt lgkmcnt(0)
	v_mfma_f32_32x32x16_bf16 a[112:127], v[28:31], v[0:3], a[112:127]
	v_mfma_f32_32x32x16_bf16 a[48:63], v[28:31], v[130:133], a[48:63]
	ds_read_b128 v[20:23], v83 offset:46080
	ds_read_b128 v[28:31], v83 offset:46112
	s_waitcnt lgkmcnt(1)
	v_mfma_f32_32x32x16_bf16 a[64:79], v[20:23], v[12:15], a[80:95]
	v_mfma_f32_32x32x16_bf16 a[80:95], v[20:23], v[24:27], a[96:111]
	ds_read_b128 v[20:23], v83 offset:46144
	s_waitcnt lgkmcnt(1)
	v_mfma_f32_32x32x16_bf16 a[64:79], v[28:31], v[8:11], a[64:79]
	v_mfma_f32_32x32x16_bf16 a[80:95], v[28:31], v[16:19], a[80:95]
	v_add_f32_e32 v28, 0, v52
	v_add_f32_e32 v28, v53, v28
	v_add_f32_e32 v28, v54, v28
	v_add_f32_e32 v28, v55, v28
	v_add_f32_e32 v52, v56, v28
	v_add_f32_e32 v52, v57, v52
	v_add_f32_e32 v52, v58, v52
	v_add_f32_e32 v52, v59, v52
	v_add_f32_e32 v52, v60, v52
	v_add_f32_e32 v52, v61, v52
	v_add_f32_e32 v52, v62, v52
	v_add_f32_e32 v52, v63, v52
	ds_read_b128 v[28:31], v83 offset:46176
	s_waitcnt lgkmcnt(1)
	v_mfma_f32_32x32x16_bf16 a[64:79], v[20:23], v[4:7], a[64:79]
	v_mfma_f32_32x32x16_bf16 a[80:95], v[20:23], v[32:35], a[80:95]
	v_add_f32_e32 v20, v64, v52
	v_add_f32_e32 v20, v65, v20
	v_add_f32_e32 v20, v66, v20
	v_add_f32_e32 v20, v67, v20
	v_add_f32_e32 v20, v36, v20
	v_add_f32_e32 v20, v37, v20
	v_add_f32_e32 v20, v38, v20
	v_add_f32_e32 v20, v39, v20
	v_add_f32_e32 v20, v68, v20
	v_add_f32_e32 v20, v69, v20
	v_add_f32_e32 v20, v70, v20
	v_add_f32_e32 v20, v40, v20
	v_add_f32_e32 v36, v41, v20
	ds_read_b128 v[20:23], v83 offset:50688
	s_waitcnt lgkmcnt(1)
	v_mfma_f32_32x32x16_bf16 a[64:79], v[28:31], v[0:3], a[64:79]
	v_mfma_f32_32x32x16_bf16 a[80:95], v[28:31], v[130:133], a[80:95]
	v_add_f32_e32 v28, v42, v36
	v_add_f32_e32 v28, v43, v28
	v_add_f32_e32 v28, v44, v28
	v_add_f32_e32 v28, v45, v28
	v_add_f32_e32 v28, v46, v28
	v_add_f32_e32 v36, v47, v28
	ds_read_b128 v[28:31], v83 offset:50720
	s_waitcnt lgkmcnt(1)
	v_mfma_f32_32x32x16_bf16 a[96:111], v[20:23], v[12:15], a[32:47]
	v_add_f32_e32 v12, v48, v36
	v_add_f32_e32 v136, v81, v12
	v_add_f32_e32 v12, 0, v49
	v_add_f32_e32 v12, v50, v12
	v_add_f32_e32 v12, v51, v12
	v_add_f32_e32 v12, v71, v12
	v_add_f32_e32 v12, v72, v12
	v_add_f32_e32 v12, v73, v12
	v_add_f32_e32 v12, v74, v12
	v_add_f32_e32 v12, v75, v12
	v_add_f32_e32 v12, v76, v12
	v_add_f32_e32 v12, v77, v12
	v_add_f32_e32 v12, v78, v12
	v_add_f32_e32 v12, v79, v12
	s_waitcnt lgkmcnt(0)
	v_mfma_f32_32x32x16_bf16 a[96:111], v[28:31], v[8:11], a[96:111]
	v_add_f32_e32 v8, v82, v12
	v_add_f32_e32 v8, v84, v8
	v_add_f32_e32 v8, v85, v8
	v_add_f32_e32 v8, v86, v8
	v_add_f32_e32 v8, v87, v8
	v_add_f32_e32 v12, v88, v8
	ds_read_b128 v[8:11], v83 offset:50752
	v_mfma_f32_32x32x16_bf16 a[32:47], v[20:23], v[24:27], a[16:31]
	v_add_f32_e32 v12, v89, v12
	v_add_f32_e32 v12, v90, v12
	v_add_f32_e32 v12, v91, v12
	v_add_f32_e32 v12, v92, v12
	v_add_f32_e32 v12, v93, v12
	v_accvgpr_read_b32 v48, a128
	v_accvgpr_read_b32 v49, a129
	v_mfma_f32_32x32x16_bf16 a[32:47], v[28:31], v[16:19], a[32:47]
	v_add_f32_e32 v16, v94, v12
	ds_read_b128 v[12:15], v83 offset:50784
	v_accvgpr_read_b32 v50, a130
	v_accvgpr_read_b32 v51, a131
	v_accvgpr_read_b32 v52, a132
	v_accvgpr_read_b32 v53, a133
	v_accvgpr_read_b32 v54, a134
	s_waitcnt lgkmcnt(1)
	v_mfma_f32_32x32x16_bf16 a[96:111], v[8:11], v[4:7], a[96:111]
	v_add_f32_e32 v4, v95, v16
	v_add_f32_e32 v4, v96, v4
	v_add_f32_e32 v4, v97, v4
	v_add_f32_e32 v4, v98, v4
	v_add_f32_e32 v4, v99, v4
	v_add_f32_e32 v4, v100, v4
	v_add_f32_e32 v4, v101, v4
	v_add_f32_e32 v4, v102, v4
	v_add_f32_e32 v137, v80, v4
	ds_bpermute_b32 v4, v161, v136
	v_mfma_f32_32x32x16_bf16 a[32:47], v[8:11], v[32:35], a[32:47]
	v_accvgpr_read_b32 v96, a112
	v_accvgpr_read_b32 v32, a48
	v_accvgpr_read_b32 v95, a79
	s_waitcnt lgkmcnt(0)
	v_add_f32_e32 v136, v136, v4
	v_div_scale_f32 v140, s[60:61], v136, v136, 1.0
	v_rcp_f32_e32 v141, v140
	v_mfma_f32_32x32x16_bf16 a[32:47], v[12:15], v[130:133], a[32:47]
	ds_bpermute_b32 v131, v161, v137
	v_accvgpr_read_b32 v16, a80
	v_fma_f32 v130, -v140, v141, 1.0
	v_fmac_f32_e32 v141, v130, v141
	v_div_scale_f32 v130, vcc, 1.0, v136, 1.0
	v_mul_f32_e32 v132, v130, v141
	v_fma_f32 v133, -v140, v132, v130
	s_waitcnt lgkmcnt(0)
	v_add_f32_e32 v131, v137, v131
	v_fmac_f32_e32 v132, v133, v141
	v_div_scale_f32 v133, s[60:61], v131, v131, 1.0
	v_rcp_f32_e32 v137, v133
	v_mfma_f32_32x32x16_bf16 a[96:111], v[12:15], v[0:3], a[96:111]
	v_fma_f32 v130, -v140, v132, v130
	v_div_fmas_f32 v130, v130, v141, v132
	v_div_fixup_f32 v224, v130, v136, 1.0
	v_fma_f32 v130, -v133, v137, 1.0
	v_fmac_f32_e32 v137, v130, v137
	v_div_scale_f32 v130, vcc, 1.0, v131, 1.0
	v_mul_f32_e32 v132, v130, v137
	v_fma_f32 v136, -v133, v132, v130
	v_fmac_f32_e32 v132, v136, v137
	v_fma_f32 v130, -v133, v132, v130
	v_accvgpr_read_b32 v0, a32
	s_nop 0
	v_accvgpr_read_b32 v64, a96
	v_div_fmas_f32 v130, v130, v137, v132
	v_accvgpr_read_b32 v55, a135
	v_accvgpr_read_b32 v56, a136
	v_accvgpr_read_b32 v57, a137
	v_accvgpr_read_b32 v58, a138
	v_accvgpr_read_b32 v59, a139
	v_accvgpr_read_b32 v60, a140
	v_accvgpr_read_b32 v61, a141
	v_accvgpr_read_b32 v62, a142
	v_accvgpr_read_b32 v63, a143
	v_accvgpr_read_b32 v97, a113
	v_accvgpr_read_b32 v98, a114
	v_accvgpr_read_b32 v99, a115
	v_accvgpr_read_b32 v100, a116
	v_accvgpr_read_b32 v101, a117
	v_accvgpr_read_b32 v102, a118
	v_accvgpr_read_b32 v103, a119
	v_accvgpr_read_b32 v104, a120
	v_accvgpr_read_b32 v105, a121
	v_accvgpr_read_b32 v106, a122
	v_accvgpr_read_b32 v107, a123
	v_accvgpr_read_b32 v108, a124
	v_accvgpr_read_b32 v109, a125
	v_accvgpr_read_b32 v110, a126
	v_accvgpr_read_b32 v111, a127
	v_accvgpr_read_b32 v33, a49
	v_accvgpr_read_b32 v34, a50
	v_accvgpr_read_b32 v35, a51
	v_accvgpr_read_b32 v36, a52
	v_accvgpr_read_b32 v37, a53
	v_accvgpr_read_b32 v38, a54
	v_accvgpr_read_b32 v39, a55
	v_accvgpr_read_b32 v40, a56
	v_accvgpr_read_b32 v41, a57
	v_accvgpr_read_b32 v42, a58
	v_accvgpr_read_b32 v43, a59
	v_accvgpr_read_b32 v44, a60
	v_accvgpr_read_b32 v45, a61
	v_accvgpr_read_b32 v46, a62
	v_accvgpr_read_b32 v47, a63
	v_accvgpr_read_b32 v94, a78
	v_accvgpr_read_b32 v93, a77
	v_accvgpr_read_b32 v92, a76
	v_accvgpr_read_b32 v91, a75
	v_accvgpr_read_b32 v90, a74
	v_accvgpr_read_b32 v89, a73
	v_accvgpr_read_b32 v88, a72
	v_accvgpr_read_b32 v87, a71
	v_accvgpr_read_b32 v86, a70
	v_accvgpr_read_b32 v85, a69
	v_accvgpr_read_b32 v84, a68
	v_accvgpr_read_b32 v83, a67
	v_accvgpr_read_b32 v82, a66
	v_accvgpr_read_b32 v81, a65
	v_accvgpr_read_b32 v80, a64
	v_accvgpr_read_b32 v17, a81
	v_accvgpr_read_b32 v18, a82
	v_accvgpr_read_b32 v19, a83
	v_accvgpr_read_b32 v20, a84
	v_accvgpr_read_b32 v21, a85
	v_accvgpr_read_b32 v22, a86
	v_accvgpr_read_b32 v23, a87
	v_accvgpr_read_b32 v24, a88
	v_accvgpr_read_b32 v25, a89
	v_accvgpr_read_b32 v26, a90
	v_accvgpr_read_b32 v27, a91
	v_accvgpr_read_b32 v28, a92
	v_accvgpr_read_b32 v29, a93
	v_accvgpr_read_b32 v30, a94
	v_accvgpr_read_b32 v31, a95
	v_accvgpr_read_b32 v65, a97
	v_accvgpr_read_b32 v66, a98
	v_accvgpr_read_b32 v67, a99
	v_accvgpr_read_b32 v68, a100
	v_accvgpr_read_b32 v69, a101
	v_accvgpr_read_b32 v70, a102
	v_accvgpr_read_b32 v71, a103
	v_accvgpr_read_b32 v72, a104
	v_accvgpr_read_b32 v73, a105
	v_accvgpr_read_b32 v74, a106
	v_accvgpr_read_b32 v75, a107
	v_accvgpr_read_b32 v76, a108
	v_accvgpr_read_b32 v77, a109
	v_accvgpr_read_b32 v78, a110
	v_accvgpr_read_b32 v79, a111
	v_accvgpr_read_b32 v1, a33
	v_accvgpr_read_b32 v2, a34
	v_accvgpr_read_b32 v3, a35
	v_accvgpr_read_b32 v4, a36
	v_accvgpr_read_b32 v5, a37
	v_accvgpr_read_b32 v6, a38
	v_accvgpr_read_b32 v7, a39
	v_accvgpr_read_b32 v8, a40
	v_accvgpr_read_b32 v9, a41
	v_accvgpr_read_b32 v10, a42
	v_accvgpr_read_b32 v11, a43
	v_accvgpr_read_b32 v12, a44
	v_accvgpr_read_b32 v13, a45
	v_accvgpr_read_b32 v14, a46
	v_accvgpr_read_b32 v15, a47
	v_div_fixup_f32 v172, v130, v131, 1.0
	s_barrier
	s_and_saveexec_b64 s[60:61], s[4:5]
	s_cbranch_execz .LBB0_1090
	v_accvgpr_read_b32 v133, a252
	v_mul_f32_e32 v130, v133, v224
	v_mul_f32_e32 v131, v112, v130
	v_mul_f32_e32 v132, v113, v130
	ds_write2st64_b32 v139, v131, v132 offset1:1
	v_mul_f32_e32 v131, v114, v130
	v_mul_f32_e32 v132, v115, v130
	ds_write2st64_b32 v139, v131, v132 offset0:2 offset1:3
	v_mul_f32_e32 v131, v116, v130
	v_mul_f32_e32 v132, v117, v130
	ds_write2st64_b32 v139, v131, v132 offset0:4 offset1:5
	v_mul_f32_e32 v131, v118, v130
	v_mul_f32_e32 v132, v119, v130
	ds_write2st64_b32 v139, v131, v132 offset0:6 offset1:7
	v_mul_f32_e32 v131, v120, v130
	v_mul_f32_e32 v132, v121, v130
	ds_write2st64_b32 v139, v131, v132 offset0:8 offset1:9
	v_mul_f32_e32 v131, v122, v130
	v_mul_f32_e32 v132, v123, v130
	ds_write2st64_b32 v139, v131, v132 offset0:10 offset1:11
	v_mul_f32_e32 v131, v124, v130
	v_mul_f32_e32 v132, v125, v130
	ds_write2st64_b32 v139, v131, v132 offset0:12 offset1:13
	v_mul_f32_e32 v131, v126, v130
	v_mul_f32_e32 v132, v127, v130
	ds_write2st64_b32 v139, v131, v132 offset0:14 offset1:15
	v_mul_f32_e32 v131, v96, v130
	v_mul_f32_e32 v132, v97, v130
	ds_write2st64_b32 v139, v131, v132 offset0:16 offset1:17
	v_mul_f32_e32 v131, v98, v130
	v_mul_f32_e32 v132, v99, v130
	ds_write2st64_b32 v139, v131, v132 offset0:18 offset1:19
	v_mul_f32_e32 v131, v100, v130
	v_mul_f32_e32 v132, v101, v130
	ds_write2st64_b32 v139, v131, v132 offset0:20 offset1:21
	v_mul_f32_e32 v131, v102, v130
	v_mul_f32_e32 v132, v103, v130
	ds_write2st64_b32 v139, v131, v132 offset0:22 offset1:23
	v_mul_f32_e32 v131, v104, v130
	v_mul_f32_e32 v132, v105, v130
	ds_write2st64_b32 v139, v131, v132 offset0:24 offset1:25
	v_mul_f32_e32 v131, v106, v130
	v_mul_f32_e32 v132, v107, v130
	ds_write2st64_b32 v139, v131, v132 offset0:26 offset1:27
	v_mul_f32_e32 v131, v108, v130
	v_mul_f32_e32 v132, v109, v130
	ds_write2st64_b32 v139, v131, v132 offset0:28 offset1:29
	v_mul_f32_e32 v131, v110, v130
	v_mul_f32_e32 v132, v111, v130
	ds_write2st64_b32 v139, v131, v132 offset0:30 offset1:31
	v_mul_f32_e32 v131, v80, v130
	v_mul_f32_e32 v132, v81, v130
	ds_write2st64_b32 v139, v131, v132 offset0:32 offset1:33
	v_mul_f32_e32 v131, v82, v130
	v_mul_f32_e32 v132, v83, v130
	ds_write2st64_b32 v139, v131, v132 offset0:34 offset1:35
	v_mul_f32_e32 v131, v84, v130
	v_mul_f32_e32 v132, v85, v130
	ds_write2st64_b32 v139, v131, v132 offset0:36 offset1:37
	v_mul_f32_e32 v131, v86, v130
	v_mul_f32_e32 v132, v87, v130
	ds_write2st64_b32 v139, v131, v132 offset0:38 offset1:39
	v_mul_f32_e32 v131, v88, v130
	v_mul_f32_e32 v132, v89, v130
	ds_write2st64_b32 v139, v131, v132 offset0:40 offset1:41
	v_mul_f32_e32 v131, v90, v130
	v_mul_f32_e32 v132, v91, v130
	ds_write2st64_b32 v139, v131, v132 offset0:42 offset1:43
	v_mul_f32_e32 v131, v92, v130
	v_mul_f32_e32 v132, v93, v130
	ds_write2st64_b32 v139, v131, v132 offset0:44 offset1:45
	v_mul_f32_e32 v131, v94, v130
	v_mul_f32_e32 v132, v95, v130
	ds_write2st64_b32 v139, v131, v132 offset0:46 offset1:47
	v_mul_f32_e32 v131, v64, v130
	v_mul_f32_e32 v132, v65, v130
	ds_write2st64_b32 v139, v131, v132 offset0:48 offset1:49
	v_mul_f32_e32 v131, v66, v130
	v_mul_f32_e32 v132, v67, v130
	ds_write2st64_b32 v139, v131, v132 offset0:50 offset1:51
	v_mul_f32_e32 v131, v68, v130
	v_mul_f32_e32 v132, v69, v130
	ds_write2st64_b32 v139, v131, v132 offset0:52 offset1:53
	v_mul_f32_e32 v131, v70, v130
	v_mul_f32_e32 v132, v71, v130
	ds_write2st64_b32 v139, v131, v132 offset0:54 offset1:55
	v_mul_f32_e32 v131, v72, v130
	v_mul_f32_e32 v132, v73, v130
	ds_write2st64_b32 v139, v131, v132 offset0:56 offset1:57
	v_mul_f32_e32 v131, v74, v130
	v_mul_f32_e32 v132, v75, v130
	ds_write2st64_b32 v139, v131, v132 offset0:58 offset1:59
	v_mul_f32_e32 v131, v76, v130
	v_mul_f32_e32 v132, v77, v130
	ds_write2st64_b32 v139, v131, v132 offset0:60 offset1:61
	v_mul_f32_e32 v131, v78, v130
	v_mul_f32_e32 v130, v79, v130
	ds_write2st64_b32 v139, v131, v130 offset0:62 offset1:63
	v_mul_f32_e32 v130, v133, v172
	v_mul_f32_e32 v131, v48, v130
	v_mul_f32_e32 v132, v49, v130
	ds_write2st64_b32 v254, v131, v132 offset1:1
	v_mul_f32_e32 v131, v50, v130
	v_mul_f32_e32 v132, v51, v130
	ds_write2st64_b32 v254, v131, v132 offset0:2 offset1:3
	v_mul_f32_e32 v131, v52, v130
	v_mul_f32_e32 v132, v53, v130
	ds_write2st64_b32 v254, v131, v132 offset0:4 offset1:5
	v_mul_f32_e32 v131, v54, v130
	v_mul_f32_e32 v132, v55, v130
	ds_write2st64_b32 v254, v131, v132 offset0:6 offset1:7
	v_mul_f32_e32 v131, v56, v130
	v_mul_f32_e32 v132, v57, v130
	ds_write2st64_b32 v254, v131, v132 offset0:8 offset1:9
	v_mul_f32_e32 v131, v58, v130
	v_mul_f32_e32 v132, v59, v130
	ds_write2st64_b32 v254, v131, v132 offset0:10 offset1:11
	v_mul_f32_e32 v131, v60, v130
	v_mul_f32_e32 v132, v61, v130
	ds_write2st64_b32 v254, v131, v132 offset0:12 offset1:13
	v_mul_f32_e32 v131, v62, v130
	v_mul_f32_e32 v132, v63, v130
	ds_write2st64_b32 v254, v131, v132 offset0:14 offset1:15
	v_mul_f32_e32 v131, v32, v130
	v_mul_f32_e32 v132, v33, v130
	ds_write2st64_b32 v254, v131, v132 offset0:16 offset1:17
	v_mul_f32_e32 v131, v34, v130
	v_mul_f32_e32 v132, v35, v130
	ds_write2st64_b32 v254, v131, v132 offset0:18 offset1:19
	v_mul_f32_e32 v131, v36, v130
	v_mul_f32_e32 v132, v37, v130
	ds_write2st64_b32 v254, v131, v132 offset0:20 offset1:21
	v_mul_f32_e32 v131, v38, v130
	v_mul_f32_e32 v132, v39, v130
	ds_write2st64_b32 v254, v131, v132 offset0:22 offset1:23
	v_mul_f32_e32 v131, v40, v130
	v_mul_f32_e32 v132, v41, v130
	ds_write2st64_b32 v254, v131, v132 offset0:24 offset1:25
	v_mul_f32_e32 v131, v42, v130
	v_mul_f32_e32 v132, v43, v130
	ds_write2st64_b32 v254, v131, v132 offset0:26 offset1:27
	v_mul_f32_e32 v131, v44, v130
	v_mul_f32_e32 v132, v45, v130
	ds_write2st64_b32 v254, v131, v132 offset0:28 offset1:29
	v_mul_f32_e32 v131, v46, v130
	v_mul_f32_e32 v132, v47, v130
	ds_write2st64_b32 v254, v131, v132 offset0:30 offset1:31
	v_mul_f32_e32 v131, v16, v130
	v_mul_f32_e32 v132, v17, v130
	ds_write2st64_b32 v254, v131, v132 offset0:32 offset1:33
	v_mul_f32_e32 v131, v18, v130
	v_mul_f32_e32 v132, v19, v130
	ds_write2st64_b32 v254, v131, v132 offset0:34 offset1:35
	v_mul_f32_e32 v131, v20, v130
	v_mul_f32_e32 v132, v21, v130
	ds_write2st64_b32 v254, v131, v132 offset0:36 offset1:37
	v_mul_f32_e32 v131, v22, v130
	v_mul_f32_e32 v132, v23, v130
	ds_write2st64_b32 v254, v131, v132 offset0:38 offset1:39
	v_mul_f32_e32 v131, v24, v130
	v_mul_f32_e32 v132, v25, v130
	ds_write2st64_b32 v254, v131, v132 offset0:40 offset1:41
	v_mul_f32_e32 v131, v26, v130
	v_mul_f32_e32 v132, v27, v130
	ds_write2st64_b32 v254, v131, v132 offset0:42 offset1:43
	v_mul_f32_e32 v131, v28, v130
	v_mul_f32_e32 v132, v29, v130
	ds_write2st64_b32 v254, v131, v132 offset0:44 offset1:45
	v_mul_f32_e32 v131, v30, v130
	v_mul_f32_e32 v132, v31, v130
	ds_write2st64_b32 v254, v131, v132 offset0:46 offset1:47
	v_mul_f32_e32 v131, v0, v130
	v_mul_f32_e32 v132, v1, v130
	ds_write2st64_b32 v254, v131, v132 offset0:48 offset1:49
	v_mul_f32_e32 v131, v2, v130
	v_mul_f32_e32 v132, v3, v130
	ds_write2st64_b32 v254, v131, v132 offset0:50 offset1:51
	v_mul_f32_e32 v131, v4, v130
	v_mul_f32_e32 v132, v5, v130
	ds_write2st64_b32 v254, v131, v132 offset0:52 offset1:53
	v_mul_f32_e32 v131, v6, v130
	v_mul_f32_e32 v132, v7, v130
	ds_write2st64_b32 v254, v131, v132 offset0:54 offset1:55
	v_mul_f32_e32 v131, v8, v130
	v_mul_f32_e32 v132, v9, v130
	ds_write2st64_b32 v254, v131, v132 offset0:56 offset1:57
	v_mul_f32_e32 v131, v10, v130
	v_mul_f32_e32 v132, v11, v130
	ds_write2st64_b32 v254, v131, v132 offset0:58 offset1:59
	v_mul_f32_e32 v131, v12, v130
	v_mul_f32_e32 v132, v13, v130
	ds_write2st64_b32 v254, v131, v132 offset0:60 offset1:61
	v_mul_f32_e32 v131, v14, v130
	v_mul_f32_e32 v130, v15, v130
	ds_write2st64_b32 v254, v131, v130 offset0:62 offset1:63

.LBB0_1265:
	s_and_b32 s50, s42, 1
	s_mul_i32 s51, s50, 0xd800
	s_xor_b32 s50, s50, 1
	s_mul_i32 s50, s50, 0xd800
	s_add_i32 s42, s42, 1
	v_add_u32_e32 v186, s50, v45
	ds_read_b128 v[68:71], v189 offset:32
	ds_read_b128 v[80:83], v187 offset:36896
	ds_read_b128 v[72:75], v189 offset:4640
	ds_read_b128 v[84:87], v187 offset:41504
	ds_read_b128 v[76:79], v189 offset:9248
	ds_read_b128 v[104:107], v188 offset:32
	s_waitcnt lgkmcnt(6)
	v_mfma_f32_32x32x16_bf16 a[32:47], v[108:111], v[14:17], a[32:47]
	s_waitcnt vmcnt(11)
	ds_write_b128 v186, v[250:253]
	v_mfma_f32_32x32x16_bf16 a[48:63], v[108:111], v[64:67], a[48:63]
	s_waitcnt vmcnt(10)
	ds_write_b128 v186, v[246:249] offset:4608
	global_load_dwordx4 v[250:253], v254, s[100:101] offset:512
	v_mfma_f32_32x32x16_bf16 a[64:79], v[112:115], v[14:17], a[64:79]
	s_waitcnt vmcnt(10)
	ds_write_b128 v186, v[242:245] offset:9216
	global_load_dwordx4 v[246:249], v205, s[100:101] offset:512
	v_mfma_f32_32x32x16_bf16 a[96:111], v[112:115], v[64:67], a[96:111]
	s_waitcnt vmcnt(10)
	ds_write_b128 v186, v[238:241] offset:13824
	global_load_dwordx4 v[242:245], v204, s[100:101] offset:512
	v_mfma_f32_32x32x16_bf16 a[80:95], v[116:119], v[14:17], a[80:95]
	s_waitcnt vmcnt(10)
	ds_write_b128 v186, v[234:237] offset:18432
	global_load_dwordx4 v[238:241], v203, s[100:101] offset:512
	v_mfma_f32_32x32x16_bf16 a[112:127], v[116:119], v[64:67], a[112:127]
	s_waitcnt vmcnt(10)
	ds_write_b128 v186, v[230:233] offset:23040
	global_load_dwordx4 v[234:237], v202, s[100:101] offset:512
	s_waitcnt lgkmcnt(6)
	v_mfma_f32_32x32x16_bf16 a[16:31], v[120:123], v[14:17], a[16:31]
	s_waitcnt vmcnt(10)
	ds_write_b128 v186, v[226:229] offset:27648
	global_load_dwordx4 v[230:233], v201, s[100:101] offset:512
	v_mfma_f32_32x32x16_bf16 a[0:15], v[120:123], v[64:67], a[0:15]
	s_waitcnt vmcnt(10)
	ds_write_b128 v186, v[222:225] offset:32256
	global_load_dwordx4 v[226:229], v200, s[100:101] offset:512
	s_waitcnt lgkmcnt(8)
	ds_read_b128 v[108:111], v189 offset:64
	ds_read_b128 v[14:17], v187 offset:36928
	ds_read_b128 v[112:115], v189 offset:4672
	ds_read_b128 v[64:67], v187 offset:41536
	ds_read_b128 v[116:119], v189 offset:9280
	ds_read_b128 v[120:123], v188 offset:64
	v_mfma_f32_32x32x16_bf16 a[32:47], v[68:71], v[80:83], a[32:47]
	s_waitcnt lgkmcnt(12)
	s_waitcnt vmcnt(10)
	ds_write_b128 v186, v[218:221] offset:36864
	global_load_dwordx4 v[222:225], v199, s[100:101] offset:512
	v_mfma_f32_32x32x16_bf16 a[48:63], v[68:71], v[84:87], a[48:63]
	s_waitcnt lgkmcnt(12)
	s_waitcnt vmcnt(10)
	ds_write_b128 v186, v[214:217] offset:41472
	global_load_dwordx4 v[218:221], v198, s[98:99] offset:256
	v_mfma_f32_32x32x16_bf16 a[64:79], v[72:75], v[80:83], a[64:79]
	s_waitcnt lgkmcnt(12)
	s_waitcnt vmcnt(10)
	ds_write_b128 v186, v[210:213] offset:46080
	global_load_dwordx4 v[214:217], v197, s[98:99] offset:256
	v_mfma_f32_32x32x16_bf16 a[96:111], v[72:75], v[84:87], a[96:111]
	s_waitcnt lgkmcnt(12)
	s_waitcnt vmcnt(10)
	ds_write_b128 v186, v[206:209] offset:50688
	global_load_dwordx4 v[210:213], v196, s[98:99] offset:256
	v_mfma_f32_32x32x16_bf16 a[80:95], v[76:79], v[80:83], a[80:95]
	global_load_dwordx4 v[206:209], v195, s[98:99] offset:256
	s_add_u32 s100, s100, 0x80
	s_addc_u32 s101, s101, 0
	s_add_u32 s98, s98, 0x80
	s_addc_u32 s99, s99, 0
	v_mfma_f32_32x32x16_bf16 a[112:127], v[76:79], v[84:87], a[112:127]
	v_mfma_f32_32x32x16_bf16 a[16:31], v[104:107], v[80:83], a[16:31]
	v_mfma_f32_32x32x16_bf16 a[0:15], v[104:107], v[84:87], a[0:15]
	s_waitcnt lgkmcnt(4)
	ds_read_b128 v[68:71], v189 offset:96
	ds_read_b128 v[80:83], v187 offset:36960
	ds_read_b128 v[72:75], v189 offset:4704
	ds_read_b128 v[84:87], v187 offset:41568
	ds_read_b128 v[76:79], v189 offset:9312
	ds_read_b128 v[104:107], v188 offset:96
	v_mfma_f32_32x32x16_bf16 a[32:47], v[108:111], v[14:17], a[32:47]
	v_mfma_f32_32x32x16_bf16 a[48:63], v[108:111], v[64:67], a[48:63]
	v_mfma_f32_32x32x16_bf16 a[64:79], v[112:115], v[14:17], a[64:79]
	v_mfma_f32_32x32x16_bf16 a[96:111], v[112:115], v[64:67], a[96:111]
	v_mfma_f32_32x32x16_bf16 a[80:95], v[116:119], v[14:17], a[80:95]
	v_mfma_f32_32x32x16_bf16 a[112:127], v[116:119], v[64:67], a[112:127]
	v_mfma_f32_32x32x16_bf16 a[16:31], v[120:123], v[14:17], a[16:31]
	v_mfma_f32_32x32x16_bf16 a[0:15], v[120:123], v[64:67], a[0:15]
	s_waitcnt lgkmcnt(0)
	v_mfma_f32_32x32x16_bf16 a[32:47], v[68:71], v[80:83], a[32:47]
	v_mfma_f32_32x32x16_bf16 a[48:63], v[68:71], v[84:87], a[48:63]
	v_mfma_f32_32x32x16_bf16 a[64:79], v[72:75], v[80:83], a[64:79]
	v_mfma_f32_32x32x16_bf16 a[96:111], v[72:75], v[84:87], a[96:111]
	s_barrier
	v_add_u32_e32 v189, s50, v192
	v_add_u32_e32 v188, s50, v191
	v_add_u32_e32 v187, s50, v190
	ds_read_b128 v[108:111], v189
	ds_read_b128 v[14:17], v187 offset:36864
	ds_read_b128 v[112:115], v189 offset:4608
	ds_read_b128 v[64:67], v187 offset:41472
	ds_read_b128 v[116:119], v189 offset:9216
	ds_read_b128 v[120:123], v188
	v_mfma_f32_32x32x16_bf16 a[80:95], v[76:79], v[80:83], a[80:95]
	v_mfma_f32_32x32x16_bf16 a[112:127], v[76:79], v[84:87], a[112:127]
	v_mfma_f32_32x32x16_bf16 a[16:31], v[104:107], v[80:83], a[16:31]
	v_mfma_f32_32x32x16_bf16 a[0:15], v[104:107], v[84:87], a[0:15]
	s_add_u32 s44, s44, 0x80
	s_addc_u32 s45, s45, 0
	s_cmpk_lg_i32 s44, 0x700
	s_cbranch_scc1 .LBB0_1265
	ds_read_b128 v[10:13], v60
	ds_read_b128 v[108:111], v62 offset:36864
	ds_read_b128 v[112:115], v60 offset:4608
	ds_read_b128 v[116:119], v62 offset:41472
	s_lshl_b32 s44, s48, 8
	s_lshl_b32 s42, s49, 8
	s_waitcnt lgkmcnt(2)
	v_mfma_f32_32x32x16_bf16 a[176:191], v[10:13], v[108:111], a[32:47]
	s_add_i32 s47, s47, s77
	s_add_i32 s46, s46, s77
	s_waitcnt lgkmcnt(0)
	v_mfma_f32_32x32x16_bf16 a[160:175], v[10:13], v[116:119], a[48:63]
	v_mfma_f32_32x32x16_bf16 a[144:159], v[112:115], v[108:111], a[64:79]
	v_mfma_f32_32x32x16_bf16 a[128:143], v[112:115], v[116:119], a[96:111]
	ds_read_b128 v[10:13], v60 offset:9216
	ds_read_b128 v[112:115], v61
	s_waitcnt vmcnt(11)
	s_waitcnt vmcnt(0)
	ds_write_b128 v63, v[250:253] offset:55296
	s_waitcnt vmcnt(10)
	ds_write_b128 v63, v[246:249] offset:59904
	s_waitcnt vmcnt(9)
	ds_write_b128 v63, v[242:245] offset:64512
	s_waitcnt vmcnt(8)
	ds_write_b128 v50, v[238:241] offset:55296
	s_waitcnt vmcnt(7)
	ds_write_b128 v51, v[234:237] offset:55296
	s_waitcnt vmcnt(6)
	ds_write_b128 v52, v[230:233] offset:55296
	s_waitcnt vmcnt(5)
	ds_write_b128 v53, v[226:229] offset:55296
	s_waitcnt vmcnt(4)
	ds_write_b128 v54, v[222:225] offset:55296
	s_waitcnt vmcnt(3)
	ds_write_b128 v55, v[218:221]
	s_waitcnt vmcnt(2)
	ds_write_b128 v55, v[214:217] offset:4608
	s_waitcnt vmcnt(1)
	ds_write_b128 v55, v[210:213] offset:9216
	s_waitcnt vmcnt(0)
	ds_write_b128 v55, v[206:209] offset:13824
	s_waitcnt lgkmcnt(13)
	v_mfma_f32_32x32x16_bf16 a[64:79], v[10:13], v[108:111], a[80:95]
	v_mfma_f32_32x32x16_bf16 a[48:63], v[10:13], v[116:119], a[112:127]
	ds_read_b128 v[10:13], v60 offset:32
	ds_read_b128 v[14:17], v62 offset:36896
	ds_read_b128 v[64:67], v62 offset:36928
	ds_read_b128 v[68:71], v60 offset:64
	ds_read_b128 v[72:75], v62 offset:41504
	ds_read_b128 v[76:79], v62 offset:36960
	s_waitcnt lgkmcnt(4)
	v_mfma_f32_32x32x16_bf16 a[176:191], v[10:13], v[14:17], a[176:191]
	s_waitcnt lgkmcnt(1)
	v_mfma_f32_32x32x16_bf16 a[160:175], v[10:13], v[72:75], a[160:175]
	ds_read_b128 v[10:13], v60 offset:4640
	ds_read_b128 v[80:83], v60 offset:96
	v_mfma_f32_32x32x16_bf16 a[32:47], v[112:115], v[108:111], a[16:31]
	v_mfma_f32_32x32x16_bf16 a[16:31], v[112:115], v[116:119], a[0:15]
	s_waitcnt lgkmcnt(1)
	v_mfma_f32_32x32x16_bf16 a[144:159], v[10:13], v[14:17], a[144:159]
	v_mfma_f32_32x32x16_bf16 a[128:143], v[10:13], v[72:75], a[128:143]
	ds_read_b128 v[10:13], v60 offset:9248
	ds_read_b128 v[84:87], v60 offset:9280
	s_waitcnt lgkmcnt(1)
	v_mfma_f32_32x32x16_bf16 a[64:79], v[10:13], v[14:17], a[64:79]
	v_mfma_f32_32x32x16_bf16 a[48:63], v[10:13], v[72:75], a[48:63]
	ds_read_b128 v[10:13], v61 offset:32
	ds_read_b128 v[88:91], v60 offset:9312
	s_waitcnt lgkmcnt(1)
	v_mfma_f32_32x32x16_bf16 a[32:47], v[10:13], v[14:17], a[32:47]
	v_mfma_f32_32x32x16_bf16 a[16:31], v[10:13], v[72:75], a[16:31]
	ds_read_b128 v[10:13], v62 offset:41536
	ds_read_b128 v[14:17], v62 offset:41568
	v_mfma_f32_32x32x16_bf16 a[176:191], v[68:71], v[64:67], a[176:191]
	s_waitcnt lgkmcnt(1)
	v_mfma_f32_32x32x16_bf16 a[160:175], v[68:71], v[10:13], a[160:175]
	ds_read_b128 v[68:71], v60 offset:4672
	ds_read_b128 v[72:75], v60 offset:4704
	s_waitcnt lgkmcnt(1)
	v_mfma_f32_32x32x16_bf16 a[144:159], v[68:71], v[64:67], a[144:159]
	v_mfma_f32_32x32x16_bf16 a[128:143], v[68:71], v[10:13], a[128:143]
	v_mfma_f32_32x32x16_bf16 a[64:79], v[84:87], v[64:67], a[64:79]
	v_mfma_f32_32x32x16_bf16 a[48:63], v[84:87], v[10:13], a[48:63]
	ds_read_b128 v[68:71], v61 offset:64
	ds_read_b128 v[84:87], v61 offset:96
	s_waitcnt lgkmcnt(0)
	s_barrier
	v_mfma_f32_32x32x16_bf16 a[32:47], v[68:71], v[64:67], a[32:47]
	v_mfma_f32_32x32x16_bf16 a[16:31], v[68:71], v[10:13], a[16:31]
	v_mfma_f32_32x32x16_bf16 a[176:191], v[80:83], v[76:79], a[176:191]
	v_mfma_f32_32x32x16_bf16 a[160:175], v[80:83], v[14:17], a[160:175]
	v_mfma_f32_32x32x16_bf16 a[144:159], v[72:75], v[76:79], a[144:159]
	v_mfma_f32_32x32x16_bf16 a[128:143], v[72:75], v[14:17], a[128:143]
	v_mfma_f32_32x32x16_bf16 a[64:79], v[88:91], v[76:79], a[64:79]
	v_mfma_f32_32x32x16_bf16 a[48:63], v[88:91], v[14:17], a[48:63]
	v_mfma_f32_32x32x16_bf16 a[32:47], v[84:87], v[76:79], a[32:47]
	v_mfma_f32_32x32x16_bf16 a[16:31], v[84:87], v[14:17], a[16:31]
	ds_read_b128 v[10:13], v60 offset:55296
	ds_read_b128 v[14:17], v56
	ds_read_b128 v[64:67], v60 offset:55328
	ds_read_b128 v[68:71], v56 offset:32
	ds_read_b128 v[72:75], v56 offset:4608
	ds_read_b128 v[76:79], v56 offset:4640
	s_waitcnt lgkmcnt(4)
	v_mfma_f32_32x32x16_bf16 a[176:191], v[10:13], v[14:17], a[176:191]
	s_waitcnt lgkmcnt(1)
	v_mfma_f32_32x32x16_bf16 a[160:175], v[10:13], v[72:75], a[160:175]
	ds_read_b128 v[10:13], v60 offset:59904
	ds_read_b128 v[80:83], v60 offset:59936
	s_waitcnt lgkmcnt(1)
	v_mfma_f32_32x32x16_bf16 a[144:159], v[10:13], v[14:17], a[144:159]
	v_mfma_f32_32x32x16_bf16 a[128:143], v[10:13], v[72:75], a[128:143]
	ds_read_b128 v[10:13], v60 offset:64512
	ds_read_b128 v[84:87], v60 offset:64544
	s_waitcnt lgkmcnt(1)
	v_mfma_f32_32x32x16_bf16 a[64:79], v[10:13], v[14:17], a[64:79]
	v_mfma_f32_32x32x16_bf16 a[48:63], v[10:13], v[72:75], a[48:63]
	ds_read_b128 v[10:13], v61 offset:55296
	ds_read_b128 v[88:91], v61 offset:55328
	s_waitcnt lgkmcnt(1)
	v_mfma_f32_32x32x16_bf16 a[32:47], v[10:13], v[14:17], a[32:47]
	v_mfma_f32_32x32x16_bf16 a[16:31], v[10:13], v[72:75], a[16:31]
	ds_read_b128 v[10:13], v60 offset:55360
	v_mfma_f32_32x32x16_bf16 a[176:191], v[64:67], v[68:71], a[176:191]
	v_mfma_f32_32x32x16_bf16 a[160:175], v[64:67], v[76:79], a[160:175]
	v_mfma_f32_32x32x16_bf16 a[144:159], v[80:83], v[68:71], a[144:159]
	v_mfma_f32_32x32x16_bf16 a[128:143], v[80:83], v[76:79], a[128:143]
	v_mfma_f32_32x32x16_bf16 a[64:79], v[84:87], v[68:71], a[64:79]
	v_mfma_f32_32x32x16_bf16 a[48:63], v[84:87], v[76:79], a[48:63]
	ds_read_b128 v[14:17], v56 offset:64
	ds_read_b128 v[64:67], v61 offset:55360
	ds_read_b128 v[72:75], v61 offset:55392
	ds_read_b128 v[80:83], v60 offset:64576
	ds_read_b128 v[84:87], v60 offset:64608
	ds_read_b128 v[92:95], v60 offset:55392
	ds_read_b128 v[96:99], v56 offset:96
	ds_read_b128 v[100:103], v60 offset:59968
	ds_read_b128 v[104:107], v60 offset:60000
	ds_read_b128 v[108:111], v56 offset:4672
	ds_read_b128 v[112:115], v56 offset:4704
	s_waitcnt lgkmcnt(0)
	s_barrier
	v_mfma_f32_32x32x16_bf16 a[32:47], v[88:91], v[68:71], a[32:47]
	v_add_u32_e32 v70, 0x2048, v21
	v_mfma_f32_32x32x16_bf16 a[16:31], v[88:91], v[76:79], a[16:31]
	v_mfma_f32_32x32x16_bf16 a[176:191], v[10:13], v[14:17], a[176:191]
	v_mfma_f32_32x32x16_bf16 a[160:175], v[10:13], v[108:111], a[160:175]
	v_lshl_add_u64 v[10:11], v[6:7], 0, s[42:43]
	v_mfma_f32_32x32x16_bf16 a[144:159], v[100:103], v[14:17], a[144:159]
	v_mfma_f32_32x32x16_bf16 a[128:143], v[100:103], v[108:111], a[128:143]
	v_mfma_f32_32x32x16_bf16 a[64:79], v[80:83], v[14:17], a[64:79]
	v_mfma_f32_32x32x16_bf16 a[48:63], v[80:83], v[108:111], a[48:63]
	v_mfma_f32_32x32x16_bf16 a[32:47], v[64:67], v[14:17], a[32:47]
	v_mfma_f32_32x32x16_bf16 a[16:31], v[64:67], v[108:111], a[16:31]
	v_add_u32_e32 v66, 0x1028, v21
	v_mfma_f32_32x32x16_bf16 a[176:191], v[92:95], v[96:99], a[176:191]
	s_nop 11
	ds_write_b32 v49, a176
	ds_write_b32 v49, a177 offset:516
	ds_write_b32 v49, a178 offset:1032
	ds_write_b32 v49, a179 offset:1548
	ds_write_b32 v49, a180 offset:4128
	ds_write_b32 v49, a181 offset:4644
	ds_write_b32 v49, a182 offset:5160
	v_mfma_f32_32x32x16_bf16 a[160:175], v[92:95], v[112:115], a[160:175]
	ds_write_b32 v49, a183 offset:5676
	ds_write_b32 v49, a184 offset:8256
	ds_write_b32 v49, a185 offset:8772
	ds_write_b32 v49, a186 offset:9288
	ds_write_b32 v49, a187 offset:9804
	ds_write_b32 v49, a188 offset:12384
	ds_write_b32 v49, a189 offset:12900
	ds_write_b32 v49, a190 offset:13416
	ds_write_b32 v49, a191 offset:13932
	s_nop 2
	ds_write_b32 v49, a160 offset:128
	ds_write_b32 v49, a161 offset:644
	ds_write_b32 v49, a162 offset:1160
	ds_write_b32 v49, a163 offset:1676
	ds_write_b32 v49, a164 offset:4256
	ds_write_b32 v49, a165 offset:4772
	ds_write_b32 v49, a166 offset:5288
	ds_write_b32 v49, a167 offset:5804
	ds_write_b32 v49, a168 offset:8384
	ds_write_b32 v49, a169 offset:8900
	ds_write_b32 v49, a170 offset:9416
	ds_write_b32 v49, a171 offset:9932
	v_mfma_f32_32x32x16_bf16 a[144:159], v[104:107], v[96:99], a[144:159]
	ds_write_b32 v49, a172 offset:12512
	ds_write_b32 v49, a173 offset:13028
	ds_write_b32 v49, a174 offset:13544
	ds_write_b32 v49, a175 offset:14060
	s_nop 7
	ds_write_b32 v49, a144 offset:16512
	ds_write_b32 v49, a145 offset:17028
	ds_write_b32 v49, a146 offset:17544
	ds_write_b32 v49, a147 offset:18060
	ds_write_b32 v49, a148 offset:20640
	ds_write_b32 v49, a149 offset:21156
	ds_write_b32 v49, a150 offset:21672
	ds_write_b32 v49, a151 offset:22188
	ds_write_b32 v49, a152 offset:24768
	ds_write_b32 v49, a153 offset:25284
	v_mfma_f32_32x32x16_bf16 a[128:143], v[104:107], v[112:115], a[128:143]
	ds_write_b32 v49, a154 offset:25800
	ds_write_b32 v49, a155 offset:26316
	ds_write_b32 v49, a156 offset:28896
	ds_write_b32 v49, a157 offset:29412
	ds_write_b32 v49, a158 offset:29928
	ds_write_b32 v49, a159 offset:30444
	s_nop 5
	ds_write_b32 v49, a128 offset:16640
	ds_write_b32 v49, a129 offset:17156
	ds_write_b32 v49, a130 offset:17672
	ds_write_b32 v49, a131 offset:18188
	ds_write_b32 v49, a132 offset:20768
	ds_write_b32 v49, a133 offset:21284
	ds_write_b32 v49, a134 offset:21800
	ds_write_b32 v49, a135 offset:22316
	v_mfma_f32_32x32x16_bf16 a[64:79], v[84:87], v[96:99], a[64:79]
	ds_write_b32 v49, a136 offset:24896
	ds_write_b32 v49, a137 offset:25412
	ds_write_b32 v49, a138 offset:25928
	ds_write_b32 v49, a139 offset:26444
	ds_write_b32 v49, a140 offset:29024
	ds_write_b32 v49, a141 offset:29540
	ds_write_b32 v49, a142 offset:30056
	ds_write_b32 v49, a143 offset:30572
	s_nop 3
	ds_write_b32 v49, a64 offset:33024
	ds_write_b32 v49, a65 offset:33540
	ds_write_b32 v49, a66 offset:34056
	ds_write_b32 v49, a67 offset:34572
	ds_write_b32 v49, a68 offset:37152
	ds_write_b32 v49, a69 offset:37668
	v_mfma_f32_32x32x16_bf16 a[48:63], v[84:87], v[112:115], a[48:63]
	ds_write_b32 v49, a70 offset:38184
	ds_write_b32 v49, a71 offset:38700
	ds_write_b32 v49, a72 offset:41280
	ds_write_b32 v49, a73 offset:41796
	ds_write_b32 v49, a74 offset:42312
	ds_write_b32 v49, a75 offset:42828
	ds_write_b32 v49, a76 offset:45408
	ds_write_b32 v49, a77 offset:45924
	ds_write_b32 v49, a78 offset:46440
	ds_write_b32 v49, a79 offset:46956
	s_nop 1
	ds_write_b32 v49, a48 offset:33152
	ds_write_b32 v49, a49 offset:33668
	ds_write_b32 v49, a50 offset:34184
	ds_write_b32 v49, a51 offset:34700
	ds_write_b32 v49, a52 offset:37280
	ds_write_b32 v49, a53 offset:37796
	ds_write_b32 v49, a54 offset:38312
	ds_write_b32 v49, a55 offset:38828
	ds_write_b32 v49, a56 offset:41408
	ds_write_b32 v49, a57 offset:41924
	ds_write_b32 v49, a58 offset:42440
	v_mfma_f32_32x32x16_bf16 a[32:47], v[72:75], v[96:99], a[32:47]
	ds_write_b32 v49, a59 offset:42956
	ds_write_b32 v49, a60 offset:45536
	ds_write_b32 v49, a61 offset:46052
	ds_write_b32 v49, a62 offset:46568
	ds_write_b32 v49, a63 offset:47084
	s_nop 6
	ds_write_b32 v49, a32 offset:49536
	ds_write_b32 v49, a33 offset:50052
	ds_write_b32 v49, a34 offset:50568
	ds_write_b32 v49, a35 offset:51084
	ds_write_b32 v49, a36 offset:53664
	ds_write_b32 v49, a37 offset:54180
	ds_write_b32 v49, a38 offset:54696
	ds_write_b32 v49, a39 offset:55212
	ds_write_b32 v49, a40 offset:57792
	v_mfma_f32_32x32x16_bf16 a[16:31], v[72:75], v[112:115], a[16:31]
	ds_write_b32 v49, a41 offset:58308
	ds_write_b32 v49, a42 offset:58824
	ds_write_b32 v49, a43 offset:59340
	ds_write_b32 v49, a44 offset:61920
	ds_write_b32 v49, a45 offset:62436
	ds_write_b32 v49, a46 offset:62952
	ds_write_b32 v49, a47 offset:63468
	s_nop 4
	ds_write_b32 v49, a16 offset:49664
	ds_write_b32 v49, a17 offset:50180
	ds_write_b32 v49, a18 offset:50696
	ds_write_b32 v49, a19 offset:51212
	ds_write_b32 v49, a20 offset:53792
	ds_write_b32 v49, a21 offset:54308
	ds_write_b32 v49, a22 offset:54824
	ds_write_b32 v49, a23 offset:55340
	ds_write_b32 v49, a24 offset:57920
	ds_write_b32 v49, a25 offset:58436
	ds_write_b32 v49, a26 offset:58952
	ds_write_b32 v49, a27 offset:59468
	ds_write_b32 v49, a28 offset:62048
	ds_write_b32 v49, a29 offset:62564
	ds_write_b32 v49, a30 offset:63080
	ds_write_b32 v49, a31 offset:63596
	s_waitcnt lgkmcnt(0)
	s_barrier
	ds_read2_b32 v[16:17], v21 offset1:1
	ds_read2_b32 v[18:19], v21 offset0:2 offset1:3
	v_accvgpr_read_b32 v72, a218
	v_or_b32_e32 v0, s44, v72
	v_lshlrev_b32_e32 v0, 11, v0
	s_waitcnt lgkmcnt(1)
	v_cvt_pk_bf16_f32 v16, v16, v17
	s_waitcnt lgkmcnt(0)
	v_cvt_pk_bf16_f32 v17, v18, v19
	v_lshl_add_u64 v[18:19], v[10:11], 0, v[0:1]
	v_add_u32_e32 v0, 0x1020, v21
	ds_read2_b32 v[12:13], v29 offset1:1
	ds_read2_b32 v[14:15], v29 offset0:2 offset1:3
	ds_read2_b32 v[64:65], v0 offset1:1
	ds_read2_b32 v[66:67], v66 offset1:1
	v_accvgpr_read_b32 v73, a219
	v_or_b32_e32 v0, s44, v73
	v_lshlrev_b32_e32 v0, 11, v0
	global_store_dwordx2 v[18:19], v[16:17], off
	s_waitcnt lgkmcnt(1)
	v_cvt_pk_bf16_f32 v64, v64, v65
	s_waitcnt lgkmcnt(0)
	v_cvt_pk_bf16_f32 v65, v66, v67
	v_lshl_add_u64 v[66:67], v[10:11], 0, v[0:1]
	v_add_u32_e32 v0, 0x2040, v21
	ds_read2_b32 v[16:17], v44 offset1:1
	ds_read2_b32 v[18:19], v44 offset0:2 offset1:3
	ds_read2_b32 v[68:69], v0 offset1:1
	ds_read2_b32 v[70:71], v70 offset1:1
	global_store_dwordx2 v[66:67], v[64:65], off
	v_add_u32_e32 v0, 0x3060, v21
	v_add_u32_e32 v66, 0x3068, v21
	ds_read2_b32 v[64:65], v0 offset1:1
	ds_read2_b32 v[66:67], v66 offset1:1
	v_or_b32_e32 v0, s44, v132
	v_lshlrev_b32_e32 v0, 11, v0
	s_waitcnt lgkmcnt(3)
	v_cvt_pk_bf16_f32 v68, v68, v69
	s_waitcnt lgkmcnt(2)
	v_cvt_pk_bf16_f32 v69, v70, v71
	v_lshl_add_u64 v[70:71], v[10:11], 0, v[0:1]
	v_or_b32_e32 v0, s44, v133
	v_lshlrev_b32_e32 v0, 11, v0
	global_store_dwordx2 v[70:71], v[68:69], off
	s_waitcnt lgkmcnt(1)
	v_cvt_pk_bf16_f32 v64, v64, v65
	s_waitcnt lgkmcnt(0)
	v_cvt_pk_bf16_f32 v65, v66, v67
	v_lshl_add_u64 v[66:67], v[10:11], 0, v[0:1]
	v_add_u32_e32 v0, 0x4080, v21
	v_add_u32_e32 v70, 0x4088, v21
	ds_read2_b32 v[68:69], v0 offset1:1
	ds_read2_b32 v[70:71], v70 offset1:1
	global_store_dwordx2 v[66:67], v[64:65], off
	v_add_u32_e32 v0, 0x50a0, v21
	v_add_u32_e32 v66, 0x50a8, v21
	ds_read2_b32 v[64:65], v0 offset1:1
	ds_read2_b32 v[66:67], v66 offset1:1
	v_or_b32_e32 v0, s44, v136
	v_lshlrev_b32_e32 v0, 11, v0
	s_waitcnt lgkmcnt(3)
	v_cvt_pk_bf16_f32 v68, v68, v69
	s_waitcnt lgkmcnt(2)
	v_cvt_pk_bf16_f32 v69, v70, v71
	v_lshl_add_u64 v[70:71], v[10:11], 0, v[0:1]
	v_or_b32_e32 v0, s44, v137
	v_lshlrev_b32_e32 v0, 11, v0
	global_store_dwordx2 v[70:71], v[68:69], off
	s_waitcnt lgkmcnt(1)
	v_cvt_pk_bf16_f32 v64, v64, v65
	s_waitcnt lgkmcnt(0)
	v_cvt_pk_bf16_f32 v65, v66, v67
	v_lshl_add_u64 v[66:67], v[10:11], 0, v[0:1]
	v_add_u32_e32 v0, 0x60c0, v21
	v_add_u32_e32 v70, 0x60c8, v21
	ds_read2_b32 v[68:69], v0 offset1:1
	ds_read2_b32 v[70:71], v70 offset1:1
	global_store_dwordx2 v[66:67], v[64:65], off
	v_add_u32_e32 v0, 0x70e0, v21
	v_add_u32_e32 v66, 0x70e8, v21
	ds_read2_b32 v[64:65], v0 offset1:1
	ds_read2_b32 v[66:67], v66 offset1:1
	v_or_b32_e32 v0, s44, v139
	v_lshlrev_b32_e32 v0, 11, v0
	v_accvgpr_read_b32 v74, a225
	s_waitcnt lgkmcnt(3)
	v_cvt_pk_bf16_f32 v68, v68, v69
	s_waitcnt lgkmcnt(2)
	v_cvt_pk_bf16_f32 v69, v70, v71
	v_lshl_add_u64 v[70:71], v[10:11], 0, v[0:1]
	v_or_b32_e32 v0, s44, v74
	v_lshlrev_b32_e32 v0, 11, v0
	global_store_dwordx2 v[70:71], v[68:69], off
	s_waitcnt lgkmcnt(1)
	v_cvt_pk_bf16_f32 v64, v64, v65
	s_waitcnt lgkmcnt(0)
	v_cvt_pk_bf16_f32 v65, v66, v67
	v_lshl_add_u64 v[66:67], v[10:11], 0, v[0:1]
	v_add_u32_e32 v0, 0x8100, v21
	v_add_u32_e32 v70, 0x8108, v21
	ds_read2_b32 v[68:69], v0 offset1:1
	ds_read2_b32 v[70:71], v70 offset1:1
	global_store_dwordx2 v[66:67], v[64:65], off
	v_add_u32_e32 v0, 0x9120, v21
	v_add_u32_e32 v66, 0x9128, v21
	ds_read2_b32 v[64:65], v0 offset1:1
	ds_read2_b32 v[66:67], v66 offset1:1
	v_accvgpr_read_b32 v75, a226
	v_or_b32_e32 v0, s44, v75
	v_lshlrev_b32_e32 v0, 11, v0
	s_waitcnt lgkmcnt(3)
	v_cvt_pk_bf16_f32 v68, v68, v69
	s_waitcnt lgkmcnt(2)
	v_cvt_pk_bf16_f32 v69, v70, v71
	v_lshl_add_u64 v[70:71], v[10:11], 0, v[0:1]
	v_or_b32_e32 v0, s44, v22
	v_lshlrev_b32_e32 v0, 11, v0
	global_store_dwordx2 v[70:71], v[68:69], off
	s_waitcnt lgkmcnt(1)
	v_cvt_pk_bf16_f32 v64, v64, v65
	s_waitcnt lgkmcnt(0)
	v_cvt_pk_bf16_f32 v65, v66, v67
	v_lshl_add_u64 v[66:67], v[10:11], 0, v[0:1]
	v_add_u32_e32 v0, 0xa140, v21
	v_add_u32_e32 v70, 0xa148, v21
	ds_read2_b32 v[68:69], v0 offset1:1
	ds_read2_b32 v[70:71], v70 offset1:1
	global_store_dwordx2 v[66:67], v[64:65], off
	v_add_u32_e32 v0, 0xb160, v21
	v_add_u32_e32 v66, 0xb168, v21
	ds_read2_b32 v[64:65], v0 offset1:1
	ds_read2_b32 v[66:67], v66 offset1:1
	v_or_b32_e32 v0, s44, v23
	v_lshlrev_b32_e32 v0, 11, v0
	s_waitcnt lgkmcnt(3)
	v_cvt_pk_bf16_f32 v68, v68, v69
	s_waitcnt lgkmcnt(2)
	v_cvt_pk_bf16_f32 v69, v70, v71
	v_lshl_add_u64 v[70:71], v[10:11], 0, v[0:1]
	v_or_b32_e32 v0, s44, v24
	v_lshlrev_b32_e32 v0, 11, v0
	global_store_dwordx2 v[70:71], v[68:69], off
	s_waitcnt lgkmcnt(1)
	v_cvt_pk_bf16_f32 v64, v64, v65
	s_waitcnt lgkmcnt(0)
	v_cvt_pk_bf16_f32 v65, v66, v67
	v_lshl_add_u64 v[66:67], v[10:11], 0, v[0:1]
	v_add_u32_e32 v0, 0xc180, v21
	v_add_u32_e32 v70, 0xc188, v21
	ds_read2_b32 v[68:69], v0 offset1:1
	ds_read2_b32 v[70:71], v70 offset1:1
	global_store_dwordx2 v[66:67], v[64:65], off
	v_add_u32_e32 v0, 0xd1a0, v21
	v_add_u32_e32 v66, 0xd1a8, v21
	ds_read2_b32 v[64:65], v0 offset1:1
	ds_read2_b32 v[66:67], v66 offset1:1
	v_or_b32_e32 v0, s44, v25
	v_lshlrev_b32_e32 v0, 11, v0
	s_waitcnt lgkmcnt(3)
	v_cvt_pk_bf16_f32 v68, v68, v69
	s_waitcnt lgkmcnt(2)
	v_cvt_pk_bf16_f32 v69, v70, v71
	v_lshl_add_u64 v[70:71], v[10:11], 0, v[0:1]
	v_or_b32_e32 v0, s44, v26
	v_lshlrev_b32_e32 v0, 11, v0
	global_store_dwordx2 v[70:71], v[68:69], off
	s_waitcnt lgkmcnt(1)
	v_cvt_pk_bf16_f32 v64, v64, v65
	s_waitcnt lgkmcnt(0)
	v_cvt_pk_bf16_f32 v65, v66, v67
	v_lshl_add_u64 v[66:67], v[10:11], 0, v[0:1]
	v_add_u32_e32 v0, 0xe1c0, v21
	v_add_u32_e32 v70, 0xe1c8, v21
	ds_read2_b32 v[68:69], v0 offset1:1
	ds_read2_b32 v[70:71], v70 offset1:1
	global_store_dwordx2 v[66:67], v[64:65], off
	v_add_u32_e32 v0, 0xf1e0, v21
	v_add_u32_e32 v66, 0xf1e8, v21
	ds_read2_b32 v[64:65], v0 offset1:1
	ds_read2_b32 v[66:67], v66 offset1:1
	v_or_b32_e32 v0, s44, v27
	v_lshlrev_b32_e32 v0, 11, v0
	s_waitcnt lgkmcnt(3)
	v_cvt_pk_bf16_f32 v68, v68, v69
	s_waitcnt lgkmcnt(2)
	v_cvt_pk_bf16_f32 v69, v70, v71
	v_lshl_add_u64 v[70:71], v[10:11], 0, v[0:1]
	v_or_b32_e32 v0, s44, v28
	v_lshlrev_b32_e32 v0, 11, v0
	s_bitset1_b32 s44, 7
	s_waitcnt lgkmcnt(1)
	v_cvt_pk_bf16_f32 v64, v64, v65
	s_waitcnt lgkmcnt(0)
	v_cvt_pk_bf16_f32 v65, v66, v67
	v_lshl_add_u64 v[66:67], v[10:11], 0, v[0:1]
	v_or_b32_e32 v0, s44, v72
	global_store_dwordx2 v[70:71], v[68:69], off
	global_store_dwordx2 v[66:67], v[64:65], off
	v_lshlrev_b32_e32 v0, 11, v0
	v_cvt_pk_bf16_f32 v12, v12, v13
	v_cvt_pk_bf16_f32 v13, v14, v15
	v_lshl_add_u64 v[14:15], v[10:11], 0, v[0:1]
	ds_read2_b32 v[64:65], v30 offset1:1
	ds_read2_b32 v[66:67], v30 offset0:2 offset1:3
	global_store_dwordx2 v[14:15], v[12:13], off
	ds_read2_b32 v[12:13], v31 offset1:1
	ds_read2_b32 v[14:15], v31 offset0:2 offset1:3
	v_or_b32_e32 v0, s44, v73
	v_lshlrev_b32_e32 v0, 11, v0
	s_waitcnt lgkmcnt(3)
	v_cvt_pk_bf16_f32 v64, v64, v65
	s_waitcnt lgkmcnt(2)
	v_cvt_pk_bf16_f32 v65, v66, v67
	v_lshl_add_u64 v[66:67], v[10:11], 0, v[0:1]
	v_or_b32_e32 v0, s44, v132
	global_store_dwordx2 v[66:67], v[64:65], off
	v_lshlrev_b32_e32 v0, 11, v0
	s_waitcnt lgkmcnt(1)
	v_cvt_pk_bf16_f32 v12, v12, v13
	s_waitcnt lgkmcnt(0)
	v_cvt_pk_bf16_f32 v13, v14, v15
	v_lshl_add_u64 v[14:15], v[10:11], 0, v[0:1]
	ds_read2_b32 v[64:65], v32 offset1:1
	ds_read2_b32 v[66:67], v32 offset0:2 offset1:3
	global_store_dwordx2 v[14:15], v[12:13], off
	ds_read2_b32 v[12:13], v33 offset1:1
	ds_read2_b32 v[14:15], v33 offset0:2 offset1:3
	v_or_b32_e32 v0, s44, v133
	v_lshlrev_b32_e32 v0, 11, v0
	s_waitcnt lgkmcnt(3)
	v_cvt_pk_bf16_f32 v64, v64, v65
	s_waitcnt lgkmcnt(2)
	v_cvt_pk_bf16_f32 v65, v66, v67
	v_lshl_add_u64 v[66:67], v[10:11], 0, v[0:1]
	v_or_b32_e32 v0, s44, v136
	global_store_dwordx2 v[66:67], v[64:65], off
	v_lshlrev_b32_e32 v0, 11, v0
	s_waitcnt lgkmcnt(1)
	v_cvt_pk_bf16_f32 v12, v12, v13
	s_waitcnt lgkmcnt(0)
	v_cvt_pk_bf16_f32 v13, v14, v15
	v_lshl_add_u64 v[14:15], v[10:11], 0, v[0:1]
	ds_read2_b32 v[64:65], v34 offset1:1
	ds_read2_b32 v[66:67], v34 offset0:2 offset1:3
	global_store_dwordx2 v[14:15], v[12:13], off
	ds_read2_b32 v[12:13], v35 offset1:1
	ds_read2_b32 v[14:15], v35 offset0:2 offset1:3
	v_or_b32_e32 v0, s44, v137
	v_lshlrev_b32_e32 v0, 11, v0
	s_waitcnt lgkmcnt(3)
	v_cvt_pk_bf16_f32 v64, v64, v65
	s_waitcnt lgkmcnt(2)
	v_cvt_pk_bf16_f32 v65, v66, v67
	v_lshl_add_u64 v[66:67], v[10:11], 0, v[0:1]
	v_or_b32_e32 v0, s44, v139
	global_store_dwordx2 v[66:67], v[64:65], off
	v_lshlrev_b32_e32 v0, 11, v0
	s_waitcnt lgkmcnt(1)
	v_cvt_pk_bf16_f32 v12, v12, v13
	s_waitcnt lgkmcnt(0)
	v_cvt_pk_bf16_f32 v13, v14, v15
	v_lshl_add_u64 v[14:15], v[10:11], 0, v[0:1]
	ds_read2_b32 v[64:65], v36 offset1:1
	ds_read2_b32 v[66:67], v36 offset0:2 offset1:3
	global_store_dwordx2 v[14:15], v[12:13], off
	ds_read2_b32 v[12:13], v37 offset1:1
	ds_read2_b32 v[14:15], v37 offset0:2 offset1:3
	v_or_b32_e32 v0, s44, v74
	v_lshlrev_b32_e32 v0, 11, v0
	s_waitcnt lgkmcnt(3)
	v_cvt_pk_bf16_f32 v64, v64, v65
	s_waitcnt lgkmcnt(2)
	v_cvt_pk_bf16_f32 v65, v66, v67
	v_lshl_add_u64 v[66:67], v[10:11], 0, v[0:1]
	v_or_b32_e32 v0, s44, v75
	global_store_dwordx2 v[66:67], v[64:65], off
	v_lshlrev_b32_e32 v0, 11, v0
	s_waitcnt lgkmcnt(1)
	v_cvt_pk_bf16_f32 v12, v12, v13
	s_waitcnt lgkmcnt(0)
	v_cvt_pk_bf16_f32 v13, v14, v15
	v_lshl_add_u64 v[14:15], v[10:11], 0, v[0:1]
	ds_read2_b32 v[64:65], v38 offset1:1
	ds_read2_b32 v[66:67], v38 offset0:2 offset1:3
	global_store_dwordx2 v[14:15], v[12:13], off
	ds_read2_b32 v[12:13], v39 offset1:1
	ds_read2_b32 v[14:15], v39 offset0:2 offset1:3
	v_or_b32_e32 v0, s44, v22
	v_lshlrev_b32_e32 v0, 11, v0
	s_waitcnt lgkmcnt(3)
	v_cvt_pk_bf16_f32 v64, v64, v65
	s_waitcnt lgkmcnt(2)
	v_cvt_pk_bf16_f32 v65, v66, v67
	v_lshl_add_u64 v[66:67], v[10:11], 0, v[0:1]
	v_or_b32_e32 v0, s44, v23
	global_store_dwordx2 v[66:67], v[64:65], off
	v_lshlrev_b32_e32 v0, 11, v0
	s_waitcnt lgkmcnt(1)
	v_cvt_pk_bf16_f32 v12, v12, v13
	s_waitcnt lgkmcnt(0)
	v_cvt_pk_bf16_f32 v13, v14, v15
	v_lshl_add_u64 v[14:15], v[10:11], 0, v[0:1]
	ds_read2_b32 v[64:65], v40 offset1:1
	ds_read2_b32 v[66:67], v40 offset0:2 offset1:3
	global_store_dwordx2 v[14:15], v[12:13], off
	ds_read2_b32 v[12:13], v41 offset1:1
	ds_read2_b32 v[14:15], v41 offset0:2 offset1:3
	v_or_b32_e32 v0, s44, v24
	v_lshlrev_b32_e32 v0, 11, v0
	s_waitcnt lgkmcnt(3)
	v_cvt_pk_bf16_f32 v64, v64, v65
	s_waitcnt lgkmcnt(2)
	v_cvt_pk_bf16_f32 v65, v66, v67
	v_lshl_add_u64 v[66:67], v[10:11], 0, v[0:1]
	v_or_b32_e32 v0, s44, v25
	v_lshlrev_b32_e32 v0, 11, v0
	global_store_dwordx2 v[66:67], v[64:65], off
	s_waitcnt lgkmcnt(1)
	v_cvt_pk_bf16_f32 v12, v12, v13
	s_waitcnt lgkmcnt(0)
	v_cvt_pk_bf16_f32 v13, v14, v15
	v_lshl_add_u64 v[14:15], v[10:11], 0, v[0:1]
	ds_read2_b32 v[64:65], v42 offset1:1
	ds_read2_b32 v[66:67], v42 offset0:2 offset1:3
	global_store_dwordx2 v[14:15], v[12:13], off
	ds_read2_b32 v[12:13], v43 offset1:1
	ds_read2_b32 v[14:15], v43 offset0:2 offset1:3
	v_add_lshl_u32 v0, s44, v26, 11
	s_waitcnt lgkmcnt(3)
	v_cvt_pk_bf16_f32 v64, v64, v65
	s_waitcnt lgkmcnt(2)
	v_cvt_pk_bf16_f32 v65, v66, v67
	v_lshl_add_u64 v[66:67], v[10:11], 0, v[0:1]
	v_add_lshl_u32 v0, s44, v27, 11
	s_waitcnt lgkmcnt(1)
	v_cvt_pk_bf16_f32 v12, v12, v13
	s_waitcnt lgkmcnt(0)
	v_cvt_pk_bf16_f32 v13, v14, v15
	v_lshl_add_u64 v[14:15], v[10:11], 0, v[0:1]
	v_add_lshl_u32 v0, s44, v28, 11
	global_store_dwordx2 v[14:15], v[12:13], off
	v_cvt_pk_bf16_f32 v12, v16, v17
	v_cvt_pk_bf16_f32 v13, v18, v19
	v_lshl_add_u64 v[10:11], v[10:11], 0, v[0:1]
	s_cmpk_lt_u32 s47, 0x60
	global_store_dwordx2 v[66:67], v[64:65], off
	global_store_dwordx2 v[10:11], v[12:13], off
	s_barrier
	s_cbranch_scc1 .LBB0_1264

.LBB0_1462:
	s_and_b32 s5, s4, 1
	s_mul_i32 s8, s5, 0xd800
	s_xor_b32 s5, s5, 1
	s_mul_i32 s5, s5, 0xd800
	s_add_i32 s4, s4, 1
	v_add_u32_e32 v186, s5, v152
	ds_read_b128 v[16:19], v189 offset:32
	ds_read_b128 v[28:31], v187 offset:36896
	ds_read_b128 v[20:23], v189 offset:4640
	ds_read_b128 v[32:35], v187 offset:41504
	ds_read_b128 v[24:27], v189 offset:9248
	ds_read_b128 v[0:3], v188 offset:32
	s_waitcnt lgkmcnt(6)
	v_mfma_f32_32x32x16_bf16 a[32:47], v[52:55], v[8:11], a[32:47]
	s_waitcnt vmcnt(11)
	ds_write_b128 v186, v[250:253]
	v_mfma_f32_32x32x16_bf16 a[48:63], v[52:55], v[12:15], a[48:63]
	s_waitcnt vmcnt(10)
	ds_write_b128 v186, v[246:249] offset:4608
	global_load_dwordx4 v[250:253], v254, s[100:101] offset:512
	v_mfma_f32_32x32x16_bf16 a[64:79], v[56:59], v[8:11], a[64:79]
	s_waitcnt vmcnt(10)
	ds_write_b128 v186, v[242:245] offset:9216
	global_load_dwordx4 v[246:249], v205, s[100:101] offset:512
	v_mfma_f32_32x32x16_bf16 a[96:111], v[56:59], v[12:15], a[96:111]
	s_waitcnt vmcnt(10)
	ds_write_b128 v186, v[238:241] offset:13824
	global_load_dwordx4 v[242:245], v204, s[100:101] offset:512
	v_mfma_f32_32x32x16_bf16 a[80:95], v[60:63], v[8:11], a[80:95]
	s_waitcnt vmcnt(10)
	ds_write_b128 v186, v[234:237] offset:18432
	global_load_dwordx4 v[238:241], v203, s[100:101] offset:512
	v_mfma_f32_32x32x16_bf16 a[112:127], v[60:63], v[12:15], a[112:127]
	s_waitcnt vmcnt(10)
	ds_write_b128 v186, v[230:233] offset:23040
	global_load_dwordx4 v[234:237], v202, s[100:101] offset:512
	s_waitcnt lgkmcnt(6)
	v_mfma_f32_32x32x16_bf16 a[16:31], v[64:67], v[8:11], a[16:31]
	s_waitcnt vmcnt(10)
	ds_write_b128 v186, v[226:229] offset:27648
	global_load_dwordx4 v[230:233], v201, s[100:101] offset:512
	v_mfma_f32_32x32x16_bf16 a[0:15], v[64:67], v[12:15], a[0:15]
	s_waitcnt vmcnt(10)
	ds_write_b128 v186, v[222:225] offset:32256
	global_load_dwordx4 v[226:229], v200, s[100:101] offset:512
	s_waitcnt lgkmcnt(8)
	ds_read_b128 v[52:55], v189 offset:64
	ds_read_b128 v[8:11], v187 offset:36928
	ds_read_b128 v[56:59], v189 offset:4672
	ds_read_b128 v[12:15], v187 offset:41536
	ds_read_b128 v[60:63], v189 offset:9280
	ds_read_b128 v[64:67], v188 offset:64
	v_mfma_f32_32x32x16_bf16 a[32:47], v[16:19], v[28:31], a[32:47]
	s_waitcnt lgkmcnt(12)
	s_waitcnt vmcnt(10)
	ds_write_b128 v186, v[218:221] offset:36864
	global_load_dwordx4 v[222:225], v199, s[100:101] offset:512
	v_mfma_f32_32x32x16_bf16 a[48:63], v[16:19], v[32:35], a[48:63]
	s_waitcnt lgkmcnt(12)
	s_waitcnt vmcnt(10)
	ds_write_b128 v186, v[214:217] offset:41472
	global_load_dwordx4 v[218:221], v198, s[98:99] offset:256
	v_mfma_f32_32x32x16_bf16 a[64:79], v[20:23], v[28:31], a[64:79]
	s_waitcnt lgkmcnt(12)
	s_waitcnt vmcnt(10)
	ds_write_b128 v186, v[210:213] offset:46080
	global_load_dwordx4 v[214:217], v197, s[98:99] offset:256
	v_mfma_f32_32x32x16_bf16 a[96:111], v[20:23], v[32:35], a[96:111]
	s_waitcnt lgkmcnt(12)
	s_waitcnt vmcnt(10)
	ds_write_b128 v186, v[206:209] offset:50688
	global_load_dwordx4 v[210:213], v196, s[98:99] offset:256
	v_mfma_f32_32x32x16_bf16 a[80:95], v[24:27], v[28:31], a[80:95]
	global_load_dwordx4 v[206:209], v195, s[98:99] offset:256
	s_add_u32 s100, s100, 0x80
	s_addc_u32 s101, s101, 0
	s_add_u32 s98, s98, 0x80
	s_addc_u32 s99, s99, 0
	v_mfma_f32_32x32x16_bf16 a[112:127], v[24:27], v[32:35], a[112:127]
	v_mfma_f32_32x32x16_bf16 a[16:31], v[0:3], v[28:31], a[16:31]
	v_mfma_f32_32x32x16_bf16 a[0:15], v[0:3], v[32:35], a[0:15]
	s_waitcnt lgkmcnt(4)
	ds_read_b128 v[16:19], v189 offset:96
	ds_read_b128 v[28:31], v187 offset:36960
	ds_read_b128 v[20:23], v189 offset:4704
	ds_read_b128 v[32:35], v187 offset:41568
	ds_read_b128 v[24:27], v189 offset:9312
	ds_read_b128 v[0:3], v188 offset:96
	v_mfma_f32_32x32x16_bf16 a[32:47], v[52:55], v[8:11], a[32:47]
	v_mfma_f32_32x32x16_bf16 a[48:63], v[52:55], v[12:15], a[48:63]
	v_mfma_f32_32x32x16_bf16 a[64:79], v[56:59], v[8:11], a[64:79]
	v_mfma_f32_32x32x16_bf16 a[96:111], v[56:59], v[12:15], a[96:111]
	v_mfma_f32_32x32x16_bf16 a[80:95], v[60:63], v[8:11], a[80:95]
	v_mfma_f32_32x32x16_bf16 a[112:127], v[60:63], v[12:15], a[112:127]
	v_mfma_f32_32x32x16_bf16 a[16:31], v[64:67], v[8:11], a[16:31]
	v_mfma_f32_32x32x16_bf16 a[0:15], v[64:67], v[12:15], a[0:15]
	s_waitcnt lgkmcnt(0)
	v_mfma_f32_32x32x16_bf16 a[32:47], v[16:19], v[28:31], a[32:47]
	v_mfma_f32_32x32x16_bf16 a[48:63], v[16:19], v[32:35], a[48:63]
	v_mfma_f32_32x32x16_bf16 a[64:79], v[20:23], v[28:31], a[64:79]
	v_mfma_f32_32x32x16_bf16 a[96:111], v[20:23], v[32:35], a[96:111]
	s_barrier
	v_add_u32_e32 v189, s5, v192
	v_add_u32_e32 v188, s5, v191
	v_add_u32_e32 v187, s5, v190
	ds_read_b128 v[52:55], v189
	ds_read_b128 v[8:11], v187 offset:36864
	ds_read_b128 v[56:59], v189 offset:4608
	ds_read_b128 v[12:15], v187 offset:41472
	ds_read_b128 v[60:63], v189 offset:9216
	ds_read_b128 v[64:67], v188
	v_mfma_f32_32x32x16_bf16 a[80:95], v[24:27], v[28:31], a[80:95]
	v_mfma_f32_32x32x16_bf16 a[112:127], v[24:27], v[32:35], a[112:127]
	v_mfma_f32_32x32x16_bf16 a[16:31], v[0:3], v[28:31], a[16:31]
	v_mfma_f32_32x32x16_bf16 a[0:15], v[0:3], v[32:35], a[0:15]
	s_add_u32 s2, s2, 0x80
	s_addc_u32 s3, s3, 0
	s_cmpk_lg_i32 s2, 0x700
	s_cbranch_scc1 .LBB0_1462
	ds_read_b128 v[4:7], v165
	ds_read_b128 v[52:55], v165 offset:4608
	ds_read_b128 v[56:59], v165 offset:9216
	ds_read_b128 v[60:63], v166
	ds_read_b128 v[64:67], v167 offset:36864
	ds_read_b128 v[68:71], v167 offset:41472
	s_waitcnt vmcnt(11)
	s_waitcnt vmcnt(0)
	ds_write_b128 v168, v[250:253] offset:55296
	s_waitcnt vmcnt(10)
	ds_write_b128 v168, v[246:249] offset:59904
	s_waitcnt vmcnt(9)
	ds_write_b128 v168, v[242:245] offset:64512
	s_waitcnt vmcnt(8)
	ds_write_b128 v129, v[238:241] offset:55296
	s_waitcnt vmcnt(7)
	ds_write_b128 v135, v[234:237] offset:55296
	s_waitcnt vmcnt(6)
	ds_write_b128 v139, v[230:233] offset:55296
	s_waitcnt vmcnt(5)
	ds_write_b128 v157, v[226:229] offset:55296
	s_waitcnt vmcnt(4)
	ds_write_b128 v158, v[222:225] offset:55296
	s_waitcnt vmcnt(3)
	ds_write_b128 v159, v[218:221]
	s_waitcnt vmcnt(2)
	ds_write_b128 v159, v[214:217] offset:4608
	s_waitcnt vmcnt(1)
	ds_write_b128 v159, v[210:213] offset:9216
	s_waitcnt vmcnt(0)
	ds_write_b128 v159, v[206:209] offset:13824
	s_lshl_b32 s22, s61, 8
	s_cmp_gt_u32 s61, 31
	s_waitcnt lgkmcnt(13)
	v_mfma_f32_32x32x16_bf16 a[144:159], v[52:55], v[64:67], a[64:79]
	s_cselect_b64 s[2:3], -1, 0
	s_add_i32 s4, s22, 0xffffe000
	s_lshr_b32 s14, s4, 12
	s_cmp_lt_u32 s61, 32
	s_cselect_b64 s[4:5], -1, 0
	s_and_b64 s[8:9], s[4:5], exec
	s_cselect_b32 s8, 32, 0xf00
	s_waitcnt lgkmcnt(12)
	v_mfma_f32_32x32x16_bf16 a[160:175], v[4:7], v[68:71], a[48:63]
	s_cselect_b32 s24, s61, s14
	s_and_b32 s23, s8, s22
	s_cmp_lg_u32 s60, 5
	s_cselect_b64 s[72:73], -1, 0
	s_mov_b64 s[8:9], -1
	s_and_b64 vcc, exec, s[72:73]
	v_mfma_f32_32x32x16_bf16 a[128:143], v[52:55], v[68:71], a[96:111]
	v_mfma_f32_32x32x16_bf16 a[64:79], v[56:59], v[64:67], a[80:95]
	v_mfma_f32_32x32x16_bf16 a[48:63], v[56:59], v[68:71], a[112:127]
	v_mfma_f32_32x32x16_bf16 a[176:191], v[4:7], v[64:67], a[32:47]
	ds_read_b128 v[0:3], v165 offset:4640
	ds_read_b128 v[4:7], v165 offset:9248
	ds_read_b128 v[8:11], v167 offset:41504
	ds_read_b128 v[12:15], v167 offset:36896
	ds_read_b128 v[16:19], v167 offset:36928
	ds_read_b128 v[20:23], v165 offset:32
	ds_read_b128 v[24:27], v165 offset:64
	v_mfma_f32_32x32x16_bf16 a[32:47], v[60:63], v[64:67], a[16:31]
	v_mfma_f32_32x32x16_bf16 a[16:31], v[60:63], v[68:71], a[0:15]
	s_waitcnt lgkmcnt(3)
	v_mfma_f32_32x32x16_bf16 a[144:159], v[0:3], v[12:15], a[144:159]
	v_mfma_f32_32x32x16_bf16 a[128:143], v[0:3], v[8:11], a[128:143]
	v_mfma_f32_32x32x16_bf16 a[64:79], v[4:7], v[12:15], a[64:79]
	v_mfma_f32_32x32x16_bf16 a[48:63], v[4:7], v[8:11], a[48:63]
	ds_read_b128 v[0:3], v166 offset:32
	ds_read_b128 v[4:7], v166 offset:64
	s_waitcnt lgkmcnt(3)
	v_mfma_f32_32x32x16_bf16 a[176:191], v[20:23], v[12:15], a[176:191]
	v_mfma_f32_32x32x16_bf16 a[160:175], v[20:23], v[8:11], a[160:175]
	s_waitcnt lgkmcnt(1)
	v_mfma_f32_32x32x16_bf16 a[32:47], v[0:3], v[12:15], a[32:47]
	v_mfma_f32_32x32x16_bf16 a[16:31], v[0:3], v[8:11], a[16:31]
	ds_read_b128 v[0:3], v167 offset:41536
	ds_read_b128 v[8:11], v165 offset:9280
	ds_read_b128 v[12:15], v165 offset:4672
	v_mfma_f32_32x32x16_bf16 a[176:191], v[24:27], v[16:19], a[176:191]
	s_waitcnt lgkmcnt(0)
	v_mfma_f32_32x32x16_bf16 a[144:159], v[12:15], v[16:19], a[144:159]
	v_mfma_f32_32x32x16_bf16 a[128:143], v[12:15], v[0:3], a[128:143]
	v_mfma_f32_32x32x16_bf16 a[64:79], v[8:11], v[16:19], a[64:79]
	v_mfma_f32_32x32x16_bf16 a[48:63], v[8:11], v[0:3], a[48:63]
	v_mfma_f32_32x32x16_bf16 a[160:175], v[24:27], v[0:3], a[160:175]
	v_mfma_f32_32x32x16_bf16 a[32:47], v[4:7], v[16:19], a[32:47]
	v_mfma_f32_32x32x16_bf16 a[16:31], v[4:7], v[0:3], a[16:31]
	ds_read_b128 v[0:3], v167 offset:41568
	ds_read_b128 v[4:7], v167 offset:36960
	ds_read_b128 v[8:11], v166 offset:96
	ds_read_b128 v[12:15], v165 offset:9312
	ds_read_b128 v[16:19], v165 offset:4704
	ds_read_b128 v[20:23], v165 offset:96
	s_waitcnt lgkmcnt(0)
	s_barrier
	v_mfma_f32_32x32x16_bf16 a[176:191], v[20:23], v[4:7], a[176:191]
	v_mfma_f32_32x32x16_bf16 a[144:159], v[16:19], v[4:7], a[144:159]
	v_mfma_f32_32x32x16_bf16 a[128:143], v[16:19], v[0:3], a[128:143]
	v_mfma_f32_32x32x16_bf16 a[64:79], v[12:15], v[4:7], a[64:79]
	v_mfma_f32_32x32x16_bf16 a[48:63], v[12:15], v[0:3], a[48:63]
	v_mfma_f32_32x32x16_bf16 a[160:175], v[20:23], v[0:3], a[160:175]
	v_mfma_f32_32x32x16_bf16 a[32:47], v[8:11], v[4:7], a[32:47]
	v_mfma_f32_32x32x16_bf16 a[16:31], v[8:11], v[0:3], a[16:31]
	ds_read_b128 v[0:3], v165 offset:59904
	ds_read_b128 v[4:7], v165 offset:64512
	ds_read_b128 v[8:11], v160 offset:4608
	ds_read_b128 v[12:15], v165 offset:55296
	ds_read_b128 v[16:19], v165 offset:55328
	ds_read_b128 v[20:23], v160
	ds_read_b128 v[24:27], v160 offset:32
	s_waitcnt lgkmcnt(1)
	v_mfma_f32_32x32x16_bf16 a[176:191], v[12:15], v[20:23], a[176:191]
	v_mfma_f32_32x32x16_bf16 a[144:159], v[0:3], v[20:23], a[144:159]
	v_mfma_f32_32x32x16_bf16 a[128:143], v[0:3], v[8:11], a[128:143]
	v_mfma_f32_32x32x16_bf16 a[64:79], v[4:7], v[20:23], a[64:79]
	v_mfma_f32_32x32x16_bf16 a[48:63], v[4:7], v[8:11], a[48:63]
	ds_read_b128 v[0:3], v166 offset:55296
	ds_read_b128 v[4:7], v166 offset:55328
	v_mfma_f32_32x32x16_bf16 a[160:175], v[12:15], v[8:11], a[160:175]
	s_waitcnt lgkmcnt(1)
	v_mfma_f32_32x32x16_bf16 a[32:47], v[0:3], v[20:23], a[32:47]
	v_mfma_f32_32x32x16_bf16 a[16:31], v[0:3], v[8:11], a[16:31]
	ds_read_b128 v[0:3], v165 offset:64544
	ds_read_b128 v[8:11], v165 offset:59936
	ds_read_b128 v[12:15], v160 offset:4640
	v_mfma_f32_32x32x16_bf16 a[176:191], v[16:19], v[24:27], a[176:191]
	s_waitcnt lgkmcnt(0)
	v_mfma_f32_32x32x16_bf16 a[160:175], v[16:19], v[12:15], a[160:175]
	v_mfma_f32_32x32x16_bf16 a[144:159], v[8:11], v[24:27], a[144:159]
	v_mfma_f32_32x32x16_bf16 a[128:143], v[8:11], v[12:15], a[128:143]
	v_mfma_f32_32x32x16_bf16 a[64:79], v[0:3], v[24:27], a[64:79]
	v_mfma_f32_32x32x16_bf16 a[48:63], v[0:3], v[12:15], a[48:63]
	v_mfma_f32_32x32x16_bf16 a[32:47], v[4:7], v[24:27], a[32:47]
	v_mfma_f32_32x32x16_bf16 a[16:31], v[4:7], v[12:15], a[16:31]
	ds_read_b128 v[0:3], v166 offset:55360
	ds_read_b128 v[4:7], v165 offset:64576
	ds_read_b128 v[8:11], v165 offset:59968
	ds_read_b128 v[12:15], v165 offset:55360
	ds_read_b128 v[16:19], v160 offset:64
	ds_read_b128 v[20:23], v160 offset:4672
	s_waitcnt lgkmcnt(1)
	v_mfma_f32_32x32x16_bf16 a[176:191], v[12:15], v[16:19], a[176:191]
	s_waitcnt lgkmcnt(0)
	v_mfma_f32_32x32x16_bf16 a[160:175], v[12:15], v[20:23], a[160:175]
	v_mfma_f32_32x32x16_bf16 a[144:159], v[8:11], v[16:19], a[144:159]
	v_mfma_f32_32x32x16_bf16 a[128:143], v[8:11], v[20:23], a[128:143]
	v_mfma_f32_32x32x16_bf16 a[64:79], v[4:7], v[16:19], a[64:79]
	v_mfma_f32_32x32x16_bf16 a[48:63], v[4:7], v[20:23], a[48:63]
	v_mfma_f32_32x32x16_bf16 a[32:47], v[0:3], v[16:19], a[32:47]
	v_mfma_f32_32x32x16_bf16 a[16:31], v[0:3], v[20:23], a[16:31]
	ds_read_b128 v[0:3], v166 offset:55392
	ds_read_b128 v[4:7], v165 offset:64608
	ds_read_b128 v[8:11], v165 offset:60000
	ds_read_b128 v[12:15], v165 offset:55392
	ds_read_b128 v[16:19], v160 offset:96
	ds_read_b128 v[20:23], v160 offset:4704
	s_waitcnt lgkmcnt(0)
	s_barrier
	v_mfma_f32_32x32x16_bf16 a[176:191], v[12:15], v[16:19], a[176:191]
	v_mfma_f32_32x32x16_bf16 a[32:47], v[0:3], v[16:19], a[32:47]
	v_mfma_f32_32x32x16_bf16 a[16:31], v[0:3], v[20:23], a[16:31]
	v_accvgpr_read_b32 v0, a212
	v_lshlrev_b32_e32 v0, 5, v0
	v_lshlrev_b32_e32 v104, 1, v0
	v_mfma_f32_32x32x16_bf16 a[160:175], v[12:15], v[20:23], a[160:175]
	v_mfma_f32_32x32x16_bf16 a[144:159], v[8:11], v[16:19], a[144:159]
	v_mfma_f32_32x32x16_bf16 a[128:143], v[8:11], v[20:23], a[128:143]
	v_mfma_f32_32x32x16_bf16 a[64:79], v[4:7], v[16:19], a[64:79]
	v_mfma_f32_32x32x16_bf16 a[48:63], v[4:7], v[20:23], a[48:63]
	s_nop 1
	ds_write_b32 v156, a176
	ds_write_b32 v156, a177 offset:516
	ds_write_b32 v156, a178 offset:1032
	ds_write_b32 v156, a179 offset:1548
	ds_write_b32 v156, a180 offset:4128
	ds_write_b32 v156, a181 offset:4644
	ds_write_b32 v156, a182 offset:5160
	ds_write_b32 v156, a183 offset:5676
	ds_write_b32 v156, a184 offset:8256
	ds_write_b32 v156, a185 offset:8772
	ds_write_b32 v156, a186 offset:9288
	ds_write_b32 v156, a187 offset:9804
	ds_write_b32 v156, a188 offset:12384
	ds_write_b32 v156, a189 offset:12900
	ds_write_b32 v156, a190 offset:13416
	ds_write_b32 v156, a191 offset:13932
	ds_write_b32 v156, a160 offset:128
	ds_write_b32 v156, a161 offset:644
	ds_write_b32 v156, a162 offset:1160
	ds_write_b32 v156, a163 offset:1676
	ds_write_b32 v156, a164 offset:4256
	ds_write_b32 v156, a165 offset:4772
	ds_write_b32 v156, a166 offset:5288
	ds_write_b32 v156, a167 offset:5804
	ds_write_b32 v156, a168 offset:8384
	ds_write_b32 v156, a169 offset:8900
	ds_write_b32 v156, a170 offset:9416
	ds_write_b32 v156, a171 offset:9932
	ds_write_b32 v156, a172 offset:12512
	ds_write_b32 v156, a173 offset:13028
	ds_write_b32 v156, a174 offset:13544
	ds_write_b32 v156, a175 offset:14060
	ds_write_b32 v156, a144 offset:16512
	ds_write_b32 v156, a145 offset:17028
	ds_write_b32 v156, a146 offset:17544
	ds_write_b32 v156, a147 offset:18060
	ds_write_b32 v156, a148 offset:20640
	ds_write_b32 v156, a149 offset:21156
	ds_write_b32 v156, a150 offset:21672
	ds_write_b32 v156, a151 offset:22188
	ds_write_b32 v156, a152 offset:24768
	ds_write_b32 v156, a153 offset:25284
	ds_write_b32 v156, a154 offset:25800
	ds_write_b32 v156, a155 offset:26316
	ds_write_b32 v156, a156 offset:28896
	ds_write_b32 v156, a157 offset:29412
	ds_write_b32 v156, a158 offset:29928
	ds_write_b32 v156, a159 offset:30444
	ds_write_b32 v156, a128 offset:16640
	ds_write_b32 v156, a129 offset:17156
	ds_write_b32 v156, a130 offset:17672
	ds_write_b32 v156, a131 offset:18188
	ds_write_b32 v156, a132 offset:20768
	ds_write_b32 v156, a133 offset:21284
	ds_write_b32 v156, a134 offset:21800
	ds_write_b32 v156, a135 offset:22316
	ds_write_b32 v156, a136 offset:24896
	ds_write_b32 v156, a137 offset:25412
	ds_write_b32 v156, a138 offset:25928
	ds_write_b32 v156, a139 offset:26444
	ds_write_b32 v156, a140 offset:29024
	ds_write_b32 v156, a141 offset:29540
	ds_write_b32 v156, a142 offset:30056
	ds_write_b32 v156, a143 offset:30572
	ds_write_b32 v156, a64 offset:33024
	ds_write_b32 v156, a65 offset:33540
	ds_write_b32 v156, a66 offset:34056
	ds_write_b32 v156, a67 offset:34572
	ds_write_b32 v156, a68 offset:37152
	ds_write_b32 v156, a69 offset:37668
	ds_write_b32 v156, a70 offset:38184
	ds_write_b32 v156, a71 offset:38700
	ds_write_b32 v156, a72 offset:41280
	ds_write_b32 v156, a73 offset:41796
	ds_write_b32 v156, a74 offset:42312
	ds_write_b32 v156, a75 offset:42828
	ds_write_b32 v156, a76 offset:45408
	ds_write_b32 v156, a77 offset:45924
	ds_write_b32 v156, a78 offset:46440
	ds_write_b32 v156, a79 offset:46956
	ds_write_b32 v156, a48 offset:33152
	ds_write_b32 v156, a49 offset:33668
	ds_write_b32 v156, a50 offset:34184
	ds_write_b32 v156, a51 offset:34700
	ds_write_b32 v156, a52 offset:37280
	ds_write_b32 v156, a53 offset:37796
	ds_write_b32 v156, a54 offset:38312
	ds_write_b32 v156, a55 offset:38828
	ds_write_b32 v156, a56 offset:41408
	ds_write_b32 v156, a57 offset:41924
	ds_write_b32 v156, a58 offset:42440
	ds_write_b32 v156, a59 offset:42956
	ds_write_b32 v156, a60 offset:45536
	ds_write_b32 v156, a61 offset:46052
	ds_write_b32 v156, a62 offset:46568
	ds_write_b32 v156, a63 offset:47084
	ds_write_b32 v156, a32 offset:49536
	ds_write_b32 v156, a33 offset:50052
	ds_write_b32 v156, a34 offset:50568
	ds_write_b32 v156, a35 offset:51084
	ds_write_b32 v156, a36 offset:53664
	ds_write_b32 v156, a37 offset:54180
	ds_write_b32 v156, a38 offset:54696
	ds_write_b32 v156, a39 offset:55212
	ds_write_b32 v156, a40 offset:57792
	ds_write_b32 v156, a41 offset:58308
	ds_write_b32 v156, a42 offset:58824
	ds_write_b32 v156, a43 offset:59340
	ds_write_b32 v156, a44 offset:61920
	ds_write_b32 v156, a45 offset:62436
	ds_write_b32 v156, a46 offset:62952
	ds_write_b32 v156, a47 offset:63468
	ds_write_b32 v156, a16 offset:49664
	ds_write_b32 v156, a17 offset:50180
	ds_write_b32 v156, a18 offset:50696
	ds_write_b32 v156, a19 offset:51212
	ds_write_b32 v156, a20 offset:53792
	ds_write_b32 v156, a21 offset:54308
	ds_write_b32 v156, a22 offset:54824
	ds_write_b32 v156, a23 offset:55340
	ds_write_b32 v156, a24 offset:57920
	ds_write_b32 v156, a25 offset:58436
	ds_write_b32 v156, a26 offset:58952
	ds_write_b32 v156, a27 offset:59468
	ds_write_b32 v156, a28 offset:62048
	ds_write_b32 v156, a29 offset:62564
	ds_write_b32 v156, a30 offset:63080
	ds_write_b32 v156, a31 offset:63596
	s_waitcnt lgkmcnt(0)
	s_barrier
	s_cbranch_vccz .LBB0_1502
	s_cmp_eq_u32 s60, 18
	s_cselect_b64 s[74:75], -1, 0
	s_cmp_gt_u32 s60, 3
	s_cselect_b64 s[78:79], -1, 0
	s_cmp_lg_u32 s60, 4
	v_accvgpr_read_b32 v0, a210
	s_cselect_b64 s[80:81], -1, 0
	s_cmp_gt_u32 s60, 7
	v_add_u32_e32 v4, s22, v0
	s_cselect_b64 s[82:83], -1, 0
	s_cmp_gt_u32 s60, 9
	s_cselect_b64 s[84:85], -1, 0
	s_cmp_gt_u32 s60, 13
	v_lshlrev_b32_e32 v80, 7, v4
	s_cselect_b64 s[86:87], -1, 0
	s_cmp_gt_u32 s60, 17
	v_lshl_add_u64 v[106:107], s[18:19], 0, v[80:81]
	v_lshlrev_b32_e32 v80, 10, v4
	v_add_u32_e32 v5, s23, v0
	s_cselect_b64 s[88:89], -1, 0
	v_lshl_add_u64 v[0:1], s[10:11], 0, v[80:81]
	s_lshl_b32 s14, s60, 8
	v_lshl_add_u64 v[2:3], v[0:1], 0, s[14:15]
	v_mov_b32_e32 v105, v81
	v_lshl_add_u64 v[2:3], v[2:3], 0, v[104:105]
	v_lshl_add_u64 v[108:109], v[2:3], 0, s[62:63]
	v_lshl_add_u64 v[110:111], v[2:3], 0, s[64:65]
	v_lshlrev_b32_e32 v2, 9, v4
	v_sub_co_u32_e32 v2, vcc, 0, v2
	s_lshl_b32 s25, s60, 7
	s_nop 0
	v_subb_co_u32_e64 v3, s[8:9], 0, 0, vcc
	v_lshl_add_u64 v[0:1], v[0:1], 0, v[2:3]
	v_lshl_add_u64 v[0:1], v[0:1], 0, s[14:15]
	v_lshl_add_u64 v[0:1], v[0:1], 0, v[104:105]
	v_lshl_add_u64 v[112:113], v[0:1], 0, s[66:67]
	v_lshl_add_u64 v[114:115], v[0:1], 0, s[68:69]
	v_lshrrev_b32_e32 v0, 6, v5
	v_accvgpr_read_b32 v1, a211
	v_cndmask_b32_e64 v0, v1, v0, s[6:7]
	v_lshlrev_b32_e32 v80, 7, v0
	v_lshlrev_b32_e32 v0, 7, v5
	v_mov_b32_e32 v1, v81
	v_lshl_add_u64 v[118:119], v[88:89], 0, v[0:1]
	s_lshl_b32 s14, s24, 9
	v_add_u32_e32 v0, 0x100, v5
	v_lshl_add_u64 v[0:1], v[0:1], 0, s[14:15]
	v_lshlrev_b64 v[0:1], 9, v[0:1]
	v_lshlrev_b32_e32 v2, 11, v4
	v_mov_b32_e32 v3, v81
	v_lshl_add_u64 v[116:117], s[16:17], 0, v[80:81]
	s_lshl_b32 s26, s24, 1
	v_mov_b32_e32 v80, v5
	v_lshl_add_u64 v[120:121], v[90:91], 0, v[2:3]
	v_lshl_add_u64 v[122:123], v[94:95], 0, v[0:1]
	s_mov_b32 s27, 0
	s_mov_b64 s[92:93], -1
	s_mov_b64 s[90:91], 0
	s_branch .LBB0_1467

.LBB0_1645:
	ds_read2_b32 v[58:59], v54 offset1:1
	ds_read2_b32 a[0:1], v54 offset0:2 offset1:3
	ds_read2_b32 a[2:3], v54 offset0:4 offset1:5
	ds_read2_b32 a[4:5], v54 offset0:6 offset1:7
	ds_read2_b32 a[6:7], v54 offset0:8 offset1:9
	ds_read2_b32 a[8:9], v54 offset0:10 offset1:11
	ds_read2_b32 a[10:11], v54 offset0:12 offset1:13
	ds_read2_b32 a[12:13], v54 offset0:14 offset1:15
	s_mov_b32 s64, 0xbfb8aa3b
	v_add_u32_e32 v56, -1, v56
	s_waitcnt vmcnt(15) lgkmcnt(7)
	v_fma_f32 v57, v48, v58, v47
	s_waitcnt vmcnt(14)
	v_fmac_f32_e32 v57, v49, v59
	s_waitcnt vmcnt(13) lgkmcnt(6)
	v_accvgpr_read_b32 v58, a0
	v_accvgpr_read_b32 v59, a1
	v_fmac_f32_e32 v57, v50, v58
	s_waitcnt vmcnt(12)
	v_fmac_f32_e32 v57, v51, v59
	s_waitcnt vmcnt(11) lgkmcnt(5)
	v_accvgpr_read_b32 v58, a2
	v_accvgpr_read_b32 v59, a3
	v_fmac_f32_e32 v57, v52, v58
	s_waitcnt vmcnt(10)
	v_fmac_f32_e32 v57, v53, v59
	s_waitcnt vmcnt(8) lgkmcnt(4)
	v_accvgpr_read_b32 v58, a4
	v_accvgpr_read_b32 v59, a5
	v_pk_mul_f32 v[58:59], v[36:37], v[58:59]
	s_nop 0
	v_add_f32_e32 v57, v57, v58
	v_add_f32_e32 v57, v57, v59
	s_waitcnt vmcnt(6) lgkmcnt(3)
	v_accvgpr_read_b32 v58, a6
	v_accvgpr_read_b32 v59, a7
	v_pk_mul_f32 v[58:59], v[38:39], v[58:59]
	s_nop 0
	v_add_f32_e32 v57, v57, v58
	v_add_f32_e32 v57, v57, v59
	s_waitcnt vmcnt(4) lgkmcnt(2)
	v_accvgpr_read_b32 v58, a8
	v_accvgpr_read_b32 v59, a9
	v_pk_mul_f32 v[58:59], v[40:41], v[58:59]
	s_nop 0
	v_add_f32_e32 v57, v57, v58
	v_add_f32_e32 v57, v57, v59
	s_waitcnt vmcnt(2) lgkmcnt(1)
	v_accvgpr_read_b32 v58, a10
	v_accvgpr_read_b32 v59, a11
	v_pk_mul_f32 v[58:59], v[42:43], v[58:59]
	s_nop 0
	v_add_f32_e32 v57, v57, v58
	v_add_f32_e32 v57, v57, v59
	v_add_u32_e32 v54, 0x84, v54
	s_waitcnt vmcnt(0) lgkmcnt(0)
	v_accvgpr_read_b32 v58, a12
	v_accvgpr_read_b32 v59, a13
	v_pk_mul_f32 v[58:59], v[44:45], v[58:59]
	s_nop 0
	v_add_f32_e32 v57, v57, v58
	v_add_f32_e32 v57, v57, v59
	v_min_f32_e32 v72, 0, v57
	v_mul_f32_e64 v57, |v57|, s64
	v_exp_f32_e32 v57, v57
	s_mov_b32 s64, 0x3f2aaaab
	s_mov_b32 s64, 0x3f317218
	s_mov_b32 s64, 0x7f800000
	s_mov_b32 s64, 0x33800000
	s_nop 0
	v_add_f32_e32 v60, 1.0, v57
	v_log_f32_e32 v58, v60
	v_add_f32_e32 v61, -1.0, v60
	v_cmp_eq_f32_e32 vcc, 1.0, v60
	v_rcp_f32_e32 v66, v61
	v_mul_f32_e32 v58, 0x3f317218, v58
	v_mul_f32_e32 v66, v57, v66
	s_nop 0
	v_mul_f32_e32 v58, v58, v66
	s_nop 0
	v_cndmask_b32_e32 v57, v58, v57, vcc
	v_sub_f32_e32 v57, v72, v57
	v_mul_f32_e32 v57, 0x3d800000, v57
	v_cmp_eq_u32_e32 vcc, 0, v56
	ds_write_b32 v55, v57
	v_add_u32_e32 v55, 0x104, v55
	s_or_b64 s[62:63], vcc, s[62:63]
	s_andn2_b64 exec, exec, s[62:63]
	s_cbranch_execnz .LBB0_1645
	s_or_b64 exec, exec, s[62:63]
	v_cndmask_b32_e64 v36, 0, 1, s[10:11]
	v_cmp_ne_u32_e64 s[10:11], 1, v36
	s_waitcnt lgkmcnt(0)
	s_barrier
	s_and_saveexec_b64 s[62:63], s[8:9]
	s_cbranch_execz .LBB0_1651
	s_mov_b64 s[64:65], -1
	s_and_b64 vcc, exec, s[10:11]
	v_add_u32_e32 v36, 0xa600, v140
	v_add_u32_e32 v37, 0xa400, v140
	v_add_u32_e32 v38, 0xa200, v140
	v_add_u32_e32 v39, 0xa000, v140
	v_add_u32_e32 v40, 0x9e00, v140
	v_add_u32_e32 v41, 0x9c00, v140
	v_add_u32_e32 v42, 0x9a00, v140
	v_add_u32_e32 v43, 0x9800, v140
	v_add_u32_e32 v44, 0x9600, v140
	v_add_u32_e32 v45, 0x9400, v140
	v_add_u32_e32 v47, 0x9200, v140
	v_add_u32_e32 v48, 0x9000, v140
	v_add_u32_e32 v49, 0x8e00, v140
	v_add_u32_e32 v50, 0x8c00, v140
	v_add_u32_e32 v51, 0x8a00, v140
	v_add_u32_e32 v52, 0x8800, v140
	v_add_u32_e32 v53, 0x8600, v140
	v_add_u32_e32 v54, 0x8400, v140
	v_add_u32_e32 v55, 0x8200, v140
	v_add_u32_e32 v56, 0x8000, v140
	v_add_u32_e32 v57, 0x7e00, v140
	v_add_u32_e32 v58, 0x7c00, v140
	v_add_u32_e32 v59, 0x7a00, v140
	v_add_u32_e32 v60, 0x7800, v140
	v_add_u32_e32 v61, 0x7600, v140
	v_add_u32_e32 v62, 0x7400, v140
	v_add_u32_e32 v63, 0x7200, v140
	v_add_u32_e32 v64, 0x7000, v140
	v_add_u32_e32 v65, 0x6e00, v140
	v_add_u32_e32 v66, 0x6c00, v140
	v_add_u32_e32 v67, 0x6a00, v140
	v_add_u32_e32 v68, 0x6800, v140
	s_cbranch_vccnz .LBB0_1649
	ds_read2_b32 v[70:71], v36 offset0:126 offset1:191
	s_mov_b64 s[64:65], 0
	s_waitcnt lgkmcnt(0)
	v_add_f32_e32 v69, 0, v71
	v_add_f32_e32 v72, v69, v70
	ds_read2_b32 v[70:71], v37 offset0:124 offset1:189
	ds_write2_b32 v36, v72, v69 offset0:126 offset1:191
	s_waitcnt lgkmcnt(1)
	v_add_f32_e32 v69, v72, v71
	v_add_f32_e32 v72, v69, v70
	ds_read2_b32 v[70:71], v38 offset0:122 offset1:187
	ds_write2_b32 v37, v72, v69 offset0:124 offset1:189
	s_waitcnt lgkmcnt(1)
	v_add_f32_e32 v69, v72, v71
	v_add_f32_e32 v72, v69, v70
	ds_read2_b32 v[70:71], v39 offset0:120 offset1:185
	ds_write2_b32 v38, v72, v69 offset0:122 offset1:187
	s_waitcnt lgkmcnt(1)
	v_add_f32_e32 v69, v72, v71
	v_add_f32_e32 v72, v69, v70
	ds_read2_b32 v[70:71], v40 offset0:118 offset1:183
	ds_write2_b32 v39, v72, v69 offset0:120 offset1:185
	s_waitcnt lgkmcnt(1)
	v_add_f32_e32 v69, v72, v71
	v_add_f32_e32 v72, v69, v70
	ds_read2_b32 v[70:71], v41 offset0:116 offset1:181
	ds_write2_b32 v40, v72, v69 offset0:118 offset1:183
	s_waitcnt lgkmcnt(1)
	v_add_f32_e32 v69, v72, v71
	v_add_f32_e32 v72, v69, v70
	ds_read2_b32 v[70:71], v42 offset0:114 offset1:179
	ds_write2_b32 v41, v72, v69 offset0:116 offset1:181
	s_waitcnt lgkmcnt(1)
	v_add_f32_e32 v69, v72, v71
	v_add_f32_e32 v72, v69, v70
	ds_read2_b32 v[70:71], v43 offset0:112 offset1:177
	ds_write2_b32 v42, v72, v69 offset0:114 offset1:179
	s_waitcnt lgkmcnt(1)
	v_add_f32_e32 v69, v72, v71
	v_add_f32_e32 v72, v69, v70
	ds_read2_b32 v[70:71], v44 offset0:110 offset1:175
	ds_write2_b32 v43, v72, v69 offset0:112 offset1:177
	s_waitcnt lgkmcnt(1)
	v_add_f32_e32 v69, v72, v71
	v_add_f32_e32 v72, v69, v70
	ds_read2_b32 v[70:71], v45 offset0:108 offset1:173
	ds_write2_b32 v44, v72, v69 offset0:110 offset1:175
	s_waitcnt lgkmcnt(1)
	v_add_f32_e32 v69, v72, v71
	v_add_f32_e32 v72, v69, v70
	ds_read2_b32 v[70:71], v47 offset0:106 offset1:171
	ds_write2_b32 v45, v72, v69 offset0:108 offset1:173
	s_waitcnt lgkmcnt(1)
	v_add_f32_e32 v69, v72, v71
	v_add_f32_e32 v72, v69, v70
	ds_read2_b32 v[70:71], v48 offset0:104 offset1:169
	ds_write2_b32 v47, v72, v69 offset0:106 offset1:171
	s_waitcnt lgkmcnt(1)
	v_add_f32_e32 v69, v72, v71
	v_add_f32_e32 v72, v69, v70
	ds_read2_b32 v[70:71], v49 offset0:102 offset1:167
	ds_write2_b32 v48, v72, v69 offset0:104 offset1:169
	s_waitcnt lgkmcnt(1)
	v_add_f32_e32 v69, v72, v71
	v_add_f32_e32 v72, v69, v70
	ds_read2_b32 v[70:71], v50 offset0:100 offset1:165
	ds_write2_b32 v49, v72, v69 offset0:102 offset1:167
	s_waitcnt lgkmcnt(1)
	v_add_f32_e32 v69, v72, v71
	v_add_f32_e32 v72, v69, v70
	ds_read2_b32 v[70:71], v51 offset0:98 offset1:163
	ds_write2_b32 v50, v72, v69 offset0:100 offset1:165
	s_waitcnt lgkmcnt(1)
	v_add_f32_e32 v69, v72, v71
	v_add_f32_e32 v72, v69, v70
	ds_read2_b32 v[70:71], v52 offset0:96 offset1:161
	ds_write2_b32 v51, v72, v69 offset0:98 offset1:163
	s_waitcnt lgkmcnt(1)
	v_add_f32_e32 v69, v72, v71
	v_add_f32_e32 v72, v69, v70
	ds_read2_b32 v[70:71], v53 offset0:94 offset1:159
	ds_write2_b32 v52, v72, v69 offset0:96 offset1:161
	s_waitcnt lgkmcnt(1)
	v_add_f32_e32 v69, v72, v71
	v_add_f32_e32 v72, v69, v70
	ds_read2_b32 v[70:71], v54 offset0:92 offset1:157
	ds_write2_b32 v53, v72, v69 offset0:94 offset1:159
	s_waitcnt lgkmcnt(1)
	v_add_f32_e32 v69, v72, v71
	v_add_f32_e32 v72, v69, v70
	ds_read2_b32 v[70:71], v55 offset0:90 offset1:155
	ds_write2_b32 v54, v72, v69 offset0:92 offset1:157
	s_waitcnt lgkmcnt(1)
	v_add_f32_e32 v69, v72, v71
	v_add_f32_e32 v72, v69, v70
	ds_read2_b32 v[70:71], v56 offset0:88 offset1:153
	ds_write2_b32 v55, v72, v69 offset0:90 offset1:155
	s_waitcnt lgkmcnt(1)
	v_add_f32_e32 v69, v72, v71
	v_add_f32_e32 v72, v69, v70
	ds_read2_b32 v[70:71], v57 offset0:86 offset1:151
	ds_write2_b32 v56, v72, v69 offset0:88 offset1:153
	s_waitcnt lgkmcnt(1)
	v_add_f32_e32 v69, v72, v71
	v_add_f32_e32 v72, v69, v70
	ds_read2_b32 v[70:71], v58 offset0:84 offset1:149
	ds_write2_b32 v57, v72, v69 offset0:86 offset1:151
	s_waitcnt lgkmcnt(1)
	v_add_f32_e32 v69, v72, v71
	v_add_f32_e32 v72, v69, v70
	ds_read2_b32 v[70:71], v59 offset0:82 offset1:147
	ds_write2_b32 v58, v72, v69 offset0:84 offset1:149
	s_waitcnt lgkmcnt(1)
	v_add_f32_e32 v69, v72, v71
	v_add_f32_e32 v72, v69, v70
	ds_read2_b32 v[70:71], v60 offset0:80 offset1:145
	ds_write2_b32 v59, v72, v69 offset0:82 offset1:147
	s_waitcnt lgkmcnt(1)
	v_add_f32_e32 v69, v72, v71
	v_add_f32_e32 v72, v69, v70
	ds_read2_b32 v[70:71], v61 offset0:78 offset1:143
	ds_write2_b32 v60, v72, v69 offset0:80 offset1:145
	s_waitcnt lgkmcnt(1)
	v_add_f32_e32 v69, v72, v71
	v_add_f32_e32 v72, v69, v70
	ds_read2_b32 v[70:71], v62 offset0:76 offset1:141
	ds_write2_b32 v61, v72, v69 offset0:78 offset1:143
	s_waitcnt lgkmcnt(1)
	v_add_f32_e32 v69, v72, v71
	v_add_f32_e32 v72, v69, v70
	ds_read2_b32 v[70:71], v63 offset0:74 offset1:139
	ds_write2_b32 v62, v72, v69 offset0:76 offset1:141
	s_waitcnt lgkmcnt(1)
	v_add_f32_e32 v69, v72, v71
	v_add_f32_e32 v72, v69, v70
	ds_read2_b32 v[70:71], v64 offset0:72 offset1:137
	ds_write2_b32 v63, v72, v69 offset0:74 offset1:139
	s_waitcnt lgkmcnt(1)
	v_add_f32_e32 v69, v72, v71
	v_add_f32_e32 v72, v69, v70
	ds_read2_b32 v[70:71], v65 offset0:70 offset1:135
	ds_write2_b32 v64, v72, v69 offset0:72 offset1:137
	s_waitcnt lgkmcnt(1)
	v_add_f32_e32 v69, v72, v71
	v_add_f32_e32 v72, v69, v70
	ds_read2_b32 v[70:71], v66 offset0:68 offset1:133
	ds_write2_b32 v65, v72, v69 offset0:70 offset1:135
	s_waitcnt lgkmcnt(1)
	v_add_f32_e32 v69, v72, v71
	v_add_f32_e32 v72, v69, v70
	ds_read2_b32 v[70:71], v67 offset0:66 offset1:131
	ds_write2_b32 v66, v72, v69 offset0:68 offset1:133
	s_waitcnt lgkmcnt(1)
	v_add_f32_e32 v69, v72, v71
	v_add_f32_e32 v72, v69, v70
	ds_read2_b32 v[70:71], v68 offset0:64 offset1:129
	ds_write2_b32 v67, v72, v69 offset0:66 offset1:131
	s_waitcnt lgkmcnt(1)
	v_add_f32_e32 v69, v72, v71
	v_add_f32_e32 v70, v69, v70
	ds_write2_b32 v68, v70, v69 offset0:64 offset1:129

.LBB0_1783:
	ds_read2_b32 v[20:21], v17 offset1:1
	ds_read2_b32 a[0:1], v17 offset0:2 offset1:3
	ds_read2_b32 a[2:3], v17 offset0:4 offset1:5
	ds_read2_b32 a[4:5], v17 offset0:6 offset1:7
	ds_read2_b32 a[6:7], v17 offset0:8 offset1:9
	ds_read2_b32 a[8:9], v17 offset0:10 offset1:11
	ds_read2_b32 a[10:11], v17 offset0:12 offset1:13
	ds_read2_b32 a[12:13], v17 offset0:14 offset1:15
	v_add_u32_e32 v19, 1, v19
	s_waitcnt vmcnt(15) lgkmcnt(7)
	v_fma_f32 v22, v11, v20, v10
	s_waitcnt vmcnt(14)
	v_fmac_f32_e32 v22, v12, v21
	s_waitcnt vmcnt(13) lgkmcnt(6)
	v_accvgpr_read_b32 v20, a0
	v_accvgpr_read_b32 v21, a1
	v_fmac_f32_e32 v22, v13, v20
	s_waitcnt vmcnt(12)
	v_fmac_f32_e32 v22, v14, v21
	s_waitcnt vmcnt(7) lgkmcnt(5)
	v_accvgpr_read_b32 v20, a2
	v_accvgpr_read_b32 v21, a3
	v_fmac_f32_e32 v22, v15, v20
	s_waitcnt vmcnt(6)
	v_fmac_f32_e32 v22, v16, v21
	s_waitcnt vmcnt(4) lgkmcnt(4)
	v_accvgpr_read_b32 v20, a4
	v_accvgpr_read_b32 v21, a5
	v_pk_mul_f32 v[20:21], v[4:5], v[20:21]
	s_nop 0
	v_add_f32_e32 v20, v22, v20
	v_add_f32_e32 v22, v20, v21
	s_waitcnt lgkmcnt(3)
	v_accvgpr_read_b32 v20, a6
	v_accvgpr_read_b32 v21, a7
	v_pk_mul_f32 v[20:21], v[0:1], v[20:21]
	s_nop 0
	v_add_f32_e32 v20, v22, v20
	v_add_f32_e32 v22, v20, v21
	s_waitcnt lgkmcnt(2)
	v_accvgpr_read_b32 v20, a8
	v_accvgpr_read_b32 v21, a9
	v_pk_mul_f32 v[20:21], v[2:3], v[20:21]
	s_nop 0
	v_add_f32_e32 v20, v22, v20
	v_add_f32_e32 v22, v20, v21
	s_waitcnt vmcnt(2) lgkmcnt(1)
	v_accvgpr_read_b32 v20, a10
	v_accvgpr_read_b32 v21, a11
	v_pk_mul_f32 v[20:21], v[6:7], v[20:21]
	s_nop 0
	v_add_f32_e32 v20, v22, v20
	v_add_f32_e32 v22, v20, v21
	v_add_u32_e32 v17, 0x84, v17
	s_waitcnt vmcnt(0) lgkmcnt(0)
	v_accvgpr_read_b32 v20, a12
	v_accvgpr_read_b32 v21, a13
	v_pk_mul_f32 v[20:21], v[8:9], v[20:21]
	s_nop 0
	v_add_f32_e32 v20, v22, v20
	v_add_f32_e32 v20, v20, v21
	v_min_f32_e32 v34, 0, v20
	v_mul_f32_e64 v20, |v20|, s14
	v_exp_f32_e32 v35, v20
	s_nop 0
	v_add_f32_e32 v22, 1.0, v35
	v_log_f32_e32 v21, v22
	v_add_f32_e32 v23, -1.0, v22
	v_cmp_eq_f32_e32 vcc, 1.0, v22
	v_rcp_f32_e32 v28, v23
	v_mul_f32_e32 v21, 0x3f317218, v21
	v_mul_f32_e32 v28, v35, v28
	s_nop 0
	v_mul_f32_e32 v21, v21, v28
	s_nop 0
	v_cndmask_b32_e32 v20, v21, v35, vcc
	v_sub_f32_e32 v20, v34, v20
	v_mul_f32_e32 v20, 0x3d800000, v20
	v_cmp_eq_u32_e32 vcc, v131, v19
	ds_write_b32 v18, v20
	v_add_u32_e32 v18, 0x104, v18
	s_or_b64 s[76:77], vcc, s[76:77]
	s_andn2_b64 exec, exec, s[76:77]
	s_cbranch_execnz .LBB0_1783
	s_or_b64 exec, exec, s[76:77]
	s_waitcnt lgkmcnt(0)
	s_barrier
	s_and_saveexec_b64 s[76:77], s[6:7]
	s_cbranch_execz .LBB0_1786
	v_accvgpr_read_b32 v3, a117
	ds_read2_b32 v[0:1], v3 offset0:64 offset1:129
	s_waitcnt lgkmcnt(0)
	v_add_f32_e32 v0, 0, v0
	v_add_f32_e32 v2, v0, v1
	ds_write2_b32 v3, v0, v2 offset0:64 offset1:129
	v_accvgpr_read_b32 v3, a118
	ds_read2_b32 v[0:1], v3 offset0:66 offset1:131
	s_waitcnt lgkmcnt(0)
	v_add_f32_e32 v0, v2, v0
	v_add_f32_e32 v2, v0, v1
	ds_write2_b32 v3, v0, v2 offset0:66 offset1:131
	v_accvgpr_read_b32 v3, a119
	ds_read2_b32 v[0:1], v3 offset0:68 offset1:133
	s_waitcnt lgkmcnt(0)
	v_add_f32_e32 v0, v2, v0
	v_add_f32_e32 v2, v0, v1
	ds_write2_b32 v3, v0, v2 offset0:68 offset1:133
	v_accvgpr_read_b32 v3, a120
	ds_read2_b32 v[0:1], v3 offset0:70 offset1:135
	s_waitcnt lgkmcnt(0)
	v_add_f32_e32 v0, v2, v0
	v_add_f32_e32 v2, v0, v1
	ds_write2_b32 v3, v0, v2 offset0:70 offset1:135
	v_accvgpr_read_b32 v3, a121
	ds_read2_b32 v[0:1], v3 offset0:72 offset1:137
	s_waitcnt lgkmcnt(0)
	v_add_f32_e32 v0, v2, v0
	v_add_f32_e32 v2, v0, v1
	ds_write2_b32 v3, v0, v2 offset0:72 offset1:137
	v_accvgpr_read_b32 v3, a122
	ds_read2_b32 v[0:1], v3 offset0:74 offset1:139
	s_waitcnt lgkmcnt(0)
	v_add_f32_e32 v0, v2, v0
	v_add_f32_e32 v2, v0, v1
	ds_write2_b32 v3, v0, v2 offset0:74 offset1:139
	v_accvgpr_read_b32 v3, a123
	ds_read2_b32 v[0:1], v3 offset0:76 offset1:141
	s_waitcnt lgkmcnt(0)
	v_add_f32_e32 v0, v2, v0
	v_add_f32_e32 v2, v0, v1
	ds_write2_b32 v3, v0, v2 offset0:76 offset1:141
	v_accvgpr_read_b32 v3, a124
	ds_read2_b32 v[0:1], v3 offset0:78 offset1:143
	s_waitcnt lgkmcnt(0)
	v_add_f32_e32 v0, v2, v0
	v_add_f32_e32 v2, v0, v1
	ds_write2_b32 v3, v0, v2 offset0:78 offset1:143
	v_accvgpr_read_b32 v3, a125
	ds_read2_b32 v[0:1], v3 offset0:80 offset1:145
	s_waitcnt lgkmcnt(0)
	v_add_f32_e32 v0, v2, v0
	v_add_f32_e32 v2, v0, v1
	ds_write2_b32 v3, v0, v2 offset0:80 offset1:145
	v_accvgpr_read_b32 v3, a126
	ds_read2_b32 v[0:1], v3 offset0:82 offset1:147
	s_waitcnt lgkmcnt(0)
	v_add_f32_e32 v0, v2, v0
	v_add_f32_e32 v2, v0, v1
	ds_write2_b32 v3, v0, v2 offset0:82 offset1:147
	v_accvgpr_read_b32 v3, a127
	ds_read2_b32 v[0:1], v3 offset0:84 offset1:149
	s_waitcnt lgkmcnt(0)
	v_add_f32_e32 v0, v2, v0
	v_add_f32_e32 v2, v0, v1
	ds_write2_b32 v3, v0, v2 offset0:84 offset1:149
	v_accvgpr_read_b32 v3, a128
	ds_read2_b32 v[0:1], v3 offset0:86 offset1:151
	s_waitcnt lgkmcnt(0)
	v_add_f32_e32 v0, v2, v0
	v_add_f32_e32 v2, v0, v1
	ds_write2_b32 v3, v0, v2 offset0:86 offset1:151
	v_accvgpr_read_b32 v3, a129
	ds_read2_b32 v[0:1], v3 offset0:88 offset1:153
	s_waitcnt lgkmcnt(0)
	v_add_f32_e32 v0, v2, v0
	v_add_f32_e32 v2, v0, v1
	ds_write2_b32 v3, v0, v2 offset0:88 offset1:153
	v_accvgpr_read_b32 v3, a130
	ds_read2_b32 v[0:1], v3 offset0:90 offset1:155
	s_waitcnt lgkmcnt(0)
	v_add_f32_e32 v0, v2, v0
	v_add_f32_e32 v2, v0, v1
	ds_write2_b32 v3, v0, v2 offset0:90 offset1:155
	v_accvgpr_read_b32 v3, a131
	ds_read2_b32 v[0:1], v3 offset0:92 offset1:157
	s_waitcnt lgkmcnt(0)
	v_add_f32_e32 v0, v2, v0
	v_add_f32_e32 v2, v0, v1
	ds_write2_b32 v3, v0, v2 offset0:92 offset1:157
	v_accvgpr_read_b32 v3, a132
	ds_read2_b32 v[0:1], v3 offset0:94 offset1:159
	s_waitcnt lgkmcnt(0)
	v_add_f32_e32 v0, v2, v0
	v_add_f32_e32 v2, v0, v1
	ds_write2_b32 v3, v0, v2 offset0:94 offset1:159
	v_accvgpr_read_b32 v3, a133
	ds_read2_b32 v[0:1], v3 offset0:96 offset1:161
	s_waitcnt lgkmcnt(0)
	v_add_f32_e32 v0, v2, v0
	v_add_f32_e32 v2, v0, v1
	ds_write2_b32 v3, v0, v2 offset0:96 offset1:161
	v_accvgpr_read_b32 v3, a134
	ds_read2_b32 v[0:1], v3 offset0:98 offset1:163
	s_waitcnt lgkmcnt(0)
	v_add_f32_e32 v0, v2, v0
	v_add_f32_e32 v2, v0, v1
	ds_write2_b32 v3, v0, v2 offset0:98 offset1:163
	v_accvgpr_read_b32 v3, a135
	ds_read2_b32 v[0:1], v3 offset0:100 offset1:165
	s_waitcnt lgkmcnt(0)
	v_add_f32_e32 v0, v2, v0
	v_add_f32_e32 v2, v0, v1
	ds_write2_b32 v3, v0, v2 offset0:100 offset1:165
	v_accvgpr_read_b32 v3, a136
	ds_read2_b32 v[0:1], v3 offset0:102 offset1:167
	s_waitcnt lgkmcnt(0)
	v_add_f32_e32 v0, v2, v0
	v_add_f32_e32 v2, v0, v1
	ds_write2_b32 v3, v0, v2 offset0:102 offset1:167
	v_accvgpr_read_b32 v3, a137
	ds_read2_b32 v[0:1], v3 offset0:104 offset1:169
	s_waitcnt lgkmcnt(0)
	v_add_f32_e32 v0, v2, v0
	v_add_f32_e32 v2, v0, v1
	ds_write2_b32 v3, v0, v2 offset0:104 offset1:169
	v_accvgpr_read_b32 v3, a138
	ds_read2_b32 v[0:1], v3 offset0:106 offset1:171
	s_waitcnt lgkmcnt(0)
	v_add_f32_e32 v0, v2, v0
	v_add_f32_e32 v2, v0, v1
	ds_write2_b32 v3, v0, v2 offset0:106 offset1:171
	v_accvgpr_read_b32 v3, a139
	ds_read2_b32 v[0:1], v3 offset0:108 offset1:173
	s_waitcnt lgkmcnt(0)
	v_add_f32_e32 v0, v2, v0
	v_add_f32_e32 v2, v0, v1
	ds_write2_b32 v3, v0, v2 offset0:108 offset1:173
	v_accvgpr_read_b32 v3, a140
	ds_read2_b32 v[0:1], v3 offset0:110 offset1:175
	s_waitcnt lgkmcnt(0)
	v_add_f32_e32 v0, v2, v0
	v_add_f32_e32 v2, v0, v1
	ds_write2_b32 v3, v0, v2 offset0:110 offset1:175
	v_accvgpr_read_b32 v3, a141
	ds_read2_b32 v[0:1], v3 offset0:112 offset1:177
	s_waitcnt lgkmcnt(0)
	v_add_f32_e32 v0, v2, v0
	v_add_f32_e32 v2, v0, v1
	ds_write2_b32 v3, v0, v2 offset0:112 offset1:177
	v_accvgpr_read_b32 v3, a142
	ds_read2_b32 v[0:1], v3 offset0:114 offset1:179
	s_waitcnt lgkmcnt(0)
	v_add_f32_e32 v0, v2, v0
	v_add_f32_e32 v2, v0, v1
	ds_write2_b32 v3, v0, v2 offset0:114 offset1:179
	v_accvgpr_read_b32 v3, a143
	ds_read2_b32 v[0:1], v3 offset0:116 offset1:181
	s_waitcnt lgkmcnt(0)
	v_add_f32_e32 v0, v2, v0
	v_add_f32_e32 v2, v0, v1
	ds_write2_b32 v3, v0, v2 offset0:116 offset1:181
	v_accvgpr_read_b32 v3, a144
	ds_read2_b32 v[0:1], v3 offset0:118 offset1:183
	s_waitcnt lgkmcnt(0)
	v_add_f32_e32 v0, v2, v0
	v_add_f32_e32 v2, v0, v1
	ds_write2_b32 v3, v0, v2 offset0:118 offset1:183
	v_accvgpr_read_b32 v3, a145
	ds_read2_b32 v[0:1], v3 offset0:120 offset1:185
	s_waitcnt lgkmcnt(0)
	v_add_f32_e32 v0, v2, v0
	v_add_f32_e32 v2, v0, v1
	ds_write2_b32 v3, v0, v2 offset0:120 offset1:185
	v_accvgpr_read_b32 v3, a146
	ds_read2_b32 v[0:1], v3 offset0:122 offset1:187
	s_waitcnt lgkmcnt(0)
	v_add_f32_e32 v0, v2, v0
	v_add_f32_e32 v2, v0, v1
	ds_write2_b32 v3, v0, v2 offset0:122 offset1:187
	v_accvgpr_read_b32 v3, a147
	ds_read2_b32 v[0:1], v3 offset0:124 offset1:189
	s_waitcnt lgkmcnt(0)
	v_add_f32_e32 v0, v2, v0
	v_add_f32_e32 v2, v0, v1
	ds_write2_b32 v3, v0, v2 offset0:124 offset1:189
	v_accvgpr_read_b32 v3, a148
	ds_read2_b32 v[0:1], v3 offset0:126 offset1:191
	s_waitcnt lgkmcnt(0)
	v_add_f32_e32 v0, v2, v0
	v_add_f32_e32 v1, v0, v1
	ds_write2_b32 v3, v0, v1 offset0:126 offset1:191

.LBB0_1787:
	ds_read2_b32 v[110:111], v106 offset1:1
	ds_read2_b32 a[0:1], v106 offset0:2 offset1:3
	ds_read2_b32 a[2:3], v106 offset0:4 offset1:5
	ds_read2_b32 a[4:5], v106 offset0:6 offset1:7
	ds_read2_b32 a[6:7], v106 offset0:8 offset1:9
	ds_read2_b32 a[8:9], v106 offset0:10 offset1:11
	ds_read2_b32 a[10:11], v106 offset0:12 offset1:13
	ds_read2_b32 a[12:13], v106 offset0:14 offset1:15
	v_add_u32_e32 v108, -1, v108
	s_waitcnt vmcnt(15) lgkmcnt(7)
	v_fma_f32 v74, v100, v110, v99
	s_waitcnt vmcnt(14)
	v_fmac_f32_e32 v74, v101, v111
	s_waitcnt vmcnt(13) lgkmcnt(6)
	v_accvgpr_read_b32 v110, a0
	v_accvgpr_read_b32 v111, a1
	v_fmac_f32_e32 v74, v102, v110
	s_waitcnt vmcnt(12)
	v_fmac_f32_e32 v74, v103, v111
	s_waitcnt vmcnt(11) lgkmcnt(5)
	v_accvgpr_read_b32 v110, a2
	v_accvgpr_read_b32 v111, a3
	v_fmac_f32_e32 v74, v104, v110
	s_waitcnt vmcnt(10)
	v_fmac_f32_e32 v74, v105, v111
	s_waitcnt vmcnt(8) lgkmcnt(4)
	v_accvgpr_read_b32 v110, a4
	v_accvgpr_read_b32 v111, a5
	v_pk_mul_f32 v[110:111], v[196:197], v[110:111]
	s_nop 0
	v_add_f32_e32 v74, v74, v110
	v_add_f32_e32 v74, v74, v111
	s_waitcnt vmcnt(6) lgkmcnt(3)
	v_accvgpr_read_b32 v110, a6
	v_accvgpr_read_b32 v111, a7
	v_pk_mul_f32 v[110:111], v[146:147], v[110:111]
	s_nop 0
	v_add_f32_e32 v74, v74, v110
	v_add_f32_e32 v74, v74, v111
	s_waitcnt vmcnt(4) lgkmcnt(2)
	v_accvgpr_read_b32 v110, a8
	v_accvgpr_read_b32 v111, a9
	v_pk_mul_f32 v[110:111], v[144:145], v[110:111]
	s_nop 0
	v_add_f32_e32 v74, v74, v110
	v_add_f32_e32 v74, v74, v111
	s_waitcnt vmcnt(2) lgkmcnt(1)
	v_accvgpr_read_b32 v110, a10
	v_accvgpr_read_b32 v111, a11
	v_pk_mul_f32 v[110:111], v[140:141], v[110:111]
	s_nop 0
	v_add_f32_e32 v74, v74, v110
	v_add_f32_e32 v74, v74, v111
	v_add_u32_e32 v106, 0x84, v106
	s_waitcnt vmcnt(0) lgkmcnt(0)
	v_accvgpr_read_b32 v110, a12
	v_accvgpr_read_b32 v111, a13
	v_pk_mul_f32 v[110:111], v[142:143], v[110:111]
	s_nop 0
	v_add_f32_e32 v74, v74, v110
	v_add_f32_e32 v74, v74, v111
	v_min_f32_e32 v109, 0, v74
	v_mul_f32_e64 v74, |v74|, s14
	v_exp_f32_e32 v80, v74
	s_nop 0
	v_add_f32_e32 v75, 1.0, v80
	v_log_f32_e32 v90, v75
	v_add_f32_e32 v110, -1.0, v75
	v_cmp_eq_f32_e32 vcc, 1.0, v75
	v_rcp_f32_e32 v111, v110
	v_mul_f32_e32 v90, 0x3f317218, v90
	v_mul_f32_e32 v111, v80, v111
	s_nop 0
	v_mul_f32_e32 v90, v90, v111
	s_nop 0
	v_cndmask_b32_e32 v74, v90, v80, vcc
	v_sub_f32_e32 v74, v109, v74
	v_mul_f32_e32 v74, 0x3d800000, v74
	v_cmp_eq_u32_e32 vcc, 0, v108
	ds_write_b32 v139, v74
	v_add_u32_e32 v139, 0x104, v139
	s_or_b64 s[80:81], vcc, s[80:81]
	s_andn2_b64 exec, exec, s[80:81]
	s_cbranch_execnz .LBB0_1787
	s_or_b64 exec, exec, s[80:81]
	v_mfma_f32_32x32x16_bf16 a[32:47], v[4:7], v[24:27], 0
	s_waitcnt lgkmcnt(0)
	s_barrier
	v_mfma_f32_32x32x16_bf16 a[32:47], v[0:3], v[12:15], a[32:47]
	v_cvt_pk_bf16_f32 v0, v67, v81
	v_cvt_pk_bf16_f32 v1, v85, v115
	v_cvt_pk_bf16_f32 v2, v119, v136
	v_cvt_pk_bf16_f32 v3, v137, v98
	s_nop 1
	v_mfma_f32_32x32x16_bf16 a[16:31], v[36:39], v[0:3], 0
	v_mfma_f32_32x32x16_bf16 a[0:15], v[40:43], v[0:3], 0
	v_cvt_pk_bf16_f32 v0, v121, v123
	v_cvt_pk_bf16_f32 v1, v125, v127
	v_cvt_pk_bf16_f32 v2, v149, v151
	v_cvt_pk_bf16_f32 v3, v153, v155
	s_nop 1
	v_mfma_f32_32x32x16_bf16 a[16:31], v[32:35], v[0:3], a[16:31]
	v_mfma_f32_32x32x16_bf16 a[0:15], v[44:47], v[0:3], a[0:15]
	v_cvt_pk_bf16_f32 v0, v157, v159
	v_cvt_pk_bf16_f32 v1, v161, v163
	v_cvt_pk_bf16_f32 v2, v165, v167
	v_cvt_pk_bf16_f32 v3, v169, v171
	v_mfma_f32_32x32x16_bf16 a[32:47], v[8:11], v[16:19], a[32:47]
	s_nop 0
	v_mfma_f32_32x32x16_bf16 a[16:31], v[52:55], v[0:3], a[16:31]
	v_mfma_f32_32x32x16_bf16 a[0:15], v[48:51], v[0:3], a[0:15]
	v_cvt_pk_bf16_f32 v0, v173, v175
	v_cvt_pk_bf16_f32 v1, v177, v179
	v_cvt_pk_bf16_f32 v2, v181, v183
	v_cvt_pk_bf16_f32 v3, v185, v187
	v_mfma_f32_32x32x16_bf16 a[32:47], v[20:23], v[28:31], a[32:47]
	s_nop 0
	v_mfma_f32_32x32x16_bf16 a[16:31], v[60:63], v[0:3], a[16:31]
	v_mfma_f32_32x32x16_bf16 a[0:15], v[56:59], v[0:3], a[0:15]
	s_and_saveexec_b64 s[80:81], s[6:7]
	s_cbranch_execz .LBB0_1779
	v_accvgpr_read_b32 v3, a148
	ds_read2_b32 v[0:1], v3 offset0:126 offset1:191
	s_waitcnt lgkmcnt(0)
	v_add_f32_e32 v1, 0, v1
	v_add_f32_e32 v2, v1, v0
	ds_write2_b32 v3, v2, v1 offset0:126 offset1:191
	v_accvgpr_read_b32 v3, a147
	ds_read2_b32 v[0:1], v3 offset0:124 offset1:189
	s_waitcnt lgkmcnt(0)
	v_add_f32_e32 v1, v2, v1
	v_add_f32_e32 v2, v1, v0
	ds_write2_b32 v3, v2, v1 offset0:124 offset1:189
	v_accvgpr_read_b32 v3, a146
	ds_read2_b32 v[0:1], v3 offset0:122 offset1:187
	s_waitcnt lgkmcnt(0)
	v_add_f32_e32 v1, v2, v1
	v_add_f32_e32 v2, v1, v0
	ds_write2_b32 v3, v2, v1 offset0:122 offset1:187
	v_accvgpr_read_b32 v3, a145
	ds_read2_b32 v[0:1], v3 offset0:120 offset1:185
	s_waitcnt lgkmcnt(0)
	v_add_f32_e32 v1, v2, v1
	v_add_f32_e32 v2, v1, v0
	ds_write2_b32 v3, v2, v1 offset0:120 offset1:185
	v_accvgpr_read_b32 v3, a144
	ds_read2_b32 v[0:1], v3 offset0:118 offset1:183
	s_waitcnt lgkmcnt(0)
	v_add_f32_e32 v1, v2, v1
	v_add_f32_e32 v2, v1, v0
	ds_write2_b32 v3, v2, v1 offset0:118 offset1:183
	v_accvgpr_read_b32 v3, a143
	ds_read2_b32 v[0:1], v3 offset0:116 offset1:181
	s_waitcnt lgkmcnt(0)
	v_add_f32_e32 v1, v2, v1
	v_add_f32_e32 v2, v1, v0
	ds_write2_b32 v3, v2, v1 offset0:116 offset1:181
	v_accvgpr_read_b32 v3, a142
	ds_read2_b32 v[0:1], v3 offset0:114 offset1:179
	s_waitcnt lgkmcnt(0)
	v_add_f32_e32 v1, v2, v1
	v_add_f32_e32 v2, v1, v0
	ds_write2_b32 v3, v2, v1 offset0:114 offset1:179
	v_accvgpr_read_b32 v3, a141
	ds_read2_b32 v[0:1], v3 offset0:112 offset1:177
	s_waitcnt lgkmcnt(0)
	v_add_f32_e32 v1, v2, v1
	v_add_f32_e32 v2, v1, v0
	ds_write2_b32 v3, v2, v1 offset0:112 offset1:177
	v_accvgpr_read_b32 v3, a140
	ds_read2_b32 v[0:1], v3 offset0:110 offset1:175
	s_waitcnt lgkmcnt(0)
	v_add_f32_e32 v1, v2, v1
	v_add_f32_e32 v2, v1, v0
	ds_write2_b32 v3, v2, v1 offset0:110 offset1:175
	v_accvgpr_read_b32 v3, a139
	ds_read2_b32 v[0:1], v3 offset0:108 offset1:173
	s_waitcnt lgkmcnt(0)
	v_add_f32_e32 v1, v2, v1
	v_add_f32_e32 v2, v1, v0
	ds_write2_b32 v3, v2, v1 offset0:108 offset1:173
	v_accvgpr_read_b32 v3, a138
	ds_read2_b32 v[0:1], v3 offset0:106 offset1:171
	s_waitcnt lgkmcnt(0)
	v_add_f32_e32 v1, v2, v1
	v_add_f32_e32 v2, v1, v0
	ds_write2_b32 v3, v2, v1 offset0:106 offset1:171
	v_accvgpr_read_b32 v3, a137
	ds_read2_b32 v[0:1], v3 offset0:104 offset1:169
	s_waitcnt lgkmcnt(0)
	v_add_f32_e32 v1, v2, v1
	v_add_f32_e32 v2, v1, v0
	ds_write2_b32 v3, v2, v1 offset0:104 offset1:169
	v_accvgpr_read_b32 v3, a136
	ds_read2_b32 v[0:1], v3 offset0:102 offset1:167
	s_waitcnt lgkmcnt(0)
	v_add_f32_e32 v1, v2, v1
	v_add_f32_e32 v2, v1, v0
	ds_write2_b32 v3, v2, v1 offset0:102 offset1:167
	v_accvgpr_read_b32 v3, a135
	ds_read2_b32 v[0:1], v3 offset0:100 offset1:165
	s_waitcnt lgkmcnt(0)
	v_add_f32_e32 v1, v2, v1
	v_add_f32_e32 v2, v1, v0
	ds_write2_b32 v3, v2, v1 offset0:100 offset1:165
	v_accvgpr_read_b32 v3, a134
	ds_read2_b32 v[0:1], v3 offset0:98 offset1:163
	s_waitcnt lgkmcnt(0)
	v_add_f32_e32 v1, v2, v1
	v_add_f32_e32 v2, v1, v0
	ds_write2_b32 v3, v2, v1 offset0:98 offset1:163
	v_accvgpr_read_b32 v3, a133
	ds_read2_b32 v[0:1], v3 offset0:96 offset1:161
	s_waitcnt lgkmcnt(0)
	v_add_f32_e32 v1, v2, v1
	v_add_f32_e32 v2, v1, v0
	ds_write2_b32 v3, v2, v1 offset0:96 offset1:161
	v_accvgpr_read_b32 v3, a132
	ds_read2_b32 v[0:1], v3 offset0:94 offset1:159
	s_waitcnt lgkmcnt(0)
	v_add_f32_e32 v1, v2, v1
	v_add_f32_e32 v2, v1, v0
	ds_write2_b32 v3, v2, v1 offset0:94 offset1:159
	v_accvgpr_read_b32 v3, a131
	ds_read2_b32 v[0:1], v3 offset0:92 offset1:157
	s_waitcnt lgkmcnt(0)
	v_add_f32_e32 v1, v2, v1
	v_add_f32_e32 v2, v1, v0
	ds_write2_b32 v3, v2, v1 offset0:92 offset1:157
	v_accvgpr_read_b32 v3, a130
	ds_read2_b32 v[0:1], v3 offset0:90 offset1:155
	s_waitcnt lgkmcnt(0)
	v_add_f32_e32 v1, v2, v1
	v_add_f32_e32 v2, v1, v0
	ds_write2_b32 v3, v2, v1 offset0:90 offset1:155
	v_accvgpr_read_b32 v3, a129
	ds_read2_b32 v[0:1], v3 offset0:88 offset1:153
	s_waitcnt lgkmcnt(0)
	v_add_f32_e32 v1, v2, v1
	v_add_f32_e32 v2, v1, v0
	ds_write2_b32 v3, v2, v1 offset0:88 offset1:153
	v_accvgpr_read_b32 v3, a128
	ds_read2_b32 v[0:1], v3 offset0:86 offset1:151
	s_waitcnt lgkmcnt(0)
	v_add_f32_e32 v1, v2, v1
	v_add_f32_e32 v2, v1, v0
	ds_write2_b32 v3, v2, v1 offset0:86 offset1:151
	v_accvgpr_read_b32 v3, a127
	ds_read2_b32 v[0:1], v3 offset0:84 offset1:149
	s_waitcnt lgkmcnt(0)
	v_add_f32_e32 v1, v2, v1
	v_add_f32_e32 v2, v1, v0
	ds_write2_b32 v3, v2, v1 offset0:84 offset1:149
	v_accvgpr_read_b32 v3, a126
	ds_read2_b32 v[0:1], v3 offset0:82 offset1:147
	s_waitcnt lgkmcnt(0)
	v_add_f32_e32 v1, v2, v1
	v_add_f32_e32 v2, v1, v0
	ds_write2_b32 v3, v2, v1 offset0:82 offset1:147
	v_accvgpr_read_b32 v3, a125
	ds_read2_b32 v[0:1], v3 offset0:80 offset1:145
	s_waitcnt lgkmcnt(0)
	v_add_f32_e32 v1, v2, v1
	v_add_f32_e32 v2, v1, v0
	ds_write2_b32 v3, v2, v1 offset0:80 offset1:145
	v_accvgpr_read_b32 v3, a124
	ds_read2_b32 v[0:1], v3 offset0:78 offset1:143
	s_waitcnt lgkmcnt(0)
	v_add_f32_e32 v1, v2, v1
	v_add_f32_e32 v2, v1, v0
	ds_write2_b32 v3, v2, v1 offset0:78 offset1:143
	v_accvgpr_read_b32 v3, a123
	ds_read2_b32 v[0:1], v3 offset0:76 offset1:141
	s_waitcnt lgkmcnt(0)
	v_add_f32_e32 v1, v2, v1
	v_add_f32_e32 v2, v1, v0
	ds_write2_b32 v3, v2, v1 offset0:76 offset1:141
	v_accvgpr_read_b32 v3, a122
	ds_read2_b32 v[0:1], v3 offset0:74 offset1:139
	s_waitcnt lgkmcnt(0)
	v_add_f32_e32 v1, v2, v1
	v_add_f32_e32 v2, v1, v0
	ds_write2_b32 v3, v2, v1 offset0:74 offset1:139
	v_accvgpr_read_b32 v3, a121
	ds_read2_b32 v[0:1], v3 offset0:72 offset1:137
	s_waitcnt lgkmcnt(0)
	v_add_f32_e32 v1, v2, v1
	v_add_f32_e32 v2, v1, v0
	ds_write2_b32 v3, v2, v1 offset0:72 offset1:137
	v_accvgpr_read_b32 v3, a120
	ds_read2_b32 v[0:1], v3 offset0:70 offset1:135
	s_waitcnt lgkmcnt(0)
	v_add_f32_e32 v1, v2, v1
	v_add_f32_e32 v2, v1, v0
	ds_write2_b32 v3, v2, v1 offset0:70 offset1:135
	v_accvgpr_read_b32 v3, a119
	ds_read2_b32 v[0:1], v3 offset0:68 offset1:133
	s_waitcnt lgkmcnt(0)
	v_add_f32_e32 v1, v2, v1
	v_add_f32_e32 v2, v1, v0
	ds_write2_b32 v3, v2, v1 offset0:68 offset1:133
	v_accvgpr_read_b32 v3, a118
	ds_read2_b32 v[0:1], v3 offset0:66 offset1:131
	s_waitcnt lgkmcnt(0)
	v_add_f32_e32 v1, v2, v1
	v_add_f32_e32 v2, v1, v0
	ds_write2_b32 v3, v2, v1 offset0:66 offset1:131
	v_accvgpr_read_b32 v3, a117
	ds_read2_b32 v[0:1], v3 offset0:64 offset1:129
	s_waitcnt lgkmcnt(0)
	v_add_f32_e32 v1, v2, v1
	v_add_f32_e32 v0, v1, v0
	ds_write2_b32 v3, v0, v1 offset0:64 offset1:129
	s_branch .LBB0_1779

.LBB0_2161:
	s_and_b32 s4, s10, 1
	s_mul_i32 s11, s4, 0xd800
	s_xor_b32 s4, s4, 1
	s_mul_i32 s4, s4, 0xd800
	s_add_i32 s10, s10, 1
	v_add_u32_e32 v186, s4, v130
	ds_read_b128 v[12:15], v189 offset:32
	ds_read_b128 v[24:27], v187 offset:36896
	ds_read_b128 v[16:19], v189 offset:4640
	ds_read_b128 v[28:31], v187 offset:41504
	ds_read_b128 v[20:23], v189 offset:9248
	ds_read_b128 v[76:79], v188 offset:32
	s_waitcnt lgkmcnt(6)
	v_mfma_f32_32x32x16_bf16 a[32:47], v[80:83], v[4:7], a[32:47]
	s_waitcnt vmcnt(11)
	ds_write_b128 v186, v[250:253]
	v_mfma_f32_32x32x16_bf16 a[48:63], v[80:83], v[8:11], a[48:63]
	s_waitcnt vmcnt(10)
	ds_write_b128 v186, v[246:249] offset:4608
	global_load_dwordx4 v[250:253], v254, s[100:101] offset:512
	v_mfma_f32_32x32x16_bf16 a[64:79], v[84:87], v[4:7], a[64:79]
	s_waitcnt vmcnt(10)
	ds_write_b128 v186, v[242:245] offset:9216
	global_load_dwordx4 v[246:249], v205, s[100:101] offset:512
	v_mfma_f32_32x32x16_bf16 a[96:111], v[84:87], v[8:11], a[96:111]
	s_waitcnt vmcnt(10)
	ds_write_b128 v186, v[238:241] offset:13824
	global_load_dwordx4 v[242:245], v204, s[100:101] offset:512
	v_mfma_f32_32x32x16_bf16 a[80:95], v[88:91], v[4:7], a[80:95]
	s_waitcnt vmcnt(10)
	ds_write_b128 v186, v[234:237] offset:18432
	global_load_dwordx4 v[238:241], v203, s[100:101] offset:512
	v_mfma_f32_32x32x16_bf16 a[112:127], v[88:91], v[8:11], a[112:127]
	s_waitcnt vmcnt(10)
	ds_write_b128 v186, v[230:233] offset:23040
	global_load_dwordx4 v[234:237], v202, s[100:101] offset:512
	s_waitcnt lgkmcnt(6)
	v_mfma_f32_32x32x16_bf16 a[16:31], v[92:95], v[4:7], a[16:31]
	s_waitcnt vmcnt(10)
	ds_write_b128 v186, v[226:229] offset:27648
	global_load_dwordx4 v[230:233], v201, s[100:101] offset:512
	v_mfma_f32_32x32x16_bf16 a[0:15], v[92:95], v[8:11], a[0:15]
	s_waitcnt vmcnt(10)
	ds_write_b128 v186, v[222:225] offset:32256
	global_load_dwordx4 v[226:229], v200, s[100:101] offset:512
	s_waitcnt lgkmcnt(8)
	ds_read_b128 v[80:83], v189 offset:64
	ds_read_b128 v[4:7], v187 offset:36928
	ds_read_b128 v[84:87], v189 offset:4672
	ds_read_b128 v[8:11], v187 offset:41536
	ds_read_b128 v[88:91], v189 offset:9280
	ds_read_b128 v[92:95], v188 offset:64
	v_mfma_f32_32x32x16_bf16 a[32:47], v[12:15], v[24:27], a[32:47]
	s_waitcnt lgkmcnt(12)
	s_waitcnt vmcnt(10)
	ds_write_b128 v186, v[218:221] offset:36864
	global_load_dwordx4 v[222:225], v199, s[100:101] offset:512
	v_mfma_f32_32x32x16_bf16 a[48:63], v[12:15], v[28:31], a[48:63]
	s_waitcnt lgkmcnt(12)
	s_waitcnt vmcnt(10)
	ds_write_b128 v186, v[214:217] offset:41472
	global_load_dwordx4 v[218:221], v198, s[98:99] offset:256
	v_mfma_f32_32x32x16_bf16 a[64:79], v[16:19], v[24:27], a[64:79]
	s_waitcnt lgkmcnt(12)
	s_waitcnt vmcnt(10)
	ds_write_b128 v186, v[210:213] offset:46080
	global_load_dwordx4 v[214:217], v197, s[98:99] offset:256
	v_mfma_f32_32x32x16_bf16 a[96:111], v[16:19], v[28:31], a[96:111]
	s_waitcnt lgkmcnt(12)
	s_waitcnt vmcnt(10)
	ds_write_b128 v186, v[206:209] offset:50688
	global_load_dwordx4 v[210:213], v196, s[98:99] offset:256
	v_mfma_f32_32x32x16_bf16 a[80:95], v[20:23], v[24:27], a[80:95]
	global_load_dwordx4 v[206:209], v195, s[98:99] offset:256
	s_add_u32 s100, s100, 0x80
	s_addc_u32 s101, s101, 0
	s_add_u32 s98, s98, 0x80
	s_addc_u32 s99, s99, 0
	v_mfma_f32_32x32x16_bf16 a[112:127], v[20:23], v[28:31], a[112:127]
	v_mfma_f32_32x32x16_bf16 a[16:31], v[76:79], v[24:27], a[16:31]
	v_mfma_f32_32x32x16_bf16 a[0:15], v[76:79], v[28:31], a[0:15]
	s_waitcnt lgkmcnt(4)
	ds_read_b128 v[12:15], v189 offset:96
	ds_read_b128 v[24:27], v187 offset:36960
	ds_read_b128 v[16:19], v189 offset:4704
	ds_read_b128 v[28:31], v187 offset:41568
	ds_read_b128 v[20:23], v189 offset:9312
	ds_read_b128 v[76:79], v188 offset:96
	v_mfma_f32_32x32x16_bf16 a[32:47], v[80:83], v[4:7], a[32:47]
	v_mfma_f32_32x32x16_bf16 a[48:63], v[80:83], v[8:11], a[48:63]
	v_mfma_f32_32x32x16_bf16 a[64:79], v[84:87], v[4:7], a[64:79]
	v_mfma_f32_32x32x16_bf16 a[96:111], v[84:87], v[8:11], a[96:111]
	v_mfma_f32_32x32x16_bf16 a[80:95], v[88:91], v[4:7], a[80:95]
	v_mfma_f32_32x32x16_bf16 a[112:127], v[88:91], v[8:11], a[112:127]
	v_mfma_f32_32x32x16_bf16 a[16:31], v[92:95], v[4:7], a[16:31]
	v_mfma_f32_32x32x16_bf16 a[0:15], v[92:95], v[8:11], a[0:15]
	s_waitcnt lgkmcnt(0)
	v_mfma_f32_32x32x16_bf16 a[32:47], v[12:15], v[24:27], a[32:47]
	v_mfma_f32_32x32x16_bf16 a[48:63], v[12:15], v[28:31], a[48:63]
	v_mfma_f32_32x32x16_bf16 a[64:79], v[16:19], v[24:27], a[64:79]
	v_mfma_f32_32x32x16_bf16 a[96:111], v[16:19], v[28:31], a[96:111]
	s_barrier
	v_add_u32_e32 v189, s4, v192
	v_add_u32_e32 v188, s4, v191
	v_add_u32_e32 v187, s4, v190
	ds_read_b128 v[80:83], v189
	ds_read_b128 v[4:7], v187 offset:36864
	ds_read_b128 v[84:87], v189 offset:4608
	ds_read_b128 v[8:11], v187 offset:41472
	ds_read_b128 v[88:91], v189 offset:9216
	ds_read_b128 v[92:95], v188
	v_mfma_f32_32x32x16_bf16 a[80:95], v[20:23], v[24:27], a[80:95]
	v_mfma_f32_32x32x16_bf16 a[112:127], v[20:23], v[28:31], a[112:127]
	v_mfma_f32_32x32x16_bf16 a[16:31], v[76:79], v[24:27], a[16:31]
	v_mfma_f32_32x32x16_bf16 a[0:15], v[76:79], v[28:31], a[0:15]
	s_add_u32 s8, s8, 0x80
	s_addc_u32 s9, s9, 0
	s_cmpk_lg_i32 s8, 0x700
	s_cbranch_scc1 .LBB0_2161
	ds_read_b128 v[0:3], v153
	ds_read_b128 v[80:83], v155 offset:36864
	ds_read_b128 v[84:87], v153 offset:4608
	ds_read_b128 v[88:91], v155 offset:41472
	s_lshl_b32 s75, s74, 8
	s_cmp_gt_u32 s74, 31
	s_waitcnt lgkmcnt(2)
	v_mfma_f32_32x32x16_bf16 a[176:191], v[0:3], v[80:83], a[32:47]
	s_cselect_b64 s[60:61], -1, 0
	s_add_i32 s4, s75, 0xffffe000
	s_lshr_b32 s4, s4, 12
	s_cmp_lt_u32 s74, 32
	s_cselect_b64 s[10:11], -1, 0
	s_and_b64 s[8:9], s[10:11], exec
	s_cselect_b32 s8, 32, 0xf00
	s_waitcnt lgkmcnt(0)
	v_mfma_f32_32x32x16_bf16 a[160:175], v[0:3], v[88:91], a[48:63]
	s_cselect_b32 s95, s74, s4
	s_and_b32 s94, s8, s75
	s_cmp_lt_u32 s73, 16
	s_cselect_b64 s[62:63], -1, 0
	s_mov_b64 s[8:9], -1
	s_and_b64 vcc, exec, s[62:63]
	v_mfma_f32_32x32x16_bf16 a[144:159], v[84:87], v[80:83], a[64:79]
	v_mfma_f32_32x32x16_bf16 a[128:143], v[84:87], v[88:91], a[96:111]
	ds_read_b128 v[0:3], v153 offset:9216
	ds_read_b128 v[84:87], v154
	s_waitcnt vmcnt(11)
	s_waitcnt vmcnt(0)
	ds_write_b128 v156, v[250:253] offset:55296
	s_waitcnt vmcnt(10)
	ds_write_b128 v156, v[246:249] offset:59904
	s_waitcnt vmcnt(9)
	ds_write_b128 v156, v[242:245] offset:64512
	s_waitcnt vmcnt(8)
	ds_write_b128 v55, v[238:241] offset:55296
	s_waitcnt vmcnt(7)
	ds_write_b128 v135, v[234:237] offset:55296
	s_waitcnt vmcnt(6)
	ds_write_b128 v137, v[230:233] offset:55296
	s_waitcnt vmcnt(5)
	ds_write_b128 v139, v[226:229] offset:55296
	s_waitcnt vmcnt(4)
	ds_write_b128 v146, v[222:225] offset:55296
	s_waitcnt vmcnt(3)
	ds_write_b128 v147, v[218:221]
	s_waitcnt vmcnt(2)
	ds_write_b128 v147, v[214:217] offset:4608
	s_waitcnt vmcnt(1)
	ds_write_b128 v147, v[210:213] offset:9216
	s_waitcnt vmcnt(0)
	ds_write_b128 v147, v[206:209] offset:13824
	s_waitcnt lgkmcnt(13)
	v_mfma_f32_32x32x16_bf16 a[64:79], v[0:3], v[80:83], a[80:95]
	v_mfma_f32_32x32x16_bf16 a[48:63], v[0:3], v[88:91], a[112:127]
	ds_read_b128 v[0:3], v153 offset:32
	ds_read_b128 v[4:7], v155 offset:36896
	ds_read_b128 v[8:11], v155 offset:36928
	ds_read_b128 v[12:15], v153 offset:64
	ds_read_b128 v[16:19], v155 offset:41504
	ds_read_b128 v[20:23], v155 offset:36960
	s_waitcnt lgkmcnt(4)
	v_mfma_f32_32x32x16_bf16 a[176:191], v[0:3], v[4:7], a[176:191]
	s_waitcnt lgkmcnt(1)
	v_mfma_f32_32x32x16_bf16 a[160:175], v[0:3], v[16:19], a[160:175]
	ds_read_b128 v[0:3], v153 offset:4640
	ds_read_b128 v[24:27], v153 offset:96
	v_mfma_f32_32x32x16_bf16 a[32:47], v[84:87], v[80:83], a[16:31]
	v_mfma_f32_32x32x16_bf16 a[16:31], v[84:87], v[88:91], a[0:15]
	s_waitcnt lgkmcnt(1)
	v_mfma_f32_32x32x16_bf16 a[144:159], v[0:3], v[4:7], a[144:159]
	v_mfma_f32_32x32x16_bf16 a[128:143], v[0:3], v[16:19], a[128:143]
	ds_read_b128 v[0:3], v153 offset:9248
	ds_read_b128 v[28:31], v153 offset:9280
	s_waitcnt lgkmcnt(1)
	v_mfma_f32_32x32x16_bf16 a[64:79], v[0:3], v[4:7], a[64:79]
	v_mfma_f32_32x32x16_bf16 a[48:63], v[0:3], v[16:19], a[48:63]
	ds_read_b128 v[0:3], v154 offset:32
	ds_read_b128 v[32:35], v153 offset:9312
	s_waitcnt lgkmcnt(1)
	v_mfma_f32_32x32x16_bf16 a[32:47], v[0:3], v[4:7], a[32:47]
	v_mfma_f32_32x32x16_bf16 a[16:31], v[0:3], v[16:19], a[16:31]
	ds_read_b128 v[0:3], v155 offset:41536
	ds_read_b128 v[4:7], v155 offset:41568
	v_mfma_f32_32x32x16_bf16 a[176:191], v[12:15], v[8:11], a[176:191]
	s_waitcnt lgkmcnt(1)
	v_mfma_f32_32x32x16_bf16 a[160:175], v[12:15], v[0:3], a[160:175]
	ds_read_b128 v[12:15], v153 offset:4672
	ds_read_b128 v[16:19], v153 offset:4704
	s_waitcnt lgkmcnt(1)
	v_mfma_f32_32x32x16_bf16 a[144:159], v[12:15], v[8:11], a[144:159]
	v_mfma_f32_32x32x16_bf16 a[128:143], v[12:15], v[0:3], a[128:143]
	v_mfma_f32_32x32x16_bf16 a[64:79], v[28:31], v[8:11], a[64:79]
	v_mfma_f32_32x32x16_bf16 a[48:63], v[28:31], v[0:3], a[48:63]
	ds_read_b128 v[12:15], v154 offset:64
	ds_read_b128 v[28:31], v154 offset:96
	s_waitcnt lgkmcnt(0)
	s_barrier
	v_mfma_f32_32x32x16_bf16 a[32:47], v[12:15], v[8:11], a[32:47]
	v_mfma_f32_32x32x16_bf16 a[16:31], v[12:15], v[0:3], a[16:31]
	v_mfma_f32_32x32x16_bf16 a[176:191], v[24:27], v[20:23], a[176:191]
	v_mfma_f32_32x32x16_bf16 a[160:175], v[24:27], v[4:7], a[160:175]
	v_mfma_f32_32x32x16_bf16 a[144:159], v[16:19], v[20:23], a[144:159]
	v_mfma_f32_32x32x16_bf16 a[128:143], v[16:19], v[4:7], a[128:143]
	v_mfma_f32_32x32x16_bf16 a[64:79], v[32:35], v[20:23], a[64:79]
	v_mfma_f32_32x32x16_bf16 a[48:63], v[32:35], v[4:7], a[48:63]
	v_mfma_f32_32x32x16_bf16 a[32:47], v[28:31], v[20:23], a[32:47]
	v_mfma_f32_32x32x16_bf16 a[16:31], v[28:31], v[4:7], a[16:31]
	ds_read_b128 v[0:3], v153 offset:55296
	ds_read_b128 v[4:7], v148
	ds_read_b128 v[8:11], v153 offset:55328
	ds_read_b128 v[12:15], v148 offset:32
	ds_read_b128 v[16:19], v148 offset:4608
	ds_read_b128 v[20:23], v148 offset:4640
	s_waitcnt lgkmcnt(4)
	v_mfma_f32_32x32x16_bf16 a[176:191], v[0:3], v[4:7], a[176:191]
	s_waitcnt lgkmcnt(1)
	v_mfma_f32_32x32x16_bf16 a[160:175], v[0:3], v[16:19], a[160:175]
	ds_read_b128 v[0:3], v153 offset:59904
	ds_read_b128 v[24:27], v153 offset:59936
	s_waitcnt lgkmcnt(1)
	v_mfma_f32_32x32x16_bf16 a[144:159], v[0:3], v[4:7], a[144:159]
	v_mfma_f32_32x32x16_bf16 a[128:143], v[0:3], v[16:19], a[128:143]
	ds_read_b128 v[0:3], v153 offset:64512
	ds_read_b128 v[28:31], v153 offset:64544
	s_waitcnt lgkmcnt(1)
	v_mfma_f32_32x32x16_bf16 a[64:79], v[0:3], v[4:7], a[64:79]
	v_mfma_f32_32x32x16_bf16 a[48:63], v[0:3], v[16:19], a[48:63]
	ds_read_b128 v[0:3], v154 offset:55296
	ds_read_b128 v[32:35], v154 offset:55328
	s_waitcnt lgkmcnt(1)
	v_mfma_f32_32x32x16_bf16 a[32:47], v[0:3], v[4:7], a[32:47]
	v_mfma_f32_32x32x16_bf16 a[16:31], v[0:3], v[16:19], a[16:31]
	ds_read_b128 v[0:3], v153 offset:55360
	v_mfma_f32_32x32x16_bf16 a[176:191], v[8:11], v[12:15], a[176:191]
	v_mfma_f32_32x32x16_bf16 a[160:175], v[8:11], v[20:23], a[160:175]
	v_mfma_f32_32x32x16_bf16 a[144:159], v[24:27], v[12:15], a[144:159]
	v_mfma_f32_32x32x16_bf16 a[128:143], v[24:27], v[20:23], a[128:143]
	v_mfma_f32_32x32x16_bf16 a[64:79], v[28:31], v[12:15], a[64:79]
	v_mfma_f32_32x32x16_bf16 a[48:63], v[28:31], v[20:23], a[48:63]
	ds_read_b128 v[4:7], v148 offset:64
	ds_read_b128 v[8:11], v154 offset:55360
	ds_read_b128 v[16:19], v154 offset:55392
	ds_read_b128 v[24:27], v153 offset:64576
	ds_read_b128 v[28:31], v153 offset:64608
	ds_read_b128 v[36:39], v153 offset:55392
	ds_read_b128 v[40:43], v148 offset:96
	ds_read_b128 v[44:47], v153 offset:59968
	ds_read_b128 v[76:79], v153 offset:60000
	ds_read_b128 v[80:83], v148 offset:4672
	ds_read_b128 v[84:87], v148 offset:4704
	s_waitcnt lgkmcnt(0)
	s_barrier
	v_mfma_f32_32x32x16_bf16 a[32:47], v[32:35], v[12:15], a[32:47]
	v_mfma_f32_32x32x16_bf16 a[16:31], v[32:35], v[20:23], a[16:31]
	v_mfma_f32_32x32x16_bf16 a[176:191], v[0:3], v[4:7], a[176:191]
	v_mfma_f32_32x32x16_bf16 a[160:175], v[0:3], v[80:83], a[160:175]
	v_mfma_f32_32x32x16_bf16 a[144:159], v[44:47], v[4:7], a[144:159]
	v_mfma_f32_32x32x16_bf16 a[128:143], v[44:47], v[80:83], a[128:143]
	v_mfma_f32_32x32x16_bf16 a[64:79], v[24:27], v[4:7], a[64:79]
	v_mfma_f32_32x32x16_bf16 a[48:63], v[24:27], v[80:83], a[48:63]
	v_mfma_f32_32x32x16_bf16 a[32:47], v[8:11], v[4:7], a[32:47]
	v_mfma_f32_32x32x16_bf16 a[16:31], v[8:11], v[80:83], a[16:31]
	v_mfma_f32_32x32x16_bf16 a[176:191], v[36:39], v[40:43], a[176:191]
	s_nop 11
	ds_write_b32 v136, a176
	ds_write_b32 v136, a177 offset:516
	ds_write_b32 v136, a178 offset:1032
	ds_write_b32 v136, a179 offset:1548
	ds_write_b32 v136, a180 offset:4128
	ds_write_b32 v136, a181 offset:4644
	ds_write_b32 v136, a182 offset:5160
	v_mfma_f32_32x32x16_bf16 a[160:175], v[36:39], v[84:87], a[160:175]
	ds_write_b32 v136, a183 offset:5676
	ds_write_b32 v136, a184 offset:8256
	ds_write_b32 v136, a185 offset:8772
	ds_write_b32 v136, a186 offset:9288
	ds_write_b32 v136, a187 offset:9804
	ds_write_b32 v136, a188 offset:12384
	ds_write_b32 v136, a189 offset:12900
	ds_write_b32 v136, a190 offset:13416
	ds_write_b32 v136, a191 offset:13932
	s_nop 2
	ds_write_b32 v136, a160 offset:128
	ds_write_b32 v136, a161 offset:644
	ds_write_b32 v136, a162 offset:1160
	ds_write_b32 v136, a163 offset:1676
	ds_write_b32 v136, a164 offset:4256
	ds_write_b32 v136, a165 offset:4772
	ds_write_b32 v136, a166 offset:5288
	ds_write_b32 v136, a167 offset:5804
	ds_write_b32 v136, a168 offset:8384
	ds_write_b32 v136, a169 offset:8900
	ds_write_b32 v136, a170 offset:9416
	ds_write_b32 v136, a171 offset:9932
	v_mfma_f32_32x32x16_bf16 a[144:159], v[76:79], v[40:43], a[144:159]
	ds_write_b32 v136, a172 offset:12512
	ds_write_b32 v136, a173 offset:13028
	ds_write_b32 v136, a174 offset:13544
	ds_write_b32 v136, a175 offset:14060
	s_nop 7
	ds_write_b32 v136, a144 offset:16512
	ds_write_b32 v136, a145 offset:17028
	ds_write_b32 v136, a146 offset:17544
	ds_write_b32 v136, a147 offset:18060
	ds_write_b32 v136, a148 offset:20640
	ds_write_b32 v136, a149 offset:21156
	ds_write_b32 v136, a150 offset:21672
	ds_write_b32 v136, a151 offset:22188
	ds_write_b32 v136, a152 offset:24768
	ds_write_b32 v136, a153 offset:25284
	v_mfma_f32_32x32x16_bf16 a[128:143], v[76:79], v[84:87], a[128:143]
	v_lshlrev_b32_e32 v76, 1, v48
	ds_write_b32 v136, a154 offset:25800
	ds_write_b32 v136, a155 offset:26316
	ds_write_b32 v136, a156 offset:28896
	ds_write_b32 v136, a157 offset:29412
	ds_write_b32 v136, a158 offset:29928
	ds_write_b32 v136, a159 offset:30444
	s_nop 4
	ds_write_b32 v136, a128 offset:16640
	ds_write_b32 v136, a129 offset:17156
	ds_write_b32 v136, a130 offset:17672
	ds_write_b32 v136, a131 offset:18188
	ds_write_b32 v136, a132 offset:20768
	ds_write_b32 v136, a133 offset:21284
	ds_write_b32 v136, a134 offset:21800
	ds_write_b32 v136, a135 offset:22316
	v_mfma_f32_32x32x16_bf16 a[64:79], v[28:31], v[40:43], a[64:79]
	ds_write_b32 v136, a136 offset:24896
	ds_write_b32 v136, a137 offset:25412
	ds_write_b32 v136, a138 offset:25928
	ds_write_b32 v136, a139 offset:26444
	ds_write_b32 v136, a140 offset:29024
	ds_write_b32 v136, a141 offset:29540
	ds_write_b32 v136, a142 offset:30056
	ds_write_b32 v136, a143 offset:30572
	s_nop 3
	ds_write_b32 v136, a64 offset:33024
	ds_write_b32 v136, a65 offset:33540
	ds_write_b32 v136, a66 offset:34056
	ds_write_b32 v136, a67 offset:34572
	ds_write_b32 v136, a68 offset:37152
	ds_write_b32 v136, a69 offset:37668
	v_mfma_f32_32x32x16_bf16 a[48:63], v[28:31], v[84:87], a[48:63]
	ds_write_b32 v136, a70 offset:38184
	ds_write_b32 v136, a71 offset:38700
	ds_write_b32 v136, a72 offset:41280
	ds_write_b32 v136, a73 offset:41796
	ds_write_b32 v136, a74 offset:42312
	ds_write_b32 v136, a75 offset:42828
	ds_write_b32 v136, a76 offset:45408
	ds_write_b32 v136, a77 offset:45924
	ds_write_b32 v136, a78 offset:46440
	ds_write_b32 v136, a79 offset:46956
	s_nop 1
	ds_write_b32 v136, a48 offset:33152
	ds_write_b32 v136, a49 offset:33668
	ds_write_b32 v136, a50 offset:34184
	ds_write_b32 v136, a51 offset:34700
	ds_write_b32 v136, a52 offset:37280
	ds_write_b32 v136, a53 offset:37796
	ds_write_b32 v136, a54 offset:38312
	ds_write_b32 v136, a55 offset:38828
	ds_write_b32 v136, a56 offset:41408
	ds_write_b32 v136, a57 offset:41924
	ds_write_b32 v136, a58 offset:42440
	v_mfma_f32_32x32x16_bf16 a[32:47], v[16:19], v[40:43], a[32:47]
	ds_write_b32 v136, a59 offset:42956
	ds_write_b32 v136, a60 offset:45536
	ds_write_b32 v136, a61 offset:46052
	ds_write_b32 v136, a62 offset:46568
	ds_write_b32 v136, a63 offset:47084
	s_nop 6
	ds_write_b32 v136, a32 offset:49536
	ds_write_b32 v136, a33 offset:50052
	ds_write_b32 v136, a34 offset:50568
	ds_write_b32 v136, a35 offset:51084
	ds_write_b32 v136, a36 offset:53664
	ds_write_b32 v136, a37 offset:54180
	ds_write_b32 v136, a38 offset:54696
	ds_write_b32 v136, a39 offset:55212
	ds_write_b32 v136, a40 offset:57792
	v_mfma_f32_32x32x16_bf16 a[16:31], v[16:19], v[84:87], a[16:31]
	ds_write_b32 v136, a41 offset:58308
	ds_write_b32 v136, a42 offset:58824
	ds_write_b32 v136, a43 offset:59340
	ds_write_b32 v136, a44 offset:61920
	ds_write_b32 v136, a45 offset:62436
	ds_write_b32 v136, a46 offset:62952
	ds_write_b32 v136, a47 offset:63468
	s_nop 4
	ds_write_b32 v136, a16 offset:49664
	ds_write_b32 v136, a17 offset:50180
	ds_write_b32 v136, a18 offset:50696
	ds_write_b32 v136, a19 offset:51212
	ds_write_b32 v136, a20 offset:53792
	ds_write_b32 v136, a21 offset:54308
	ds_write_b32 v136, a22 offset:54824
	ds_write_b32 v136, a23 offset:55340
	ds_write_b32 v136, a24 offset:57920
	ds_write_b32 v136, a25 offset:58436
	ds_write_b32 v136, a26 offset:58952
	ds_write_b32 v136, a27 offset:59468
	ds_write_b32 v136, a28 offset:62048
	ds_write_b32 v136, a29 offset:62564
	ds_write_b32 v136, a30 offset:63080
	ds_write_b32 v136, a31 offset:63596
	s_waitcnt lgkmcnt(0)
	s_barrier
	s_cbranch_vccz .LBB0_2179
	v_accvgpr_read_b32 v1, a210
	v_add_u32_e32 v4, s94, v1
	v_add_u32_e32 v0, s75, v1
	v_lshrrev_b32_e32 v1, 6, v4
	v_accvgpr_read_b32 v2, a211
	s_cmp_gt_u32 s73, 7
	v_cndmask_b32_e64 v1, v2, v1, s[6:7]
	s_cselect_b64 s[64:65], -1, 0
	s_add_i32 s8, s73, -8
	v_lshlrev_b32_e32 v50, 7, v1
	s_lshl_b32 s4, s95, 3
	v_mov_b32_e32 v1, v51
	s_add_i32 s68, s4, s8
	s_lshl_b32 s4, s95, 9
	v_add_u32_e32 v2, 0x100, v4
	v_mov_b32_e32 v3, v51
	s_mov_b32 s9, s5
	v_lshlrev_b64 v[0:1], 11, v[0:1]
	s_ashr_i32 s69, s68, 31
	v_lshl_add_u64 v[2:3], v[2:3], 0, s[4:5]
	s_lshl_b64 s[8:9], s[8:9], 1
	v_lshl_add_u64 v[0:1], s[14:15], 0, v[0:1]
	s_lshl_b32 s4, s73, 8
	v_lshl_add_u64 v[80:81], v[2:3], 4, s[8:9]
	v_lshl_add_u64 v[0:1], v[0:1], 0, s[4:5]
	v_mov_b32_e32 v77, v51
	s_lshl_b64 s[8:9], s[68:69], 16
	v_lshl_add_u64 v[82:83], v[0:1], 0, v[76:77]
	v_lshlrev_b32_e32 v0, 7, v4
	v_mov_b32_e32 v1, v51
	v_lshl_add_u64 v[2:3], v[62:63], 0, s[8:9]
	v_lshl_add_u64 v[84:85], v[2:3], 0, v[0:1]
	v_and_b32_e32 v1, 64, v157
	v_xor_b32_e32 v0, 1, v157
	v_add_u32_e32 v1, 64, v1
	v_cmp_lt_i32_e32 vcc, v0, v1
	v_lshl_add_u64 v[78:79], s[12:13], 0, v[50:51]
	s_lshl_b64 s[66:67], s[68:69], 1
	v_cndmask_b32_e32 v0, v157, v0, vcc
	v_mov_b32_e32 v50, v4
	s_mov_b32 s4, 0
	v_lshlrev_b32_e32 v77, 2, v0
	s_mov_b64 s[68:69], -1
	s_branch .LBB0_2166

.LBB0_2271:
	v_lshl_add_u64 v[32:33], v[82:83], 0, v[154:155]
	s_and_b32 s61, s60, 1
	s_waitcnt lgkmcnt(0)
	s_barrier
	v_accvgpr_read_b32 v184, a0
	v_accvgpr_read_b32 v185, a0
	v_accvgpr_read_b32 v186, a0
	v_accvgpr_read_b32 v187, a0
	v_accvgpr_read_b32 v188, a0
	v_accvgpr_read_b32 v189, a0
	v_accvgpr_read_b32 v190, a0
	v_accvgpr_read_b32 v191, a0
	v_accvgpr_read_b32 v192, a0
	v_accvgpr_read_b32 v193, a0
	v_accvgpr_read_b32 v194, a0
	v_accvgpr_read_b32 v195, a0
	v_accvgpr_read_b32 v196, a0
	v_accvgpr_read_b32 v197, a0
	v_accvgpr_read_b32 v198, a0
	v_accvgpr_read_b32 v199, a0
	v_accvgpr_read_b32 v168, a0
	v_accvgpr_read_b32 v169, a0
	v_accvgpr_read_b32 v170, a0
	v_accvgpr_read_b32 v171, a0
	v_accvgpr_read_b32 v172, a0
	v_accvgpr_read_b32 v173, a0
	v_accvgpr_read_b32 v174, a0
	v_accvgpr_read_b32 v175, a0
	v_accvgpr_read_b32 v176, a0
	v_accvgpr_read_b32 v177, a0
	v_accvgpr_read_b32 v178, a0
	v_accvgpr_read_b32 v179, a0
	v_accvgpr_read_b32 v180, a0
	v_accvgpr_read_b32 v181, a0
	v_accvgpr_read_b32 v182, a0
	v_accvgpr_read_b32 v183, a0
	v_accvgpr_read_b32 v200, a0
	v_accvgpr_read_b32 v201, a0
	v_accvgpr_read_b32 v202, a0
	v_accvgpr_read_b32 v203, a0
	v_accvgpr_read_b32 v204, a0
	v_accvgpr_read_b32 v205, a0
	v_accvgpr_read_b32 v206, a0
	v_accvgpr_read_b32 v207, a0
	v_accvgpr_read_b32 v208, a0
	v_accvgpr_read_b32 v209, a0
	v_accvgpr_read_b32 v210, a0
	v_accvgpr_read_b32 v211, a0
	v_accvgpr_read_b32 v212, a0
	v_accvgpr_read_b32 v213, a0
	v_accvgpr_read_b32 v214, a0
	v_accvgpr_read_b32 v215, a0
	v_accvgpr_read_b32 v100, a0
	v_accvgpr_read_b32 v101, a0
	v_accvgpr_read_b32 v102, a0
	v_accvgpr_read_b32 v103, a0
	v_accvgpr_read_b32 v104, a0
	v_accvgpr_read_b32 v105, a0
	v_accvgpr_read_b32 v106, a0
	v_accvgpr_read_b32 v107, a0
	v_accvgpr_read_b32 v108, a0
	v_accvgpr_read_b32 v109, a0
	v_accvgpr_read_b32 v110, a0
	v_accvgpr_read_b32 v111, a0
	v_accvgpr_read_b32 v112, a0
	v_accvgpr_read_b32 v113, a0
	v_accvgpr_read_b32 v114, a0
	v_accvgpr_read_b32 v115, a0
	global_load_dwordx4 v[64:67], v[32:33], off
	v_lshl_add_u64 v[32:33], v[84:85], 0, v[154:155]
	s_xor_b32 s62, s61, 1
	global_load_dwordx4 v[68:71], v[32:33], off
	v_lshl_add_u64 v[32:33], v[86:87], 0, v[154:155]
	s_mulk_i32 s61, 0x4800
	global_load_dwordx4 v[72:75], v[32:33], off
	v_lshl_add_u64 v[32:33], v[88:89], 0, v[154:155]
	v_add_u32_e32 v40, s61, v128
	global_load_dwordx4 v[76:79], v[32:33], off
	ds_read_b128 a[144:147], v40
	ds_read_b128 a[148:151], v40 offset:32
	ds_read_b128 a[152:155], v40 offset:64
	ds_read_b128 a[156:159], v40 offset:96
	s_waitcnt vmcnt(11)
	s_waitcnt lgkmcnt(3)
	v_mfma_f32_32x32x16_bf16 v[184:199], a[144:147], v[28:31], v[184:199]
	s_waitcnt vmcnt(7)
	v_mfma_f32_32x32x16_bf16 v[168:183], a[144:147], v[12:15], v[168:183]
	ds_read_b128 a[144:147], v40 offset:4608
	s_waitcnt lgkmcnt(3)
	v_mfma_f32_32x32x16_bf16 v[184:199], a[148:151], v[24:27], v[184:199]
	s_waitcnt vmcnt(6)
	v_mfma_f32_32x32x16_bf16 v[168:183], a[148:151], v[8:11], v[168:183]
	ds_read_b128 a[148:151], v40 offset:4640
	s_waitcnt lgkmcnt(3)
	v_mfma_f32_32x32x16_bf16 v[184:199], a[152:155], v[20:23], v[184:199]
	s_mulk_i32 s62, 0x4800
	s_add_i32 s60, s60, 1
	s_waitcnt vmcnt(5)
	v_mfma_f32_32x32x16_bf16 v[168:183], a[152:155], v[4:7], v[168:183]
	ds_read_b128 a[152:155], v40 offset:4672
	v_lshl_add_u64 v[82:83], v[82:83], 0, s[54:55]
	v_lshl_add_u64 v[84:85], v[84:85], 0, s[54:55]
	v_lshl_add_u64 v[86:87], v[86:87], 0, s[54:55]
	v_lshl_add_u64 v[88:89], v[88:89], 0, s[54:55]
	s_cmp_eq_u32 s4, s60
	s_waitcnt lgkmcnt(3)
	v_mfma_f32_32x32x16_bf16 v[184:199], a[156:159], v[16:19], v[184:199]
	s_waitcnt vmcnt(4)
	v_mfma_f32_32x32x16_bf16 v[168:183], a[156:159], v[0:3], v[168:183]
	ds_read_b128 a[156:159], v40 offset:4704
	s_waitcnt lgkmcnt(3)
	v_mfma_f32_32x32x16_bf16 v[200:215], a[144:147], v[28:31], v[200:215]
	v_mfma_f32_32x32x16_bf16 v[100:115], a[144:147], v[12:15], v[100:115]
	s_waitcnt lgkmcnt(2)
	v_mfma_f32_32x32x16_bf16 v[200:215], a[148:151], v[24:27], v[200:215]
	v_mfma_f32_32x32x16_bf16 v[100:115], a[148:151], v[8:11], v[100:115]
	s_waitcnt lgkmcnt(1)
	v_mfma_f32_32x32x16_bf16 v[200:215], a[152:155], v[20:23], v[200:215]
	v_mfma_f32_32x32x16_bf16 v[100:115], a[152:155], v[4:7], v[100:115]
	s_waitcnt lgkmcnt(0)
	v_mfma_f32_32x32x16_bf16 v[200:215], a[156:159], v[16:19], v[200:215]
	v_mfma_f32_32x32x16_bf16 v[100:115], a[156:159], v[0:3], v[100:115]
	v_exp_f32_e32 v45, v184
	v_exp_f32_e32 v47, v185
	v_exp_f32_e32 v49, v186
	v_exp_f32_e32 v51, v187
	v_exp_f32_e32 v53, v188
	v_exp_f32_e32 v55, v189
	v_exp_f32_e32 v99, v190
	v_exp_f32_e32 v117, v191
	v_exp_f32_e32 v119, v192
	v_exp_f32_e32 v121, v193
	v_exp_f32_e32 v123, v194
	v_exp_f32_e32 v125, v195
	v_exp_f32_e32 v127, v196
	v_exp_f32_e32 v131, v197
	v_exp_f32_e32 v133, v198
	v_exp_f32_e32 v137, v199
	v_exp_f32_e32 v141, v200
	v_exp_f32_e32 v143, v201
	v_exp_f32_e32 v145, v202
	v_exp_f32_e32 v217, v203
	v_exp_f32_e32 v219, v204
	v_exp_f32_e32 v221, v205
	v_exp_f32_e32 v223, v206
	v_exp_f32_e32 v225, v207
	v_exp_f32_e32 v227, v208
	v_exp_f32_e32 v229, v209
	v_exp_f32_e32 v231, v210
	v_exp_f32_e32 v233, v211
	v_exp_f32_e32 v235, v212
	v_exp_f32_e32 v237, v213
	v_exp_f32_e32 v239, v214
	v_exp_f32_e32 v241, v215
	v_exp_f32_e32 v44, v168
	v_exp_f32_e32 v46, v169
	v_exp_f32_e32 v48, v170
	v_exp_f32_e32 v50, v171
	v_exp_f32_e32 v52, v172
	v_exp_f32_e32 v54, v173
	v_exp_f32_e32 v98, v174
	v_exp_f32_e32 v116, v175
	v_exp_f32_e32 v118, v176
	v_exp_f32_e32 v120, v177
	v_exp_f32_e32 v122, v178
	v_pk_add_f32 v[32:33], v[44:45], 0 op_sel_hi:[1,0]
	v_pk_add_f32 v[32:33], v[46:47], v[32:33]
	v_exp_f32_e32 v222, v106
	v_pk_add_f32 v[32:33], v[48:49], v[32:33]
	v_pk_add_f32 v[32:33], v[50:51], v[32:33]
	v_exp_f32_e32 v224, v107
	v_pk_add_f32 v[32:33], v[52:53], v[32:33]
	v_pk_add_f32 v[32:33], v[54:55], v[32:33]
	v_exp_f32_e32 v226, v108
	v_pk_add_f32 v[32:33], v[98:99], v[32:33]
	v_pk_add_f32 v[32:33], v[116:117], v[32:33]
	v_exp_f32_e32 v228, v109
	v_pk_add_f32 v[32:33], v[118:119], v[32:33]
	v_pk_add_f32 v[32:33], v[120:121], v[32:33]
	v_exp_f32_e32 v230, v110
	v_pk_add_f32 v[40:41], v[122:123], v[32:33]
	v_exp_f32_e32 v124, v179
	v_exp_f32_e32 v126, v180
	v_exp_f32_e32 v130, v181
	v_exp_f32_e32 v132, v182
	v_exp_f32_e32 v136, v183
	v_pk_add_f32 v[40:41], v[124:125], v[40:41]
	v_exp_f32_e32 v140, v100
	v_pk_add_f32 v[40:41], v[126:127], v[40:41]
	v_exp_f32_e32 v142, v101
	v_pk_add_f32 v[40:41], v[130:131], v[40:41]
	v_exp_f32_e32 v144, v102
	v_pk_add_f32 v[40:41], v[132:133], v[40:41]
	v_exp_f32_e32 v216, v103
	v_pk_add_f32 v[40:41], v[136:137], v[40:41]
	v_exp_f32_e32 v218, v104
	v_pk_add_f32 v[40:41], v[140:141], v[40:41]
	v_exp_f32_e32 v220, v105
	v_pk_add_f32 v[40:41], v[142:143], v[40:41]
	v_pk_add_f32 v[40:41], v[144:145], v[40:41]
	v_exp_f32_e32 v232, v111
	v_pk_add_f32 v[40:41], v[216:217], v[40:41]
	v_pk_add_f32 v[40:41], v[218:219], v[40:41]
	v_exp_f32_e32 v234, v112
	v_pk_add_f32 v[40:41], v[220:221], v[40:41]
	v_pk_add_f32 v[40:41], v[222:223], v[40:41]
	v_exp_f32_e32 v236, v113
	v_pk_add_f32 v[40:41], v[224:225], v[40:41]
	v_pk_add_f32 v[40:41], v[226:227], v[40:41]
	v_exp_f32_e32 v238, v114
	v_pk_add_f32 v[40:41], v[228:229], v[40:41]
	v_pk_add_f32 v[40:41], v[230:231], v[40:41]
	v_cvt_pk_bf16_f32 v59, v99, v117
	v_exp_f32_e32 v240, v115
	v_pk_add_f32 v[40:41], v[232:233], v[40:41]
	v_cvt_pk_bf16_f32 v63, v98, v116
	v_add3_u32 v98, s62, v151, v134
	v_add3_u32 v99, s62, v156, v134
	v_cvt_pk_bf16_f32 v58, v53, v55
	v_pk_add_f32 v[40:41], v[234:235], v[40:41]
	v_cvt_pk_bf16_f32 v53, v122, v124
	s_waitcnt vmcnt(3)
	ds_write_b128 v98, v[64:67]
	s_waitcnt vmcnt(2)
	ds_write_b128 v99, v[68:71]
	s_waitcnt vmcnt(1)
	ds_write_b128 v98, v[72:75] offset:9216
	s_waitcnt vmcnt(0)
	ds_write_b128 v99, v[76:79] offset:9216
	v_lshl_add_u64 v[64:65], v[90:91], 0, v[154:155]
	v_lshl_add_u64 v[68:69], v[92:93], 0, v[154:155]
	v_lshl_add_u64 v[72:73], v[94:95], 0, v[154:155]
	v_lshl_add_u64 v[76:77], v[96:97], 0, v[154:155]
	v_add_u32_e32 v124, s61, v150
	v_cvt_pk_bf16_f32 v36, v119, v121
	v_cvt_pk_bf16_f32 v37, v123, v125
	v_pk_add_f32 v[40:41], v[236:237], v[40:41]
	v_cvt_pk_bf16_f32 v62, v52, v54
	v_cvt_pk_bf16_f32 v52, v118, v120
	global_load_dwordx4 v[64:67], v[64:65], off
	v_pk_add_f32 v[40:41], v[238:239], v[40:41]
	global_load_dwordx4 v[68:71], v[68:69], off
	v_pk_add_f32 v[60:61], v[240:241], v[40:41]
	global_load_dwordx4 v[72:75], v[72:73], off
	v_cvt_pk_bf16_f32 v56, v45, v47
	global_load_dwordx4 v[76:79], v[76:77], off
	ds_read_b128 a[144:147], v124 offset:36864
	ds_read_b128 a[148:151], v124 offset:36896
	ds_read_b128 a[152:155], v124 offset:36928
	ds_read_b128 a[156:159], v124 offset:36960
	v_cvt_pk_bf16_f32 v57, v49, v51
	v_pk_add_f32 v[80:81], v[80:81], v[60:61]
	v_cvt_pk_bf16_f32 v60, v44, v46
	v_cvt_pk_bf16_f32 v61, v48, v50
	s_waitcnt lgkmcnt(3)
	v_mfma_f32_32x32x16_bf16 a[128:143], a[144:147], v[56:59], a[128:143]
	v_cvt_pk_bf16_f32 v38, v127, v131
	v_cvt_pk_bf16_f32 v39, v133, v137
	v_cvt_pk_bf16_f32 v54, v126, v130
	v_cvt_pk_bf16_f32 v55, v132, v136
	v_cvt_pk_bf16_f32 v32, v141, v143
	v_cvt_pk_bf16_f32 v33, v145, v217
	v_cvt_pk_bf16_f32 v34, v219, v221
	v_mfma_f32_32x32x16_bf16 a[112:127], a[144:147], v[60:63], a[112:127]
	ds_read_b128 a[144:147], v124 offset:41472
	v_cvt_pk_bf16_f32 v35, v223, v225
	v_cvt_pk_bf16_f32 v48, v140, v142
	v_cvt_pk_bf16_f32 v49, v144, v216
	v_cvt_pk_bf16_f32 v50, v218, v220
	v_cvt_pk_bf16_f32 v51, v222, v224
	v_cvt_pk_bf16_f32 v40, v227, v229
	s_waitcnt lgkmcnt(3)
	v_mfma_f32_32x32x16_bf16 a[128:143], a[148:151], v[36:39], a[128:143]
	v_cvt_pk_bf16_f32 v41, v231, v233
	v_cvt_pk_bf16_f32 v42, v235, v237
	v_cvt_pk_bf16_f32 v43, v239, v241
	v_cvt_pk_bf16_f32 v44, v226, v228
	v_cvt_pk_bf16_f32 v45, v230, v232
	v_cvt_pk_bf16_f32 v46, v234, v236
	v_cvt_pk_bf16_f32 v47, v238, v240
	v_mfma_f32_32x32x16_bf16 a[112:127], a[148:151], v[52:55], a[112:127]
	ds_read_b128 a[148:151], v124 offset:41504
	s_waitcnt lgkmcnt(3)
	v_mfma_f32_32x32x16_bf16 a[128:143], a[152:155], v[32:35], a[128:143]
	v_mfma_f32_32x32x16_bf16 a[112:127], a[152:155], v[48:51], a[112:127]
	ds_read_b128 a[152:155], v124 offset:41536
	s_waitcnt lgkmcnt(3)
	v_mfma_f32_32x32x16_bf16 a[128:143], a[156:159], v[40:43], a[128:143]
	v_mfma_f32_32x32x16_bf16 a[112:127], a[156:159], v[44:47], a[112:127]
	ds_read_b128 a[156:159], v124 offset:41568
	s_waitcnt lgkmcnt(3)
	v_mfma_f32_32x32x16_bf16 a[48:63], a[144:147], v[56:59], a[48:63]
	v_mfma_f32_32x32x16_bf16 a[64:79], a[144:147], v[60:63], a[64:79]
	ds_read_b128 a[144:147], v124 offset:46080
	s_waitcnt lgkmcnt(3)
	v_mfma_f32_32x32x16_bf16 a[48:63], a[148:151], v[36:39], a[48:63]
	v_mfma_f32_32x32x16_bf16 a[64:79], a[148:151], v[52:55], a[64:79]
	ds_read_b128 a[148:151], v124 offset:46112
	s_waitcnt lgkmcnt(3)
	v_mfma_f32_32x32x16_bf16 a[48:63], a[152:155], v[32:35], a[48:63]
	v_lshl_add_u64 v[90:91], v[90:91], 0, s[56:57]
	v_lshl_add_u64 v[92:93], v[92:93], 0, s[56:57]
	v_mfma_f32_32x32x16_bf16 a[64:79], a[152:155], v[48:51], a[64:79]
	ds_read_b128 a[152:155], v124 offset:46144
	v_lshl_add_u64 v[94:95], v[94:95], 0, s[56:57]
	v_lshl_add_u64 v[96:97], v[96:97], 0, s[56:57]
	s_waitcnt lgkmcnt(3)
	v_mfma_f32_32x32x16_bf16 a[48:63], a[156:159], v[40:43], a[48:63]
	v_mfma_f32_32x32x16_bf16 a[64:79], a[156:159], v[44:47], a[64:79]
	ds_read_b128 a[156:159], v124 offset:46176
	s_waitcnt lgkmcnt(3)
	v_mfma_f32_32x32x16_bf16 a[80:95], a[144:147], v[56:59], a[80:95]
	v_mfma_f32_32x32x16_bf16 a[96:111], a[144:147], v[60:63], a[96:111]
	ds_read_b128 a[144:147], v124 offset:50688
	s_waitcnt lgkmcnt(3)
	v_mfma_f32_32x32x16_bf16 a[80:95], a[148:151], v[36:39], a[80:95]
	v_mfma_f32_32x32x16_bf16 a[96:111], a[148:151], v[52:55], a[96:111]
	ds_read_b128 a[148:151], v124 offset:50720
	s_waitcnt lgkmcnt(3)
	v_mfma_f32_32x32x16_bf16 a[80:95], a[152:155], v[32:35], a[80:95]
	v_mfma_f32_32x32x16_bf16 a[96:111], a[152:155], v[48:51], a[96:111]
	ds_read_b128 a[152:155], v124 offset:50752
	s_waitcnt lgkmcnt(3)
	v_mfma_f32_32x32x16_bf16 a[80:95], a[156:159], v[40:43], a[80:95]
	v_mfma_f32_32x32x16_bf16 a[96:111], a[156:159], v[44:47], a[96:111]
	ds_read_b128 a[156:159], v124 offset:50784
	s_waitcnt lgkmcnt(3)
	v_mfma_f32_32x32x16_bf16 a[32:47], a[144:147], v[56:59], a[32:47]
	v_mfma_f32_32x32x16_bf16 a[16:31], a[144:147], v[60:63], a[16:31]
	s_waitcnt lgkmcnt(2)
	v_mfma_f32_32x32x16_bf16 a[32:47], a[148:151], v[36:39], a[32:47]
	v_mfma_f32_32x32x16_bf16 a[16:31], a[148:151], v[52:55], a[16:31]
	s_waitcnt lgkmcnt(1)
	v_mfma_f32_32x32x16_bf16 a[32:47], a[152:155], v[32:35], a[32:47]
	s_waitcnt vmcnt(3)
	ds_write_b128 v98, v[64:67] offset:36864
	s_waitcnt vmcnt(2)
	ds_write_b128 v99, v[68:71] offset:36864
	v_mfma_f32_32x32x16_bf16 a[16:31], a[152:155], v[48:51], a[16:31]
	s_waitcnt lgkmcnt(2)
	v_mfma_f32_32x32x16_bf16 a[32:47], a[156:159], v[40:43], a[32:47]
	v_mfma_f32_32x32x16_bf16 a[16:31], a[156:159], v[44:47], a[16:31]
	v_add3_u32 v32, s62, v157, v134
	s_waitcnt vmcnt(1)
	ds_write_b128 v32, v[72:75] offset:36864
	v_add3_u32 v32, s62, v158, v134
	s_waitcnt vmcnt(0)
	ds_write_b128 v32, v[76:79] offset:36864
	s_cbranch_scc0 .LBB0_2271
	s_bitcmp1_b32 s4, 0
	s_cselect_b32 s4, 0x4800, 0
	v_add_u32_e32 v48, s4, v128
	s_waitcnt lgkmcnt(0)
	s_barrier
	ds_read_b128 v[32:35], v48
	ds_read_b128 v[36:39], v48 offset:32
	s_waitcnt lgkmcnt(1)
	v_mfma_f32_32x32x16_bf16 a[186:201], v[32:35], v[28:31], a[0:15]
	v_add_u32_e32 v83, s4, v150
	v_mfma_f32_32x32x16_bf16 a[144:159], v[32:35], v[12:15], a[0:15]
	s_waitcnt lgkmcnt(0)
	v_mfma_f32_32x32x16_bf16 a[186:201], v[36:39], v[24:27], a[186:201]
	v_mfma_f32_32x32x16_bf16 a[144:159], v[36:39], v[8:11], a[144:159]
	ds_read_b128 v[32:35], v48 offset:64
	ds_read_b128 v[36:39], v48 offset:96
	s_waitcnt lgkmcnt(1)
	v_mfma_f32_32x32x16_bf16 a[186:201], v[32:35], v[20:23], a[186:201]
	s_waitcnt lgkmcnt(0)
	v_mfma_f32_32x32x16_bf16 a[186:201], v[36:39], v[16:19], a[186:201]
	v_mfma_f32_32x32x16_bf16 a[144:159], v[32:35], v[4:7], a[144:159]
	ds_read_b128 v[32:35], v48 offset:4608
	ds_read_b128 v[40:43], v48 offset:4640
	ds_read_b128 v[44:47], v48 offset:4672
	ds_read_b128 v[48:51], v48 offset:4704
	s_nop 6
	v_accvgpr_read_b32 v52, a186
	v_accvgpr_read_b32 v53, a187
	v_accvgpr_read_b32 v54, a188
	v_exp_f32_e32 v52, v52
	v_exp_f32_e32 v53, v53
	s_waitcnt lgkmcnt(3)
	v_mfma_f32_32x32x16_bf16 a[172:187], v[32:35], v[28:31], a[0:15]
	v_accvgpr_read_b32 v28, a189
	v_exp_f32_e32 v55, v28
	v_accvgpr_read_b32 v28, a190
	v_exp_f32_e32 v56, v28
	v_accvgpr_read_b32 v28, a191
	v_exp_f32_e32 v54, v54
	v_exp_f32_e32 v57, v28
	s_waitcnt lgkmcnt(2)
	v_mfma_f32_32x32x16_bf16 a[172:187], v[40:43], v[24:27], a[172:187]
	v_accvgpr_read_b32 v24, a192
	v_exp_f32_e32 v58, v24
	v_accvgpr_read_b32 v24, a193
	v_exp_f32_e32 v59, v24
	v_accvgpr_read_b32 v24, a194
	v_exp_f32_e32 v60, v24
	v_accvgpr_read_b32 v24, a195
	s_waitcnt lgkmcnt(1)
	v_mfma_f32_32x32x16_bf16 a[172:187], v[44:47], v[20:23], a[172:187]
	v_accvgpr_read_b32 v20, a196
	v_exp_f32_e32 v62, v20
	v_accvgpr_read_b32 v20, a197
	v_exp_f32_e32 v63, v20
	v_accvgpr_read_b32 v20, a198
	v_exp_f32_e32 v64, v20
	v_exp_f32_e32 v61, v24
	s_waitcnt lgkmcnt(0)
	v_mfma_f32_32x32x16_bf16 a[172:187], v[48:51], v[16:19], a[172:187]
	v_accvgpr_read_b32 v16, a199
	v_exp_f32_e32 v65, v16
	v_accvgpr_read_b32 v16, a200
	v_exp_f32_e32 v66, v16
	v_accvgpr_read_b32 v16, a201
	v_exp_f32_e32 v67, v16
	ds_read_b128 v[28:31], v83 offset:36928
	v_mfma_f32_32x32x16_bf16 a[144:159], v[36:39], v[0:3], a[144:159]
	s_nop 3
	v_accvgpr_read_b32 v16, a172
	v_exp_f32_e32 v36, v16
	v_accvgpr_read_b32 v16, a173
	v_exp_f32_e32 v37, v16
	v_accvgpr_read_b32 v16, a174
	v_exp_f32_e32 v38, v16
	v_accvgpr_read_b32 v16, a175
	v_mfma_f32_32x32x16_bf16 a[160:175], v[32:35], v[12:15], a[0:15]
	v_exp_f32_e32 v39, v16
	v_accvgpr_read_b32 v16, a144
	v_accvgpr_read_b32 v12, a176
	v_exp_f32_e32 v68, v12
	v_accvgpr_read_b32 v12, a177
	v_accvgpr_read_b32 v20, a157
	v_exp_f32_e32 v69, v12
	v_mfma_f32_32x32x16_bf16 a[160:175], v[40:43], v[8:11], a[160:175]
	v_accvgpr_read_b32 v12, a178
	v_exp_f32_e32 v84, v20
	v_accvgpr_read_b32 v20, a158
	v_exp_f32_e32 v70, v12
	v_accvgpr_read_b32 v12, a179
	v_exp_f32_e32 v85, v20
	v_accvgpr_read_b32 v20, a159
	v_mfma_f32_32x32x16_bf16 a[160:175], v[44:47], v[4:7], a[160:175]
	v_exp_f32_e32 v40, v12
	v_cvt_pk_bf16_f32 v12, v52, v53
	v_cvt_pk_bf16_f32 v13, v54, v55
	v_cvt_pk_bf16_f32 v14, v56, v57
	v_cvt_pk_bf16_f32 v15, v58, v59
	v_exp_f32_e32 v86, v20
	ds_read_b128 v[20:23], v83 offset:36896
	v_mfma_f32_32x32x16_bf16 a[160:175], v[48:51], v[0:3], a[160:175]
	v_exp_f32_e32 v49, v16
	v_accvgpr_read_b32 v16, a145
	v_exp_f32_e32 v50, v16
	v_accvgpr_read_b32 v16, a146
	v_exp_f32_e32 v51, v16
	v_accvgpr_read_b32 v16, a147
	v_exp_f32_e32 v71, v16
	v_accvgpr_read_b32 v16, a148
	v_exp_f32_e32 v72, v16
	v_accvgpr_read_b32 v16, a149
	v_exp_f32_e32 v73, v16
	v_accvgpr_read_b32 v16, a150
	v_exp_f32_e32 v74, v16
	v_accvgpr_read_b32 v16, a151
	v_exp_f32_e32 v75, v16
	v_accvgpr_read_b32 v16, a152
	v_exp_f32_e32 v76, v16
	v_accvgpr_read_b32 v16, a153
	v_exp_f32_e32 v77, v16
	v_accvgpr_read_b32 v16, a154
	v_exp_f32_e32 v78, v16
	v_accvgpr_read_b32 v16, a155
	v_exp_f32_e32 v79, v16
	v_accvgpr_read_b32 v16, a156
	v_exp_f32_e32 v82, v16
	ds_read_b128 v[16:19], v83 offset:36864
	v_accvgpr_read_b32 v24, a160
	v_exp_f32_e32 v87, v24
	v_accvgpr_read_b32 v24, a161
	v_exp_f32_e32 v88, v24
	v_cvt_pk_bf16_f32 v24, v49, v50
	v_cvt_pk_bf16_f32 v25, v51, v71
	v_cvt_pk_bf16_f32 v26, v72, v73
	v_cvt_pk_bf16_f32 v27, v74, v75
	s_waitcnt lgkmcnt(0)
	v_mfma_f32_32x32x16_bf16 a[144:159], v[16:19], v[12:15], a[128:143]
	v_accvgpr_read_b32 v8, a180
	v_exp_f32_e32 v41, v8
	v_accvgpr_read_b32 v8, a181
	v_exp_f32_e32 v42, v8
	v_accvgpr_read_b32 v8, a182
	v_exp_f32_e32 v43, v8
	v_cvt_pk_bf16_f32 v8, v60, v61
	v_mfma_f32_32x32x16_bf16 a[128:143], v[16:19], v[24:27], a[112:127]
	v_accvgpr_read_b32 v16, a162
	v_exp_f32_e32 v89, v16
	v_accvgpr_read_b32 v16, a163
	v_exp_f32_e32 v90, v16
	v_accvgpr_read_b32 v16, a164
	v_exp_f32_e32 v91, v16
	v_accvgpr_read_b32 v16, a165
	v_cvt_pk_bf16_f32 v9, v62, v63
	v_cvt_pk_bf16_f32 v10, v64, v65
	v_cvt_pk_bf16_f32 v11, v66, v67
	v_exp_f32_e32 v92, v16
	v_cvt_pk_bf16_f32 v16, v76, v77
	v_cvt_pk_bf16_f32 v17, v78, v79
	v_cvt_pk_bf16_f32 v18, v82, v84
	v_cvt_pk_bf16_f32 v19, v85, v86
	v_mfma_f32_32x32x16_bf16 a[144:159], v[20:23], v[8:11], a[144:159]
	v_accvgpr_read_b32 v32, a166
	v_accvgpr_read_b32 v4, a183
	v_exp_f32_e32 v93, v32
	v_exp_f32_e32 v44, v4
	v_accvgpr_read_b32 v4, a184
	v_exp_f32_e32 v45, v4
	v_accvgpr_read_b32 v4, a185
	v_mfma_f32_32x32x16_bf16 a[128:143], v[20:23], v[16:19], a[128:143]
	v_accvgpr_read_b32 v20, a167
	v_exp_f32_e32 v94, v20
	v_accvgpr_read_b32 v32, a169
	v_exp_f32_e32 v46, v4
	v_accvgpr_read_b32 v4, a186
	v_exp_f32_e32 v96, v32
	v_accvgpr_read_b32 v32, a170
	v_exp_f32_e32 v47, v4
	v_cvt_pk_bf16_f32 v4, v36, v37
	v_cvt_pk_bf16_f32 v5, v38, v39
	v_cvt_pk_bf16_f32 v6, v68, v69
	v_cvt_pk_bf16_f32 v7, v70, v40
	v_accvgpr_read_b32 v20, a168
	v_exp_f32_e32 v97, v32
	v_cvt_pk_bf16_f32 v32, v87, v88
	v_cvt_pk_bf16_f32 v33, v89, v90
	v_cvt_pk_bf16_f32 v34, v91, v92
	v_cvt_pk_bf16_f32 v35, v93, v94
	v_exp_f32_e32 v95, v20
	ds_read_b128 v[20:23], v83 offset:36960
	v_mfma_f32_32x32x16_bf16 a[144:159], v[28:31], v[4:7], a[144:159]
	v_accvgpr_read_b32 v0, a187
	v_exp_f32_e32 v48, v0
	v_cvt_pk_bf16_f32 v0, v41, v42
	v_cvt_pk_bf16_f32 v1, v43, v44
	v_cvt_pk_bf16_f32 v2, v45, v46
	v_cvt_pk_bf16_f32 v3, v47, v48
	v_cvt_pk_bf16_f32 v130, v95, v96
	v_mfma_f32_32x32x16_bf16 a[128:143], v[28:31], v[32:35], a[128:143]
	v_accvgpr_read_b32 v28, a171
	v_exp_f32_e32 v98, v28
	v_accvgpr_read_b32 v28, a172
	v_exp_f32_e32 v99, v28
	v_accvgpr_read_b32 v28, a173
	v_exp_f32_e32 v100, v28
	v_accvgpr_read_b32 v28, a174
	v_exp_f32_e32 v101, v28
	v_accvgpr_read_b32 v28, a175
	v_exp_f32_e32 v102, v28
	v_cvt_pk_bf16_f32 v131, v97, v98
	v_cvt_pk_bf16_f32 v132, v99, v100
	s_waitcnt lgkmcnt(0)
	v_mfma_f32_32x32x16_bf16 a[144:159], v[20:23], v[0:3], a[144:159]
	v_cvt_pk_bf16_f32 v133, v101, v102
	s_nop 1
	v_mfma_f32_32x32x16_bf16 a[128:143], v[20:23], v[130:133], a[128:143]
	ds_read_b128 v[20:23], v83 offset:41472
	ds_read_b128 v[28:31], v83 offset:41504
	s_nop 5
	v_accvgpr_read_b32 v112, a144
	v_accvgpr_read_b32 v113, a145
	v_accvgpr_read_b32 v114, a146
	v_accvgpr_read_b32 v115, a147
	s_waitcnt lgkmcnt(1)
	v_mfma_f32_32x32x16_bf16 a[112:127], v[20:23], v[12:15], a[48:63]
	v_accvgpr_read_b32 v116, a148
	v_accvgpr_read_b32 v117, a149
	v_accvgpr_read_b32 v118, a150
	v_accvgpr_read_b32 v119, a151
	v_accvgpr_read_b32 v120, a152
	v_accvgpr_read_b32 v121, a153
	v_accvgpr_read_b32 v122, a154
	v_mfma_f32_32x32x16_bf16 a[48:63], v[20:23], v[24:27], a[64:79]
	v_accvgpr_read_b32 v123, a155
	v_accvgpr_read_b32 v124, a156
	v_accvgpr_read_b32 v125, a157
	v_accvgpr_read_b32 v126, a158
	v_accvgpr_read_b32 v127, a159
	s_waitcnt lgkmcnt(0)
	v_mfma_f32_32x32x16_bf16 a[112:127], v[28:31], v[8:11], a[112:127]
	v_mfma_f32_32x32x16_bf16 a[48:63], v[28:31], v[16:19], a[48:63]
	ds_read_b128 v[20:23], v83 offset:41536
	ds_read_b128 v[28:31], v83 offset:41568
	s_waitcnt lgkmcnt(1)
	v_mfma_f32_32x32x16_bf16 a[112:127], v[20:23], v[4:7], a[112:127]
	v_mfma_f32_32x32x16_bf16 a[48:63], v[20:23], v[32:35], a[48:63]
	s_waitcnt lgkmcnt(0)
	v_mfma_f32_32x32x16_bf16 a[112:127], v[28:31], v[0:3], a[112:127]
	v_mfma_f32_32x32x16_bf16 a[48:63], v[28:31], v[130:133], a[48:63]
	ds_read_b128 v[20:23], v83 offset:46080
	ds_read_b128 v[28:31], v83 offset:46112
	s_waitcnt lgkmcnt(1)
	v_mfma_f32_32x32x16_bf16 a[64:79], v[20:23], v[12:15], a[80:95]
	v_mfma_f32_32x32x16_bf16 a[80:95], v[20:23], v[24:27], a[96:111]
	ds_read_b128 v[20:23], v83 offset:46144
	s_waitcnt lgkmcnt(1)
	v_mfma_f32_32x32x16_bf16 a[64:79], v[28:31], v[8:11], a[64:79]
	v_mfma_f32_32x32x16_bf16 a[80:95], v[28:31], v[16:19], a[80:95]
	v_add_f32_e32 v28, 0, v52
	v_add_f32_e32 v28, v53, v28
	v_add_f32_e32 v28, v54, v28
	v_add_f32_e32 v28, v55, v28
	v_add_f32_e32 v52, v56, v28
	v_add_f32_e32 v52, v57, v52
	v_add_f32_e32 v52, v58, v52
	v_add_f32_e32 v52, v59, v52
	v_add_f32_e32 v52, v60, v52
	v_add_f32_e32 v52, v61, v52
	v_add_f32_e32 v52, v62, v52
	v_add_f32_e32 v52, v63, v52
	ds_read_b128 v[28:31], v83 offset:46176
	s_waitcnt lgkmcnt(1)
	v_mfma_f32_32x32x16_bf16 a[64:79], v[20:23], v[4:7], a[64:79]
	v_mfma_f32_32x32x16_bf16 a[80:95], v[20:23], v[32:35], a[80:95]
	v_add_f32_e32 v20, v64, v52
	v_add_f32_e32 v20, v65, v20
	v_add_f32_e32 v20, v66, v20
	v_add_f32_e32 v20, v67, v20
	v_add_f32_e32 v20, v36, v20
	v_add_f32_e32 v20, v37, v20
	v_add_f32_e32 v20, v38, v20
	v_add_f32_e32 v20, v39, v20
	v_add_f32_e32 v20, v68, v20
	v_add_f32_e32 v20, v69, v20
	v_add_f32_e32 v20, v70, v20
	v_add_f32_e32 v20, v40, v20
	v_add_f32_e32 v36, v41, v20
	ds_read_b128 v[20:23], v83 offset:50688
	s_waitcnt lgkmcnt(1)
	v_mfma_f32_32x32x16_bf16 a[64:79], v[28:31], v[0:3], a[64:79]
	v_mfma_f32_32x32x16_bf16 a[80:95], v[28:31], v[130:133], a[80:95]
	v_add_f32_e32 v28, v42, v36
	v_add_f32_e32 v28, v43, v28
	v_add_f32_e32 v28, v44, v28
	v_add_f32_e32 v28, v45, v28
	v_add_f32_e32 v28, v46, v28
	v_add_f32_e32 v36, v47, v28
	ds_read_b128 v[28:31], v83 offset:50720
	s_waitcnt lgkmcnt(1)
	v_mfma_f32_32x32x16_bf16 a[96:111], v[20:23], v[12:15], a[32:47]
	v_add_f32_e32 v12, v48, v36
	v_add_f32_e32 v136, v81, v12
	v_add_f32_e32 v12, 0, v49
	v_add_f32_e32 v12, v50, v12
	v_add_f32_e32 v12, v51, v12
	v_add_f32_e32 v12, v71, v12
	v_add_f32_e32 v12, v72, v12
	v_add_f32_e32 v12, v73, v12
	v_add_f32_e32 v12, v74, v12
	v_add_f32_e32 v12, v75, v12
	v_add_f32_e32 v12, v76, v12
	v_add_f32_e32 v12, v77, v12
	v_add_f32_e32 v12, v78, v12
	v_add_f32_e32 v12, v79, v12
	s_waitcnt lgkmcnt(0)
	v_mfma_f32_32x32x16_bf16 a[96:111], v[28:31], v[8:11], a[96:111]
	v_add_f32_e32 v8, v82, v12
	v_add_f32_e32 v8, v84, v8
	v_add_f32_e32 v8, v85, v8
	v_add_f32_e32 v8, v86, v8
	v_add_f32_e32 v8, v87, v8
	v_add_f32_e32 v12, v88, v8
	ds_read_b128 v[8:11], v83 offset:50752
	v_mfma_f32_32x32x16_bf16 a[32:47], v[20:23], v[24:27], a[16:31]
	v_add_f32_e32 v12, v89, v12
	v_add_f32_e32 v12, v90, v12
	v_add_f32_e32 v12, v91, v12
	v_add_f32_e32 v12, v92, v12
	v_add_f32_e32 v12, v93, v12
	v_accvgpr_read_b32 v48, a128
	v_accvgpr_read_b32 v49, a129
	v_mfma_f32_32x32x16_bf16 a[32:47], v[28:31], v[16:19], a[32:47]
	v_add_f32_e32 v16, v94, v12
	ds_read_b128 v[12:15], v83 offset:50784
	v_accvgpr_read_b32 v50, a130
	v_accvgpr_read_b32 v51, a131
	v_accvgpr_read_b32 v52, a132
	v_accvgpr_read_b32 v53, a133
	v_accvgpr_read_b32 v54, a134
	s_waitcnt lgkmcnt(1)
	v_mfma_f32_32x32x16_bf16 a[96:111], v[8:11], v[4:7], a[96:111]
	v_add_f32_e32 v4, v95, v16
	v_add_f32_e32 v4, v96, v4
	v_add_f32_e32 v4, v97, v4
	v_add_f32_e32 v4, v98, v4
	v_add_f32_e32 v4, v99, v4
	v_add_f32_e32 v4, v100, v4
	v_add_f32_e32 v4, v101, v4
	v_add_f32_e32 v4, v102, v4
	v_add_f32_e32 v137, v80, v4
	ds_bpermute_b32 v4, v159, v136
	v_mfma_f32_32x32x16_bf16 a[32:47], v[8:11], v[32:35], a[32:47]
	v_accvgpr_read_b32 v96, a112
	v_accvgpr_read_b32 v32, a48
	v_accvgpr_read_b32 v95, a79
	s_waitcnt lgkmcnt(0)
	v_add_f32_e32 v136, v136, v4
	v_div_scale_f32 v140, s[60:61], v136, v136, 1.0
	v_rcp_f32_e32 v141, v140
	v_mfma_f32_32x32x16_bf16 a[32:47], v[12:15], v[130:133], a[32:47]
	ds_bpermute_b32 v131, v159, v137
	v_accvgpr_read_b32 v16, a80
	v_fma_f32 v130, -v140, v141, 1.0
	v_fmac_f32_e32 v141, v130, v141
	v_div_scale_f32 v130, vcc, 1.0, v136, 1.0
	v_mul_f32_e32 v132, v130, v141
	v_fma_f32 v133, -v140, v132, v130
	s_waitcnt lgkmcnt(0)
	v_add_f32_e32 v131, v137, v131
	v_fmac_f32_e32 v132, v133, v141
	v_div_scale_f32 v133, s[60:61], v131, v131, 1.0
	v_rcp_f32_e32 v137, v133
	v_mfma_f32_32x32x16_bf16 a[96:111], v[12:15], v[0:3], a[96:111]
	v_fma_f32 v130, -v140, v132, v130
	v_div_fmas_f32 v130, v130, v141, v132
	v_div_fixup_f32 v222, v130, v136, 1.0
	v_fma_f32 v130, -v133, v137, 1.0
	v_fmac_f32_e32 v137, v130, v137
	v_div_scale_f32 v130, vcc, 1.0, v131, 1.0
	v_mul_f32_e32 v132, v130, v137
	v_fma_f32 v136, -v133, v132, v130
	v_fmac_f32_e32 v132, v136, v137
	v_fma_f32 v130, -v133, v132, v130
	v_accvgpr_read_b32 v0, a32
	s_nop 0
	v_accvgpr_read_b32 v64, a96
	v_div_fmas_f32 v130, v130, v137, v132
	v_accvgpr_read_b32 v55, a135
	v_accvgpr_read_b32 v56, a136
	v_accvgpr_read_b32 v57, a137
	v_accvgpr_read_b32 v58, a138
	v_accvgpr_read_b32 v59, a139
	v_accvgpr_read_b32 v60, a140
	v_accvgpr_read_b32 v61, a141
	v_accvgpr_read_b32 v62, a142
	v_accvgpr_read_b32 v63, a143
	v_accvgpr_read_b32 v97, a113
	v_accvgpr_read_b32 v98, a114
	v_accvgpr_read_b32 v99, a115
	v_accvgpr_read_b32 v100, a116
	v_accvgpr_read_b32 v101, a117
	v_accvgpr_read_b32 v102, a118
	v_accvgpr_read_b32 v103, a119
	v_accvgpr_read_b32 v104, a120
	v_accvgpr_read_b32 v105, a121
	v_accvgpr_read_b32 v106, a122
	v_accvgpr_read_b32 v107, a123
	v_accvgpr_read_b32 v108, a124
	v_accvgpr_read_b32 v109, a125
	v_accvgpr_read_b32 v110, a126
	v_accvgpr_read_b32 v111, a127
	v_accvgpr_read_b32 v33, a49
	v_accvgpr_read_b32 v34, a50
	v_accvgpr_read_b32 v35, a51
	v_accvgpr_read_b32 v36, a52
	v_accvgpr_read_b32 v37, a53
	v_accvgpr_read_b32 v38, a54
	v_accvgpr_read_b32 v39, a55
	v_accvgpr_read_b32 v40, a56
	v_accvgpr_read_b32 v41, a57
	v_accvgpr_read_b32 v42, a58
	v_accvgpr_read_b32 v43, a59
	v_accvgpr_read_b32 v44, a60
	v_accvgpr_read_b32 v45, a61
	v_accvgpr_read_b32 v46, a62
	v_accvgpr_read_b32 v47, a63
	v_accvgpr_read_b32 v94, a78
	v_accvgpr_read_b32 v93, a77
	v_accvgpr_read_b32 v92, a76
	v_accvgpr_read_b32 v91, a75
	v_accvgpr_read_b32 v90, a74
	v_accvgpr_read_b32 v89, a73
	v_accvgpr_read_b32 v88, a72
	v_accvgpr_read_b32 v87, a71
	v_accvgpr_read_b32 v86, a70
	v_accvgpr_read_b32 v85, a69
	v_accvgpr_read_b32 v84, a68
	v_accvgpr_read_b32 v83, a67
	v_accvgpr_read_b32 v82, a66
	v_accvgpr_read_b32 v81, a65
	v_accvgpr_read_b32 v80, a64
	v_accvgpr_read_b32 v17, a81
	v_accvgpr_read_b32 v18, a82
	v_accvgpr_read_b32 v19, a83
	v_accvgpr_read_b32 v20, a84
	v_accvgpr_read_b32 v21, a85
	v_accvgpr_read_b32 v22, a86
	v_accvgpr_read_b32 v23, a87
	v_accvgpr_read_b32 v24, a88
	v_accvgpr_read_b32 v25, a89
	v_accvgpr_read_b32 v26, a90
	v_accvgpr_read_b32 v27, a91
	v_accvgpr_read_b32 v28, a92
	v_accvgpr_read_b32 v29, a93
	v_accvgpr_read_b32 v30, a94
	v_accvgpr_read_b32 v31, a95
	v_accvgpr_read_b32 v65, a97
	v_accvgpr_read_b32 v66, a98
	v_accvgpr_read_b32 v67, a99
	v_accvgpr_read_b32 v68, a100
	v_accvgpr_read_b32 v69, a101
	v_accvgpr_read_b32 v70, a102
	v_accvgpr_read_b32 v71, a103
	v_accvgpr_read_b32 v72, a104
	v_accvgpr_read_b32 v73, a105
	v_accvgpr_read_b32 v74, a106
	v_accvgpr_read_b32 v75, a107
	v_accvgpr_read_b32 v76, a108
	v_accvgpr_read_b32 v77, a109
	v_accvgpr_read_b32 v78, a110
	v_accvgpr_read_b32 v79, a111
	v_accvgpr_read_b32 v1, a33
	v_accvgpr_read_b32 v2, a34
	v_accvgpr_read_b32 v3, a35
	v_accvgpr_read_b32 v4, a36
	v_accvgpr_read_b32 v5, a37
	v_accvgpr_read_b32 v6, a38
	v_accvgpr_read_b32 v7, a39
	v_accvgpr_read_b32 v8, a40
	v_accvgpr_read_b32 v9, a41
	v_accvgpr_read_b32 v10, a42
	v_accvgpr_read_b32 v11, a43
	v_accvgpr_read_b32 v12, a44
	v_accvgpr_read_b32 v13, a45
	v_accvgpr_read_b32 v14, a46
	v_accvgpr_read_b32 v15, a47
	v_div_fixup_f32 v168, v130, v131, 1.0
	s_barrier
	s_and_saveexec_b64 s[60:61], s[6:7]
	s_cbranch_execz .LBB0_2274
	v_accvgpr_read_b32 v133, a216
	v_mul_f32_e32 v130, v133, v222
	v_mul_f32_e32 v131, v112, v130
	v_mul_f32_e32 v132, v113, v130
	ds_write2st64_b32 v139, v131, v132 offset1:1
	v_mul_f32_e32 v131, v114, v130
	v_mul_f32_e32 v132, v115, v130
	ds_write2st64_b32 v139, v131, v132 offset0:2 offset1:3
	v_mul_f32_e32 v131, v116, v130
	v_mul_f32_e32 v132, v117, v130
	ds_write2st64_b32 v139, v131, v132 offset0:4 offset1:5
	v_mul_f32_e32 v131, v118, v130
	v_mul_f32_e32 v132, v119, v130
	ds_write2st64_b32 v139, v131, v132 offset0:6 offset1:7
	v_mul_f32_e32 v131, v120, v130
	v_mul_f32_e32 v132, v121, v130
	ds_write2st64_b32 v139, v131, v132 offset0:8 offset1:9
	v_mul_f32_e32 v131, v122, v130
	v_mul_f32_e32 v132, v123, v130
	ds_write2st64_b32 v139, v131, v132 offset0:10 offset1:11
	v_mul_f32_e32 v131, v124, v130
	v_mul_f32_e32 v132, v125, v130
	ds_write2st64_b32 v139, v131, v132 offset0:12 offset1:13
	v_mul_f32_e32 v131, v126, v130
	v_mul_f32_e32 v132, v127, v130
	ds_write2st64_b32 v139, v131, v132 offset0:14 offset1:15
	v_mul_f32_e32 v131, v96, v130
	v_mul_f32_e32 v132, v97, v130
	ds_write2st64_b32 v139, v131, v132 offset0:16 offset1:17
	v_mul_f32_e32 v131, v98, v130
	v_mul_f32_e32 v132, v99, v130
	ds_write2st64_b32 v139, v131, v132 offset0:18 offset1:19
	v_mul_f32_e32 v131, v100, v130
	v_mul_f32_e32 v132, v101, v130
	ds_write2st64_b32 v139, v131, v132 offset0:20 offset1:21
	v_mul_f32_e32 v131, v102, v130
	v_mul_f32_e32 v132, v103, v130
	ds_write2st64_b32 v139, v131, v132 offset0:22 offset1:23
	v_mul_f32_e32 v131, v104, v130
	v_mul_f32_e32 v132, v105, v130
	ds_write2st64_b32 v139, v131, v132 offset0:24 offset1:25
	v_mul_f32_e32 v131, v106, v130
	v_mul_f32_e32 v132, v107, v130
	ds_write2st64_b32 v139, v131, v132 offset0:26 offset1:27
	v_mul_f32_e32 v131, v108, v130
	v_mul_f32_e32 v132, v109, v130
	ds_write2st64_b32 v139, v131, v132 offset0:28 offset1:29
	v_mul_f32_e32 v131, v110, v130
	v_mul_f32_e32 v132, v111, v130
	ds_write2st64_b32 v139, v131, v132 offset0:30 offset1:31
	v_mul_f32_e32 v131, v80, v130
	v_mul_f32_e32 v132, v81, v130
	ds_write2st64_b32 v139, v131, v132 offset0:32 offset1:33
	v_mul_f32_e32 v131, v82, v130
	v_mul_f32_e32 v132, v83, v130
	ds_write2st64_b32 v139, v131, v132 offset0:34 offset1:35
	v_mul_f32_e32 v131, v84, v130
	v_mul_f32_e32 v132, v85, v130
	ds_write2st64_b32 v139, v131, v132 offset0:36 offset1:37
	v_mul_f32_e32 v131, v86, v130
	v_mul_f32_e32 v132, v87, v130
	ds_write2st64_b32 v139, v131, v132 offset0:38 offset1:39
	v_mul_f32_e32 v131, v88, v130
	v_mul_f32_e32 v132, v89, v130
	ds_write2st64_b32 v139, v131, v132 offset0:40 offset1:41
	v_mul_f32_e32 v131, v90, v130
	v_mul_f32_e32 v132, v91, v130
	ds_write2st64_b32 v139, v131, v132 offset0:42 offset1:43
	v_mul_f32_e32 v131, v92, v130
	v_mul_f32_e32 v132, v93, v130
	ds_write2st64_b32 v139, v131, v132 offset0:44 offset1:45
	v_mul_f32_e32 v131, v94, v130
	v_mul_f32_e32 v132, v95, v130
	ds_write2st64_b32 v139, v131, v132 offset0:46 offset1:47
	v_mul_f32_e32 v131, v64, v130
	v_mul_f32_e32 v132, v65, v130
	ds_write2st64_b32 v139, v131, v132 offset0:48 offset1:49
	v_mul_f32_e32 v131, v66, v130
	v_mul_f32_e32 v132, v67, v130
	ds_write2st64_b32 v139, v131, v132 offset0:50 offset1:51
	v_mul_f32_e32 v131, v68, v130
	v_mul_f32_e32 v132, v69, v130
	ds_write2st64_b32 v139, v131, v132 offset0:52 offset1:53
	v_mul_f32_e32 v131, v70, v130
	v_mul_f32_e32 v132, v71, v130
	ds_write2st64_b32 v139, v131, v132 offset0:54 offset1:55
	v_mul_f32_e32 v131, v72, v130
	v_mul_f32_e32 v132, v73, v130
	ds_write2st64_b32 v139, v131, v132 offset0:56 offset1:57
	v_mul_f32_e32 v131, v74, v130
	v_mul_f32_e32 v132, v75, v130
	ds_write2st64_b32 v139, v131, v132 offset0:58 offset1:59
	v_mul_f32_e32 v131, v76, v130
	v_mul_f32_e32 v132, v77, v130
	ds_write2st64_b32 v139, v131, v132 offset0:60 offset1:61
	v_mul_f32_e32 v131, v78, v130
	v_mul_f32_e32 v130, v79, v130
	ds_write2st64_b32 v139, v131, v130 offset0:62 offset1:63
	v_mul_f32_e32 v130, v133, v168
	v_mul_f32_e32 v131, v48, v130
	v_mul_f32_e32 v132, v49, v130
	ds_write2st64_b32 v254, v131, v132 offset1:1
	v_mul_f32_e32 v131, v50, v130
	v_mul_f32_e32 v132, v51, v130
	ds_write2st64_b32 v254, v131, v132 offset0:2 offset1:3
	v_mul_f32_e32 v131, v52, v130
	v_mul_f32_e32 v132, v53, v130
	ds_write2st64_b32 v254, v131, v132 offset0:4 offset1:5
	v_mul_f32_e32 v131, v54, v130
	v_mul_f32_e32 v132, v55, v130
	ds_write2st64_b32 v254, v131, v132 offset0:6 offset1:7
	v_mul_f32_e32 v131, v56, v130
	v_mul_f32_e32 v132, v57, v130
	ds_write2st64_b32 v254, v131, v132 offset0:8 offset1:9
	v_mul_f32_e32 v131, v58, v130
	v_mul_f32_e32 v132, v59, v130
	ds_write2st64_b32 v254, v131, v132 offset0:10 offset1:11
	v_mul_f32_e32 v131, v60, v130
	v_mul_f32_e32 v132, v61, v130
	ds_write2st64_b32 v254, v131, v132 offset0:12 offset1:13
	v_mul_f32_e32 v131, v62, v130
	v_mul_f32_e32 v132, v63, v130
	ds_write2st64_b32 v254, v131, v132 offset0:14 offset1:15
	v_mul_f32_e32 v131, v32, v130
	v_mul_f32_e32 v132, v33, v130
	ds_write2st64_b32 v254, v131, v132 offset0:16 offset1:17
	v_mul_f32_e32 v131, v34, v130
	v_mul_f32_e32 v132, v35, v130
	ds_write2st64_b32 v254, v131, v132 offset0:18 offset1:19
	v_mul_f32_e32 v131, v36, v130
	v_mul_f32_e32 v132, v37, v130
	ds_write2st64_b32 v254, v131, v132 offset0:20 offset1:21
	v_mul_f32_e32 v131, v38, v130
	v_mul_f32_e32 v132, v39, v130
	ds_write2st64_b32 v254, v131, v132 offset0:22 offset1:23
	v_mul_f32_e32 v131, v40, v130
	v_mul_f32_e32 v132, v41, v130
	ds_write2st64_b32 v254, v131, v132 offset0:24 offset1:25
	v_mul_f32_e32 v131, v42, v130
	v_mul_f32_e32 v132, v43, v130
	ds_write2st64_b32 v254, v131, v132 offset0:26 offset1:27
	v_mul_f32_e32 v131, v44, v130
	v_mul_f32_e32 v132, v45, v130
	ds_write2st64_b32 v254, v131, v132 offset0:28 offset1:29
	v_mul_f32_e32 v131, v46, v130
	v_mul_f32_e32 v132, v47, v130
	ds_write2st64_b32 v254, v131, v132 offset0:30 offset1:31
	v_mul_f32_e32 v131, v16, v130
	v_mul_f32_e32 v132, v17, v130
	ds_write2st64_b32 v254, v131, v132 offset0:32 offset1:33
	v_mul_f32_e32 v131, v18, v130
	v_mul_f32_e32 v132, v19, v130
	ds_write2st64_b32 v254, v131, v132 offset0:34 offset1:35
	v_mul_f32_e32 v131, v20, v130
	v_mul_f32_e32 v132, v21, v130
	ds_write2st64_b32 v254, v131, v132 offset0:36 offset1:37
	v_mul_f32_e32 v131, v22, v130
	v_mul_f32_e32 v132, v23, v130
	ds_write2st64_b32 v254, v131, v132 offset0:38 offset1:39
	v_mul_f32_e32 v131, v24, v130
	v_mul_f32_e32 v132, v25, v130
	ds_write2st64_b32 v254, v131, v132 offset0:40 offset1:41
	v_mul_f32_e32 v131, v26, v130
	v_mul_f32_e32 v132, v27, v130
	ds_write2st64_b32 v254, v131, v132 offset0:42 offset1:43
	v_mul_f32_e32 v131, v28, v130
	v_mul_f32_e32 v132, v29, v130
	ds_write2st64_b32 v254, v131, v132 offset0:44 offset1:45
	v_mul_f32_e32 v131, v30, v130
	v_mul_f32_e32 v132, v31, v130
	ds_write2st64_b32 v254, v131, v132 offset0:46 offset1:47
	v_mul_f32_e32 v131, v0, v130
	v_mul_f32_e32 v132, v1, v130
	ds_write2st64_b32 v254, v131, v132 offset0:48 offset1:49
	v_mul_f32_e32 v131, v2, v130
	v_mul_f32_e32 v132, v3, v130
	ds_write2st64_b32 v254, v131, v132 offset0:50 offset1:51
	v_mul_f32_e32 v131, v4, v130
	v_mul_f32_e32 v132, v5, v130
	ds_write2st64_b32 v254, v131, v132 offset0:52 offset1:53
	v_mul_f32_e32 v131, v6, v130
	v_mul_f32_e32 v132, v7, v130
	ds_write2st64_b32 v254, v131, v132 offset0:54 offset1:55
	v_mul_f32_e32 v131, v8, v130
	v_mul_f32_e32 v132, v9, v130
	ds_write2st64_b32 v254, v131, v132 offset0:56 offset1:57
	v_mul_f32_e32 v131, v10, v130
	v_mul_f32_e32 v132, v11, v130
	ds_write2st64_b32 v254, v131, v132 offset0:58 offset1:59
	v_mul_f32_e32 v131, v12, v130
	v_mul_f32_e32 v132, v13, v130
	ds_write2st64_b32 v254, v131, v132 offset0:60 offset1:61
	v_mul_f32_e32 v131, v14, v130
	v_mul_f32_e32 v130, v15, v130
	ds_write2st64_b32 v254, v131, v130 offset0:62 offset1:63

.LBB0_2449:
	s_and_b32 s50, s42, 1
	s_mul_i32 s51, s50, 0xd800
	s_xor_b32 s50, s50, 1
	s_mul_i32 s50, s50, 0xd800
	s_add_i32 s42, s42, 1
	v_add_u32_e32 v186, s50, v45
	ds_read_b128 v[68:71], v189 offset:32
	ds_read_b128 v[80:83], v187 offset:36896
	ds_read_b128 v[72:75], v189 offset:4640
	ds_read_b128 v[84:87], v187 offset:41504
	ds_read_b128 v[76:79], v189 offset:9248
	ds_read_b128 v[104:107], v188 offset:32
	s_waitcnt lgkmcnt(6)
	v_mfma_f32_32x32x16_bf16 a[32:47], v[108:111], v[14:17], a[32:47]
	s_waitcnt vmcnt(11)
	ds_write_b128 v186, v[250:253]
	v_mfma_f32_32x32x16_bf16 a[48:63], v[108:111], v[64:67], a[48:63]
	s_waitcnt vmcnt(10)
	ds_write_b128 v186, v[246:249] offset:4608
	global_load_dwordx4 v[250:253], v254, s[100:101] offset:512
	v_mfma_f32_32x32x16_bf16 a[64:79], v[112:115], v[14:17], a[64:79]
	s_waitcnt vmcnt(10)
	ds_write_b128 v186, v[242:245] offset:9216
	global_load_dwordx4 v[246:249], v205, s[100:101] offset:512
	v_mfma_f32_32x32x16_bf16 a[96:111], v[112:115], v[64:67], a[96:111]
	s_waitcnt vmcnt(10)
	ds_write_b128 v186, v[238:241] offset:13824
	global_load_dwordx4 v[242:245], v204, s[100:101] offset:512
	v_mfma_f32_32x32x16_bf16 a[80:95], v[116:119], v[14:17], a[80:95]
	s_waitcnt vmcnt(10)
	ds_write_b128 v186, v[234:237] offset:18432
	global_load_dwordx4 v[238:241], v203, s[100:101] offset:512
	v_mfma_f32_32x32x16_bf16 a[112:127], v[116:119], v[64:67], a[112:127]
	s_waitcnt vmcnt(10)
	ds_write_b128 v186, v[230:233] offset:23040
	global_load_dwordx4 v[234:237], v202, s[100:101] offset:512
	s_waitcnt lgkmcnt(6)
	v_mfma_f32_32x32x16_bf16 a[16:31], v[120:123], v[14:17], a[16:31]
	s_waitcnt vmcnt(10)
	ds_write_b128 v186, v[226:229] offset:27648
	global_load_dwordx4 v[230:233], v201, s[100:101] offset:512
	v_mfma_f32_32x32x16_bf16 a[0:15], v[120:123], v[64:67], a[0:15]
	s_waitcnt vmcnt(10)
	ds_write_b128 v186, v[222:225] offset:32256
	global_load_dwordx4 v[226:229], v200, s[100:101] offset:512
	s_waitcnt lgkmcnt(8)
	ds_read_b128 v[108:111], v189 offset:64
	ds_read_b128 v[14:17], v187 offset:36928
	ds_read_b128 v[112:115], v189 offset:4672
	ds_read_b128 v[64:67], v187 offset:41536
	ds_read_b128 v[116:119], v189 offset:9280
	ds_read_b128 v[120:123], v188 offset:64
	v_mfma_f32_32x32x16_bf16 a[32:47], v[68:71], v[80:83], a[32:47]
	s_waitcnt lgkmcnt(12)
	s_waitcnt vmcnt(10)
	ds_write_b128 v186, v[218:221] offset:36864
	global_load_dwordx4 v[222:225], v199, s[100:101] offset:512
	v_mfma_f32_32x32x16_bf16 a[48:63], v[68:71], v[84:87], a[48:63]
	s_waitcnt lgkmcnt(12)
	s_waitcnt vmcnt(10)
	ds_write_b128 v186, v[214:217] offset:41472
	global_load_dwordx4 v[218:221], v198, s[98:99] offset:256
	v_mfma_f32_32x32x16_bf16 a[64:79], v[72:75], v[80:83], a[64:79]
	s_waitcnt lgkmcnt(12)
	s_waitcnt vmcnt(10)
	ds_write_b128 v186, v[210:213] offset:46080
	global_load_dwordx4 v[214:217], v197, s[98:99] offset:256
	v_mfma_f32_32x32x16_bf16 a[96:111], v[72:75], v[84:87], a[96:111]
	s_waitcnt lgkmcnt(12)
	s_waitcnt vmcnt(10)
	ds_write_b128 v186, v[206:209] offset:50688
	global_load_dwordx4 v[210:213], v196, s[98:99] offset:256
	v_mfma_f32_32x32x16_bf16 a[80:95], v[76:79], v[80:83], a[80:95]
	global_load_dwordx4 v[206:209], v195, s[98:99] offset:256
	s_add_u32 s100, s100, 0x80
	s_addc_u32 s101, s101, 0
	s_add_u32 s98, s98, 0x80
	s_addc_u32 s99, s99, 0
	v_mfma_f32_32x32x16_bf16 a[112:127], v[76:79], v[84:87], a[112:127]
	v_mfma_f32_32x32x16_bf16 a[16:31], v[104:107], v[80:83], a[16:31]
	v_mfma_f32_32x32x16_bf16 a[0:15], v[104:107], v[84:87], a[0:15]
	s_waitcnt lgkmcnt(4)
	ds_read_b128 v[68:71], v189 offset:96
	ds_read_b128 v[80:83], v187 offset:36960
	ds_read_b128 v[72:75], v189 offset:4704
	ds_read_b128 v[84:87], v187 offset:41568
	ds_read_b128 v[76:79], v189 offset:9312
	ds_read_b128 v[104:107], v188 offset:96
	v_mfma_f32_32x32x16_bf16 a[32:47], v[108:111], v[14:17], a[32:47]
	v_mfma_f32_32x32x16_bf16 a[48:63], v[108:111], v[64:67], a[48:63]
	v_mfma_f32_32x32x16_bf16 a[64:79], v[112:115], v[14:17], a[64:79]
	v_mfma_f32_32x32x16_bf16 a[96:111], v[112:115], v[64:67], a[96:111]
	v_mfma_f32_32x32x16_bf16 a[80:95], v[116:119], v[14:17], a[80:95]
	v_mfma_f32_32x32x16_bf16 a[112:127], v[116:119], v[64:67], a[112:127]
	v_mfma_f32_32x32x16_bf16 a[16:31], v[120:123], v[14:17], a[16:31]
	v_mfma_f32_32x32x16_bf16 a[0:15], v[120:123], v[64:67], a[0:15]
	s_waitcnt lgkmcnt(0)
	v_mfma_f32_32x32x16_bf16 a[32:47], v[68:71], v[80:83], a[32:47]
	v_mfma_f32_32x32x16_bf16 a[48:63], v[68:71], v[84:87], a[48:63]
	v_mfma_f32_32x32x16_bf16 a[64:79], v[72:75], v[80:83], a[64:79]
	v_mfma_f32_32x32x16_bf16 a[96:111], v[72:75], v[84:87], a[96:111]
	s_barrier
	v_add_u32_e32 v189, s50, v192
	v_add_u32_e32 v188, s50, v191
	v_add_u32_e32 v187, s50, v190
	ds_read_b128 v[108:111], v189
	ds_read_b128 v[14:17], v187 offset:36864
	ds_read_b128 v[112:115], v189 offset:4608
	ds_read_b128 v[64:67], v187 offset:41472
	ds_read_b128 v[116:119], v189 offset:9216
	ds_read_b128 v[120:123], v188
	v_mfma_f32_32x32x16_bf16 a[80:95], v[76:79], v[80:83], a[80:95]
	v_mfma_f32_32x32x16_bf16 a[112:127], v[76:79], v[84:87], a[112:127]
	v_mfma_f32_32x32x16_bf16 a[16:31], v[104:107], v[80:83], a[16:31]
	v_mfma_f32_32x32x16_bf16 a[0:15], v[104:107], v[84:87], a[0:15]
	s_add_u32 s44, s44, 0x80
	s_addc_u32 s45, s45, 0
	s_cmpk_lg_i32 s44, 0x700
	s_cbranch_scc1 .LBB0_2449
	ds_read_b128 v[10:13], v60
	ds_read_b128 v[108:111], v62 offset:36864
	ds_read_b128 v[112:115], v60 offset:4608
	ds_read_b128 v[116:119], v62 offset:41472
	s_lshl_b32 s44, s48, 8
	s_lshl_b32 s42, s49, 8
	s_waitcnt lgkmcnt(2)
	v_mfma_f32_32x32x16_bf16 a[176:191], v[10:13], v[108:111], a[32:47]
	s_add_i32 s47, s47, s76
	s_add_i32 s46, s46, s76
	s_waitcnt lgkmcnt(0)
	v_mfma_f32_32x32x16_bf16 a[160:175], v[10:13], v[116:119], a[48:63]
	v_mfma_f32_32x32x16_bf16 a[144:159], v[112:115], v[108:111], a[64:79]
	v_mfma_f32_32x32x16_bf16 a[128:143], v[112:115], v[116:119], a[96:111]
	ds_read_b128 v[10:13], v60 offset:9216
	ds_read_b128 v[112:115], v61
	s_waitcnt vmcnt(11)
	s_waitcnt vmcnt(0)
	ds_write_b128 v63, v[250:253] offset:55296
	s_waitcnt vmcnt(10)
	ds_write_b128 v63, v[246:249] offset:59904
	s_waitcnt vmcnt(9)
	ds_write_b128 v63, v[242:245] offset:64512
	s_waitcnt vmcnt(8)
	ds_write_b128 v50, v[238:241] offset:55296
	s_waitcnt vmcnt(7)
	ds_write_b128 v51, v[234:237] offset:55296
	s_waitcnt vmcnt(6)
	ds_write_b128 v52, v[230:233] offset:55296
	s_waitcnt vmcnt(5)
	ds_write_b128 v53, v[226:229] offset:55296
	s_waitcnt vmcnt(4)
	ds_write_b128 v54, v[222:225] offset:55296
	s_waitcnt vmcnt(3)
	ds_write_b128 v55, v[218:221]
	s_waitcnt vmcnt(2)
	ds_write_b128 v55, v[214:217] offset:4608
	s_waitcnt vmcnt(1)
	ds_write_b128 v55, v[210:213] offset:9216
	s_waitcnt vmcnt(0)
	ds_write_b128 v55, v[206:209] offset:13824
	s_waitcnt lgkmcnt(13)
	v_mfma_f32_32x32x16_bf16 a[64:79], v[10:13], v[108:111], a[80:95]
	v_mfma_f32_32x32x16_bf16 a[48:63], v[10:13], v[116:119], a[112:127]
	ds_read_b128 v[10:13], v60 offset:32
	ds_read_b128 v[14:17], v62 offset:36896
	ds_read_b128 v[64:67], v62 offset:36928
	ds_read_b128 v[68:71], v60 offset:64
	ds_read_b128 v[72:75], v62 offset:41504
	ds_read_b128 v[76:79], v62 offset:36960
	s_waitcnt lgkmcnt(4)
	v_mfma_f32_32x32x16_bf16 a[176:191], v[10:13], v[14:17], a[176:191]
	s_waitcnt lgkmcnt(1)
	v_mfma_f32_32x32x16_bf16 a[160:175], v[10:13], v[72:75], a[160:175]
	ds_read_b128 v[10:13], v60 offset:4640
	ds_read_b128 v[80:83], v60 offset:96
	v_mfma_f32_32x32x16_bf16 a[32:47], v[112:115], v[108:111], a[16:31]
	v_mfma_f32_32x32x16_bf16 a[16:31], v[112:115], v[116:119], a[0:15]
	s_waitcnt lgkmcnt(1)
	v_mfma_f32_32x32x16_bf16 a[144:159], v[10:13], v[14:17], a[144:159]
	v_mfma_f32_32x32x16_bf16 a[128:143], v[10:13], v[72:75], a[128:143]
	ds_read_b128 v[10:13], v60 offset:9248
	ds_read_b128 v[84:87], v60 offset:9280
	s_waitcnt lgkmcnt(1)
	v_mfma_f32_32x32x16_bf16 a[64:79], v[10:13], v[14:17], a[64:79]
	v_mfma_f32_32x32x16_bf16 a[48:63], v[10:13], v[72:75], a[48:63]
	ds_read_b128 v[10:13], v61 offset:32
	ds_read_b128 v[88:91], v60 offset:9312
	s_waitcnt lgkmcnt(1)
	v_mfma_f32_32x32x16_bf16 a[32:47], v[10:13], v[14:17], a[32:47]
	v_mfma_f32_32x32x16_bf16 a[16:31], v[10:13], v[72:75], a[16:31]
	ds_read_b128 v[10:13], v62 offset:41536
	ds_read_b128 v[14:17], v62 offset:41568
	v_mfma_f32_32x32x16_bf16 a[176:191], v[68:71], v[64:67], a[176:191]
	s_waitcnt lgkmcnt(1)
	v_mfma_f32_32x32x16_bf16 a[160:175], v[68:71], v[10:13], a[160:175]
	ds_read_b128 v[68:71], v60 offset:4672
	ds_read_b128 v[72:75], v60 offset:4704
	s_waitcnt lgkmcnt(1)
	v_mfma_f32_32x32x16_bf16 a[144:159], v[68:71], v[64:67], a[144:159]
	v_mfma_f32_32x32x16_bf16 a[128:143], v[68:71], v[10:13], a[128:143]
	v_mfma_f32_32x32x16_bf16 a[64:79], v[84:87], v[64:67], a[64:79]
	v_mfma_f32_32x32x16_bf16 a[48:63], v[84:87], v[10:13], a[48:63]
	ds_read_b128 v[68:71], v61 offset:64
	ds_read_b128 v[84:87], v61 offset:96
	s_waitcnt lgkmcnt(0)
	s_barrier
	v_mfma_f32_32x32x16_bf16 a[32:47], v[68:71], v[64:67], a[32:47]
	v_mfma_f32_32x32x16_bf16 a[16:31], v[68:71], v[10:13], a[16:31]
	v_mfma_f32_32x32x16_bf16 a[176:191], v[80:83], v[76:79], a[176:191]
	v_mfma_f32_32x32x16_bf16 a[160:175], v[80:83], v[14:17], a[160:175]
	v_mfma_f32_32x32x16_bf16 a[144:159], v[72:75], v[76:79], a[144:159]
	v_mfma_f32_32x32x16_bf16 a[128:143], v[72:75], v[14:17], a[128:143]
	v_mfma_f32_32x32x16_bf16 a[64:79], v[88:91], v[76:79], a[64:79]
	v_mfma_f32_32x32x16_bf16 a[48:63], v[88:91], v[14:17], a[48:63]
	v_mfma_f32_32x32x16_bf16 a[32:47], v[84:87], v[76:79], a[32:47]
	v_mfma_f32_32x32x16_bf16 a[16:31], v[84:87], v[14:17], a[16:31]
	ds_read_b128 v[10:13], v60 offset:55296
	ds_read_b128 v[14:17], v56
	ds_read_b128 v[64:67], v60 offset:55328
	ds_read_b128 v[68:71], v56 offset:32
	ds_read_b128 v[72:75], v56 offset:4608
	ds_read_b128 v[76:79], v56 offset:4640
	s_waitcnt lgkmcnt(4)
	v_mfma_f32_32x32x16_bf16 a[176:191], v[10:13], v[14:17], a[176:191]
	s_waitcnt lgkmcnt(1)
	v_mfma_f32_32x32x16_bf16 a[160:175], v[10:13], v[72:75], a[160:175]
	ds_read_b128 v[10:13], v60 offset:59904
	ds_read_b128 v[80:83], v60 offset:59936
	s_waitcnt lgkmcnt(1)
	v_mfma_f32_32x32x16_bf16 a[144:159], v[10:13], v[14:17], a[144:159]
	v_mfma_f32_32x32x16_bf16 a[128:143], v[10:13], v[72:75], a[128:143]
	ds_read_b128 v[10:13], v60 offset:64512
	ds_read_b128 v[84:87], v60 offset:64544
	s_waitcnt lgkmcnt(1)
	v_mfma_f32_32x32x16_bf16 a[64:79], v[10:13], v[14:17], a[64:79]
	v_mfma_f32_32x32x16_bf16 a[48:63], v[10:13], v[72:75], a[48:63]
	ds_read_b128 v[10:13], v61 offset:55296
	ds_read_b128 v[88:91], v61 offset:55328
	s_waitcnt lgkmcnt(1)
	v_mfma_f32_32x32x16_bf16 a[32:47], v[10:13], v[14:17], a[32:47]
	v_mfma_f32_32x32x16_bf16 a[16:31], v[10:13], v[72:75], a[16:31]
	ds_read_b128 v[10:13], v60 offset:55360
	v_mfma_f32_32x32x16_bf16 a[176:191], v[64:67], v[68:71], a[176:191]
	v_mfma_f32_32x32x16_bf16 a[160:175], v[64:67], v[76:79], a[160:175]
	v_mfma_f32_32x32x16_bf16 a[144:159], v[80:83], v[68:71], a[144:159]
	v_mfma_f32_32x32x16_bf16 a[128:143], v[80:83], v[76:79], a[128:143]
	v_mfma_f32_32x32x16_bf16 a[64:79], v[84:87], v[68:71], a[64:79]
	v_mfma_f32_32x32x16_bf16 a[48:63], v[84:87], v[76:79], a[48:63]
	ds_read_b128 v[14:17], v56 offset:64
	ds_read_b128 v[64:67], v61 offset:55360
	ds_read_b128 v[72:75], v61 offset:55392
	ds_read_b128 v[80:83], v60 offset:64576
	ds_read_b128 v[84:87], v60 offset:64608
	ds_read_b128 v[92:95], v60 offset:55392
	ds_read_b128 v[96:99], v56 offset:96
	ds_read_b128 v[100:103], v60 offset:59968
	ds_read_b128 v[104:107], v60 offset:60000
	ds_read_b128 v[108:111], v56 offset:4672
	ds_read_b128 v[112:115], v56 offset:4704
	s_waitcnt lgkmcnt(0)
	s_barrier
	v_mfma_f32_32x32x16_bf16 a[32:47], v[88:91], v[68:71], a[32:47]
	v_add_u32_e32 v70, 0x2048, v21
	v_mfma_f32_32x32x16_bf16 a[16:31], v[88:91], v[76:79], a[16:31]
	v_accvgpr_read_b32 v76, a225
	v_accvgpr_read_b32 v77, a226
	v_mfma_f32_32x32x16_bf16 a[176:191], v[10:13], v[14:17], a[176:191]
	v_mfma_f32_32x32x16_bf16 a[160:175], v[10:13], v[108:111], a[160:175]
	v_lshl_add_u64 v[10:11], v[6:7], 0, s[42:43]
	v_mfma_f32_32x32x16_bf16 a[144:159], v[100:103], v[14:17], a[144:159]
	v_mfma_f32_32x32x16_bf16 a[128:143], v[100:103], v[108:111], a[128:143]
	v_mfma_f32_32x32x16_bf16 a[64:79], v[80:83], v[14:17], a[64:79]
	v_mfma_f32_32x32x16_bf16 a[48:63], v[80:83], v[108:111], a[48:63]
	v_mfma_f32_32x32x16_bf16 a[32:47], v[64:67], v[14:17], a[32:47]
	v_mfma_f32_32x32x16_bf16 a[16:31], v[64:67], v[108:111], a[16:31]
	v_add_u32_e32 v66, 0x1028, v21
	v_mfma_f32_32x32x16_bf16 a[176:191], v[92:95], v[96:99], a[176:191]
	s_nop 11
	ds_write_b32 v49, a176
	ds_write_b32 v49, a177 offset:516
	ds_write_b32 v49, a178 offset:1032
	ds_write_b32 v49, a179 offset:1548
	ds_write_b32 v49, a180 offset:4128
	ds_write_b32 v49, a181 offset:4644
	ds_write_b32 v49, a182 offset:5160
	v_mfma_f32_32x32x16_bf16 a[160:175], v[92:95], v[112:115], a[160:175]
	ds_write_b32 v49, a183 offset:5676
	ds_write_b32 v49, a184 offset:8256
	ds_write_b32 v49, a185 offset:8772
	ds_write_b32 v49, a186 offset:9288
	ds_write_b32 v49, a187 offset:9804
	ds_write_b32 v49, a188 offset:12384
	ds_write_b32 v49, a189 offset:12900
	ds_write_b32 v49, a190 offset:13416
	ds_write_b32 v49, a191 offset:13932
	s_nop 2
	ds_write_b32 v49, a160 offset:128
	ds_write_b32 v49, a161 offset:644
	ds_write_b32 v49, a162 offset:1160
	ds_write_b32 v49, a163 offset:1676
	ds_write_b32 v49, a164 offset:4256
	ds_write_b32 v49, a165 offset:4772
	ds_write_b32 v49, a166 offset:5288
	ds_write_b32 v49, a167 offset:5804
	ds_write_b32 v49, a168 offset:8384
	ds_write_b32 v49, a169 offset:8900
	ds_write_b32 v49, a170 offset:9416
	ds_write_b32 v49, a171 offset:9932
	v_mfma_f32_32x32x16_bf16 a[144:159], v[104:107], v[96:99], a[144:159]
	ds_write_b32 v49, a172 offset:12512
	ds_write_b32 v49, a173 offset:13028
	ds_write_b32 v49, a174 offset:13544
	ds_write_b32 v49, a175 offset:14060
	s_nop 7
	ds_write_b32 v49, a144 offset:16512
	ds_write_b32 v49, a145 offset:17028
	ds_write_b32 v49, a146 offset:17544
	ds_write_b32 v49, a147 offset:18060
	ds_write_b32 v49, a148 offset:20640
	ds_write_b32 v49, a149 offset:21156
	ds_write_b32 v49, a150 offset:21672
	ds_write_b32 v49, a151 offset:22188
	ds_write_b32 v49, a152 offset:24768
	ds_write_b32 v49, a153 offset:25284
	v_mfma_f32_32x32x16_bf16 a[128:143], v[104:107], v[112:115], a[128:143]
	ds_write_b32 v49, a154 offset:25800
	ds_write_b32 v49, a155 offset:26316
	ds_write_b32 v49, a156 offset:28896
	ds_write_b32 v49, a157 offset:29412
	ds_write_b32 v49, a158 offset:29928
	ds_write_b32 v49, a159 offset:30444
	s_nop 5
	ds_write_b32 v49, a128 offset:16640
	ds_write_b32 v49, a129 offset:17156
	ds_write_b32 v49, a130 offset:17672
	ds_write_b32 v49, a131 offset:18188
	ds_write_b32 v49, a132 offset:20768
	ds_write_b32 v49, a133 offset:21284
	ds_write_b32 v49, a134 offset:21800
	ds_write_b32 v49, a135 offset:22316
	v_mfma_f32_32x32x16_bf16 a[64:79], v[84:87], v[96:99], a[64:79]
	ds_write_b32 v49, a136 offset:24896
	ds_write_b32 v49, a137 offset:25412
	ds_write_b32 v49, a138 offset:25928
	ds_write_b32 v49, a139 offset:26444
	ds_write_b32 v49, a140 offset:29024
	ds_write_b32 v49, a141 offset:29540
	ds_write_b32 v49, a142 offset:30056
	ds_write_b32 v49, a143 offset:30572
	s_nop 3
	ds_write_b32 v49, a64 offset:33024
	ds_write_b32 v49, a65 offset:33540
	ds_write_b32 v49, a66 offset:34056
	ds_write_b32 v49, a67 offset:34572
	ds_write_b32 v49, a68 offset:37152
	ds_write_b32 v49, a69 offset:37668
	v_mfma_f32_32x32x16_bf16 a[48:63], v[84:87], v[112:115], a[48:63]
	ds_write_b32 v49, a70 offset:38184
	ds_write_b32 v49, a71 offset:38700
	ds_write_b32 v49, a72 offset:41280
	ds_write_b32 v49, a73 offset:41796
	ds_write_b32 v49, a74 offset:42312
	ds_write_b32 v49, a75 offset:42828
	ds_write_b32 v49, a76 offset:45408
	ds_write_b32 v49, a77 offset:45924
	ds_write_b32 v49, a78 offset:46440
	ds_write_b32 v49, a79 offset:46956
	s_nop 1
	ds_write_b32 v49, a48 offset:33152
	ds_write_b32 v49, a49 offset:33668
	ds_write_b32 v49, a50 offset:34184
	ds_write_b32 v49, a51 offset:34700
	ds_write_b32 v49, a52 offset:37280
	ds_write_b32 v49, a53 offset:37796
	ds_write_b32 v49, a54 offset:38312
	ds_write_b32 v49, a55 offset:38828
	ds_write_b32 v49, a56 offset:41408
	ds_write_b32 v49, a57 offset:41924
	ds_write_b32 v49, a58 offset:42440
	v_mfma_f32_32x32x16_bf16 a[32:47], v[72:75], v[96:99], a[32:47]
	ds_write_b32 v49, a59 offset:42956
	ds_write_b32 v49, a60 offset:45536
	ds_write_b32 v49, a61 offset:46052
	ds_write_b32 v49, a62 offset:46568
	ds_write_b32 v49, a63 offset:47084
	s_nop 6
	ds_write_b32 v49, a32 offset:49536
	ds_write_b32 v49, a33 offset:50052
	ds_write_b32 v49, a34 offset:50568
	ds_write_b32 v49, a35 offset:51084
	ds_write_b32 v49, a36 offset:53664
	ds_write_b32 v49, a37 offset:54180
	ds_write_b32 v49, a38 offset:54696
	ds_write_b32 v49, a39 offset:55212
	ds_write_b32 v49, a40 offset:57792
	v_mfma_f32_32x32x16_bf16 a[16:31], v[72:75], v[112:115], a[16:31]
	ds_write_b32 v49, a41 offset:58308
	ds_write_b32 v49, a42 offset:58824
	ds_write_b32 v49, a43 offset:59340
	ds_write_b32 v49, a44 offset:61920
	ds_write_b32 v49, a45 offset:62436
	ds_write_b32 v49, a46 offset:62952
	ds_write_b32 v49, a47 offset:63468
	s_nop 4
	ds_write_b32 v49, a16 offset:49664
	ds_write_b32 v49, a17 offset:50180
	ds_write_b32 v49, a18 offset:50696
	ds_write_b32 v49, a19 offset:51212
	ds_write_b32 v49, a20 offset:53792
	ds_write_b32 v49, a21 offset:54308
	ds_write_b32 v49, a22 offset:54824
	ds_write_b32 v49, a23 offset:55340
	ds_write_b32 v49, a24 offset:57920
	ds_write_b32 v49, a25 offset:58436
	ds_write_b32 v49, a26 offset:58952
	ds_write_b32 v49, a27 offset:59468
	ds_write_b32 v49, a28 offset:62048
	ds_write_b32 v49, a29 offset:62564
	ds_write_b32 v49, a30 offset:63080
	ds_write_b32 v49, a31 offset:63596
	s_waitcnt lgkmcnt(0)
	s_barrier
	ds_read2_b32 v[16:17], v21 offset1:1
	ds_read2_b32 v[18:19], v21 offset0:2 offset1:3
	v_accvgpr_read_b32 v72, a218
	v_or_b32_e32 v0, s44, v72
	v_lshlrev_b32_e32 v0, 11, v0
	s_waitcnt lgkmcnt(1)
	v_cvt_pk_bf16_f32 v16, v16, v17
	s_waitcnt lgkmcnt(0)
	v_cvt_pk_bf16_f32 v17, v18, v19
	v_lshl_add_u64 v[18:19], v[10:11], 0, v[0:1]
	v_add_u32_e32 v0, 0x1020, v21
	ds_read2_b32 v[12:13], v29 offset1:1
	ds_read2_b32 v[14:15], v29 offset0:2 offset1:3
	ds_read2_b32 v[64:65], v0 offset1:1
	ds_read2_b32 v[66:67], v66 offset1:1
	v_accvgpr_read_b32 v73, a219
	v_or_b32_e32 v0, s44, v73
	v_lshlrev_b32_e32 v0, 11, v0
	global_store_dwordx2 v[18:19], v[16:17], off
	s_waitcnt lgkmcnt(1)
	v_cvt_pk_bf16_f32 v64, v64, v65
	s_waitcnt lgkmcnt(0)
	v_cvt_pk_bf16_f32 v65, v66, v67
	v_lshl_add_u64 v[66:67], v[10:11], 0, v[0:1]
	v_add_u32_e32 v0, 0x2040, v21
	ds_read2_b32 v[16:17], v44 offset1:1
	ds_read2_b32 v[18:19], v44 offset0:2 offset1:3
	ds_read2_b32 v[68:69], v0 offset1:1
	ds_read2_b32 v[70:71], v70 offset1:1
	global_store_dwordx2 v[66:67], v[64:65], off
	v_add_u32_e32 v0, 0x3060, v21
	v_add_u32_e32 v66, 0x3068, v21
	ds_read2_b32 v[64:65], v0 offset1:1
	ds_read2_b32 v[66:67], v66 offset1:1
	v_or_b32_e32 v0, s44, v136
	v_lshlrev_b32_e32 v0, 11, v0
	s_waitcnt lgkmcnt(3)
	v_cvt_pk_bf16_f32 v68, v68, v69
	s_waitcnt lgkmcnt(2)
	v_cvt_pk_bf16_f32 v69, v70, v71
	v_lshl_add_u64 v[70:71], v[10:11], 0, v[0:1]
	v_or_b32_e32 v0, s44, v137
	v_lshlrev_b32_e32 v0, 11, v0
	global_store_dwordx2 v[70:71], v[68:69], off
	s_waitcnt lgkmcnt(1)
	v_cvt_pk_bf16_f32 v64, v64, v65
	s_waitcnt lgkmcnt(0)
	v_cvt_pk_bf16_f32 v65, v66, v67
	v_lshl_add_u64 v[66:67], v[10:11], 0, v[0:1]
	v_add_u32_e32 v0, 0x4080, v21
	v_add_u32_e32 v70, 0x4088, v21
	ds_read2_b32 v[68:69], v0 offset1:1
	ds_read2_b32 v[70:71], v70 offset1:1
	global_store_dwordx2 v[66:67], v[64:65], off
	v_add_u32_e32 v0, 0x50a0, v21
	v_add_u32_e32 v66, 0x50a8, v21
	ds_read2_b32 v[64:65], v0 offset1:1
	ds_read2_b32 v[66:67], v66 offset1:1
	v_or_b32_e32 v0, s44, v139
	v_lshlrev_b32_e32 v0, 11, v0
	v_accvgpr_read_b32 v74, a223
	s_waitcnt lgkmcnt(3)
	v_cvt_pk_bf16_f32 v68, v68, v69
	s_waitcnt lgkmcnt(2)
	v_cvt_pk_bf16_f32 v69, v70, v71
	v_lshl_add_u64 v[70:71], v[10:11], 0, v[0:1]
	v_or_b32_e32 v0, s44, v74
	v_lshlrev_b32_e32 v0, 11, v0
	global_store_dwordx2 v[70:71], v[68:69], off
	s_waitcnt lgkmcnt(1)
	v_cvt_pk_bf16_f32 v64, v64, v65
	s_waitcnt lgkmcnt(0)
	v_cvt_pk_bf16_f32 v65, v66, v67
	v_lshl_add_u64 v[66:67], v[10:11], 0, v[0:1]
	v_add_u32_e32 v0, 0x60c0, v21
	v_add_u32_e32 v70, 0x60c8, v21
	ds_read2_b32 v[68:69], v0 offset1:1
	ds_read2_b32 v[70:71], v70 offset1:1
	global_store_dwordx2 v[66:67], v[64:65], off
	v_add_u32_e32 v0, 0x70e0, v21
	v_add_u32_e32 v66, 0x70e8, v21
	ds_read2_b32 v[64:65], v0 offset1:1
	ds_read2_b32 v[66:67], v66 offset1:1
	v_accvgpr_read_b32 v75, a224
	v_or_b32_e32 v0, s44, v75
	v_lshlrev_b32_e32 v0, 11, v0
	s_waitcnt lgkmcnt(3)
	v_cvt_pk_bf16_f32 v68, v68, v69
	s_waitcnt lgkmcnt(2)
	v_cvt_pk_bf16_f32 v69, v70, v71
	v_lshl_add_u64 v[70:71], v[10:11], 0, v[0:1]
	v_or_b32_e32 v0, s44, v76
	v_lshlrev_b32_e32 v0, 11, v0
	global_store_dwordx2 v[70:71], v[68:69], off
	s_waitcnt lgkmcnt(1)
	v_cvt_pk_bf16_f32 v64, v64, v65
	s_waitcnt lgkmcnt(0)
	v_cvt_pk_bf16_f32 v65, v66, v67
	v_lshl_add_u64 v[66:67], v[10:11], 0, v[0:1]
	v_add_u32_e32 v0, 0x8100, v21
	v_add_u32_e32 v70, 0x8108, v21
	ds_read2_b32 v[68:69], v0 offset1:1
	ds_read2_b32 v[70:71], v70 offset1:1
	global_store_dwordx2 v[66:67], v[64:65], off
	v_add_u32_e32 v0, 0x9120, v21
	v_add_u32_e32 v66, 0x9128, v21
	ds_read2_b32 v[64:65], v0 offset1:1
	ds_read2_b32 v[66:67], v66 offset1:1
	v_or_b32_e32 v0, s44, v77
	v_lshlrev_b32_e32 v0, 11, v0
	s_waitcnt lgkmcnt(3)
	v_cvt_pk_bf16_f32 v68, v68, v69
	s_waitcnt lgkmcnt(2)
	v_cvt_pk_bf16_f32 v69, v70, v71
	v_lshl_add_u64 v[70:71], v[10:11], 0, v[0:1]
	v_or_b32_e32 v0, s44, v22
	v_lshlrev_b32_e32 v0, 11, v0
	global_store_dwordx2 v[70:71], v[68:69], off
	s_waitcnt lgkmcnt(1)
	v_cvt_pk_bf16_f32 v64, v64, v65
	s_waitcnt lgkmcnt(0)
	v_cvt_pk_bf16_f32 v65, v66, v67
	v_lshl_add_u64 v[66:67], v[10:11], 0, v[0:1]
	v_add_u32_e32 v0, 0xa140, v21
	v_add_u32_e32 v70, 0xa148, v21
	ds_read2_b32 v[68:69], v0 offset1:1
	ds_read2_b32 v[70:71], v70 offset1:1
	global_store_dwordx2 v[66:67], v[64:65], off
	v_add_u32_e32 v0, 0xb160, v21
	v_add_u32_e32 v66, 0xb168, v21
	ds_read2_b32 v[64:65], v0 offset1:1
	ds_read2_b32 v[66:67], v66 offset1:1
	v_or_b32_e32 v0, s44, v23
	v_lshlrev_b32_e32 v0, 11, v0
	s_waitcnt lgkmcnt(3)
	v_cvt_pk_bf16_f32 v68, v68, v69
	s_waitcnt lgkmcnt(2)
	v_cvt_pk_bf16_f32 v69, v70, v71
	v_lshl_add_u64 v[70:71], v[10:11], 0, v[0:1]
	v_or_b32_e32 v0, s44, v24
	v_lshlrev_b32_e32 v0, 11, v0
	global_store_dwordx2 v[70:71], v[68:69], off
	s_waitcnt lgkmcnt(1)
	v_cvt_pk_bf16_f32 v64, v64, v65
	s_waitcnt lgkmcnt(0)
	v_cvt_pk_bf16_f32 v65, v66, v67
	v_lshl_add_u64 v[66:67], v[10:11], 0, v[0:1]
	v_add_u32_e32 v0, 0xc180, v21
	v_add_u32_e32 v70, 0xc188, v21
	ds_read2_b32 v[68:69], v0 offset1:1
	ds_read2_b32 v[70:71], v70 offset1:1
	global_store_dwordx2 v[66:67], v[64:65], off
	v_add_u32_e32 v0, 0xd1a0, v21
	v_add_u32_e32 v66, 0xd1a8, v21
	ds_read2_b32 v[64:65], v0 offset1:1
	ds_read2_b32 v[66:67], v66 offset1:1
	v_or_b32_e32 v0, s44, v25
	v_lshlrev_b32_e32 v0, 11, v0
	s_waitcnt lgkmcnt(3)
	v_cvt_pk_bf16_f32 v68, v68, v69
	s_waitcnt lgkmcnt(2)
	v_cvt_pk_bf16_f32 v69, v70, v71
	v_lshl_add_u64 v[70:71], v[10:11], 0, v[0:1]
	v_or_b32_e32 v0, s44, v26
	v_lshlrev_b32_e32 v0, 11, v0
	global_store_dwordx2 v[70:71], v[68:69], off
	s_waitcnt lgkmcnt(1)
	v_cvt_pk_bf16_f32 v64, v64, v65
	s_waitcnt lgkmcnt(0)
	v_cvt_pk_bf16_f32 v65, v66, v67
	v_lshl_add_u64 v[66:67], v[10:11], 0, v[0:1]
	v_add_u32_e32 v0, 0xe1c0, v21
	v_add_u32_e32 v70, 0xe1c8, v21
	ds_read2_b32 v[68:69], v0 offset1:1
	ds_read2_b32 v[70:71], v70 offset1:1
	global_store_dwordx2 v[66:67], v[64:65], off
	v_add_u32_e32 v0, 0xf1e0, v21
	v_add_u32_e32 v66, 0xf1e8, v21
	ds_read2_b32 v[64:65], v0 offset1:1
	ds_read2_b32 v[66:67], v66 offset1:1
	v_or_b32_e32 v0, s44, v27
	v_lshlrev_b32_e32 v0, 11, v0
	s_waitcnt lgkmcnt(3)
	v_cvt_pk_bf16_f32 v68, v68, v69
	s_waitcnt lgkmcnt(2)
	v_cvt_pk_bf16_f32 v69, v70, v71
	v_lshl_add_u64 v[70:71], v[10:11], 0, v[0:1]
	v_or_b32_e32 v0, s44, v28
	v_lshlrev_b32_e32 v0, 11, v0
	s_bitset1_b32 s44, 7
	s_waitcnt lgkmcnt(1)
	v_cvt_pk_bf16_f32 v64, v64, v65
	s_waitcnt lgkmcnt(0)
	v_cvt_pk_bf16_f32 v65, v66, v67
	v_lshl_add_u64 v[66:67], v[10:11], 0, v[0:1]
	v_or_b32_e32 v0, s44, v72
	global_store_dwordx2 v[70:71], v[68:69], off
	global_store_dwordx2 v[66:67], v[64:65], off
	v_lshlrev_b32_e32 v0, 11, v0
	v_cvt_pk_bf16_f32 v12, v12, v13
	v_cvt_pk_bf16_f32 v13, v14, v15
	v_lshl_add_u64 v[14:15], v[10:11], 0, v[0:1]
	ds_read2_b32 v[64:65], v30 offset1:1
	ds_read2_b32 v[66:67], v30 offset0:2 offset1:3
	global_store_dwordx2 v[14:15], v[12:13], off
	ds_read2_b32 v[12:13], v31 offset1:1
	ds_read2_b32 v[14:15], v31 offset0:2 offset1:3
	v_or_b32_e32 v0, s44, v73
	v_lshlrev_b32_e32 v0, 11, v0
	s_waitcnt lgkmcnt(3)
	v_cvt_pk_bf16_f32 v64, v64, v65
	s_waitcnt lgkmcnt(2)
	v_cvt_pk_bf16_f32 v65, v66, v67
	v_lshl_add_u64 v[66:67], v[10:11], 0, v[0:1]
	v_or_b32_e32 v0, s44, v136
	global_store_dwordx2 v[66:67], v[64:65], off
	v_lshlrev_b32_e32 v0, 11, v0
	s_waitcnt lgkmcnt(1)
	v_cvt_pk_bf16_f32 v12, v12, v13
	s_waitcnt lgkmcnt(0)
	v_cvt_pk_bf16_f32 v13, v14, v15
	v_lshl_add_u64 v[14:15], v[10:11], 0, v[0:1]
	ds_read2_b32 v[64:65], v32 offset1:1
	ds_read2_b32 v[66:67], v32 offset0:2 offset1:3
	global_store_dwordx2 v[14:15], v[12:13], off
	ds_read2_b32 v[12:13], v33 offset1:1
	ds_read2_b32 v[14:15], v33 offset0:2 offset1:3
	v_or_b32_e32 v0, s44, v137
	v_lshlrev_b32_e32 v0, 11, v0
	s_waitcnt lgkmcnt(3)
	v_cvt_pk_bf16_f32 v64, v64, v65
	s_waitcnt lgkmcnt(2)
	v_cvt_pk_bf16_f32 v65, v66, v67
	v_lshl_add_u64 v[66:67], v[10:11], 0, v[0:1]
	v_or_b32_e32 v0, s44, v139
	global_store_dwordx2 v[66:67], v[64:65], off
	v_lshlrev_b32_e32 v0, 11, v0
	s_waitcnt lgkmcnt(1)
	v_cvt_pk_bf16_f32 v12, v12, v13
	s_waitcnt lgkmcnt(0)
	v_cvt_pk_bf16_f32 v13, v14, v15
	v_lshl_add_u64 v[14:15], v[10:11], 0, v[0:1]
	ds_read2_b32 v[64:65], v34 offset1:1
	ds_read2_b32 v[66:67], v34 offset0:2 offset1:3
	global_store_dwordx2 v[14:15], v[12:13], off
	ds_read2_b32 v[12:13], v35 offset1:1
	ds_read2_b32 v[14:15], v35 offset0:2 offset1:3
	v_or_b32_e32 v0, s44, v74
	v_lshlrev_b32_e32 v0, 11, v0
	s_waitcnt lgkmcnt(3)
	v_cvt_pk_bf16_f32 v64, v64, v65
	s_waitcnt lgkmcnt(2)
	v_cvt_pk_bf16_f32 v65, v66, v67
	v_lshl_add_u64 v[66:67], v[10:11], 0, v[0:1]
	v_or_b32_e32 v0, s44, v75
	global_store_dwordx2 v[66:67], v[64:65], off
	v_lshlrev_b32_e32 v0, 11, v0
	s_waitcnt lgkmcnt(1)
	v_cvt_pk_bf16_f32 v12, v12, v13
	s_waitcnt lgkmcnt(0)
	v_cvt_pk_bf16_f32 v13, v14, v15
	v_lshl_add_u64 v[14:15], v[10:11], 0, v[0:1]
	ds_read2_b32 v[64:65], v36 offset1:1
	ds_read2_b32 v[66:67], v36 offset0:2 offset1:3
	global_store_dwordx2 v[14:15], v[12:13], off
	ds_read2_b32 v[12:13], v37 offset1:1
	ds_read2_b32 v[14:15], v37 offset0:2 offset1:3
	v_or_b32_e32 v0, s44, v76
	v_lshlrev_b32_e32 v0, 11, v0
	s_waitcnt lgkmcnt(3)
	v_cvt_pk_bf16_f32 v64, v64, v65
	s_waitcnt lgkmcnt(2)
	v_cvt_pk_bf16_f32 v65, v66, v67
	v_lshl_add_u64 v[66:67], v[10:11], 0, v[0:1]
	v_or_b32_e32 v0, s44, v77
	global_store_dwordx2 v[66:67], v[64:65], off
	v_lshlrev_b32_e32 v0, 11, v0
	s_waitcnt lgkmcnt(1)
	v_cvt_pk_bf16_f32 v12, v12, v13
	s_waitcnt lgkmcnt(0)
	v_cvt_pk_bf16_f32 v13, v14, v15
	v_lshl_add_u64 v[14:15], v[10:11], 0, v[0:1]
	ds_read2_b32 v[64:65], v38 offset1:1
	ds_read2_b32 v[66:67], v38 offset0:2 offset1:3
	global_store_dwordx2 v[14:15], v[12:13], off
	ds_read2_b32 v[12:13], v39 offset1:1
	ds_read2_b32 v[14:15], v39 offset0:2 offset1:3
	v_or_b32_e32 v0, s44, v22
	v_lshlrev_b32_e32 v0, 11, v0
	s_waitcnt lgkmcnt(3)
	v_cvt_pk_bf16_f32 v64, v64, v65
	s_waitcnt lgkmcnt(2)
	v_cvt_pk_bf16_f32 v65, v66, v67
	v_lshl_add_u64 v[66:67], v[10:11], 0, v[0:1]
	v_or_b32_e32 v0, s44, v23
	global_store_dwordx2 v[66:67], v[64:65], off
	v_lshlrev_b32_e32 v0, 11, v0
	s_waitcnt lgkmcnt(1)
	v_cvt_pk_bf16_f32 v12, v12, v13
	s_waitcnt lgkmcnt(0)
	v_cvt_pk_bf16_f32 v13, v14, v15
	v_lshl_add_u64 v[14:15], v[10:11], 0, v[0:1]
	ds_read2_b32 v[64:65], v40 offset1:1
	ds_read2_b32 v[66:67], v40 offset0:2 offset1:3
	global_store_dwordx2 v[14:15], v[12:13], off
	ds_read2_b32 v[12:13], v41 offset1:1
	ds_read2_b32 v[14:15], v41 offset0:2 offset1:3
	v_or_b32_e32 v0, s44, v24
	v_lshlrev_b32_e32 v0, 11, v0
	s_waitcnt lgkmcnt(3)
	v_cvt_pk_bf16_f32 v64, v64, v65
	s_waitcnt lgkmcnt(2)
	v_cvt_pk_bf16_f32 v65, v66, v67
	v_lshl_add_u64 v[66:67], v[10:11], 0, v[0:1]
	v_or_b32_e32 v0, s44, v25
	v_lshlrev_b32_e32 v0, 11, v0
	global_store_dwordx2 v[66:67], v[64:65], off
	s_waitcnt lgkmcnt(1)
	v_cvt_pk_bf16_f32 v12, v12, v13
	s_waitcnt lgkmcnt(0)
	v_cvt_pk_bf16_f32 v13, v14, v15
	v_lshl_add_u64 v[14:15], v[10:11], 0, v[0:1]
	ds_read2_b32 v[64:65], v42 offset1:1
	ds_read2_b32 v[66:67], v42 offset0:2 offset1:3
	global_store_dwordx2 v[14:15], v[12:13], off
	ds_read2_b32 v[12:13], v43 offset1:1
	ds_read2_b32 v[14:15], v43 offset0:2 offset1:3
	v_add_lshl_u32 v0, s44, v26, 11
	s_waitcnt lgkmcnt(3)
	v_cvt_pk_bf16_f32 v64, v64, v65
	s_waitcnt lgkmcnt(2)
	v_cvt_pk_bf16_f32 v65, v66, v67
	v_lshl_add_u64 v[66:67], v[10:11], 0, v[0:1]
	v_add_lshl_u32 v0, s44, v27, 11
	s_waitcnt lgkmcnt(1)
	v_cvt_pk_bf16_f32 v12, v12, v13
	s_waitcnt lgkmcnt(0)
	v_cvt_pk_bf16_f32 v13, v14, v15
	v_lshl_add_u64 v[14:15], v[10:11], 0, v[0:1]
	v_add_lshl_u32 v0, s44, v28, 11
	global_store_dwordx2 v[14:15], v[12:13], off
	v_cvt_pk_bf16_f32 v12, v16, v17
	v_cvt_pk_bf16_f32 v13, v18, v19
	v_lshl_add_u64 v[10:11], v[10:11], 0, v[0:1]
	s_cmpk_lt_u32 s47, 0x60
	global_store_dwordx2 v[66:67], v[64:65], off
	global_store_dwordx2 v[10:11], v[12:13], off
	s_barrier
	s_cbranch_scc1 .LBB0_2448
